# GEMM K-loops: LDS-DMA source addresses formed on the scalar unit (saddr + 32-bit voffset), 27 VALU per iteration removed
# baseline (speedup 1.0000x reference)
.LBB0_169:
	v_cmp_gt_i32_e32 vcc, 1, v138
	s_cbranch_vccnz .LBB0_231
	v_lshl_add_u64 v[152:153], v[2:3], 0, s[22:23]
	v_add_u32_e32 v154, -2, v138
	s_waitcnt lgkmcnt(0)
	v_lshl_add_u64 v[150:151], v[4:5], 0, s[28:29]
	s_mov_b32 s7, 0
	s_nop 0
	v_readfirstlane_b32 s86, v152
	v_readfirstlane_b32 s87, v153
	v_readfirstlane_b32 s88, v150
	v_readfirstlane_b32 s89, v151
	v_readfirstlane_b32 s90, v146
	v_readfirstlane_b32 s91, v147
	v_readfirstlane_b32 s92, v148
	v_readfirstlane_b32 s93, v149
	v_readfirstlane_b32 s100, v154
	s_add_u32 s98, s86, 0xfffc0080
	s_addc_u32 s99, s87, -1
	s_cmp_eq_u32 s7, s100
	s_cselect_b64 s[94:95], s[90:91], s[98:99]
	s_cselect_b64 s[96:97], s[92:93], s[88:89]
	v_add_u32_e32 v155, s76, v141
	ds_read_b128 v[164:167], v155
	ds_read_b128 v[168:171], v155 offset:1024
	ds_read_b128 v[172:175], v155 offset:2048
	ds_read_b128 v[176:179], v155 offset:3072
	v_add_u32_e32 v155, s77, v141
	ds_read_b128 v[180:183], v155
	ds_read_b128 v[184:187], v155 offset:1024
	ds_read_b128 v[188:191], v155 offset:2048
	ds_read_b128 v[192:195], v155 offset:3072
	s_add_i32 s51, s7, 2
	s_nop 0
	s_mov_b32 m0, s78
	ds_read_b128 v[196:199], v160
	ds_read_b128 v[200:203], v160 offset:1024
	ds_read_b128 v[204:207], v160 offset:2048
	ds_read_b128 v[208:211], v160 offset:3072
	ds_read_b128 v[212:215], v160 offset:4096
	ds_read_b128 v[216:219], v160 offset:5120
	ds_read_b128 v[220:223], v160 offset:6144
	ds_read_b128 v[224:227], v160 offset:7168
	global_load_lds_dwordx4 v144, s[86:87]
	s_mov_b32 m0, s79
	s_nop 0
	global_load_lds_dwordx4 v142, s[86:87]
	s_waitcnt vmcnt(8)
	s_waitcnt lgkmcnt(0)
	s_barrier
	s_setprio 1
	s_waitcnt lgkmcnt(0)
	v_mfma_f32_16x16x32_bf16 v[122:125], v[164:167], v[196:199], 0
	v_mfma_f32_16x16x32_bf16 v[118:121], v[172:175], v[196:199], 0
	v_mfma_f32_16x16x32_bf16 v[110:113], v[164:167], v[204:207], 0
	v_mfma_f32_16x16x32_bf16 v[102:105], v[172:175], v[204:207], 0
	v_mfma_f32_16x16x32_bf16 v[94:97], v[164:167], v[212:215], 0
	v_mfma_f32_16x16x32_bf16 v[86:89], v[172:175], v[212:215], 0
	v_mfma_f32_16x16x32_bf16 v[78:81], v[164:167], v[220:223], 0
	v_mfma_f32_16x16x32_bf16 v[70:73], v[172:175], v[220:223], 0
	v_mfma_f32_16x16x32_bf16 v[122:125], v[168:171], v[200:203], v[122:125]
	v_mfma_f32_16x16x32_bf16 v[118:121], v[176:179], v[200:203], v[118:121]
	v_mfma_f32_16x16x32_bf16 v[110:113], v[168:171], v[208:211], v[110:113]
	v_mfma_f32_16x16x32_bf16 v[102:105], v[176:179], v[208:211], v[102:105]
	v_mfma_f32_16x16x32_bf16 v[94:97], v[168:171], v[216:219], v[94:97]
	v_mfma_f32_16x16x32_bf16 v[86:89], v[176:179], v[216:219], v[86:89]
	v_mfma_f32_16x16x32_bf16 v[78:81], v[168:171], v[224:227], v[78:81]
	v_mfma_f32_16x16x32_bf16 v[70:73], v[176:179], v[224:227], v[70:73]
	s_setprio 0
	s_setprio 1
	v_mfma_f32_16x16x32_bf16 v[126:129], v[180:183], v[196:199], 0
	v_mfma_f32_16x16x32_bf16 v[114:117], v[188:191], v[196:199], 0
	v_mfma_f32_16x16x32_bf16 v[106:109], v[180:183], v[204:207], 0
	v_mfma_f32_16x16x32_bf16 v[98:101], v[188:191], v[204:207], 0
	v_mfma_f32_16x16x32_bf16 v[90:93], v[180:183], v[212:215], 0
	v_mfma_f32_16x16x32_bf16 v[82:85], v[188:191], v[212:215], 0
	v_mfma_f32_16x16x32_bf16 v[74:77], v[180:183], v[220:223], 0
	v_mfma_f32_16x16x32_bf16 v[66:69], v[188:191], v[220:223], 0
	v_mfma_f32_16x16x32_bf16 v[126:129], v[184:187], v[200:203], v[126:129]
	v_mfma_f32_16x16x32_bf16 v[114:117], v[192:195], v[200:203], v[114:117]
	v_mfma_f32_16x16x32_bf16 v[106:109], v[184:187], v[208:211], v[106:109]
	v_mfma_f32_16x16x32_bf16 v[98:101], v[192:195], v[208:211], v[98:101]
	v_mfma_f32_16x16x32_bf16 v[90:93], v[184:187], v[216:219], v[90:93]
	v_mfma_f32_16x16x32_bf16 v[82:85], v[192:195], v[216:219], v[82:85]
	v_mfma_f32_16x16x32_bf16 v[74:77], v[184:187], v[224:227], v[74:77]
	v_mfma_f32_16x16x32_bf16 v[66:69], v[192:195], v[224:227], v[66:69]
	s_setprio 0
	s_barrier
	s_add_u32 s98, s96, 0x40000
	s_addc_u32 s99, s97, 0
	s_mov_b32 m0, s80
	ds_read_b128 v[196:199], v160 offset:16384
	ds_read_b128 v[200:203], v160 offset:17408
	ds_read_b128 v[204:207], v160 offset:18432
	ds_read_b128 v[208:211], v160 offset:19456
	ds_read_b128 v[212:215], v160 offset:20480
	ds_read_b128 v[216:219], v160 offset:21504
	ds_read_b128 v[220:223], v160 offset:22528
	ds_read_b128 v[224:227], v160 offset:23552
	global_load_lds_dwordx4 v132, s[96:97]
	s_mov_b32 m0, s81
	s_add_i32 s7, s77, s47
	global_load_lds_dwordx4 v136, s[96:97]
	s_mov_b32 m0, s7
	s_nop 0
	global_load_lds_dwordx4 v132, s[98:99]
	s_add_i32 m0, s7, 0x2000
	s_nop 0
	global_load_lds_dwordx4 v136, s[98:99]
	s_mov_b32 m0, s57
	s_nop 0
	global_load_lds_dwordx4 v130, s[94:95]
	s_mov_b32 m0, s62
	s_nop 0
	global_load_lds_dwordx4 v134, s[94:95]
	s_waitcnt vmcnt(8)
	s_waitcnt lgkmcnt(0)
	s_barrier
	s_setprio 1
	s_waitcnt lgkmcnt(0)
	v_mfma_f32_16x16x32_bf16 v[62:65], v[164:167], v[196:199], 0
	v_mfma_f32_16x16x32_bf16 v[54:57], v[172:175], v[196:199], 0
	v_mfma_f32_16x16x32_bf16 v[46:49], v[164:167], v[204:207], 0
	v_mfma_f32_16x16x32_bf16 v[38:41], v[172:175], v[204:207], 0
	v_mfma_f32_16x16x32_bf16 v[30:33], v[164:167], v[212:215], 0
	v_mfma_f32_16x16x32_bf16 v[22:25], v[172:175], v[212:215], 0
	v_mfma_f32_16x16x32_bf16 v[14:17], v[164:167], v[220:223], 0
	v_mfma_f32_16x16x32_bf16 v[6:9], v[172:175], v[220:223], 0
	v_mfma_f32_16x16x32_bf16 v[62:65], v[168:171], v[200:203], v[62:65]
	v_mfma_f32_16x16x32_bf16 v[54:57], v[176:179], v[200:203], v[54:57]
	v_mfma_f32_16x16x32_bf16 v[46:49], v[168:171], v[208:211], v[46:49]
	v_mfma_f32_16x16x32_bf16 v[38:41], v[176:179], v[208:211], v[38:41]
	v_mfma_f32_16x16x32_bf16 v[30:33], v[168:171], v[216:219], v[30:33]
	v_mfma_f32_16x16x32_bf16 v[22:25], v[176:179], v[216:219], v[22:25]
	v_mfma_f32_16x16x32_bf16 v[14:17], v[168:171], v[224:227], v[14:17]
	v_mfma_f32_16x16x32_bf16 v[6:9], v[176:179], v[224:227], v[6:9]
	s_setprio 0
	s_setprio 1
	v_mfma_f32_16x16x32_bf16 v[58:61], v[180:183], v[196:199], 0
	v_mfma_f32_16x16x32_bf16 v[50:53], v[188:191], v[196:199], 0
	v_mfma_f32_16x16x32_bf16 v[42:45], v[180:183], v[204:207], 0
	v_mfma_f32_16x16x32_bf16 v[34:37], v[188:191], v[204:207], 0
	v_mfma_f32_16x16x32_bf16 v[26:29], v[180:183], v[212:215], 0
	v_mfma_f32_16x16x32_bf16 v[18:21], v[188:191], v[212:215], 0
	v_mfma_f32_16x16x32_bf16 v[10:13], v[180:183], v[220:223], 0
	v_mfma_f32_16x16x32_bf16 v[2:5], v[188:191], v[220:223], 0
	v_mfma_f32_16x16x32_bf16 v[58:61], v[184:187], v[200:203], v[58:61]
	v_mfma_f32_16x16x32_bf16 v[50:53], v[192:195], v[200:203], v[50:53]
	v_mfma_f32_16x16x32_bf16 v[42:45], v[184:187], v[208:211], v[42:45]
	v_mfma_f32_16x16x32_bf16 v[34:37], v[192:195], v[208:211], v[34:37]
	v_mfma_f32_16x16x32_bf16 v[26:29], v[184:187], v[216:219], v[26:29]
	v_mfma_f32_16x16x32_bf16 v[18:21], v[192:195], v[216:219], v[18:21]
	v_mfma_f32_16x16x32_bf16 v[10:13], v[184:187], v[224:227], v[10:13]
	v_mfma_f32_16x16x32_bf16 v[2:5], v[192:195], v[224:227], v[2:5]
	s_setprio 0
	s_barrier
	s_add_u32 s98, s94, 0x40000
	s_addc_u32 s99, s95, 0
	s_add_i32 s7, 0, 0x18000
	v_add_u32_e32 v155, s7, v141
	s_add_i32 s55, 0, 0x1c000
	ds_read_b128 v[164:167], v155
	ds_read_b128 v[168:171], v155 offset:1024
	ds_read_b128 v[172:175], v155 offset:2048
	ds_read_b128 v[176:179], v155 offset:3072
	v_add_u32_e32 v155, s55, v141
	ds_read_b128 v[180:183], v155
	ds_read_b128 v[184:187], v155 offset:1024
	ds_read_b128 v[188:191], v155 offset:2048
	ds_read_b128 v[192:195], v155 offset:3072
	s_mov_b32 m0, s63
	ds_read_b128 v[196:199], v160 offset:32768
	ds_read_b128 v[200:203], v160 offset:33792
	ds_read_b128 v[204:207], v160 offset:34816
	ds_read_b128 v[208:211], v160 offset:35840
	ds_read_b128 v[212:215], v160 offset:36864
	ds_read_b128 v[216:219], v160 offset:37888
	ds_read_b128 v[220:223], v160 offset:38912
	ds_read_b128 v[224:227], v160 offset:39936
	global_load_lds_dwordx4 v130, s[98:99]
	s_mov_b32 m0, s64
	s_nop 0
	global_load_lds_dwordx4 v134, s[98:99]
	s_waitcnt vmcnt(8)
	s_waitcnt lgkmcnt(0)
	s_barrier
	s_setprio 1
	s_waitcnt lgkmcnt(0)
	v_mfma_f32_16x16x32_bf16 v[122:125], v[164:167], v[196:199], v[122:125]
	v_mfma_f32_16x16x32_bf16 v[118:121], v[172:175], v[196:199], v[118:121]
	v_mfma_f32_16x16x32_bf16 v[110:113], v[164:167], v[204:207], v[110:113]
	v_mfma_f32_16x16x32_bf16 v[102:105], v[172:175], v[204:207], v[102:105]
	v_mfma_f32_16x16x32_bf16 v[94:97], v[164:167], v[212:215], v[94:97]
	v_mfma_f32_16x16x32_bf16 v[86:89], v[172:175], v[212:215], v[86:89]
	v_mfma_f32_16x16x32_bf16 v[78:81], v[164:167], v[220:223], v[78:81]
	v_mfma_f32_16x16x32_bf16 v[70:73], v[172:175], v[220:223], v[70:73]
	v_mfma_f32_16x16x32_bf16 v[122:125], v[168:171], v[200:203], v[122:125]
	v_mfma_f32_16x16x32_bf16 v[118:121], v[176:179], v[200:203], v[118:121]
	v_mfma_f32_16x16x32_bf16 v[110:113], v[168:171], v[208:211], v[110:113]
	v_mfma_f32_16x16x32_bf16 v[102:105], v[176:179], v[208:211], v[102:105]
	v_mfma_f32_16x16x32_bf16 v[94:97], v[168:171], v[216:219], v[94:97]
	v_mfma_f32_16x16x32_bf16 v[86:89], v[176:179], v[216:219], v[86:89]
	v_mfma_f32_16x16x32_bf16 v[78:81], v[168:171], v[224:227], v[78:81]
	v_mfma_f32_16x16x32_bf16 v[70:73], v[176:179], v[224:227], v[70:73]
	s_setprio 0
	s_setprio 1
	v_mfma_f32_16x16x32_bf16 v[126:129], v[180:183], v[196:199], v[126:129]
	v_mfma_f32_16x16x32_bf16 v[114:117], v[188:191], v[196:199], v[114:117]
	v_mfma_f32_16x16x32_bf16 v[106:109], v[180:183], v[204:207], v[106:109]
	v_mfma_f32_16x16x32_bf16 v[98:101], v[188:191], v[204:207], v[98:101]
	v_mfma_f32_16x16x32_bf16 v[90:93], v[180:183], v[212:215], v[90:93]
	v_mfma_f32_16x16x32_bf16 v[82:85], v[188:191], v[212:215], v[82:85]
	v_mfma_f32_16x16x32_bf16 v[74:77], v[180:183], v[220:223], v[74:77]
	v_mfma_f32_16x16x32_bf16 v[66:69], v[188:191], v[220:223], v[66:69]
	v_mfma_f32_16x16x32_bf16 v[126:129], v[184:187], v[200:203], v[126:129]
	v_mfma_f32_16x16x32_bf16 v[114:117], v[192:195], v[200:203], v[114:117]
	v_mfma_f32_16x16x32_bf16 v[106:109], v[184:187], v[208:211], v[106:109]
	v_mfma_f32_16x16x32_bf16 v[98:101], v[192:195], v[208:211], v[98:101]
	v_mfma_f32_16x16x32_bf16 v[90:93], v[184:187], v[216:219], v[90:93]
	v_mfma_f32_16x16x32_bf16 v[82:85], v[192:195], v[216:219], v[82:85]
	v_mfma_f32_16x16x32_bf16 v[74:77], v[184:187], v[224:227], v[74:77]
	v_mfma_f32_16x16x32_bf16 v[66:69], v[192:195], v[224:227], v[66:69]
	s_setprio 0
	s_barrier
	s_add_u32 s96, s96, 0x80
	s_addc_u32 s97, s97, 0
	s_add_u32 s98, s96, 0x40000
	s_addc_u32 s99, s97, 0
	s_add_u32 s94, s94, 0x80
	s_addc_u32 s95, s95, 0
	s_add_i32 s7, s7, s47
	s_mov_b32 m0, s7
	ds_read_b128 v[196:199], v160 offset:49152
	ds_read_b128 v[200:203], v160 offset:50176
	ds_read_b128 v[204:207], v160 offset:51200
	ds_read_b128 v[208:211], v160 offset:52224
	ds_read_b128 v[212:215], v160 offset:53248
	ds_read_b128 v[216:219], v160 offset:54272
	ds_read_b128 v[220:223], v160 offset:55296
	ds_read_b128 v[224:227], v160 offset:56320
	global_load_lds_dwordx4 v132, s[96:97]
	s_add_i32 m0, s7, 0x2000
	s_add_i32 s7, s55, s47
	global_load_lds_dwordx4 v136, s[96:97]
	s_mov_b32 m0, s7
	s_nop 0
	global_load_lds_dwordx4 v132, s[98:99]
	s_add_i32 m0, s7, 0x2000
	s_nop 0
	global_load_lds_dwordx4 v136, s[98:99]
	s_mov_b32 m0, s65
	s_nop 0
	global_load_lds_dwordx4 v130, s[94:95]
	s_mov_b32 m0, s66
	s_nop 0
	global_load_lds_dwordx4 v134, s[94:95]
	s_waitcnt vmcnt(8)
	s_waitcnt lgkmcnt(0)
	s_barrier
	s_setprio 1
	s_waitcnt lgkmcnt(0)
	v_mfma_f32_16x16x32_bf16 v[62:65], v[164:167], v[196:199], v[62:65]
	v_mfma_f32_16x16x32_bf16 v[54:57], v[172:175], v[196:199], v[54:57]
	v_mfma_f32_16x16x32_bf16 v[46:49], v[164:167], v[204:207], v[46:49]
	v_mfma_f32_16x16x32_bf16 v[38:41], v[172:175], v[204:207], v[38:41]
	v_mfma_f32_16x16x32_bf16 v[30:33], v[164:167], v[212:215], v[30:33]
	v_mfma_f32_16x16x32_bf16 v[22:25], v[172:175], v[212:215], v[22:25]
	v_mfma_f32_16x16x32_bf16 v[14:17], v[164:167], v[220:223], v[14:17]
	v_mfma_f32_16x16x32_bf16 v[6:9], v[172:175], v[220:223], v[6:9]
	v_mfma_f32_16x16x32_bf16 v[62:65], v[168:171], v[200:203], v[62:65]
	v_mfma_f32_16x16x32_bf16 v[54:57], v[176:179], v[200:203], v[54:57]
	v_mfma_f32_16x16x32_bf16 v[46:49], v[168:171], v[208:211], v[46:49]
	v_mfma_f32_16x16x32_bf16 v[38:41], v[176:179], v[208:211], v[38:41]
	v_mfma_f32_16x16x32_bf16 v[30:33], v[168:171], v[216:219], v[30:33]
	v_mfma_f32_16x16x32_bf16 v[22:25], v[176:179], v[216:219], v[22:25]
	v_mfma_f32_16x16x32_bf16 v[14:17], v[168:171], v[224:227], v[14:17]
	v_mfma_f32_16x16x32_bf16 v[6:9], v[176:179], v[224:227], v[6:9]
	s_setprio 0
	s_setprio 1
	v_mfma_f32_16x16x32_bf16 v[58:61], v[180:183], v[196:199], v[58:61]
	v_mfma_f32_16x16x32_bf16 v[50:53], v[188:191], v[196:199], v[50:53]
	v_mfma_f32_16x16x32_bf16 v[42:45], v[180:183], v[204:207], v[42:45]
	v_mfma_f32_16x16x32_bf16 v[34:37], v[188:191], v[204:207], v[34:37]
	v_mfma_f32_16x16x32_bf16 v[26:29], v[180:183], v[212:215], v[26:29]
	v_mfma_f32_16x16x32_bf16 v[18:21], v[188:191], v[212:215], v[18:21]
	v_mfma_f32_16x16x32_bf16 v[10:13], v[180:183], v[220:223], v[10:13]
	v_mfma_f32_16x16x32_bf16 v[2:5], v[188:191], v[220:223], v[2:5]
	v_mfma_f32_16x16x32_bf16 v[58:61], v[184:187], v[200:203], v[58:61]
	v_mfma_f32_16x16x32_bf16 v[50:53], v[192:195], v[200:203], v[50:53]
	v_mfma_f32_16x16x32_bf16 v[42:45], v[184:187], v[208:211], v[42:45]
	v_mfma_f32_16x16x32_bf16 v[34:37], v[192:195], v[208:211], v[34:37]
	v_mfma_f32_16x16x32_bf16 v[26:29], v[184:187], v[216:219], v[26:29]
	v_mfma_f32_16x16x32_bf16 v[18:21], v[192:195], v[216:219], v[18:21]
	v_mfma_f32_16x16x32_bf16 v[10:13], v[184:187], v[224:227], v[10:13]
	v_mfma_f32_16x16x32_bf16 v[2:5], v[192:195], v[224:227], v[2:5]
	s_setprio 0
	s_barrier
	v_cmp_ge_i32_e32 vcc, s51, v138
	s_mov_b32 s7, s51
	s_add_u32 s88, s88, 0x100
	s_addc_u32 s89, s89, 0
	s_add_u32 s86, s86, 0x100
	s_addc_u32 s87, s87, 0
	s_cbranch_vccnz .Lmy_kexit_0
.LBB0_171:
	s_add_u32 s98, s86, 0xfffc0080
	s_addc_u32 s99, s87, -1
	s_cmp_eq_u32 s7, s100
	s_cselect_b64 s[94:95], s[90:91], s[98:99]
	s_cselect_b64 s[96:97], s[92:93], s[88:89]
	v_add_u32_e32 v155, s76, v141
	ds_read_b128 v[164:167], v155
	ds_read_b128 v[168:171], v155 offset:1024
	ds_read_b128 v[172:175], v155 offset:2048
	ds_read_b128 v[176:179], v155 offset:3072
	v_add_u32_e32 v155, s77, v141
	ds_read_b128 v[180:183], v155
	ds_read_b128 v[184:187], v155 offset:1024
	ds_read_b128 v[188:191], v155 offset:2048
	ds_read_b128 v[192:195], v155 offset:3072
	s_add_i32 s51, s7, 2
	s_nop 0
	s_mov_b32 m0, s78
	ds_read_b128 v[196:199], v160
	ds_read_b128 v[200:203], v160 offset:1024
	ds_read_b128 v[204:207], v160 offset:2048
	ds_read_b128 v[208:211], v160 offset:3072
	ds_read_b128 v[212:215], v160 offset:4096
	ds_read_b128 v[216:219], v160 offset:5120
	ds_read_b128 v[220:223], v160 offset:6144
	ds_read_b128 v[224:227], v160 offset:7168
	global_load_lds_dwordx4 v144, s[86:87]
	s_mov_b32 m0, s79
	s_nop 0
	global_load_lds_dwordx4 v142, s[86:87]
	s_waitcnt vmcnt(8)
	s_waitcnt lgkmcnt(0)
	s_barrier
	s_setprio 1
	s_waitcnt lgkmcnt(0)
	v_mfma_f32_16x16x32_bf16 v[122:125], v[164:167], v[196:199], v[122:125]
	v_mfma_f32_16x16x32_bf16 v[118:121], v[172:175], v[196:199], v[118:121]
	v_mfma_f32_16x16x32_bf16 v[110:113], v[164:167], v[204:207], v[110:113]
	v_mfma_f32_16x16x32_bf16 v[102:105], v[172:175], v[204:207], v[102:105]
	v_mfma_f32_16x16x32_bf16 v[94:97], v[164:167], v[212:215], v[94:97]
	v_mfma_f32_16x16x32_bf16 v[86:89], v[172:175], v[212:215], v[86:89]
	v_mfma_f32_16x16x32_bf16 v[78:81], v[164:167], v[220:223], v[78:81]
	v_mfma_f32_16x16x32_bf16 v[70:73], v[172:175], v[220:223], v[70:73]
	v_mfma_f32_16x16x32_bf16 v[122:125], v[168:171], v[200:203], v[122:125]
	v_mfma_f32_16x16x32_bf16 v[118:121], v[176:179], v[200:203], v[118:121]
	v_mfma_f32_16x16x32_bf16 v[110:113], v[168:171], v[208:211], v[110:113]
	v_mfma_f32_16x16x32_bf16 v[102:105], v[176:179], v[208:211], v[102:105]
	v_mfma_f32_16x16x32_bf16 v[94:97], v[168:171], v[216:219], v[94:97]
	v_mfma_f32_16x16x32_bf16 v[86:89], v[176:179], v[216:219], v[86:89]
	v_mfma_f32_16x16x32_bf16 v[78:81], v[168:171], v[224:227], v[78:81]
	v_mfma_f32_16x16x32_bf16 v[70:73], v[176:179], v[224:227], v[70:73]
	s_setprio 0
	s_setprio 1
	v_mfma_f32_16x16x32_bf16 v[126:129], v[180:183], v[196:199], v[126:129]
	v_mfma_f32_16x16x32_bf16 v[114:117], v[188:191], v[196:199], v[114:117]
	v_mfma_f32_16x16x32_bf16 v[106:109], v[180:183], v[204:207], v[106:109]
	v_mfma_f32_16x16x32_bf16 v[98:101], v[188:191], v[204:207], v[98:101]
	v_mfma_f32_16x16x32_bf16 v[90:93], v[180:183], v[212:215], v[90:93]
	v_mfma_f32_16x16x32_bf16 v[82:85], v[188:191], v[212:215], v[82:85]
	v_mfma_f32_16x16x32_bf16 v[74:77], v[180:183], v[220:223], v[74:77]
	v_mfma_f32_16x16x32_bf16 v[66:69], v[188:191], v[220:223], v[66:69]
	v_mfma_f32_16x16x32_bf16 v[126:129], v[184:187], v[200:203], v[126:129]
	v_mfma_f32_16x16x32_bf16 v[114:117], v[192:195], v[200:203], v[114:117]
	v_mfma_f32_16x16x32_bf16 v[106:109], v[184:187], v[208:211], v[106:109]
	v_mfma_f32_16x16x32_bf16 v[98:101], v[192:195], v[208:211], v[98:101]
	v_mfma_f32_16x16x32_bf16 v[90:93], v[184:187], v[216:219], v[90:93]
	v_mfma_f32_16x16x32_bf16 v[82:85], v[192:195], v[216:219], v[82:85]
	v_mfma_f32_16x16x32_bf16 v[74:77], v[184:187], v[224:227], v[74:77]
	v_mfma_f32_16x16x32_bf16 v[66:69], v[192:195], v[224:227], v[66:69]
	s_setprio 0
	s_barrier
	s_add_u32 s98, s96, 0x40000
	s_addc_u32 s99, s97, 0
	s_mov_b32 m0, s80
	ds_read_b128 v[196:199], v160 offset:16384
	ds_read_b128 v[200:203], v160 offset:17408
	ds_read_b128 v[204:207], v160 offset:18432
	ds_read_b128 v[208:211], v160 offset:19456
	ds_read_b128 v[212:215], v160 offset:20480
	ds_read_b128 v[216:219], v160 offset:21504
	ds_read_b128 v[220:223], v160 offset:22528
	ds_read_b128 v[224:227], v160 offset:23552
	global_load_lds_dwordx4 v132, s[96:97]
	s_mov_b32 m0, s81
	s_add_i32 s7, s77, s47
	global_load_lds_dwordx4 v136, s[96:97]
	s_mov_b32 m0, s7
	s_nop 0
	global_load_lds_dwordx4 v132, s[98:99]
	s_add_i32 m0, s7, 0x2000
	s_nop 0
	global_load_lds_dwordx4 v136, s[98:99]
	s_mov_b32 m0, s57
	s_nop 0
	global_load_lds_dwordx4 v130, s[94:95]
	s_mov_b32 m0, s62
	s_nop 0
	global_load_lds_dwordx4 v134, s[94:95]
	s_waitcnt vmcnt(8)
	s_waitcnt lgkmcnt(0)
	s_barrier
	s_setprio 1
	s_waitcnt lgkmcnt(0)
	v_mfma_f32_16x16x32_bf16 v[62:65], v[164:167], v[196:199], v[62:65]
	v_mfma_f32_16x16x32_bf16 v[54:57], v[172:175], v[196:199], v[54:57]
	v_mfma_f32_16x16x32_bf16 v[46:49], v[164:167], v[204:207], v[46:49]
	v_mfma_f32_16x16x32_bf16 v[38:41], v[172:175], v[204:207], v[38:41]
	v_mfma_f32_16x16x32_bf16 v[30:33], v[164:167], v[212:215], v[30:33]
	v_mfma_f32_16x16x32_bf16 v[22:25], v[172:175], v[212:215], v[22:25]
	v_mfma_f32_16x16x32_bf16 v[14:17], v[164:167], v[220:223], v[14:17]
	v_mfma_f32_16x16x32_bf16 v[6:9], v[172:175], v[220:223], v[6:9]
	v_mfma_f32_16x16x32_bf16 v[62:65], v[168:171], v[200:203], v[62:65]
	v_mfma_f32_16x16x32_bf16 v[54:57], v[176:179], v[200:203], v[54:57]
	v_mfma_f32_16x16x32_bf16 v[46:49], v[168:171], v[208:211], v[46:49]
	v_mfma_f32_16x16x32_bf16 v[38:41], v[176:179], v[208:211], v[38:41]
	v_mfma_f32_16x16x32_bf16 v[30:33], v[168:171], v[216:219], v[30:33]
	v_mfma_f32_16x16x32_bf16 v[22:25], v[176:179], v[216:219], v[22:25]
	v_mfma_f32_16x16x32_bf16 v[14:17], v[168:171], v[224:227], v[14:17]
	v_mfma_f32_16x16x32_bf16 v[6:9], v[176:179], v[224:227], v[6:9]
	s_setprio 0
	s_setprio 1
	v_mfma_f32_16x16x32_bf16 v[58:61], v[180:183], v[196:199], v[58:61]
	v_mfma_f32_16x16x32_bf16 v[50:53], v[188:191], v[196:199], v[50:53]
	v_mfma_f32_16x16x32_bf16 v[42:45], v[180:183], v[204:207], v[42:45]
	v_mfma_f32_16x16x32_bf16 v[34:37], v[188:191], v[204:207], v[34:37]
	v_mfma_f32_16x16x32_bf16 v[26:29], v[180:183], v[212:215], v[26:29]
	v_mfma_f32_16x16x32_bf16 v[18:21], v[188:191], v[212:215], v[18:21]
	v_mfma_f32_16x16x32_bf16 v[10:13], v[180:183], v[220:223], v[10:13]
	v_mfma_f32_16x16x32_bf16 v[2:5], v[188:191], v[220:223], v[2:5]
	v_mfma_f32_16x16x32_bf16 v[58:61], v[184:187], v[200:203], v[58:61]
	v_mfma_f32_16x16x32_bf16 v[50:53], v[192:195], v[200:203], v[50:53]
	v_mfma_f32_16x16x32_bf16 v[42:45], v[184:187], v[208:211], v[42:45]
	v_mfma_f32_16x16x32_bf16 v[34:37], v[192:195], v[208:211], v[34:37]
	v_mfma_f32_16x16x32_bf16 v[26:29], v[184:187], v[216:219], v[26:29]
	v_mfma_f32_16x16x32_bf16 v[18:21], v[192:195], v[216:219], v[18:21]
	v_mfma_f32_16x16x32_bf16 v[10:13], v[184:187], v[224:227], v[10:13]
	v_mfma_f32_16x16x32_bf16 v[2:5], v[192:195], v[224:227], v[2:5]
	s_setprio 0
	s_barrier
	s_add_u32 s98, s94, 0x40000
	s_addc_u32 s99, s95, 0
	s_add_i32 s7, 0, 0x18000
	v_add_u32_e32 v155, s7, v141
	s_add_i32 s55, 0, 0x1c000
	ds_read_b128 v[164:167], v155
	ds_read_b128 v[168:171], v155 offset:1024
	ds_read_b128 v[172:175], v155 offset:2048
	ds_read_b128 v[176:179], v155 offset:3072
	v_add_u32_e32 v155, s55, v141
	ds_read_b128 v[180:183], v155
	ds_read_b128 v[184:187], v155 offset:1024
	ds_read_b128 v[188:191], v155 offset:2048
	ds_read_b128 v[192:195], v155 offset:3072
	s_mov_b32 m0, s63
	ds_read_b128 v[196:199], v160 offset:32768
	ds_read_b128 v[200:203], v160 offset:33792
	ds_read_b128 v[204:207], v160 offset:34816
	ds_read_b128 v[208:211], v160 offset:35840
	ds_read_b128 v[212:215], v160 offset:36864
	ds_read_b128 v[216:219], v160 offset:37888
	ds_read_b128 v[220:223], v160 offset:38912
	ds_read_b128 v[224:227], v160 offset:39936
	global_load_lds_dwordx4 v130, s[98:99]
	s_mov_b32 m0, s64
	s_nop 0
	global_load_lds_dwordx4 v134, s[98:99]
	s_waitcnt vmcnt(8)
	s_waitcnt lgkmcnt(0)
	s_barrier
	s_setprio 1
	s_waitcnt lgkmcnt(0)
	v_mfma_f32_16x16x32_bf16 v[122:125], v[164:167], v[196:199], v[122:125]
	v_mfma_f32_16x16x32_bf16 v[118:121], v[172:175], v[196:199], v[118:121]
	v_mfma_f32_16x16x32_bf16 v[110:113], v[164:167], v[204:207], v[110:113]
	v_mfma_f32_16x16x32_bf16 v[102:105], v[172:175], v[204:207], v[102:105]
	v_mfma_f32_16x16x32_bf16 v[94:97], v[164:167], v[212:215], v[94:97]
	v_mfma_f32_16x16x32_bf16 v[86:89], v[172:175], v[212:215], v[86:89]
	v_mfma_f32_16x16x32_bf16 v[78:81], v[164:167], v[220:223], v[78:81]
	v_mfma_f32_16x16x32_bf16 v[70:73], v[172:175], v[220:223], v[70:73]
	v_mfma_f32_16x16x32_bf16 v[122:125], v[168:171], v[200:203], v[122:125]
	v_mfma_f32_16x16x32_bf16 v[118:121], v[176:179], v[200:203], v[118:121]
	v_mfma_f32_16x16x32_bf16 v[110:113], v[168:171], v[208:211], v[110:113]
	v_mfma_f32_16x16x32_bf16 v[102:105], v[176:179], v[208:211], v[102:105]
	v_mfma_f32_16x16x32_bf16 v[94:97], v[168:171], v[216:219], v[94:97]
	v_mfma_f32_16x16x32_bf16 v[86:89], v[176:179], v[216:219], v[86:89]
	v_mfma_f32_16x16x32_bf16 v[78:81], v[168:171], v[224:227], v[78:81]
	v_mfma_f32_16x16x32_bf16 v[70:73], v[176:179], v[224:227], v[70:73]
	s_setprio 0
	s_setprio 1
	v_mfma_f32_16x16x32_bf16 v[126:129], v[180:183], v[196:199], v[126:129]
	v_mfma_f32_16x16x32_bf16 v[114:117], v[188:191], v[196:199], v[114:117]
	v_mfma_f32_16x16x32_bf16 v[106:109], v[180:183], v[204:207], v[106:109]
	v_mfma_f32_16x16x32_bf16 v[98:101], v[188:191], v[204:207], v[98:101]
	v_mfma_f32_16x16x32_bf16 v[90:93], v[180:183], v[212:215], v[90:93]
	v_mfma_f32_16x16x32_bf16 v[82:85], v[188:191], v[212:215], v[82:85]
	v_mfma_f32_16x16x32_bf16 v[74:77], v[180:183], v[220:223], v[74:77]
	v_mfma_f32_16x16x32_bf16 v[66:69], v[188:191], v[220:223], v[66:69]
	v_mfma_f32_16x16x32_bf16 v[126:129], v[184:187], v[200:203], v[126:129]
	v_mfma_f32_16x16x32_bf16 v[114:117], v[192:195], v[200:203], v[114:117]
	v_mfma_f32_16x16x32_bf16 v[106:109], v[184:187], v[208:211], v[106:109]
	v_mfma_f32_16x16x32_bf16 v[98:101], v[192:195], v[208:211], v[98:101]
	v_mfma_f32_16x16x32_bf16 v[90:93], v[184:187], v[216:219], v[90:93]
	v_mfma_f32_16x16x32_bf16 v[82:85], v[192:195], v[216:219], v[82:85]
	v_mfma_f32_16x16x32_bf16 v[74:77], v[184:187], v[224:227], v[74:77]
	v_mfma_f32_16x16x32_bf16 v[66:69], v[192:195], v[224:227], v[66:69]
	s_setprio 0
	s_barrier
	s_add_u32 s96, s96, 0x80
	s_addc_u32 s97, s97, 0
	s_add_u32 s98, s96, 0x40000
	s_addc_u32 s99, s97, 0
	s_add_u32 s94, s94, 0x80
	s_addc_u32 s95, s95, 0
	s_add_i32 s7, s7, s47
	s_mov_b32 m0, s7
	ds_read_b128 v[196:199], v160 offset:49152
	ds_read_b128 v[200:203], v160 offset:50176
	ds_read_b128 v[204:207], v160 offset:51200
	ds_read_b128 v[208:211], v160 offset:52224
	ds_read_b128 v[212:215], v160 offset:53248
	ds_read_b128 v[216:219], v160 offset:54272
	ds_read_b128 v[220:223], v160 offset:55296
	ds_read_b128 v[224:227], v160 offset:56320
	global_load_lds_dwordx4 v132, s[96:97]
	s_add_i32 m0, s7, 0x2000
	s_add_i32 s7, s55, s47
	global_load_lds_dwordx4 v136, s[96:97]
	s_mov_b32 m0, s7
	s_nop 0
	global_load_lds_dwordx4 v132, s[98:99]
	s_add_i32 m0, s7, 0x2000
	s_nop 0
	global_load_lds_dwordx4 v136, s[98:99]
	s_mov_b32 m0, s65
	s_nop 0
	global_load_lds_dwordx4 v130, s[94:95]
	s_mov_b32 m0, s66
	s_nop 0
	global_load_lds_dwordx4 v134, s[94:95]
	s_waitcnt vmcnt(8)
	s_waitcnt lgkmcnt(0)
	s_barrier
	s_setprio 1
	s_waitcnt lgkmcnt(0)
	v_mfma_f32_16x16x32_bf16 v[62:65], v[164:167], v[196:199], v[62:65]
	v_mfma_f32_16x16x32_bf16 v[54:57], v[172:175], v[196:199], v[54:57]
	v_mfma_f32_16x16x32_bf16 v[46:49], v[164:167], v[204:207], v[46:49]
	v_mfma_f32_16x16x32_bf16 v[38:41], v[172:175], v[204:207], v[38:41]
	v_mfma_f32_16x16x32_bf16 v[30:33], v[164:167], v[212:215], v[30:33]
	v_mfma_f32_16x16x32_bf16 v[22:25], v[172:175], v[212:215], v[22:25]
	v_mfma_f32_16x16x32_bf16 v[14:17], v[164:167], v[220:223], v[14:17]
	v_mfma_f32_16x16x32_bf16 v[6:9], v[172:175], v[220:223], v[6:9]
	v_mfma_f32_16x16x32_bf16 v[62:65], v[168:171], v[200:203], v[62:65]
	v_mfma_f32_16x16x32_bf16 v[54:57], v[176:179], v[200:203], v[54:57]
	v_mfma_f32_16x16x32_bf16 v[46:49], v[168:171], v[208:211], v[46:49]
	v_mfma_f32_16x16x32_bf16 v[38:41], v[176:179], v[208:211], v[38:41]
	v_mfma_f32_16x16x32_bf16 v[30:33], v[168:171], v[216:219], v[30:33]
	v_mfma_f32_16x16x32_bf16 v[22:25], v[176:179], v[216:219], v[22:25]
	v_mfma_f32_16x16x32_bf16 v[14:17], v[168:171], v[224:227], v[14:17]
	v_mfma_f32_16x16x32_bf16 v[6:9], v[176:179], v[224:227], v[6:9]
	s_setprio 0
	s_setprio 1
	v_mfma_f32_16x16x32_bf16 v[58:61], v[180:183], v[196:199], v[58:61]
	v_mfma_f32_16x16x32_bf16 v[50:53], v[188:191], v[196:199], v[50:53]
	v_mfma_f32_16x16x32_bf16 v[42:45], v[180:183], v[204:207], v[42:45]
	v_mfma_f32_16x16x32_bf16 v[34:37], v[188:191], v[204:207], v[34:37]
	v_mfma_f32_16x16x32_bf16 v[26:29], v[180:183], v[212:215], v[26:29]
	v_mfma_f32_16x16x32_bf16 v[18:21], v[188:191], v[212:215], v[18:21]
	v_mfma_f32_16x16x32_bf16 v[10:13], v[180:183], v[220:223], v[10:13]
	v_mfma_f32_16x16x32_bf16 v[2:5], v[188:191], v[220:223], v[2:5]
	v_mfma_f32_16x16x32_bf16 v[58:61], v[184:187], v[200:203], v[58:61]
	v_mfma_f32_16x16x32_bf16 v[50:53], v[192:195], v[200:203], v[50:53]
	v_mfma_f32_16x16x32_bf16 v[42:45], v[184:187], v[208:211], v[42:45]
	v_mfma_f32_16x16x32_bf16 v[34:37], v[192:195], v[208:211], v[34:37]
	v_mfma_f32_16x16x32_bf16 v[26:29], v[184:187], v[216:219], v[26:29]
	v_mfma_f32_16x16x32_bf16 v[18:21], v[192:195], v[216:219], v[18:21]
	v_mfma_f32_16x16x32_bf16 v[10:13], v[184:187], v[224:227], v[10:13]
	v_mfma_f32_16x16x32_bf16 v[2:5], v[192:195], v[224:227], v[2:5]
	s_setprio 0
	s_barrier
	v_cmp_ge_i32_e32 vcc, s51, v138
	s_mov_b32 s7, s51
	s_add_u32 s88, s88, 0x100
	s_addc_u32 s89, s89, 0
	s_add_u32 s86, s86, 0x100
	s_addc_u32 s87, s87, 0
	s_cbranch_vccz .LBB0_171

.LBB0_308:
	v_cmp_gt_i32_e32 vcc, 1, v141
	s_cbranch_vccnz .LBB0_370
	v_lshl_add_u64 v[154:155], v[2:3], 0, s[28:29]
	v_add_u32_e32 v138, -2, v141
	s_mov_b32 s8, 0
	s_nop 0
	v_readfirstlane_b32 s86, v152
	v_readfirstlane_b32 s87, v153
	v_readfirstlane_b32 s88, v154
	v_readfirstlane_b32 s89, v155
	v_readfirstlane_b32 s90, v148
	v_readfirstlane_b32 s91, v149
	v_readfirstlane_b32 s92, v150
	v_readfirstlane_b32 s93, v151
	v_readfirstlane_b32 s100, v138
	s_add_u32 s98, s86, 0x100
	s_addc_u32 s99, s87, 0
	s_cmp_eq_u32 s8, s100
	s_cselect_b64 s[94:95], s[90:91], s[98:99]
	s_cselect_b64 s[96:97], s[92:93], s[88:89]
	v_add_u32_e32 v146, s69, v160
	ds_read_b128 v[166:169], v146
	ds_read_b128 v[170:173], v146 offset:1024
	ds_read_b128 v[174:177], v146 offset:2048
	ds_read_b128 v[178:181], v146 offset:3072
	v_add_u32_e32 v146, s72, v160
	ds_read_b128 v[182:185], v146
	ds_read_b128 v[186:189], v146 offset:1024
	ds_read_b128 v[190:193], v146 offset:2048
	ds_read_b128 v[194:197], v146 offset:3072
	s_add_i32 s9, s8, 2
	s_nop 0
	s_add_i32 m0, s55, 0xc000
	ds_read_b128 v[198:201], v163
	ds_read_b128 v[202:205], v163 offset:1024
	ds_read_b128 v[206:209], v163 offset:2048
	ds_read_b128 v[210:213], v163 offset:3072
	ds_read_b128 v[214:217], v163 offset:4096
	ds_read_b128 v[218:221], v163 offset:5120
	ds_read_b128 v[222:225], v163 offset:6144
	ds_read_b128 v[226:229], v163 offset:7168
	global_load_lds_dwordx4 v144, s[86:87]
	s_add_i32 m0, s55, 0xe000
	s_nop 0
	global_load_lds_dwordx4 v142, s[86:87]
	s_waitcnt vmcnt(8)
	s_waitcnt lgkmcnt(0)
	s_barrier
	s_setprio 1
	s_waitcnt lgkmcnt(0)
	v_mfma_f32_16x16x32_bf16 v[122:125], v[166:169], v[198:201], 0
	v_mfma_f32_16x16x32_bf16 v[118:121], v[174:177], v[198:201], 0
	v_mfma_f32_16x16x32_bf16 v[110:113], v[166:169], v[206:209], 0
	v_mfma_f32_16x16x32_bf16 v[102:105], v[174:177], v[206:209], 0
	v_mfma_f32_16x16x32_bf16 v[94:97], v[166:169], v[214:217], 0
	v_mfma_f32_16x16x32_bf16 v[86:89], v[174:177], v[214:217], 0
	v_mfma_f32_16x16x32_bf16 v[78:81], v[166:169], v[222:225], 0
	v_mfma_f32_16x16x32_bf16 v[70:73], v[174:177], v[222:225], 0
	v_mfma_f32_16x16x32_bf16 v[122:125], v[170:173], v[202:205], v[122:125]
	v_mfma_f32_16x16x32_bf16 v[118:121], v[178:181], v[202:205], v[118:121]
	v_mfma_f32_16x16x32_bf16 v[110:113], v[170:173], v[210:213], v[110:113]
	v_mfma_f32_16x16x32_bf16 v[102:105], v[178:181], v[210:213], v[102:105]
	v_mfma_f32_16x16x32_bf16 v[94:97], v[170:173], v[218:221], v[94:97]
	v_mfma_f32_16x16x32_bf16 v[86:89], v[178:181], v[218:221], v[86:89]
	v_mfma_f32_16x16x32_bf16 v[78:81], v[170:173], v[226:229], v[78:81]
	v_mfma_f32_16x16x32_bf16 v[70:73], v[178:181], v[226:229], v[70:73]
	s_setprio 0
	s_setprio 1
	v_mfma_f32_16x16x32_bf16 v[126:129], v[182:185], v[198:201], 0
	v_mfma_f32_16x16x32_bf16 v[114:117], v[190:193], v[198:201], 0
	v_mfma_f32_16x16x32_bf16 v[106:109], v[182:185], v[206:209], 0
	v_mfma_f32_16x16x32_bf16 v[98:101], v[190:193], v[206:209], 0
	v_mfma_f32_16x16x32_bf16 v[90:93], v[182:185], v[214:217], 0
	v_mfma_f32_16x16x32_bf16 v[82:85], v[190:193], v[214:217], 0
	v_mfma_f32_16x16x32_bf16 v[74:77], v[182:185], v[222:225], 0
	v_mfma_f32_16x16x32_bf16 v[66:69], v[190:193], v[222:225], 0
	v_mfma_f32_16x16x32_bf16 v[126:129], v[186:189], v[202:205], v[126:129]
	v_mfma_f32_16x16x32_bf16 v[114:117], v[194:197], v[202:205], v[114:117]
	v_mfma_f32_16x16x32_bf16 v[106:109], v[186:189], v[210:213], v[106:109]
	v_mfma_f32_16x16x32_bf16 v[98:101], v[194:197], v[210:213], v[98:101]
	v_mfma_f32_16x16x32_bf16 v[90:93], v[186:189], v[218:221], v[90:93]
	v_mfma_f32_16x16x32_bf16 v[82:85], v[194:197], v[218:221], v[82:85]
	v_mfma_f32_16x16x32_bf16 v[74:77], v[186:189], v[226:229], v[74:77]
	v_mfma_f32_16x16x32_bf16 v[66:69], v[194:197], v[226:229], v[66:69]
	s_setprio 0
	s_barrier
	s_add_u32 s98, s96, 0xb0000
	s_addc_u32 s99, s97, 0
	s_add_i32 s8, s69, s54
	s_mov_b32 m0, s8
	ds_read_b128 v[198:201], v163 offset:16384
	ds_read_b128 v[202:205], v163 offset:17408
	ds_read_b128 v[206:209], v163 offset:18432
	ds_read_b128 v[210:213], v163 offset:19456
	ds_read_b128 v[214:217], v163 offset:20480
	ds_read_b128 v[218:221], v163 offset:21504
	ds_read_b128 v[222:225], v163 offset:22528
	ds_read_b128 v[226:229], v163 offset:23552
	global_load_lds_dwordx4 v132, s[96:97]
	s_add_i32 m0, s8, 0x2000
	s_add_i32 s8, s72, s54
	global_load_lds_dwordx4 v136, s[96:97]
	s_mov_b32 m0, s8
	s_nop 0
	global_load_lds_dwordx4 v132, s[98:99]
	s_add_i32 m0, s8, 0x2000
	s_nop 0
	global_load_lds_dwordx4 v136, s[98:99]
	s_mov_b32 m0, s55
	s_nop 0
	global_load_lds_dwordx4 v130, s[94:95]
	s_mov_b32 m0, s56
	s_nop 0
	global_load_lds_dwordx4 v134, s[94:95]
	s_waitcnt vmcnt(8)
	s_waitcnt lgkmcnt(0)
	s_barrier
	s_setprio 1
	s_waitcnt lgkmcnt(0)
	v_mfma_f32_16x16x32_bf16 v[62:65], v[166:169], v[198:201], 0
	v_mfma_f32_16x16x32_bf16 v[54:57], v[174:177], v[198:201], 0
	v_mfma_f32_16x16x32_bf16 v[46:49], v[166:169], v[206:209], 0
	v_mfma_f32_16x16x32_bf16 v[38:41], v[174:177], v[206:209], 0
	v_mfma_f32_16x16x32_bf16 v[30:33], v[166:169], v[214:217], 0
	v_mfma_f32_16x16x32_bf16 v[22:25], v[174:177], v[214:217], 0
	v_mfma_f32_16x16x32_bf16 v[14:17], v[166:169], v[222:225], 0
	v_mfma_f32_16x16x32_bf16 v[6:9], v[174:177], v[222:225], 0
	v_mfma_f32_16x16x32_bf16 v[62:65], v[170:173], v[202:205], v[62:65]
	v_mfma_f32_16x16x32_bf16 v[54:57], v[178:181], v[202:205], v[54:57]
	v_mfma_f32_16x16x32_bf16 v[46:49], v[170:173], v[210:213], v[46:49]
	v_mfma_f32_16x16x32_bf16 v[38:41], v[178:181], v[210:213], v[38:41]
	v_mfma_f32_16x16x32_bf16 v[30:33], v[170:173], v[218:221], v[30:33]
	v_mfma_f32_16x16x32_bf16 v[22:25], v[178:181], v[218:221], v[22:25]
	v_mfma_f32_16x16x32_bf16 v[14:17], v[170:173], v[226:229], v[14:17]
	v_mfma_f32_16x16x32_bf16 v[6:9], v[178:181], v[226:229], v[6:9]
	s_setprio 0
	s_setprio 1
	v_mfma_f32_16x16x32_bf16 v[58:61], v[182:185], v[198:201], 0
	v_mfma_f32_16x16x32_bf16 v[50:53], v[190:193], v[198:201], 0
	v_mfma_f32_16x16x32_bf16 v[42:45], v[182:185], v[206:209], 0
	v_mfma_f32_16x16x32_bf16 v[34:37], v[190:193], v[206:209], 0
	v_mfma_f32_16x16x32_bf16 v[26:29], v[182:185], v[214:217], 0
	v_mfma_f32_16x16x32_bf16 v[18:21], v[190:193], v[214:217], 0
	v_mfma_f32_16x16x32_bf16 v[10:13], v[182:185], v[222:225], 0
	v_mfma_f32_16x16x32_bf16 v[2:5], v[190:193], v[222:225], 0
	v_mfma_f32_16x16x32_bf16 v[58:61], v[186:189], v[202:205], v[58:61]
	v_mfma_f32_16x16x32_bf16 v[50:53], v[194:197], v[202:205], v[50:53]
	v_mfma_f32_16x16x32_bf16 v[42:45], v[186:189], v[210:213], v[42:45]
	v_mfma_f32_16x16x32_bf16 v[34:37], v[194:197], v[210:213], v[34:37]
	v_mfma_f32_16x16x32_bf16 v[26:29], v[186:189], v[218:221], v[26:29]
	v_mfma_f32_16x16x32_bf16 v[18:21], v[194:197], v[218:221], v[18:21]
	v_mfma_f32_16x16x32_bf16 v[10:13], v[186:189], v[226:229], v[10:13]
	v_mfma_f32_16x16x32_bf16 v[2:5], v[194:197], v[226:229], v[2:5]
	s_setprio 0
	s_barrier
	s_add_u32 s98, s94, 0xb0000
	s_addc_u32 s99, s95, 0
	s_add_i32 s8, 0, 0x18000
	v_add_u32_e32 v146, s8, v160
	s_add_i32 s50, 0, 0x1c000
	ds_read_b128 v[166:169], v146
	ds_read_b128 v[170:173], v146 offset:1024
	ds_read_b128 v[174:177], v146 offset:2048
	ds_read_b128 v[178:181], v146 offset:3072
	v_add_u32_e32 v146, s50, v160
	ds_read_b128 v[182:185], v146
	ds_read_b128 v[186:189], v146 offset:1024
	ds_read_b128 v[190:193], v146 offset:2048
	ds_read_b128 v[194:197], v146 offset:3072
	s_mov_b32 m0, s57
	ds_read_b128 v[198:201], v163 offset:32768
	ds_read_b128 v[202:205], v163 offset:33792
	ds_read_b128 v[206:209], v163 offset:34816
	ds_read_b128 v[210:213], v163 offset:35840
	ds_read_b128 v[214:217], v163 offset:36864
	ds_read_b128 v[218:221], v163 offset:37888
	ds_read_b128 v[222:225], v163 offset:38912
	ds_read_b128 v[226:229], v163 offset:39936
	global_load_lds_dwordx4 v130, s[98:99]
	s_mov_b32 m0, s58
	s_nop 0
	global_load_lds_dwordx4 v134, s[98:99]
	s_waitcnt vmcnt(8)
	s_waitcnt lgkmcnt(0)
	s_barrier
	s_setprio 1
	s_waitcnt lgkmcnt(0)
	v_mfma_f32_16x16x32_bf16 v[122:125], v[166:169], v[198:201], v[122:125]
	v_mfma_f32_16x16x32_bf16 v[118:121], v[174:177], v[198:201], v[118:121]
	v_mfma_f32_16x16x32_bf16 v[110:113], v[166:169], v[206:209], v[110:113]
	v_mfma_f32_16x16x32_bf16 v[102:105], v[174:177], v[206:209], v[102:105]
	v_mfma_f32_16x16x32_bf16 v[94:97], v[166:169], v[214:217], v[94:97]
	v_mfma_f32_16x16x32_bf16 v[86:89], v[174:177], v[214:217], v[86:89]
	v_mfma_f32_16x16x32_bf16 v[78:81], v[166:169], v[222:225], v[78:81]
	v_mfma_f32_16x16x32_bf16 v[70:73], v[174:177], v[222:225], v[70:73]
	v_mfma_f32_16x16x32_bf16 v[122:125], v[170:173], v[202:205], v[122:125]
	v_mfma_f32_16x16x32_bf16 v[118:121], v[178:181], v[202:205], v[118:121]
	v_mfma_f32_16x16x32_bf16 v[110:113], v[170:173], v[210:213], v[110:113]
	v_mfma_f32_16x16x32_bf16 v[102:105], v[178:181], v[210:213], v[102:105]
	v_mfma_f32_16x16x32_bf16 v[94:97], v[170:173], v[218:221], v[94:97]
	v_mfma_f32_16x16x32_bf16 v[86:89], v[178:181], v[218:221], v[86:89]
	v_mfma_f32_16x16x32_bf16 v[78:81], v[170:173], v[226:229], v[78:81]
	v_mfma_f32_16x16x32_bf16 v[70:73], v[178:181], v[226:229], v[70:73]
	s_setprio 0
	s_setprio 1
	v_mfma_f32_16x16x32_bf16 v[126:129], v[182:185], v[198:201], v[126:129]
	v_mfma_f32_16x16x32_bf16 v[114:117], v[190:193], v[198:201], v[114:117]
	v_mfma_f32_16x16x32_bf16 v[106:109], v[182:185], v[206:209], v[106:109]
	v_mfma_f32_16x16x32_bf16 v[98:101], v[190:193], v[206:209], v[98:101]
	v_mfma_f32_16x16x32_bf16 v[90:93], v[182:185], v[214:217], v[90:93]
	v_mfma_f32_16x16x32_bf16 v[82:85], v[190:193], v[214:217], v[82:85]
	v_mfma_f32_16x16x32_bf16 v[74:77], v[182:185], v[222:225], v[74:77]
	v_mfma_f32_16x16x32_bf16 v[66:69], v[190:193], v[222:225], v[66:69]
	v_mfma_f32_16x16x32_bf16 v[126:129], v[186:189], v[202:205], v[126:129]
	v_mfma_f32_16x16x32_bf16 v[114:117], v[194:197], v[202:205], v[114:117]
	v_mfma_f32_16x16x32_bf16 v[106:109], v[186:189], v[210:213], v[106:109]
	v_mfma_f32_16x16x32_bf16 v[98:101], v[194:197], v[210:213], v[98:101]
	v_mfma_f32_16x16x32_bf16 v[90:93], v[186:189], v[218:221], v[90:93]
	v_mfma_f32_16x16x32_bf16 v[82:85], v[194:197], v[218:221], v[82:85]
	v_mfma_f32_16x16x32_bf16 v[74:77], v[186:189], v[226:229], v[74:77]
	v_mfma_f32_16x16x32_bf16 v[66:69], v[194:197], v[226:229], v[66:69]
	s_setprio 0
	s_barrier
	s_add_u32 s96, s96, 0x80
	s_addc_u32 s97, s97, 0
	s_add_u32 s98, s96, 0xb0000
	s_addc_u32 s99, s97, 0
	s_add_u32 s94, s94, 0x80
	s_addc_u32 s95, s95, 0
	s_add_i32 s8, s8, s54
	s_mov_b32 m0, s8
	ds_read_b128 v[198:201], v163 offset:49152
	ds_read_b128 v[202:205], v163 offset:50176
	ds_read_b128 v[206:209], v163 offset:51200
	ds_read_b128 v[210:213], v163 offset:52224
	ds_read_b128 v[214:217], v163 offset:53248
	ds_read_b128 v[218:221], v163 offset:54272
	ds_read_b128 v[222:225], v163 offset:55296
	ds_read_b128 v[226:229], v163 offset:56320
	global_load_lds_dwordx4 v132, s[96:97]
	s_add_i32 m0, s8, 0x2000
	s_add_i32 s8, s50, s54
	global_load_lds_dwordx4 v136, s[96:97]
	s_mov_b32 m0, s8
	s_nop 0
	global_load_lds_dwordx4 v132, s[98:99]
	s_add_i32 m0, s8, 0x2000
	s_nop 0
	global_load_lds_dwordx4 v136, s[98:99]
	s_mov_b32 m0, s64
	s_nop 0
	global_load_lds_dwordx4 v130, s[94:95]
	s_mov_b32 m0, s65
	s_nop 0
	global_load_lds_dwordx4 v134, s[94:95]
	s_waitcnt vmcnt(8)
	s_waitcnt lgkmcnt(0)
	s_barrier
	s_setprio 1
	s_waitcnt lgkmcnt(0)
	v_mfma_f32_16x16x32_bf16 v[62:65], v[166:169], v[198:201], v[62:65]
	v_mfma_f32_16x16x32_bf16 v[54:57], v[174:177], v[198:201], v[54:57]
	v_mfma_f32_16x16x32_bf16 v[46:49], v[166:169], v[206:209], v[46:49]
	v_mfma_f32_16x16x32_bf16 v[38:41], v[174:177], v[206:209], v[38:41]
	v_mfma_f32_16x16x32_bf16 v[30:33], v[166:169], v[214:217], v[30:33]
	v_mfma_f32_16x16x32_bf16 v[22:25], v[174:177], v[214:217], v[22:25]
	v_mfma_f32_16x16x32_bf16 v[14:17], v[166:169], v[222:225], v[14:17]
	v_mfma_f32_16x16x32_bf16 v[6:9], v[174:177], v[222:225], v[6:9]
	v_mfma_f32_16x16x32_bf16 v[62:65], v[170:173], v[202:205], v[62:65]
	v_mfma_f32_16x16x32_bf16 v[54:57], v[178:181], v[202:205], v[54:57]
	v_mfma_f32_16x16x32_bf16 v[46:49], v[170:173], v[210:213], v[46:49]
	v_mfma_f32_16x16x32_bf16 v[38:41], v[178:181], v[210:213], v[38:41]
	v_mfma_f32_16x16x32_bf16 v[30:33], v[170:173], v[218:221], v[30:33]
	v_mfma_f32_16x16x32_bf16 v[22:25], v[178:181], v[218:221], v[22:25]
	v_mfma_f32_16x16x32_bf16 v[14:17], v[170:173], v[226:229], v[14:17]
	v_mfma_f32_16x16x32_bf16 v[6:9], v[178:181], v[226:229], v[6:9]
	s_setprio 0
	s_setprio 1
	v_mfma_f32_16x16x32_bf16 v[58:61], v[182:185], v[198:201], v[58:61]
	v_mfma_f32_16x16x32_bf16 v[50:53], v[190:193], v[198:201], v[50:53]
	v_mfma_f32_16x16x32_bf16 v[42:45], v[182:185], v[206:209], v[42:45]
	v_mfma_f32_16x16x32_bf16 v[34:37], v[190:193], v[206:209], v[34:37]
	v_mfma_f32_16x16x32_bf16 v[26:29], v[182:185], v[214:217], v[26:29]
	v_mfma_f32_16x16x32_bf16 v[18:21], v[190:193], v[214:217], v[18:21]
	v_mfma_f32_16x16x32_bf16 v[10:13], v[182:185], v[222:225], v[10:13]
	v_mfma_f32_16x16x32_bf16 v[2:5], v[190:193], v[222:225], v[2:5]
	v_mfma_f32_16x16x32_bf16 v[58:61], v[186:189], v[202:205], v[58:61]
	v_mfma_f32_16x16x32_bf16 v[50:53], v[194:197], v[202:205], v[50:53]
	v_mfma_f32_16x16x32_bf16 v[42:45], v[186:189], v[210:213], v[42:45]
	v_mfma_f32_16x16x32_bf16 v[34:37], v[194:197], v[210:213], v[34:37]
	v_mfma_f32_16x16x32_bf16 v[26:29], v[186:189], v[218:221], v[26:29]
	v_mfma_f32_16x16x32_bf16 v[18:21], v[194:197], v[218:221], v[18:21]
	v_mfma_f32_16x16x32_bf16 v[10:13], v[186:189], v[226:229], v[10:13]
	v_mfma_f32_16x16x32_bf16 v[2:5], v[194:197], v[226:229], v[2:5]
	s_setprio 0
	s_barrier
	v_cmp_ge_i32_e32 vcc, s9, v141
	s_mov_b32 s8, s9
	s_add_u32 s88, s88, 0x100
	s_addc_u32 s89, s89, 0
	s_add_u32 s86, s86, 0x100
	s_addc_u32 s87, s87, 0
	s_cbranch_vccnz .Lmy_kexit_1
.LBB0_310:
	s_add_u32 s98, s86, 0x100
	s_addc_u32 s99, s87, 0
	s_cmp_eq_u32 s8, s100
	s_cselect_b64 s[94:95], s[90:91], s[98:99]
	s_cselect_b64 s[96:97], s[92:93], s[88:89]
	v_add_u32_e32 v146, s69, v160
	ds_read_b128 v[166:169], v146
	ds_read_b128 v[170:173], v146 offset:1024
	ds_read_b128 v[174:177], v146 offset:2048
	ds_read_b128 v[178:181], v146 offset:3072
	v_add_u32_e32 v146, s72, v160
	ds_read_b128 v[182:185], v146
	ds_read_b128 v[186:189], v146 offset:1024
	ds_read_b128 v[190:193], v146 offset:2048
	ds_read_b128 v[194:197], v146 offset:3072
	s_add_i32 s9, s8, 2
	s_nop 0
	s_add_i32 m0, s55, 0xc000
	ds_read_b128 v[198:201], v163
	ds_read_b128 v[202:205], v163 offset:1024
	ds_read_b128 v[206:209], v163 offset:2048
	ds_read_b128 v[210:213], v163 offset:3072
	ds_read_b128 v[214:217], v163 offset:4096
	ds_read_b128 v[218:221], v163 offset:5120
	ds_read_b128 v[222:225], v163 offset:6144
	ds_read_b128 v[226:229], v163 offset:7168
	global_load_lds_dwordx4 v144, s[86:87]
	s_add_i32 m0, s55, 0xe000
	s_nop 0
	global_load_lds_dwordx4 v142, s[86:87]
	s_waitcnt vmcnt(8)
	s_waitcnt lgkmcnt(0)
	s_barrier
	s_setprio 1
	s_waitcnt lgkmcnt(0)
	v_mfma_f32_16x16x32_bf16 v[122:125], v[166:169], v[198:201], v[122:125]
	v_mfma_f32_16x16x32_bf16 v[118:121], v[174:177], v[198:201], v[118:121]
	v_mfma_f32_16x16x32_bf16 v[110:113], v[166:169], v[206:209], v[110:113]
	v_mfma_f32_16x16x32_bf16 v[102:105], v[174:177], v[206:209], v[102:105]
	v_mfma_f32_16x16x32_bf16 v[94:97], v[166:169], v[214:217], v[94:97]
	v_mfma_f32_16x16x32_bf16 v[86:89], v[174:177], v[214:217], v[86:89]
	v_mfma_f32_16x16x32_bf16 v[78:81], v[166:169], v[222:225], v[78:81]
	v_mfma_f32_16x16x32_bf16 v[70:73], v[174:177], v[222:225], v[70:73]
	v_mfma_f32_16x16x32_bf16 v[122:125], v[170:173], v[202:205], v[122:125]
	v_mfma_f32_16x16x32_bf16 v[118:121], v[178:181], v[202:205], v[118:121]
	v_mfma_f32_16x16x32_bf16 v[110:113], v[170:173], v[210:213], v[110:113]
	v_mfma_f32_16x16x32_bf16 v[102:105], v[178:181], v[210:213], v[102:105]
	v_mfma_f32_16x16x32_bf16 v[94:97], v[170:173], v[218:221], v[94:97]
	v_mfma_f32_16x16x32_bf16 v[86:89], v[178:181], v[218:221], v[86:89]
	v_mfma_f32_16x16x32_bf16 v[78:81], v[170:173], v[226:229], v[78:81]
	v_mfma_f32_16x16x32_bf16 v[70:73], v[178:181], v[226:229], v[70:73]
	s_setprio 0
	s_setprio 1
	v_mfma_f32_16x16x32_bf16 v[126:129], v[182:185], v[198:201], v[126:129]
	v_mfma_f32_16x16x32_bf16 v[114:117], v[190:193], v[198:201], v[114:117]
	v_mfma_f32_16x16x32_bf16 v[106:109], v[182:185], v[206:209], v[106:109]
	v_mfma_f32_16x16x32_bf16 v[98:101], v[190:193], v[206:209], v[98:101]
	v_mfma_f32_16x16x32_bf16 v[90:93], v[182:185], v[214:217], v[90:93]
	v_mfma_f32_16x16x32_bf16 v[82:85], v[190:193], v[214:217], v[82:85]
	v_mfma_f32_16x16x32_bf16 v[74:77], v[182:185], v[222:225], v[74:77]
	v_mfma_f32_16x16x32_bf16 v[66:69], v[190:193], v[222:225], v[66:69]
	v_mfma_f32_16x16x32_bf16 v[126:129], v[186:189], v[202:205], v[126:129]
	v_mfma_f32_16x16x32_bf16 v[114:117], v[194:197], v[202:205], v[114:117]
	v_mfma_f32_16x16x32_bf16 v[106:109], v[186:189], v[210:213], v[106:109]
	v_mfma_f32_16x16x32_bf16 v[98:101], v[194:197], v[210:213], v[98:101]
	v_mfma_f32_16x16x32_bf16 v[90:93], v[186:189], v[218:221], v[90:93]
	v_mfma_f32_16x16x32_bf16 v[82:85], v[194:197], v[218:221], v[82:85]
	v_mfma_f32_16x16x32_bf16 v[74:77], v[186:189], v[226:229], v[74:77]
	v_mfma_f32_16x16x32_bf16 v[66:69], v[194:197], v[226:229], v[66:69]
	s_setprio 0
	s_barrier
	s_add_u32 s98, s96, 0xb0000
	s_addc_u32 s99, s97, 0
	s_add_i32 s8, s69, s54
	s_mov_b32 m0, s8
	ds_read_b128 v[198:201], v163 offset:16384
	ds_read_b128 v[202:205], v163 offset:17408
	ds_read_b128 v[206:209], v163 offset:18432
	ds_read_b128 v[210:213], v163 offset:19456
	ds_read_b128 v[214:217], v163 offset:20480
	ds_read_b128 v[218:221], v163 offset:21504
	ds_read_b128 v[222:225], v163 offset:22528
	ds_read_b128 v[226:229], v163 offset:23552
	global_load_lds_dwordx4 v132, s[96:97]
	s_add_i32 m0, s8, 0x2000
	s_add_i32 s8, s72, s54
	global_load_lds_dwordx4 v136, s[96:97]
	s_mov_b32 m0, s8
	s_nop 0
	global_load_lds_dwordx4 v132, s[98:99]
	s_add_i32 m0, s8, 0x2000
	s_nop 0
	global_load_lds_dwordx4 v136, s[98:99]
	s_mov_b32 m0, s55
	s_nop 0
	global_load_lds_dwordx4 v130, s[94:95]
	s_mov_b32 m0, s56
	s_nop 0
	global_load_lds_dwordx4 v134, s[94:95]
	s_waitcnt vmcnt(8)
	s_waitcnt lgkmcnt(0)
	s_barrier
	s_setprio 1
	s_waitcnt lgkmcnt(0)
	v_mfma_f32_16x16x32_bf16 v[62:65], v[166:169], v[198:201], v[62:65]
	v_mfma_f32_16x16x32_bf16 v[54:57], v[174:177], v[198:201], v[54:57]
	v_mfma_f32_16x16x32_bf16 v[46:49], v[166:169], v[206:209], v[46:49]
	v_mfma_f32_16x16x32_bf16 v[38:41], v[174:177], v[206:209], v[38:41]
	v_mfma_f32_16x16x32_bf16 v[30:33], v[166:169], v[214:217], v[30:33]
	v_mfma_f32_16x16x32_bf16 v[22:25], v[174:177], v[214:217], v[22:25]
	v_mfma_f32_16x16x32_bf16 v[14:17], v[166:169], v[222:225], v[14:17]
	v_mfma_f32_16x16x32_bf16 v[6:9], v[174:177], v[222:225], v[6:9]
	v_mfma_f32_16x16x32_bf16 v[62:65], v[170:173], v[202:205], v[62:65]
	v_mfma_f32_16x16x32_bf16 v[54:57], v[178:181], v[202:205], v[54:57]
	v_mfma_f32_16x16x32_bf16 v[46:49], v[170:173], v[210:213], v[46:49]
	v_mfma_f32_16x16x32_bf16 v[38:41], v[178:181], v[210:213], v[38:41]
	v_mfma_f32_16x16x32_bf16 v[30:33], v[170:173], v[218:221], v[30:33]
	v_mfma_f32_16x16x32_bf16 v[22:25], v[178:181], v[218:221], v[22:25]
	v_mfma_f32_16x16x32_bf16 v[14:17], v[170:173], v[226:229], v[14:17]
	v_mfma_f32_16x16x32_bf16 v[6:9], v[178:181], v[226:229], v[6:9]
	s_setprio 0
	s_setprio 1
	v_mfma_f32_16x16x32_bf16 v[58:61], v[182:185], v[198:201], v[58:61]
	v_mfma_f32_16x16x32_bf16 v[50:53], v[190:193], v[198:201], v[50:53]
	v_mfma_f32_16x16x32_bf16 v[42:45], v[182:185], v[206:209], v[42:45]
	v_mfma_f32_16x16x32_bf16 v[34:37], v[190:193], v[206:209], v[34:37]
	v_mfma_f32_16x16x32_bf16 v[26:29], v[182:185], v[214:217], v[26:29]
	v_mfma_f32_16x16x32_bf16 v[18:21], v[190:193], v[214:217], v[18:21]
	v_mfma_f32_16x16x32_bf16 v[10:13], v[182:185], v[222:225], v[10:13]
	v_mfma_f32_16x16x32_bf16 v[2:5], v[190:193], v[222:225], v[2:5]
	v_mfma_f32_16x16x32_bf16 v[58:61], v[186:189], v[202:205], v[58:61]
	v_mfma_f32_16x16x32_bf16 v[50:53], v[194:197], v[202:205], v[50:53]
	v_mfma_f32_16x16x32_bf16 v[42:45], v[186:189], v[210:213], v[42:45]
	v_mfma_f32_16x16x32_bf16 v[34:37], v[194:197], v[210:213], v[34:37]
	v_mfma_f32_16x16x32_bf16 v[26:29], v[186:189], v[218:221], v[26:29]
	v_mfma_f32_16x16x32_bf16 v[18:21], v[194:197], v[218:221], v[18:21]
	v_mfma_f32_16x16x32_bf16 v[10:13], v[186:189], v[226:229], v[10:13]
	v_mfma_f32_16x16x32_bf16 v[2:5], v[194:197], v[226:229], v[2:5]
	s_setprio 0
	s_barrier
	s_add_u32 s98, s94, 0xb0000
	s_addc_u32 s99, s95, 0
	s_add_i32 s8, 0, 0x18000
	v_add_u32_e32 v146, s8, v160
	s_add_i32 s50, 0, 0x1c000
	ds_read_b128 v[166:169], v146
	ds_read_b128 v[170:173], v146 offset:1024
	ds_read_b128 v[174:177], v146 offset:2048
	ds_read_b128 v[178:181], v146 offset:3072
	v_add_u32_e32 v146, s50, v160
	ds_read_b128 v[182:185], v146
	ds_read_b128 v[186:189], v146 offset:1024
	ds_read_b128 v[190:193], v146 offset:2048
	ds_read_b128 v[194:197], v146 offset:3072
	s_mov_b32 m0, s57
	ds_read_b128 v[198:201], v163 offset:32768
	ds_read_b128 v[202:205], v163 offset:33792
	ds_read_b128 v[206:209], v163 offset:34816
	ds_read_b128 v[210:213], v163 offset:35840
	ds_read_b128 v[214:217], v163 offset:36864
	ds_read_b128 v[218:221], v163 offset:37888
	ds_read_b128 v[222:225], v163 offset:38912
	ds_read_b128 v[226:229], v163 offset:39936
	global_load_lds_dwordx4 v130, s[98:99]
	s_mov_b32 m0, s58
	s_nop 0
	global_load_lds_dwordx4 v134, s[98:99]
	s_waitcnt vmcnt(8)
	s_waitcnt lgkmcnt(0)
	s_barrier
	s_setprio 1
	s_waitcnt lgkmcnt(0)
	v_mfma_f32_16x16x32_bf16 v[122:125], v[166:169], v[198:201], v[122:125]
	v_mfma_f32_16x16x32_bf16 v[118:121], v[174:177], v[198:201], v[118:121]
	v_mfma_f32_16x16x32_bf16 v[110:113], v[166:169], v[206:209], v[110:113]
	v_mfma_f32_16x16x32_bf16 v[102:105], v[174:177], v[206:209], v[102:105]
	v_mfma_f32_16x16x32_bf16 v[94:97], v[166:169], v[214:217], v[94:97]
	v_mfma_f32_16x16x32_bf16 v[86:89], v[174:177], v[214:217], v[86:89]
	v_mfma_f32_16x16x32_bf16 v[78:81], v[166:169], v[222:225], v[78:81]
	v_mfma_f32_16x16x32_bf16 v[70:73], v[174:177], v[222:225], v[70:73]
	v_mfma_f32_16x16x32_bf16 v[122:125], v[170:173], v[202:205], v[122:125]
	v_mfma_f32_16x16x32_bf16 v[118:121], v[178:181], v[202:205], v[118:121]
	v_mfma_f32_16x16x32_bf16 v[110:113], v[170:173], v[210:213], v[110:113]
	v_mfma_f32_16x16x32_bf16 v[102:105], v[178:181], v[210:213], v[102:105]
	v_mfma_f32_16x16x32_bf16 v[94:97], v[170:173], v[218:221], v[94:97]
	v_mfma_f32_16x16x32_bf16 v[86:89], v[178:181], v[218:221], v[86:89]
	v_mfma_f32_16x16x32_bf16 v[78:81], v[170:173], v[226:229], v[78:81]
	v_mfma_f32_16x16x32_bf16 v[70:73], v[178:181], v[226:229], v[70:73]
	s_setprio 0
	s_setprio 1
	v_mfma_f32_16x16x32_bf16 v[126:129], v[182:185], v[198:201], v[126:129]
	v_mfma_f32_16x16x32_bf16 v[114:117], v[190:193], v[198:201], v[114:117]
	v_mfma_f32_16x16x32_bf16 v[106:109], v[182:185], v[206:209], v[106:109]
	v_mfma_f32_16x16x32_bf16 v[98:101], v[190:193], v[206:209], v[98:101]
	v_mfma_f32_16x16x32_bf16 v[90:93], v[182:185], v[214:217], v[90:93]
	v_mfma_f32_16x16x32_bf16 v[82:85], v[190:193], v[214:217], v[82:85]
	v_mfma_f32_16x16x32_bf16 v[74:77], v[182:185], v[222:225], v[74:77]
	v_mfma_f32_16x16x32_bf16 v[66:69], v[190:193], v[222:225], v[66:69]
	v_mfma_f32_16x16x32_bf16 v[126:129], v[186:189], v[202:205], v[126:129]
	v_mfma_f32_16x16x32_bf16 v[114:117], v[194:197], v[202:205], v[114:117]
	v_mfma_f32_16x16x32_bf16 v[106:109], v[186:189], v[210:213], v[106:109]
	v_mfma_f32_16x16x32_bf16 v[98:101], v[194:197], v[210:213], v[98:101]
	v_mfma_f32_16x16x32_bf16 v[90:93], v[186:189], v[218:221], v[90:93]
	v_mfma_f32_16x16x32_bf16 v[82:85], v[194:197], v[218:221], v[82:85]
	v_mfma_f32_16x16x32_bf16 v[74:77], v[186:189], v[226:229], v[74:77]
	v_mfma_f32_16x16x32_bf16 v[66:69], v[194:197], v[226:229], v[66:69]
	s_setprio 0
	s_barrier
	s_add_u32 s96, s96, 0x80
	s_addc_u32 s97, s97, 0
	s_add_u32 s98, s96, 0xb0000
	s_addc_u32 s99, s97, 0
	s_add_u32 s94, s94, 0x80
	s_addc_u32 s95, s95, 0
	s_add_i32 s8, s8, s54
	s_mov_b32 m0, s8
	ds_read_b128 v[198:201], v163 offset:49152
	ds_read_b128 v[202:205], v163 offset:50176
	ds_read_b128 v[206:209], v163 offset:51200
	ds_read_b128 v[210:213], v163 offset:52224
	ds_read_b128 v[214:217], v163 offset:53248
	ds_read_b128 v[218:221], v163 offset:54272
	ds_read_b128 v[222:225], v163 offset:55296
	ds_read_b128 v[226:229], v163 offset:56320
	global_load_lds_dwordx4 v132, s[96:97]
	s_add_i32 m0, s8, 0x2000
	s_add_i32 s8, s50, s54
	global_load_lds_dwordx4 v136, s[96:97]
	s_mov_b32 m0, s8
	s_nop 0
	global_load_lds_dwordx4 v132, s[98:99]
	s_add_i32 m0, s8, 0x2000
	s_nop 0
	global_load_lds_dwordx4 v136, s[98:99]
	s_mov_b32 m0, s64
	s_nop 0
	global_load_lds_dwordx4 v130, s[94:95]
	s_mov_b32 m0, s65
	s_nop 0
	global_load_lds_dwordx4 v134, s[94:95]
	s_waitcnt vmcnt(8)
	s_waitcnt lgkmcnt(0)
	s_barrier
	s_setprio 1
	s_waitcnt lgkmcnt(0)
	v_mfma_f32_16x16x32_bf16 v[62:65], v[166:169], v[198:201], v[62:65]
	v_mfma_f32_16x16x32_bf16 v[54:57], v[174:177], v[198:201], v[54:57]
	v_mfma_f32_16x16x32_bf16 v[46:49], v[166:169], v[206:209], v[46:49]
	v_mfma_f32_16x16x32_bf16 v[38:41], v[174:177], v[206:209], v[38:41]
	v_mfma_f32_16x16x32_bf16 v[30:33], v[166:169], v[214:217], v[30:33]
	v_mfma_f32_16x16x32_bf16 v[22:25], v[174:177], v[214:217], v[22:25]
	v_mfma_f32_16x16x32_bf16 v[14:17], v[166:169], v[222:225], v[14:17]
	v_mfma_f32_16x16x32_bf16 v[6:9], v[174:177], v[222:225], v[6:9]
	v_mfma_f32_16x16x32_bf16 v[62:65], v[170:173], v[202:205], v[62:65]
	v_mfma_f32_16x16x32_bf16 v[54:57], v[178:181], v[202:205], v[54:57]
	v_mfma_f32_16x16x32_bf16 v[46:49], v[170:173], v[210:213], v[46:49]
	v_mfma_f32_16x16x32_bf16 v[38:41], v[178:181], v[210:213], v[38:41]
	v_mfma_f32_16x16x32_bf16 v[30:33], v[170:173], v[218:221], v[30:33]
	v_mfma_f32_16x16x32_bf16 v[22:25], v[178:181], v[218:221], v[22:25]
	v_mfma_f32_16x16x32_bf16 v[14:17], v[170:173], v[226:229], v[14:17]
	v_mfma_f32_16x16x32_bf16 v[6:9], v[178:181], v[226:229], v[6:9]
	s_setprio 0
	s_setprio 1
	v_mfma_f32_16x16x32_bf16 v[58:61], v[182:185], v[198:201], v[58:61]
	v_mfma_f32_16x16x32_bf16 v[50:53], v[190:193], v[198:201], v[50:53]
	v_mfma_f32_16x16x32_bf16 v[42:45], v[182:185], v[206:209], v[42:45]
	v_mfma_f32_16x16x32_bf16 v[34:37], v[190:193], v[206:209], v[34:37]
	v_mfma_f32_16x16x32_bf16 v[26:29], v[182:185], v[214:217], v[26:29]
	v_mfma_f32_16x16x32_bf16 v[18:21], v[190:193], v[214:217], v[18:21]
	v_mfma_f32_16x16x32_bf16 v[10:13], v[182:185], v[222:225], v[10:13]
	v_mfma_f32_16x16x32_bf16 v[2:5], v[190:193], v[222:225], v[2:5]
	v_mfma_f32_16x16x32_bf16 v[58:61], v[186:189], v[202:205], v[58:61]
	v_mfma_f32_16x16x32_bf16 v[50:53], v[194:197], v[202:205], v[50:53]
	v_mfma_f32_16x16x32_bf16 v[42:45], v[186:189], v[210:213], v[42:45]
	v_mfma_f32_16x16x32_bf16 v[34:37], v[194:197], v[210:213], v[34:37]
	v_mfma_f32_16x16x32_bf16 v[26:29], v[186:189], v[218:221], v[26:29]
	v_mfma_f32_16x16x32_bf16 v[18:21], v[194:197], v[218:221], v[18:21]
	v_mfma_f32_16x16x32_bf16 v[10:13], v[186:189], v[226:229], v[10:13]
	v_mfma_f32_16x16x32_bf16 v[2:5], v[194:197], v[226:229], v[2:5]
	s_setprio 0
	s_barrier
	v_cmp_ge_i32_e32 vcc, s9, v141
	s_mov_b32 s8, s9
	s_add_u32 s88, s88, 0x100
	s_addc_u32 s89, s89, 0
	s_add_u32 s86, s86, 0x100
	s_addc_u32 s87, s87, 0
	s_cbranch_vccz .LBB0_310

.LBB0_497:
	v_cmp_gt_i32_e32 vcc, 1, v141
	s_cbranch_vccnz .LBB0_559
	v_lshl_add_u64 v[154:155], v[2:3], 0, s[16:17]
	v_add_u32_e32 v138, -2, v141
	v_lshl_add_u64 v[152:153], v[4:5], 0, s[20:21]
	s_mov_b32 s7, 0
	s_nop 0
	v_readfirstlane_b32 s86, v154
	v_readfirstlane_b32 s87, v155
	v_readfirstlane_b32 s88, v152
	v_readfirstlane_b32 s89, v153
	v_readfirstlane_b32 s90, v148
	v_readfirstlane_b32 s91, v149
	v_readfirstlane_b32 s92, v150
	v_readfirstlane_b32 s93, v151
	v_readfirstlane_b32 s100, v138
	s_add_u32 s98, s86, 0xfffc0080
	s_addc_u32 s99, s87, -1
	s_cmp_eq_u32 s7, s100
	s_cselect_b64 s[94:95], s[90:91], s[98:99]
	s_cselect_b64 s[96:97], s[92:93], s[88:89]
	v_add_u32_e32 v146, s77, v160
	ds_read_b128 v[156:159], v146
	ds_read_b128 v[166:169], v146 offset:1024
	ds_read_b128 v[170:173], v146 offset:2048
	ds_read_b128 v[174:177], v146 offset:3072
	v_add_u32_e32 v146, s78, v160
	ds_read_b128 v[178:181], v146
	ds_read_b128 v[182:185], v146 offset:1024
	ds_read_b128 v[186:189], v146 offset:2048
	ds_read_b128 v[190:193], v146 offset:3072
	s_add_i32 s45, s7, 2
	s_nop 0
	s_add_i32 m0, s49, 0xc000
	ds_read_b128 v[194:197], v163
	ds_read_b128 v[198:201], v163 offset:1024
	ds_read_b128 v[202:205], v163 offset:2048
	ds_read_b128 v[206:209], v163 offset:3072
	ds_read_b128 v[210:213], v163 offset:4096
	ds_read_b128 v[214:217], v163 offset:5120
	ds_read_b128 v[218:221], v163 offset:6144
	ds_read_b128 v[222:225], v163 offset:7168
	global_load_lds_dwordx4 v144, s[86:87]
	s_add_i32 m0, s49, 0xe000
	s_nop 0
	global_load_lds_dwordx4 v142, s[86:87]
	s_waitcnt vmcnt(8)
	s_waitcnt lgkmcnt(0)
	s_barrier
	s_setprio 1
	s_waitcnt lgkmcnt(0)
	v_mfma_f32_16x16x32_bf16 v[122:125], v[156:159], v[194:197], 0
	v_mfma_f32_16x16x32_bf16 v[118:121], v[170:173], v[194:197], 0
	v_mfma_f32_16x16x32_bf16 v[110:113], v[156:159], v[202:205], 0
	v_mfma_f32_16x16x32_bf16 v[102:105], v[170:173], v[202:205], 0
	v_mfma_f32_16x16x32_bf16 v[94:97], v[156:159], v[210:213], 0
	v_mfma_f32_16x16x32_bf16 v[86:89], v[170:173], v[210:213], 0
	v_mfma_f32_16x16x32_bf16 v[78:81], v[156:159], v[218:221], 0
	v_mfma_f32_16x16x32_bf16 v[70:73], v[170:173], v[218:221], 0
	v_mfma_f32_16x16x32_bf16 v[122:125], v[166:169], v[198:201], v[122:125]
	v_mfma_f32_16x16x32_bf16 v[118:121], v[174:177], v[198:201], v[118:121]
	v_mfma_f32_16x16x32_bf16 v[110:113], v[166:169], v[206:209], v[110:113]
	v_mfma_f32_16x16x32_bf16 v[102:105], v[174:177], v[206:209], v[102:105]
	v_mfma_f32_16x16x32_bf16 v[94:97], v[166:169], v[214:217], v[94:97]
	v_mfma_f32_16x16x32_bf16 v[86:89], v[174:177], v[214:217], v[86:89]
	v_mfma_f32_16x16x32_bf16 v[78:81], v[166:169], v[222:225], v[78:81]
	v_mfma_f32_16x16x32_bf16 v[70:73], v[174:177], v[222:225], v[70:73]
	s_setprio 0
	s_setprio 1
	v_mfma_f32_16x16x32_bf16 v[126:129], v[178:181], v[194:197], 0
	v_mfma_f32_16x16x32_bf16 v[114:117], v[186:189], v[194:197], 0
	v_mfma_f32_16x16x32_bf16 v[106:109], v[178:181], v[202:205], 0
	v_mfma_f32_16x16x32_bf16 v[98:101], v[186:189], v[202:205], 0
	v_mfma_f32_16x16x32_bf16 v[90:93], v[178:181], v[210:213], 0
	v_mfma_f32_16x16x32_bf16 v[82:85], v[186:189], v[210:213], 0
	v_mfma_f32_16x16x32_bf16 v[74:77], v[178:181], v[218:221], 0
	v_mfma_f32_16x16x32_bf16 v[66:69], v[186:189], v[218:221], 0
	v_mfma_f32_16x16x32_bf16 v[126:129], v[182:185], v[198:201], v[126:129]
	v_mfma_f32_16x16x32_bf16 v[114:117], v[190:193], v[198:201], v[114:117]
	v_mfma_f32_16x16x32_bf16 v[106:109], v[182:185], v[206:209], v[106:109]
	v_mfma_f32_16x16x32_bf16 v[98:101], v[190:193], v[206:209], v[98:101]
	v_mfma_f32_16x16x32_bf16 v[90:93], v[182:185], v[214:217], v[90:93]
	v_mfma_f32_16x16x32_bf16 v[82:85], v[190:193], v[214:217], v[82:85]
	v_mfma_f32_16x16x32_bf16 v[74:77], v[182:185], v[222:225], v[74:77]
	v_mfma_f32_16x16x32_bf16 v[66:69], v[190:193], v[222:225], v[66:69]
	s_setprio 0
	s_barrier
	s_add_u32 s98, s96, 0x40000
	s_addc_u32 s99, s97, 0
	s_add_i32 s7, s77, s25
	s_mov_b32 m0, s7
	ds_read_b128 v[194:197], v163 offset:16384
	ds_read_b128 v[198:201], v163 offset:17408
	ds_read_b128 v[202:205], v163 offset:18432
	ds_read_b128 v[206:209], v163 offset:19456
	ds_read_b128 v[210:213], v163 offset:20480
	ds_read_b128 v[214:217], v163 offset:21504
	ds_read_b128 v[218:221], v163 offset:22528
	ds_read_b128 v[222:225], v163 offset:23552
	global_load_lds_dwordx4 v132, s[96:97]
	s_add_i32 m0, s7, 0x2000
	s_add_i32 s7, s78, s25
	global_load_lds_dwordx4 v136, s[96:97]
	s_mov_b32 m0, s7
	s_nop 0
	global_load_lds_dwordx4 v132, s[98:99]
	s_add_i32 m0, s7, 0x2000
	s_nop 0
	global_load_lds_dwordx4 v136, s[98:99]
	s_mov_b32 m0, s49
	s_nop 0
	global_load_lds_dwordx4 v130, s[94:95]
	s_mov_b32 m0, s58
	s_nop 0
	global_load_lds_dwordx4 v134, s[94:95]
	s_waitcnt vmcnt(8)
	s_waitcnt lgkmcnt(0)
	s_barrier
	s_setprio 1
	s_waitcnt lgkmcnt(0)
	v_mfma_f32_16x16x32_bf16 v[62:65], v[156:159], v[194:197], 0
	v_mfma_f32_16x16x32_bf16 v[54:57], v[170:173], v[194:197], 0
	v_mfma_f32_16x16x32_bf16 v[46:49], v[156:159], v[202:205], 0
	v_mfma_f32_16x16x32_bf16 v[38:41], v[170:173], v[202:205], 0
	v_mfma_f32_16x16x32_bf16 v[30:33], v[156:159], v[210:213], 0
	v_mfma_f32_16x16x32_bf16 v[22:25], v[170:173], v[210:213], 0
	v_mfma_f32_16x16x32_bf16 v[14:17], v[156:159], v[218:221], 0
	v_mfma_f32_16x16x32_bf16 v[6:9], v[170:173], v[218:221], 0
	v_mfma_f32_16x16x32_bf16 v[62:65], v[166:169], v[198:201], v[62:65]
	v_mfma_f32_16x16x32_bf16 v[54:57], v[174:177], v[198:201], v[54:57]
	v_mfma_f32_16x16x32_bf16 v[46:49], v[166:169], v[206:209], v[46:49]
	v_mfma_f32_16x16x32_bf16 v[38:41], v[174:177], v[206:209], v[38:41]
	v_mfma_f32_16x16x32_bf16 v[30:33], v[166:169], v[214:217], v[30:33]
	v_mfma_f32_16x16x32_bf16 v[22:25], v[174:177], v[214:217], v[22:25]
	v_mfma_f32_16x16x32_bf16 v[14:17], v[166:169], v[222:225], v[14:17]
	v_mfma_f32_16x16x32_bf16 v[6:9], v[174:177], v[222:225], v[6:9]
	s_setprio 0
	s_setprio 1
	v_mfma_f32_16x16x32_bf16 v[58:61], v[178:181], v[194:197], 0
	v_mfma_f32_16x16x32_bf16 v[50:53], v[186:189], v[194:197], 0
	v_mfma_f32_16x16x32_bf16 v[42:45], v[178:181], v[202:205], 0
	v_mfma_f32_16x16x32_bf16 v[34:37], v[186:189], v[202:205], 0
	v_mfma_f32_16x16x32_bf16 v[26:29], v[178:181], v[210:213], 0
	v_mfma_f32_16x16x32_bf16 v[18:21], v[186:189], v[210:213], 0
	v_mfma_f32_16x16x32_bf16 v[10:13], v[178:181], v[218:221], 0
	v_mfma_f32_16x16x32_bf16 v[2:5], v[186:189], v[218:221], 0
	v_mfma_f32_16x16x32_bf16 v[58:61], v[182:185], v[198:201], v[58:61]
	v_mfma_f32_16x16x32_bf16 v[50:53], v[190:193], v[198:201], v[50:53]
	v_mfma_f32_16x16x32_bf16 v[42:45], v[182:185], v[206:209], v[42:45]
	v_mfma_f32_16x16x32_bf16 v[34:37], v[190:193], v[206:209], v[34:37]
	v_mfma_f32_16x16x32_bf16 v[26:29], v[182:185], v[214:217], v[26:29]
	v_mfma_f32_16x16x32_bf16 v[18:21], v[190:193], v[214:217], v[18:21]
	v_mfma_f32_16x16x32_bf16 v[10:13], v[182:185], v[222:225], v[10:13]
	v_mfma_f32_16x16x32_bf16 v[2:5], v[190:193], v[222:225], v[2:5]
	s_setprio 0
	s_barrier
	s_add_u32 s98, s94, 0x40000
	s_addc_u32 s99, s95, 0
	s_add_i32 s7, 0, 0x18000
	v_add_u32_e32 v146, s7, v160
	s_add_i32 s47, 0, 0x1c000
	ds_read_b128 v[156:159], v146
	ds_read_b128 v[166:169], v146 offset:1024
	ds_read_b128 v[170:173], v146 offset:2048
	ds_read_b128 v[174:177], v146 offset:3072
	v_add_u32_e32 v146, s47, v160
	ds_read_b128 v[178:181], v146
	ds_read_b128 v[182:185], v146 offset:1024
	ds_read_b128 v[186:189], v146 offset:2048
	ds_read_b128 v[190:193], v146 offset:3072
	s_mov_b32 m0, s59
	ds_read_b128 v[194:197], v163 offset:32768
	ds_read_b128 v[198:201], v163 offset:33792
	ds_read_b128 v[202:205], v163 offset:34816
	ds_read_b128 v[206:209], v163 offset:35840
	ds_read_b128 v[210:213], v163 offset:36864
	ds_read_b128 v[214:217], v163 offset:37888
	ds_read_b128 v[218:221], v163 offset:38912
	ds_read_b128 v[222:225], v163 offset:39936
	global_load_lds_dwordx4 v130, s[98:99]
	s_mov_b32 m0, s60
	s_nop 0
	global_load_lds_dwordx4 v134, s[98:99]
	s_waitcnt vmcnt(8)
	s_waitcnt lgkmcnt(0)
	s_barrier
	s_setprio 1
	s_waitcnt lgkmcnt(0)
	v_mfma_f32_16x16x32_bf16 v[122:125], v[156:159], v[194:197], v[122:125]
	v_mfma_f32_16x16x32_bf16 v[118:121], v[170:173], v[194:197], v[118:121]
	v_mfma_f32_16x16x32_bf16 v[110:113], v[156:159], v[202:205], v[110:113]
	v_mfma_f32_16x16x32_bf16 v[102:105], v[170:173], v[202:205], v[102:105]
	v_mfma_f32_16x16x32_bf16 v[94:97], v[156:159], v[210:213], v[94:97]
	v_mfma_f32_16x16x32_bf16 v[86:89], v[170:173], v[210:213], v[86:89]
	v_mfma_f32_16x16x32_bf16 v[78:81], v[156:159], v[218:221], v[78:81]
	v_mfma_f32_16x16x32_bf16 v[70:73], v[170:173], v[218:221], v[70:73]
	v_mfma_f32_16x16x32_bf16 v[122:125], v[166:169], v[198:201], v[122:125]
	v_mfma_f32_16x16x32_bf16 v[118:121], v[174:177], v[198:201], v[118:121]
	v_mfma_f32_16x16x32_bf16 v[110:113], v[166:169], v[206:209], v[110:113]
	v_mfma_f32_16x16x32_bf16 v[102:105], v[174:177], v[206:209], v[102:105]
	v_mfma_f32_16x16x32_bf16 v[94:97], v[166:169], v[214:217], v[94:97]
	v_mfma_f32_16x16x32_bf16 v[86:89], v[174:177], v[214:217], v[86:89]
	v_mfma_f32_16x16x32_bf16 v[78:81], v[166:169], v[222:225], v[78:81]
	v_mfma_f32_16x16x32_bf16 v[70:73], v[174:177], v[222:225], v[70:73]
	s_setprio 0
	s_setprio 1
	v_mfma_f32_16x16x32_bf16 v[126:129], v[178:181], v[194:197], v[126:129]
	v_mfma_f32_16x16x32_bf16 v[114:117], v[186:189], v[194:197], v[114:117]
	v_mfma_f32_16x16x32_bf16 v[106:109], v[178:181], v[202:205], v[106:109]
	v_mfma_f32_16x16x32_bf16 v[98:101], v[186:189], v[202:205], v[98:101]
	v_mfma_f32_16x16x32_bf16 v[90:93], v[178:181], v[210:213], v[90:93]
	v_mfma_f32_16x16x32_bf16 v[82:85], v[186:189], v[210:213], v[82:85]
	v_mfma_f32_16x16x32_bf16 v[74:77], v[178:181], v[218:221], v[74:77]
	v_mfma_f32_16x16x32_bf16 v[66:69], v[186:189], v[218:221], v[66:69]
	v_mfma_f32_16x16x32_bf16 v[126:129], v[182:185], v[198:201], v[126:129]
	v_mfma_f32_16x16x32_bf16 v[114:117], v[190:193], v[198:201], v[114:117]
	v_mfma_f32_16x16x32_bf16 v[106:109], v[182:185], v[206:209], v[106:109]
	v_mfma_f32_16x16x32_bf16 v[98:101], v[190:193], v[206:209], v[98:101]
	v_mfma_f32_16x16x32_bf16 v[90:93], v[182:185], v[214:217], v[90:93]
	v_mfma_f32_16x16x32_bf16 v[82:85], v[190:193], v[214:217], v[82:85]
	v_mfma_f32_16x16x32_bf16 v[74:77], v[182:185], v[222:225], v[74:77]
	v_mfma_f32_16x16x32_bf16 v[66:69], v[190:193], v[222:225], v[66:69]
	s_setprio 0
	s_barrier
	s_add_u32 s96, s96, 0x80
	s_addc_u32 s97, s97, 0
	s_add_u32 s98, s96, 0x40000
	s_addc_u32 s99, s97, 0
	s_add_u32 s94, s94, 0x80
	s_addc_u32 s95, s95, 0
	s_add_i32 s7, s7, s25
	s_mov_b32 m0, s7
	ds_read_b128 v[194:197], v163 offset:49152
	ds_read_b128 v[198:201], v163 offset:50176
	ds_read_b128 v[202:205], v163 offset:51200
	ds_read_b128 v[206:209], v163 offset:52224
	ds_read_b128 v[210:213], v163 offset:53248
	ds_read_b128 v[214:217], v163 offset:54272
	ds_read_b128 v[218:221], v163 offset:55296
	ds_read_b128 v[222:225], v163 offset:56320
	global_load_lds_dwordx4 v132, s[96:97]
	s_add_i32 m0, s7, 0x2000
	s_add_i32 s7, s47, s25
	global_load_lds_dwordx4 v136, s[96:97]
	s_mov_b32 m0, s7
	s_nop 0
	global_load_lds_dwordx4 v132, s[98:99]
	s_add_i32 m0, s7, 0x2000
	s_nop 0
	global_load_lds_dwordx4 v136, s[98:99]
	s_mov_b32 m0, s66
	s_nop 0
	global_load_lds_dwordx4 v130, s[94:95]
	s_mov_b32 m0, s67
	s_nop 0
	global_load_lds_dwordx4 v134, s[94:95]
	s_waitcnt vmcnt(8)
	s_waitcnt lgkmcnt(0)
	s_barrier
	s_setprio 1
	s_waitcnt lgkmcnt(0)
	v_mfma_f32_16x16x32_bf16 v[62:65], v[156:159], v[194:197], v[62:65]
	v_mfma_f32_16x16x32_bf16 v[54:57], v[170:173], v[194:197], v[54:57]
	v_mfma_f32_16x16x32_bf16 v[46:49], v[156:159], v[202:205], v[46:49]
	v_mfma_f32_16x16x32_bf16 v[38:41], v[170:173], v[202:205], v[38:41]
	v_mfma_f32_16x16x32_bf16 v[30:33], v[156:159], v[210:213], v[30:33]
	v_mfma_f32_16x16x32_bf16 v[22:25], v[170:173], v[210:213], v[22:25]
	v_mfma_f32_16x16x32_bf16 v[14:17], v[156:159], v[218:221], v[14:17]
	v_mfma_f32_16x16x32_bf16 v[6:9], v[170:173], v[218:221], v[6:9]
	v_mfma_f32_16x16x32_bf16 v[62:65], v[166:169], v[198:201], v[62:65]
	v_mfma_f32_16x16x32_bf16 v[54:57], v[174:177], v[198:201], v[54:57]
	v_mfma_f32_16x16x32_bf16 v[46:49], v[166:169], v[206:209], v[46:49]
	v_mfma_f32_16x16x32_bf16 v[38:41], v[174:177], v[206:209], v[38:41]
	v_mfma_f32_16x16x32_bf16 v[30:33], v[166:169], v[214:217], v[30:33]
	v_mfma_f32_16x16x32_bf16 v[22:25], v[174:177], v[214:217], v[22:25]
	v_mfma_f32_16x16x32_bf16 v[14:17], v[166:169], v[222:225], v[14:17]
	v_mfma_f32_16x16x32_bf16 v[6:9], v[174:177], v[222:225], v[6:9]
	s_setprio 0
	s_setprio 1
	v_mfma_f32_16x16x32_bf16 v[58:61], v[178:181], v[194:197], v[58:61]
	v_mfma_f32_16x16x32_bf16 v[50:53], v[186:189], v[194:197], v[50:53]
	v_mfma_f32_16x16x32_bf16 v[42:45], v[178:181], v[202:205], v[42:45]
	v_mfma_f32_16x16x32_bf16 v[34:37], v[186:189], v[202:205], v[34:37]
	v_mfma_f32_16x16x32_bf16 v[26:29], v[178:181], v[210:213], v[26:29]
	v_mfma_f32_16x16x32_bf16 v[18:21], v[186:189], v[210:213], v[18:21]
	v_mfma_f32_16x16x32_bf16 v[10:13], v[178:181], v[218:221], v[10:13]
	v_mfma_f32_16x16x32_bf16 v[2:5], v[186:189], v[218:221], v[2:5]
	v_mfma_f32_16x16x32_bf16 v[58:61], v[182:185], v[198:201], v[58:61]
	v_mfma_f32_16x16x32_bf16 v[50:53], v[190:193], v[198:201], v[50:53]
	v_mfma_f32_16x16x32_bf16 v[42:45], v[182:185], v[206:209], v[42:45]
	v_mfma_f32_16x16x32_bf16 v[34:37], v[190:193], v[206:209], v[34:37]
	v_mfma_f32_16x16x32_bf16 v[26:29], v[182:185], v[214:217], v[26:29]
	v_mfma_f32_16x16x32_bf16 v[18:21], v[190:193], v[214:217], v[18:21]
	v_mfma_f32_16x16x32_bf16 v[10:13], v[182:185], v[222:225], v[10:13]
	v_mfma_f32_16x16x32_bf16 v[2:5], v[190:193], v[222:225], v[2:5]
	s_setprio 0
	s_barrier
	v_cmp_ge_i32_e32 vcc, s45, v141
	s_mov_b32 s7, s45
	s_add_u32 s88, s88, 0x100
	s_addc_u32 s89, s89, 0
	s_add_u32 s86, s86, 0x100
	s_addc_u32 s87, s87, 0
	s_cbranch_vccnz .Lmy_kexit_2
.LBB0_499:
	s_add_u32 s98, s86, 0xfffc0080
	s_addc_u32 s99, s87, -1
	s_cmp_eq_u32 s7, s100
	s_cselect_b64 s[94:95], s[90:91], s[98:99]
	s_cselect_b64 s[96:97], s[92:93], s[88:89]
	v_add_u32_e32 v146, s77, v160
	ds_read_b128 v[156:159], v146
	ds_read_b128 v[166:169], v146 offset:1024
	ds_read_b128 v[170:173], v146 offset:2048
	ds_read_b128 v[174:177], v146 offset:3072
	v_add_u32_e32 v146, s78, v160
	ds_read_b128 v[178:181], v146
	ds_read_b128 v[182:185], v146 offset:1024
	ds_read_b128 v[186:189], v146 offset:2048
	ds_read_b128 v[190:193], v146 offset:3072
	s_add_i32 s45, s7, 2
	s_nop 0
	s_add_i32 m0, s49, 0xc000
	ds_read_b128 v[194:197], v163
	ds_read_b128 v[198:201], v163 offset:1024
	ds_read_b128 v[202:205], v163 offset:2048
	ds_read_b128 v[206:209], v163 offset:3072
	ds_read_b128 v[210:213], v163 offset:4096
	ds_read_b128 v[214:217], v163 offset:5120
	ds_read_b128 v[218:221], v163 offset:6144
	ds_read_b128 v[222:225], v163 offset:7168
	global_load_lds_dwordx4 v144, s[86:87]
	s_add_i32 m0, s49, 0xe000
	s_nop 0
	global_load_lds_dwordx4 v142, s[86:87]
	s_waitcnt vmcnt(8)
	s_waitcnt lgkmcnt(0)
	s_barrier
	s_setprio 1
	s_waitcnt lgkmcnt(0)
	v_mfma_f32_16x16x32_bf16 v[122:125], v[156:159], v[194:197], v[122:125]
	v_mfma_f32_16x16x32_bf16 v[118:121], v[170:173], v[194:197], v[118:121]
	v_mfma_f32_16x16x32_bf16 v[110:113], v[156:159], v[202:205], v[110:113]
	v_mfma_f32_16x16x32_bf16 v[102:105], v[170:173], v[202:205], v[102:105]
	v_mfma_f32_16x16x32_bf16 v[94:97], v[156:159], v[210:213], v[94:97]
	v_mfma_f32_16x16x32_bf16 v[86:89], v[170:173], v[210:213], v[86:89]
	v_mfma_f32_16x16x32_bf16 v[78:81], v[156:159], v[218:221], v[78:81]
	v_mfma_f32_16x16x32_bf16 v[70:73], v[170:173], v[218:221], v[70:73]
	v_mfma_f32_16x16x32_bf16 v[122:125], v[166:169], v[198:201], v[122:125]
	v_mfma_f32_16x16x32_bf16 v[118:121], v[174:177], v[198:201], v[118:121]
	v_mfma_f32_16x16x32_bf16 v[110:113], v[166:169], v[206:209], v[110:113]
	v_mfma_f32_16x16x32_bf16 v[102:105], v[174:177], v[206:209], v[102:105]
	v_mfma_f32_16x16x32_bf16 v[94:97], v[166:169], v[214:217], v[94:97]
	v_mfma_f32_16x16x32_bf16 v[86:89], v[174:177], v[214:217], v[86:89]
	v_mfma_f32_16x16x32_bf16 v[78:81], v[166:169], v[222:225], v[78:81]
	v_mfma_f32_16x16x32_bf16 v[70:73], v[174:177], v[222:225], v[70:73]
	s_setprio 0
	s_setprio 1
	v_mfma_f32_16x16x32_bf16 v[126:129], v[178:181], v[194:197], v[126:129]
	v_mfma_f32_16x16x32_bf16 v[114:117], v[186:189], v[194:197], v[114:117]
	v_mfma_f32_16x16x32_bf16 v[106:109], v[178:181], v[202:205], v[106:109]
	v_mfma_f32_16x16x32_bf16 v[98:101], v[186:189], v[202:205], v[98:101]
	v_mfma_f32_16x16x32_bf16 v[90:93], v[178:181], v[210:213], v[90:93]
	v_mfma_f32_16x16x32_bf16 v[82:85], v[186:189], v[210:213], v[82:85]
	v_mfma_f32_16x16x32_bf16 v[74:77], v[178:181], v[218:221], v[74:77]
	v_mfma_f32_16x16x32_bf16 v[66:69], v[186:189], v[218:221], v[66:69]
	v_mfma_f32_16x16x32_bf16 v[126:129], v[182:185], v[198:201], v[126:129]
	v_mfma_f32_16x16x32_bf16 v[114:117], v[190:193], v[198:201], v[114:117]
	v_mfma_f32_16x16x32_bf16 v[106:109], v[182:185], v[206:209], v[106:109]
	v_mfma_f32_16x16x32_bf16 v[98:101], v[190:193], v[206:209], v[98:101]
	v_mfma_f32_16x16x32_bf16 v[90:93], v[182:185], v[214:217], v[90:93]
	v_mfma_f32_16x16x32_bf16 v[82:85], v[190:193], v[214:217], v[82:85]
	v_mfma_f32_16x16x32_bf16 v[74:77], v[182:185], v[222:225], v[74:77]
	v_mfma_f32_16x16x32_bf16 v[66:69], v[190:193], v[222:225], v[66:69]
	s_setprio 0
	s_barrier
	s_add_u32 s98, s96, 0x40000
	s_addc_u32 s99, s97, 0
	s_add_i32 s7, s77, s25
	s_mov_b32 m0, s7
	ds_read_b128 v[194:197], v163 offset:16384
	ds_read_b128 v[198:201], v163 offset:17408
	ds_read_b128 v[202:205], v163 offset:18432
	ds_read_b128 v[206:209], v163 offset:19456
	ds_read_b128 v[210:213], v163 offset:20480
	ds_read_b128 v[214:217], v163 offset:21504
	ds_read_b128 v[218:221], v163 offset:22528
	ds_read_b128 v[222:225], v163 offset:23552
	global_load_lds_dwordx4 v132, s[96:97]
	s_add_i32 m0, s7, 0x2000
	s_add_i32 s7, s78, s25
	global_load_lds_dwordx4 v136, s[96:97]
	s_mov_b32 m0, s7
	s_nop 0
	global_load_lds_dwordx4 v132, s[98:99]
	s_add_i32 m0, s7, 0x2000
	s_nop 0
	global_load_lds_dwordx4 v136, s[98:99]
	s_mov_b32 m0, s49
	s_nop 0
	global_load_lds_dwordx4 v130, s[94:95]
	s_mov_b32 m0, s58
	s_nop 0
	global_load_lds_dwordx4 v134, s[94:95]
	s_waitcnt vmcnt(8)
	s_waitcnt lgkmcnt(0)
	s_barrier
	s_setprio 1
	s_waitcnt lgkmcnt(0)
	v_mfma_f32_16x16x32_bf16 v[62:65], v[156:159], v[194:197], v[62:65]
	v_mfma_f32_16x16x32_bf16 v[54:57], v[170:173], v[194:197], v[54:57]
	v_mfma_f32_16x16x32_bf16 v[46:49], v[156:159], v[202:205], v[46:49]
	v_mfma_f32_16x16x32_bf16 v[38:41], v[170:173], v[202:205], v[38:41]
	v_mfma_f32_16x16x32_bf16 v[30:33], v[156:159], v[210:213], v[30:33]
	v_mfma_f32_16x16x32_bf16 v[22:25], v[170:173], v[210:213], v[22:25]
	v_mfma_f32_16x16x32_bf16 v[14:17], v[156:159], v[218:221], v[14:17]
	v_mfma_f32_16x16x32_bf16 v[6:9], v[170:173], v[218:221], v[6:9]
	v_mfma_f32_16x16x32_bf16 v[62:65], v[166:169], v[198:201], v[62:65]
	v_mfma_f32_16x16x32_bf16 v[54:57], v[174:177], v[198:201], v[54:57]
	v_mfma_f32_16x16x32_bf16 v[46:49], v[166:169], v[206:209], v[46:49]
	v_mfma_f32_16x16x32_bf16 v[38:41], v[174:177], v[206:209], v[38:41]
	v_mfma_f32_16x16x32_bf16 v[30:33], v[166:169], v[214:217], v[30:33]
	v_mfma_f32_16x16x32_bf16 v[22:25], v[174:177], v[214:217], v[22:25]
	v_mfma_f32_16x16x32_bf16 v[14:17], v[166:169], v[222:225], v[14:17]
	v_mfma_f32_16x16x32_bf16 v[6:9], v[174:177], v[222:225], v[6:9]
	s_setprio 0
	s_setprio 1
	v_mfma_f32_16x16x32_bf16 v[58:61], v[178:181], v[194:197], v[58:61]
	v_mfma_f32_16x16x32_bf16 v[50:53], v[186:189], v[194:197], v[50:53]
	v_mfma_f32_16x16x32_bf16 v[42:45], v[178:181], v[202:205], v[42:45]
	v_mfma_f32_16x16x32_bf16 v[34:37], v[186:189], v[202:205], v[34:37]
	v_mfma_f32_16x16x32_bf16 v[26:29], v[178:181], v[210:213], v[26:29]
	v_mfma_f32_16x16x32_bf16 v[18:21], v[186:189], v[210:213], v[18:21]
	v_mfma_f32_16x16x32_bf16 v[10:13], v[178:181], v[218:221], v[10:13]
	v_mfma_f32_16x16x32_bf16 v[2:5], v[186:189], v[218:221], v[2:5]
	v_mfma_f32_16x16x32_bf16 v[58:61], v[182:185], v[198:201], v[58:61]
	v_mfma_f32_16x16x32_bf16 v[50:53], v[190:193], v[198:201], v[50:53]
	v_mfma_f32_16x16x32_bf16 v[42:45], v[182:185], v[206:209], v[42:45]
	v_mfma_f32_16x16x32_bf16 v[34:37], v[190:193], v[206:209], v[34:37]
	v_mfma_f32_16x16x32_bf16 v[26:29], v[182:185], v[214:217], v[26:29]
	v_mfma_f32_16x16x32_bf16 v[18:21], v[190:193], v[214:217], v[18:21]
	v_mfma_f32_16x16x32_bf16 v[10:13], v[182:185], v[222:225], v[10:13]
	v_mfma_f32_16x16x32_bf16 v[2:5], v[190:193], v[222:225], v[2:5]
	s_setprio 0
	s_barrier
	s_add_u32 s98, s94, 0x40000
	s_addc_u32 s99, s95, 0
	s_add_i32 s7, 0, 0x18000
	v_add_u32_e32 v146, s7, v160
	s_add_i32 s47, 0, 0x1c000
	ds_read_b128 v[156:159], v146
	ds_read_b128 v[166:169], v146 offset:1024
	ds_read_b128 v[170:173], v146 offset:2048
	ds_read_b128 v[174:177], v146 offset:3072
	v_add_u32_e32 v146, s47, v160
	ds_read_b128 v[178:181], v146
	ds_read_b128 v[182:185], v146 offset:1024
	ds_read_b128 v[186:189], v146 offset:2048
	ds_read_b128 v[190:193], v146 offset:3072
	s_mov_b32 m0, s59
	ds_read_b128 v[194:197], v163 offset:32768
	ds_read_b128 v[198:201], v163 offset:33792
	ds_read_b128 v[202:205], v163 offset:34816
	ds_read_b128 v[206:209], v163 offset:35840
	ds_read_b128 v[210:213], v163 offset:36864
	ds_read_b128 v[214:217], v163 offset:37888
	ds_read_b128 v[218:221], v163 offset:38912
	ds_read_b128 v[222:225], v163 offset:39936
	global_load_lds_dwordx4 v130, s[98:99]
	s_mov_b32 m0, s60
	s_nop 0
	global_load_lds_dwordx4 v134, s[98:99]
	s_waitcnt vmcnt(8)
	s_waitcnt lgkmcnt(0)
	s_barrier
	s_setprio 1
	s_waitcnt lgkmcnt(0)
	v_mfma_f32_16x16x32_bf16 v[122:125], v[156:159], v[194:197], v[122:125]
	v_mfma_f32_16x16x32_bf16 v[118:121], v[170:173], v[194:197], v[118:121]
	v_mfma_f32_16x16x32_bf16 v[110:113], v[156:159], v[202:205], v[110:113]
	v_mfma_f32_16x16x32_bf16 v[102:105], v[170:173], v[202:205], v[102:105]
	v_mfma_f32_16x16x32_bf16 v[94:97], v[156:159], v[210:213], v[94:97]
	v_mfma_f32_16x16x32_bf16 v[86:89], v[170:173], v[210:213], v[86:89]
	v_mfma_f32_16x16x32_bf16 v[78:81], v[156:159], v[218:221], v[78:81]
	v_mfma_f32_16x16x32_bf16 v[70:73], v[170:173], v[218:221], v[70:73]
	v_mfma_f32_16x16x32_bf16 v[122:125], v[166:169], v[198:201], v[122:125]
	v_mfma_f32_16x16x32_bf16 v[118:121], v[174:177], v[198:201], v[118:121]
	v_mfma_f32_16x16x32_bf16 v[110:113], v[166:169], v[206:209], v[110:113]
	v_mfma_f32_16x16x32_bf16 v[102:105], v[174:177], v[206:209], v[102:105]
	v_mfma_f32_16x16x32_bf16 v[94:97], v[166:169], v[214:217], v[94:97]
	v_mfma_f32_16x16x32_bf16 v[86:89], v[174:177], v[214:217], v[86:89]
	v_mfma_f32_16x16x32_bf16 v[78:81], v[166:169], v[222:225], v[78:81]
	v_mfma_f32_16x16x32_bf16 v[70:73], v[174:177], v[222:225], v[70:73]
	s_setprio 0
	s_setprio 1
	v_mfma_f32_16x16x32_bf16 v[126:129], v[178:181], v[194:197], v[126:129]
	v_mfma_f32_16x16x32_bf16 v[114:117], v[186:189], v[194:197], v[114:117]
	v_mfma_f32_16x16x32_bf16 v[106:109], v[178:181], v[202:205], v[106:109]
	v_mfma_f32_16x16x32_bf16 v[98:101], v[186:189], v[202:205], v[98:101]
	v_mfma_f32_16x16x32_bf16 v[90:93], v[178:181], v[210:213], v[90:93]
	v_mfma_f32_16x16x32_bf16 v[82:85], v[186:189], v[210:213], v[82:85]
	v_mfma_f32_16x16x32_bf16 v[74:77], v[178:181], v[218:221], v[74:77]
	v_mfma_f32_16x16x32_bf16 v[66:69], v[186:189], v[218:221], v[66:69]
	v_mfma_f32_16x16x32_bf16 v[126:129], v[182:185], v[198:201], v[126:129]
	v_mfma_f32_16x16x32_bf16 v[114:117], v[190:193], v[198:201], v[114:117]
	v_mfma_f32_16x16x32_bf16 v[106:109], v[182:185], v[206:209], v[106:109]
	v_mfma_f32_16x16x32_bf16 v[98:101], v[190:193], v[206:209], v[98:101]
	v_mfma_f32_16x16x32_bf16 v[90:93], v[182:185], v[214:217], v[90:93]
	v_mfma_f32_16x16x32_bf16 v[82:85], v[190:193], v[214:217], v[82:85]
	v_mfma_f32_16x16x32_bf16 v[74:77], v[182:185], v[222:225], v[74:77]
	v_mfma_f32_16x16x32_bf16 v[66:69], v[190:193], v[222:225], v[66:69]
	s_setprio 0
	s_barrier
	s_add_u32 s96, s96, 0x80
	s_addc_u32 s97, s97, 0
	s_add_u32 s98, s96, 0x40000
	s_addc_u32 s99, s97, 0
	s_add_u32 s94, s94, 0x80
	s_addc_u32 s95, s95, 0
	s_add_i32 s7, s7, s25
	s_mov_b32 m0, s7
	ds_read_b128 v[194:197], v163 offset:49152
	ds_read_b128 v[198:201], v163 offset:50176
	ds_read_b128 v[202:205], v163 offset:51200
	ds_read_b128 v[206:209], v163 offset:52224
	ds_read_b128 v[210:213], v163 offset:53248
	ds_read_b128 v[214:217], v163 offset:54272
	ds_read_b128 v[218:221], v163 offset:55296
	ds_read_b128 v[222:225], v163 offset:56320
	global_load_lds_dwordx4 v132, s[96:97]
	s_add_i32 m0, s7, 0x2000
	s_add_i32 s7, s47, s25
	global_load_lds_dwordx4 v136, s[96:97]
	s_mov_b32 m0, s7
	s_nop 0
	global_load_lds_dwordx4 v132, s[98:99]
	s_add_i32 m0, s7, 0x2000
	s_nop 0
	global_load_lds_dwordx4 v136, s[98:99]
	s_mov_b32 m0, s66
	s_nop 0
	global_load_lds_dwordx4 v130, s[94:95]
	s_mov_b32 m0, s67
	s_nop 0
	global_load_lds_dwordx4 v134, s[94:95]
	s_waitcnt vmcnt(8)
	s_waitcnt lgkmcnt(0)
	s_barrier
	s_setprio 1
	s_waitcnt lgkmcnt(0)
	v_mfma_f32_16x16x32_bf16 v[62:65], v[156:159], v[194:197], v[62:65]
	v_mfma_f32_16x16x32_bf16 v[54:57], v[170:173], v[194:197], v[54:57]
	v_mfma_f32_16x16x32_bf16 v[46:49], v[156:159], v[202:205], v[46:49]
	v_mfma_f32_16x16x32_bf16 v[38:41], v[170:173], v[202:205], v[38:41]
	v_mfma_f32_16x16x32_bf16 v[30:33], v[156:159], v[210:213], v[30:33]
	v_mfma_f32_16x16x32_bf16 v[22:25], v[170:173], v[210:213], v[22:25]
	v_mfma_f32_16x16x32_bf16 v[14:17], v[156:159], v[218:221], v[14:17]
	v_mfma_f32_16x16x32_bf16 v[6:9], v[170:173], v[218:221], v[6:9]
	v_mfma_f32_16x16x32_bf16 v[62:65], v[166:169], v[198:201], v[62:65]
	v_mfma_f32_16x16x32_bf16 v[54:57], v[174:177], v[198:201], v[54:57]
	v_mfma_f32_16x16x32_bf16 v[46:49], v[166:169], v[206:209], v[46:49]
	v_mfma_f32_16x16x32_bf16 v[38:41], v[174:177], v[206:209], v[38:41]
	v_mfma_f32_16x16x32_bf16 v[30:33], v[166:169], v[214:217], v[30:33]
	v_mfma_f32_16x16x32_bf16 v[22:25], v[174:177], v[214:217], v[22:25]
	v_mfma_f32_16x16x32_bf16 v[14:17], v[166:169], v[222:225], v[14:17]
	v_mfma_f32_16x16x32_bf16 v[6:9], v[174:177], v[222:225], v[6:9]
	s_setprio 0
	s_setprio 1
	v_mfma_f32_16x16x32_bf16 v[58:61], v[178:181], v[194:197], v[58:61]
	v_mfma_f32_16x16x32_bf16 v[50:53], v[186:189], v[194:197], v[50:53]
	v_mfma_f32_16x16x32_bf16 v[42:45], v[178:181], v[202:205], v[42:45]
	v_mfma_f32_16x16x32_bf16 v[34:37], v[186:189], v[202:205], v[34:37]
	v_mfma_f32_16x16x32_bf16 v[26:29], v[178:181], v[210:213], v[26:29]
	v_mfma_f32_16x16x32_bf16 v[18:21], v[186:189], v[210:213], v[18:21]
	v_mfma_f32_16x16x32_bf16 v[10:13], v[178:181], v[218:221], v[10:13]
	v_mfma_f32_16x16x32_bf16 v[2:5], v[186:189], v[218:221], v[2:5]
	v_mfma_f32_16x16x32_bf16 v[58:61], v[182:185], v[198:201], v[58:61]
	v_mfma_f32_16x16x32_bf16 v[50:53], v[190:193], v[198:201], v[50:53]
	v_mfma_f32_16x16x32_bf16 v[42:45], v[182:185], v[206:209], v[42:45]
	v_mfma_f32_16x16x32_bf16 v[34:37], v[190:193], v[206:209], v[34:37]
	v_mfma_f32_16x16x32_bf16 v[26:29], v[182:185], v[214:217], v[26:29]
	v_mfma_f32_16x16x32_bf16 v[18:21], v[190:193], v[214:217], v[18:21]
	v_mfma_f32_16x16x32_bf16 v[10:13], v[182:185], v[222:225], v[10:13]
	v_mfma_f32_16x16x32_bf16 v[2:5], v[190:193], v[222:225], v[2:5]
	s_setprio 0
	s_barrier
	v_cmp_ge_i32_e32 vcc, s45, v141
	s_mov_b32 s7, s45
	s_add_u32 s88, s88, 0x100
	s_addc_u32 s89, s89, 0
	s_add_u32 s86, s86, 0x100
	s_addc_u32 s87, s87, 0
	s_cbranch_vccz .LBB0_499

.LBB0_766:
	v_cmp_gt_i32_e32 vcc, 1, v138
	s_cbranch_vccnz .LBB0_828
	v_lshl_add_u64 v[152:153], v[2:3], 0, s[16:17]
	v_add_u32_e32 v154, -2, v138
	s_waitcnt lgkmcnt(0)
	v_lshl_add_u64 v[150:151], v[4:5], 0, s[20:21]
	s_mov_b32 s7, 0
	s_nop 0
	v_readfirstlane_b32 s86, v152
	v_readfirstlane_b32 s87, v153
	v_readfirstlane_b32 s88, v150
	v_readfirstlane_b32 s89, v151
	v_readfirstlane_b32 s90, v146
	v_readfirstlane_b32 s91, v147
	v_readfirstlane_b32 s92, v148
	v_readfirstlane_b32 s93, v149
	v_readfirstlane_b32 s100, v154
	s_add_u32 s98, s86, 0xfffc0080
	s_addc_u32 s99, s87, -1
	s_cmp_eq_u32 s7, s100
	s_cselect_b64 s[94:95], s[90:91], s[98:99]
	s_cselect_b64 s[96:97], s[92:93], s[88:89]
	v_add_u32_e32 v155, s76, v141
	ds_read_b128 v[164:167], v155
	ds_read_b128 v[168:171], v155 offset:1024
	ds_read_b128 v[172:175], v155 offset:2048
	ds_read_b128 v[176:179], v155 offset:3072
	v_add_u32_e32 v155, s77, v141
	ds_read_b128 v[180:183], v155
	ds_read_b128 v[184:187], v155 offset:1024
	ds_read_b128 v[188:191], v155 offset:2048
	ds_read_b128 v[192:195], v155 offset:3072
	s_add_i32 s45, s7, 2
	s_nop 0
	s_add_i32 m0, s49, 0xc000
	ds_read_b128 v[196:199], v160
	ds_read_b128 v[200:203], v160 offset:1024
	ds_read_b128 v[204:207], v160 offset:2048
	ds_read_b128 v[208:211], v160 offset:3072
	ds_read_b128 v[212:215], v160 offset:4096
	ds_read_b128 v[216:219], v160 offset:5120
	ds_read_b128 v[220:223], v160 offset:6144
	ds_read_b128 v[224:227], v160 offset:7168
	global_load_lds_dwordx4 v144, s[86:87]
	s_add_i32 m0, s49, 0xe000
	s_nop 0
	global_load_lds_dwordx4 v142, s[86:87]
	s_waitcnt vmcnt(8)
	s_waitcnt lgkmcnt(0)
	s_barrier
	s_setprio 1
	s_waitcnt lgkmcnt(0)
	v_mfma_f32_16x16x32_bf16 v[122:125], v[164:167], v[196:199], 0
	v_mfma_f32_16x16x32_bf16 v[118:121], v[172:175], v[196:199], 0
	v_mfma_f32_16x16x32_bf16 v[110:113], v[164:167], v[204:207], 0
	v_mfma_f32_16x16x32_bf16 v[102:105], v[172:175], v[204:207], 0
	v_mfma_f32_16x16x32_bf16 v[94:97], v[164:167], v[212:215], 0
	v_mfma_f32_16x16x32_bf16 v[86:89], v[172:175], v[212:215], 0
	v_mfma_f32_16x16x32_bf16 v[78:81], v[164:167], v[220:223], 0
	v_mfma_f32_16x16x32_bf16 v[70:73], v[172:175], v[220:223], 0
	v_mfma_f32_16x16x32_bf16 v[122:125], v[168:171], v[200:203], v[122:125]
	v_mfma_f32_16x16x32_bf16 v[118:121], v[176:179], v[200:203], v[118:121]
	v_mfma_f32_16x16x32_bf16 v[110:113], v[168:171], v[208:211], v[110:113]
	v_mfma_f32_16x16x32_bf16 v[102:105], v[176:179], v[208:211], v[102:105]
	v_mfma_f32_16x16x32_bf16 v[94:97], v[168:171], v[216:219], v[94:97]
	v_mfma_f32_16x16x32_bf16 v[86:89], v[176:179], v[216:219], v[86:89]
	v_mfma_f32_16x16x32_bf16 v[78:81], v[168:171], v[224:227], v[78:81]
	v_mfma_f32_16x16x32_bf16 v[70:73], v[176:179], v[224:227], v[70:73]
	s_setprio 0
	s_setprio 1
	v_mfma_f32_16x16x32_bf16 v[126:129], v[180:183], v[196:199], 0
	v_mfma_f32_16x16x32_bf16 v[114:117], v[188:191], v[196:199], 0
	v_mfma_f32_16x16x32_bf16 v[106:109], v[180:183], v[204:207], 0
	v_mfma_f32_16x16x32_bf16 v[98:101], v[188:191], v[204:207], 0
	v_mfma_f32_16x16x32_bf16 v[90:93], v[180:183], v[212:215], 0
	v_mfma_f32_16x16x32_bf16 v[82:85], v[188:191], v[212:215], 0
	v_mfma_f32_16x16x32_bf16 v[74:77], v[180:183], v[220:223], 0
	v_mfma_f32_16x16x32_bf16 v[66:69], v[188:191], v[220:223], 0
	v_mfma_f32_16x16x32_bf16 v[126:129], v[184:187], v[200:203], v[126:129]
	v_mfma_f32_16x16x32_bf16 v[114:117], v[192:195], v[200:203], v[114:117]
	v_mfma_f32_16x16x32_bf16 v[106:109], v[184:187], v[208:211], v[106:109]
	v_mfma_f32_16x16x32_bf16 v[98:101], v[192:195], v[208:211], v[98:101]
	v_mfma_f32_16x16x32_bf16 v[90:93], v[184:187], v[216:219], v[90:93]
	v_mfma_f32_16x16x32_bf16 v[82:85], v[192:195], v[216:219], v[82:85]
	v_mfma_f32_16x16x32_bf16 v[74:77], v[184:187], v[224:227], v[74:77]
	v_mfma_f32_16x16x32_bf16 v[66:69], v[192:195], v[224:227], v[66:69]
	s_setprio 0
	s_barrier
	s_add_u32 s98, s96, 0x40000
	s_addc_u32 s99, s97, 0
	s_add_i32 s7, s76, s25
	s_mov_b32 m0, s7
	ds_read_b128 v[196:199], v160 offset:16384
	ds_read_b128 v[200:203], v160 offset:17408
	ds_read_b128 v[204:207], v160 offset:18432
	ds_read_b128 v[208:211], v160 offset:19456
	ds_read_b128 v[212:215], v160 offset:20480
	ds_read_b128 v[216:219], v160 offset:21504
	ds_read_b128 v[220:223], v160 offset:22528
	ds_read_b128 v[224:227], v160 offset:23552
	global_load_lds_dwordx4 v132, s[96:97]
	s_add_i32 m0, s7, 0x2000
	s_add_i32 s7, s77, s25
	global_load_lds_dwordx4 v136, s[96:97]
	s_mov_b32 m0, s7
	s_nop 0
	global_load_lds_dwordx4 v132, s[98:99]
	s_add_i32 m0, s7, 0x2000
	s_nop 0
	global_load_lds_dwordx4 v136, s[98:99]
	s_mov_b32 m0, s49
	s_nop 0
	global_load_lds_dwordx4 v130, s[94:95]
	s_mov_b32 m0, s58
	s_nop 0
	global_load_lds_dwordx4 v134, s[94:95]
	s_waitcnt vmcnt(8)
	s_waitcnt lgkmcnt(0)
	s_barrier
	s_setprio 1
	s_waitcnt lgkmcnt(0)
	v_mfma_f32_16x16x32_bf16 v[62:65], v[164:167], v[196:199], 0
	v_mfma_f32_16x16x32_bf16 v[54:57], v[172:175], v[196:199], 0
	v_mfma_f32_16x16x32_bf16 v[46:49], v[164:167], v[204:207], 0
	v_mfma_f32_16x16x32_bf16 v[38:41], v[172:175], v[204:207], 0
	v_mfma_f32_16x16x32_bf16 v[30:33], v[164:167], v[212:215], 0
	v_mfma_f32_16x16x32_bf16 v[22:25], v[172:175], v[212:215], 0
	v_mfma_f32_16x16x32_bf16 v[14:17], v[164:167], v[220:223], 0
	v_mfma_f32_16x16x32_bf16 v[6:9], v[172:175], v[220:223], 0
	v_mfma_f32_16x16x32_bf16 v[62:65], v[168:171], v[200:203], v[62:65]
	v_mfma_f32_16x16x32_bf16 v[54:57], v[176:179], v[200:203], v[54:57]
	v_mfma_f32_16x16x32_bf16 v[46:49], v[168:171], v[208:211], v[46:49]
	v_mfma_f32_16x16x32_bf16 v[38:41], v[176:179], v[208:211], v[38:41]
	v_mfma_f32_16x16x32_bf16 v[30:33], v[168:171], v[216:219], v[30:33]
	v_mfma_f32_16x16x32_bf16 v[22:25], v[176:179], v[216:219], v[22:25]
	v_mfma_f32_16x16x32_bf16 v[14:17], v[168:171], v[224:227], v[14:17]
	v_mfma_f32_16x16x32_bf16 v[6:9], v[176:179], v[224:227], v[6:9]
	s_setprio 0
	s_setprio 1
	v_mfma_f32_16x16x32_bf16 v[58:61], v[180:183], v[196:199], 0
	v_mfma_f32_16x16x32_bf16 v[50:53], v[188:191], v[196:199], 0
	v_mfma_f32_16x16x32_bf16 v[42:45], v[180:183], v[204:207], 0
	v_mfma_f32_16x16x32_bf16 v[34:37], v[188:191], v[204:207], 0
	v_mfma_f32_16x16x32_bf16 v[26:29], v[180:183], v[212:215], 0
	v_mfma_f32_16x16x32_bf16 v[18:21], v[188:191], v[212:215], 0
	v_mfma_f32_16x16x32_bf16 v[10:13], v[180:183], v[220:223], 0
	v_mfma_f32_16x16x32_bf16 v[2:5], v[188:191], v[220:223], 0
	v_mfma_f32_16x16x32_bf16 v[58:61], v[184:187], v[200:203], v[58:61]
	v_mfma_f32_16x16x32_bf16 v[50:53], v[192:195], v[200:203], v[50:53]
	v_mfma_f32_16x16x32_bf16 v[42:45], v[184:187], v[208:211], v[42:45]
	v_mfma_f32_16x16x32_bf16 v[34:37], v[192:195], v[208:211], v[34:37]
	v_mfma_f32_16x16x32_bf16 v[26:29], v[184:187], v[216:219], v[26:29]
	v_mfma_f32_16x16x32_bf16 v[18:21], v[192:195], v[216:219], v[18:21]
	v_mfma_f32_16x16x32_bf16 v[10:13], v[184:187], v[224:227], v[10:13]
	v_mfma_f32_16x16x32_bf16 v[2:5], v[192:195], v[224:227], v[2:5]
	s_setprio 0
	s_barrier
	s_add_u32 s98, s94, 0x40000
	s_addc_u32 s99, s95, 0
	s_add_i32 s7, 0, 0x18000
	v_add_u32_e32 v155, s7, v141
	s_add_i32 s47, 0, 0x1c000
	ds_read_b128 v[164:167], v155
	ds_read_b128 v[168:171], v155 offset:1024
	ds_read_b128 v[172:175], v155 offset:2048
	ds_read_b128 v[176:179], v155 offset:3072
	v_add_u32_e32 v155, s47, v141
	ds_read_b128 v[180:183], v155
	ds_read_b128 v[184:187], v155 offset:1024
	ds_read_b128 v[188:191], v155 offset:2048
	ds_read_b128 v[192:195], v155 offset:3072
	s_mov_b32 m0, s59
	ds_read_b128 v[196:199], v160 offset:32768
	ds_read_b128 v[200:203], v160 offset:33792
	ds_read_b128 v[204:207], v160 offset:34816
	ds_read_b128 v[208:211], v160 offset:35840
	ds_read_b128 v[212:215], v160 offset:36864
	ds_read_b128 v[216:219], v160 offset:37888
	ds_read_b128 v[220:223], v160 offset:38912
	ds_read_b128 v[224:227], v160 offset:39936
	global_load_lds_dwordx4 v130, s[98:99]
	s_mov_b32 m0, s60
	s_nop 0
	global_load_lds_dwordx4 v134, s[98:99]
	s_waitcnt vmcnt(8)
	s_waitcnt lgkmcnt(0)
	s_barrier
	s_setprio 1
	s_waitcnt lgkmcnt(0)
	v_mfma_f32_16x16x32_bf16 v[122:125], v[164:167], v[196:199], v[122:125]
	v_mfma_f32_16x16x32_bf16 v[118:121], v[172:175], v[196:199], v[118:121]
	v_mfma_f32_16x16x32_bf16 v[110:113], v[164:167], v[204:207], v[110:113]
	v_mfma_f32_16x16x32_bf16 v[102:105], v[172:175], v[204:207], v[102:105]
	v_mfma_f32_16x16x32_bf16 v[94:97], v[164:167], v[212:215], v[94:97]
	v_mfma_f32_16x16x32_bf16 v[86:89], v[172:175], v[212:215], v[86:89]
	v_mfma_f32_16x16x32_bf16 v[78:81], v[164:167], v[220:223], v[78:81]
	v_mfma_f32_16x16x32_bf16 v[70:73], v[172:175], v[220:223], v[70:73]
	v_mfma_f32_16x16x32_bf16 v[122:125], v[168:171], v[200:203], v[122:125]
	v_mfma_f32_16x16x32_bf16 v[118:121], v[176:179], v[200:203], v[118:121]
	v_mfma_f32_16x16x32_bf16 v[110:113], v[168:171], v[208:211], v[110:113]
	v_mfma_f32_16x16x32_bf16 v[102:105], v[176:179], v[208:211], v[102:105]
	v_mfma_f32_16x16x32_bf16 v[94:97], v[168:171], v[216:219], v[94:97]
	v_mfma_f32_16x16x32_bf16 v[86:89], v[176:179], v[216:219], v[86:89]
	v_mfma_f32_16x16x32_bf16 v[78:81], v[168:171], v[224:227], v[78:81]
	v_mfma_f32_16x16x32_bf16 v[70:73], v[176:179], v[224:227], v[70:73]
	s_setprio 0
	s_setprio 1
	v_mfma_f32_16x16x32_bf16 v[126:129], v[180:183], v[196:199], v[126:129]
	v_mfma_f32_16x16x32_bf16 v[114:117], v[188:191], v[196:199], v[114:117]
	v_mfma_f32_16x16x32_bf16 v[106:109], v[180:183], v[204:207], v[106:109]
	v_mfma_f32_16x16x32_bf16 v[98:101], v[188:191], v[204:207], v[98:101]
	v_mfma_f32_16x16x32_bf16 v[90:93], v[180:183], v[212:215], v[90:93]
	v_mfma_f32_16x16x32_bf16 v[82:85], v[188:191], v[212:215], v[82:85]
	v_mfma_f32_16x16x32_bf16 v[74:77], v[180:183], v[220:223], v[74:77]
	v_mfma_f32_16x16x32_bf16 v[66:69], v[188:191], v[220:223], v[66:69]
	v_mfma_f32_16x16x32_bf16 v[126:129], v[184:187], v[200:203], v[126:129]
	v_mfma_f32_16x16x32_bf16 v[114:117], v[192:195], v[200:203], v[114:117]
	v_mfma_f32_16x16x32_bf16 v[106:109], v[184:187], v[208:211], v[106:109]
	v_mfma_f32_16x16x32_bf16 v[98:101], v[192:195], v[208:211], v[98:101]
	v_mfma_f32_16x16x32_bf16 v[90:93], v[184:187], v[216:219], v[90:93]
	v_mfma_f32_16x16x32_bf16 v[82:85], v[192:195], v[216:219], v[82:85]
	v_mfma_f32_16x16x32_bf16 v[74:77], v[184:187], v[224:227], v[74:77]
	v_mfma_f32_16x16x32_bf16 v[66:69], v[192:195], v[224:227], v[66:69]
	s_setprio 0
	s_barrier
	s_add_u32 s96, s96, 0x80
	s_addc_u32 s97, s97, 0
	s_add_u32 s98, s96, 0x40000
	s_addc_u32 s99, s97, 0
	s_add_u32 s94, s94, 0x80
	s_addc_u32 s95, s95, 0
	s_add_i32 s7, s7, s25
	s_mov_b32 m0, s7
	ds_read_b128 v[196:199], v160 offset:49152
	ds_read_b128 v[200:203], v160 offset:50176
	ds_read_b128 v[204:207], v160 offset:51200
	ds_read_b128 v[208:211], v160 offset:52224
	ds_read_b128 v[212:215], v160 offset:53248
	ds_read_b128 v[216:219], v160 offset:54272
	ds_read_b128 v[220:223], v160 offset:55296
	ds_read_b128 v[224:227], v160 offset:56320
	global_load_lds_dwordx4 v132, s[96:97]
	s_add_i32 m0, s7, 0x2000
	s_add_i32 s7, s47, s25
	global_load_lds_dwordx4 v136, s[96:97]
	s_mov_b32 m0, s7
	s_nop 0
	global_load_lds_dwordx4 v132, s[98:99]
	s_add_i32 m0, s7, 0x2000
	s_nop 0
	global_load_lds_dwordx4 v136, s[98:99]
	s_mov_b32 m0, s66
	s_nop 0
	global_load_lds_dwordx4 v130, s[94:95]
	s_mov_b32 m0, s67
	s_nop 0
	global_load_lds_dwordx4 v134, s[94:95]
	s_waitcnt vmcnt(8)
	s_waitcnt lgkmcnt(0)
	s_barrier
	s_setprio 1
	s_waitcnt lgkmcnt(0)
	v_mfma_f32_16x16x32_bf16 v[62:65], v[164:167], v[196:199], v[62:65]
	v_mfma_f32_16x16x32_bf16 v[54:57], v[172:175], v[196:199], v[54:57]
	v_mfma_f32_16x16x32_bf16 v[46:49], v[164:167], v[204:207], v[46:49]
	v_mfma_f32_16x16x32_bf16 v[38:41], v[172:175], v[204:207], v[38:41]
	v_mfma_f32_16x16x32_bf16 v[30:33], v[164:167], v[212:215], v[30:33]
	v_mfma_f32_16x16x32_bf16 v[22:25], v[172:175], v[212:215], v[22:25]
	v_mfma_f32_16x16x32_bf16 v[14:17], v[164:167], v[220:223], v[14:17]
	v_mfma_f32_16x16x32_bf16 v[6:9], v[172:175], v[220:223], v[6:9]
	v_mfma_f32_16x16x32_bf16 v[62:65], v[168:171], v[200:203], v[62:65]
	v_mfma_f32_16x16x32_bf16 v[54:57], v[176:179], v[200:203], v[54:57]
	v_mfma_f32_16x16x32_bf16 v[46:49], v[168:171], v[208:211], v[46:49]
	v_mfma_f32_16x16x32_bf16 v[38:41], v[176:179], v[208:211], v[38:41]
	v_mfma_f32_16x16x32_bf16 v[30:33], v[168:171], v[216:219], v[30:33]
	v_mfma_f32_16x16x32_bf16 v[22:25], v[176:179], v[216:219], v[22:25]
	v_mfma_f32_16x16x32_bf16 v[14:17], v[168:171], v[224:227], v[14:17]
	v_mfma_f32_16x16x32_bf16 v[6:9], v[176:179], v[224:227], v[6:9]
	s_setprio 0
	s_setprio 1
	v_mfma_f32_16x16x32_bf16 v[58:61], v[180:183], v[196:199], v[58:61]
	v_mfma_f32_16x16x32_bf16 v[50:53], v[188:191], v[196:199], v[50:53]
	v_mfma_f32_16x16x32_bf16 v[42:45], v[180:183], v[204:207], v[42:45]
	v_mfma_f32_16x16x32_bf16 v[34:37], v[188:191], v[204:207], v[34:37]
	v_mfma_f32_16x16x32_bf16 v[26:29], v[180:183], v[212:215], v[26:29]
	v_mfma_f32_16x16x32_bf16 v[18:21], v[188:191], v[212:215], v[18:21]
	v_mfma_f32_16x16x32_bf16 v[10:13], v[180:183], v[220:223], v[10:13]
	v_mfma_f32_16x16x32_bf16 v[2:5], v[188:191], v[220:223], v[2:5]
	v_mfma_f32_16x16x32_bf16 v[58:61], v[184:187], v[200:203], v[58:61]
	v_mfma_f32_16x16x32_bf16 v[50:53], v[192:195], v[200:203], v[50:53]
	v_mfma_f32_16x16x32_bf16 v[42:45], v[184:187], v[208:211], v[42:45]
	v_mfma_f32_16x16x32_bf16 v[34:37], v[192:195], v[208:211], v[34:37]
	v_mfma_f32_16x16x32_bf16 v[26:29], v[184:187], v[216:219], v[26:29]
	v_mfma_f32_16x16x32_bf16 v[18:21], v[192:195], v[216:219], v[18:21]
	v_mfma_f32_16x16x32_bf16 v[10:13], v[184:187], v[224:227], v[10:13]
	v_mfma_f32_16x16x32_bf16 v[2:5], v[192:195], v[224:227], v[2:5]
	s_setprio 0
	s_barrier
	v_cmp_ge_i32_e32 vcc, s45, v138
	s_mov_b32 s7, s45
	s_add_u32 s88, s88, 0x100
	s_addc_u32 s89, s89, 0
	s_add_u32 s86, s86, 0x100
	s_addc_u32 s87, s87, 0
	s_cbranch_vccnz .Lmy_kexit_3
.LBB0_768:
	s_add_u32 s98, s86, 0xfffc0080
	s_addc_u32 s99, s87, -1
	s_cmp_eq_u32 s7, s100
	s_cselect_b64 s[94:95], s[90:91], s[98:99]
	s_cselect_b64 s[96:97], s[92:93], s[88:89]
	v_add_u32_e32 v155, s76, v141
	ds_read_b128 v[164:167], v155
	ds_read_b128 v[168:171], v155 offset:1024
	ds_read_b128 v[172:175], v155 offset:2048
	ds_read_b128 v[176:179], v155 offset:3072
	v_add_u32_e32 v155, s77, v141
	ds_read_b128 v[180:183], v155
	ds_read_b128 v[184:187], v155 offset:1024
	ds_read_b128 v[188:191], v155 offset:2048
	ds_read_b128 v[192:195], v155 offset:3072
	s_add_i32 s45, s7, 2
	s_nop 0
	s_add_i32 m0, s49, 0xc000
	ds_read_b128 v[196:199], v160
	ds_read_b128 v[200:203], v160 offset:1024
	ds_read_b128 v[204:207], v160 offset:2048
	ds_read_b128 v[208:211], v160 offset:3072
	ds_read_b128 v[212:215], v160 offset:4096
	ds_read_b128 v[216:219], v160 offset:5120
	ds_read_b128 v[220:223], v160 offset:6144
	ds_read_b128 v[224:227], v160 offset:7168
	global_load_lds_dwordx4 v144, s[86:87]
	s_add_i32 m0, s49, 0xe000
	s_nop 0
	global_load_lds_dwordx4 v142, s[86:87]
	s_waitcnt vmcnt(8)
	s_waitcnt lgkmcnt(0)
	s_barrier
	s_setprio 1
	s_waitcnt lgkmcnt(0)
	v_mfma_f32_16x16x32_bf16 v[122:125], v[164:167], v[196:199], v[122:125]
	v_mfma_f32_16x16x32_bf16 v[118:121], v[172:175], v[196:199], v[118:121]
	v_mfma_f32_16x16x32_bf16 v[110:113], v[164:167], v[204:207], v[110:113]
	v_mfma_f32_16x16x32_bf16 v[102:105], v[172:175], v[204:207], v[102:105]
	v_mfma_f32_16x16x32_bf16 v[94:97], v[164:167], v[212:215], v[94:97]
	v_mfma_f32_16x16x32_bf16 v[86:89], v[172:175], v[212:215], v[86:89]
	v_mfma_f32_16x16x32_bf16 v[78:81], v[164:167], v[220:223], v[78:81]
	v_mfma_f32_16x16x32_bf16 v[70:73], v[172:175], v[220:223], v[70:73]
	v_mfma_f32_16x16x32_bf16 v[122:125], v[168:171], v[200:203], v[122:125]
	v_mfma_f32_16x16x32_bf16 v[118:121], v[176:179], v[200:203], v[118:121]
	v_mfma_f32_16x16x32_bf16 v[110:113], v[168:171], v[208:211], v[110:113]
	v_mfma_f32_16x16x32_bf16 v[102:105], v[176:179], v[208:211], v[102:105]
	v_mfma_f32_16x16x32_bf16 v[94:97], v[168:171], v[216:219], v[94:97]
	v_mfma_f32_16x16x32_bf16 v[86:89], v[176:179], v[216:219], v[86:89]
	v_mfma_f32_16x16x32_bf16 v[78:81], v[168:171], v[224:227], v[78:81]
	v_mfma_f32_16x16x32_bf16 v[70:73], v[176:179], v[224:227], v[70:73]
	s_setprio 0
	s_setprio 1
	v_mfma_f32_16x16x32_bf16 v[126:129], v[180:183], v[196:199], v[126:129]
	v_mfma_f32_16x16x32_bf16 v[114:117], v[188:191], v[196:199], v[114:117]
	v_mfma_f32_16x16x32_bf16 v[106:109], v[180:183], v[204:207], v[106:109]
	v_mfma_f32_16x16x32_bf16 v[98:101], v[188:191], v[204:207], v[98:101]
	v_mfma_f32_16x16x32_bf16 v[90:93], v[180:183], v[212:215], v[90:93]
	v_mfma_f32_16x16x32_bf16 v[82:85], v[188:191], v[212:215], v[82:85]
	v_mfma_f32_16x16x32_bf16 v[74:77], v[180:183], v[220:223], v[74:77]
	v_mfma_f32_16x16x32_bf16 v[66:69], v[188:191], v[220:223], v[66:69]
	v_mfma_f32_16x16x32_bf16 v[126:129], v[184:187], v[200:203], v[126:129]
	v_mfma_f32_16x16x32_bf16 v[114:117], v[192:195], v[200:203], v[114:117]
	v_mfma_f32_16x16x32_bf16 v[106:109], v[184:187], v[208:211], v[106:109]
	v_mfma_f32_16x16x32_bf16 v[98:101], v[192:195], v[208:211], v[98:101]
	v_mfma_f32_16x16x32_bf16 v[90:93], v[184:187], v[216:219], v[90:93]
	v_mfma_f32_16x16x32_bf16 v[82:85], v[192:195], v[216:219], v[82:85]
	v_mfma_f32_16x16x32_bf16 v[74:77], v[184:187], v[224:227], v[74:77]
	v_mfma_f32_16x16x32_bf16 v[66:69], v[192:195], v[224:227], v[66:69]
	s_setprio 0
	s_barrier
	s_add_u32 s98, s96, 0x40000
	s_addc_u32 s99, s97, 0
	s_add_i32 s7, s76, s25
	s_mov_b32 m0, s7
	ds_read_b128 v[196:199], v160 offset:16384
	ds_read_b128 v[200:203], v160 offset:17408
	ds_read_b128 v[204:207], v160 offset:18432
	ds_read_b128 v[208:211], v160 offset:19456
	ds_read_b128 v[212:215], v160 offset:20480
	ds_read_b128 v[216:219], v160 offset:21504
	ds_read_b128 v[220:223], v160 offset:22528
	ds_read_b128 v[224:227], v160 offset:23552
	global_load_lds_dwordx4 v132, s[96:97]
	s_add_i32 m0, s7, 0x2000
	s_add_i32 s7, s77, s25
	global_load_lds_dwordx4 v136, s[96:97]
	s_mov_b32 m0, s7
	s_nop 0
	global_load_lds_dwordx4 v132, s[98:99]
	s_add_i32 m0, s7, 0x2000
	s_nop 0
	global_load_lds_dwordx4 v136, s[98:99]
	s_mov_b32 m0, s49
	s_nop 0
	global_load_lds_dwordx4 v130, s[94:95]
	s_mov_b32 m0, s58
	s_nop 0
	global_load_lds_dwordx4 v134, s[94:95]
	s_waitcnt vmcnt(8)
	s_waitcnt lgkmcnt(0)
	s_barrier
	s_setprio 1
	s_waitcnt lgkmcnt(0)
	v_mfma_f32_16x16x32_bf16 v[62:65], v[164:167], v[196:199], v[62:65]
	v_mfma_f32_16x16x32_bf16 v[54:57], v[172:175], v[196:199], v[54:57]
	v_mfma_f32_16x16x32_bf16 v[46:49], v[164:167], v[204:207], v[46:49]
	v_mfma_f32_16x16x32_bf16 v[38:41], v[172:175], v[204:207], v[38:41]
	v_mfma_f32_16x16x32_bf16 v[30:33], v[164:167], v[212:215], v[30:33]
	v_mfma_f32_16x16x32_bf16 v[22:25], v[172:175], v[212:215], v[22:25]
	v_mfma_f32_16x16x32_bf16 v[14:17], v[164:167], v[220:223], v[14:17]
	v_mfma_f32_16x16x32_bf16 v[6:9], v[172:175], v[220:223], v[6:9]
	v_mfma_f32_16x16x32_bf16 v[62:65], v[168:171], v[200:203], v[62:65]
	v_mfma_f32_16x16x32_bf16 v[54:57], v[176:179], v[200:203], v[54:57]
	v_mfma_f32_16x16x32_bf16 v[46:49], v[168:171], v[208:211], v[46:49]
	v_mfma_f32_16x16x32_bf16 v[38:41], v[176:179], v[208:211], v[38:41]
	v_mfma_f32_16x16x32_bf16 v[30:33], v[168:171], v[216:219], v[30:33]
	v_mfma_f32_16x16x32_bf16 v[22:25], v[176:179], v[216:219], v[22:25]
	v_mfma_f32_16x16x32_bf16 v[14:17], v[168:171], v[224:227], v[14:17]
	v_mfma_f32_16x16x32_bf16 v[6:9], v[176:179], v[224:227], v[6:9]
	s_setprio 0
	s_setprio 1
	v_mfma_f32_16x16x32_bf16 v[58:61], v[180:183], v[196:199], v[58:61]
	v_mfma_f32_16x16x32_bf16 v[50:53], v[188:191], v[196:199], v[50:53]
	v_mfma_f32_16x16x32_bf16 v[42:45], v[180:183], v[204:207], v[42:45]
	v_mfma_f32_16x16x32_bf16 v[34:37], v[188:191], v[204:207], v[34:37]
	v_mfma_f32_16x16x32_bf16 v[26:29], v[180:183], v[212:215], v[26:29]
	v_mfma_f32_16x16x32_bf16 v[18:21], v[188:191], v[212:215], v[18:21]
	v_mfma_f32_16x16x32_bf16 v[10:13], v[180:183], v[220:223], v[10:13]
	v_mfma_f32_16x16x32_bf16 v[2:5], v[188:191], v[220:223], v[2:5]
	v_mfma_f32_16x16x32_bf16 v[58:61], v[184:187], v[200:203], v[58:61]
	v_mfma_f32_16x16x32_bf16 v[50:53], v[192:195], v[200:203], v[50:53]
	v_mfma_f32_16x16x32_bf16 v[42:45], v[184:187], v[208:211], v[42:45]
	v_mfma_f32_16x16x32_bf16 v[34:37], v[192:195], v[208:211], v[34:37]
	v_mfma_f32_16x16x32_bf16 v[26:29], v[184:187], v[216:219], v[26:29]
	v_mfma_f32_16x16x32_bf16 v[18:21], v[192:195], v[216:219], v[18:21]
	v_mfma_f32_16x16x32_bf16 v[10:13], v[184:187], v[224:227], v[10:13]
	v_mfma_f32_16x16x32_bf16 v[2:5], v[192:195], v[224:227], v[2:5]
	s_setprio 0
	s_barrier
	s_add_u32 s98, s94, 0x40000
	s_addc_u32 s99, s95, 0
	s_add_i32 s7, 0, 0x18000
	v_add_u32_e32 v155, s7, v141
	s_add_i32 s47, 0, 0x1c000
	ds_read_b128 v[164:167], v155
	ds_read_b128 v[168:171], v155 offset:1024
	ds_read_b128 v[172:175], v155 offset:2048
	ds_read_b128 v[176:179], v155 offset:3072
	v_add_u32_e32 v155, s47, v141
	ds_read_b128 v[180:183], v155
	ds_read_b128 v[184:187], v155 offset:1024
	ds_read_b128 v[188:191], v155 offset:2048
	ds_read_b128 v[192:195], v155 offset:3072
	s_mov_b32 m0, s59
	ds_read_b128 v[196:199], v160 offset:32768
	ds_read_b128 v[200:203], v160 offset:33792
	ds_read_b128 v[204:207], v160 offset:34816
	ds_read_b128 v[208:211], v160 offset:35840
	ds_read_b128 v[212:215], v160 offset:36864
	ds_read_b128 v[216:219], v160 offset:37888
	ds_read_b128 v[220:223], v160 offset:38912
	ds_read_b128 v[224:227], v160 offset:39936
	global_load_lds_dwordx4 v130, s[98:99]
	s_mov_b32 m0, s60
	s_nop 0
	global_load_lds_dwordx4 v134, s[98:99]
	s_waitcnt vmcnt(8)
	s_waitcnt lgkmcnt(0)
	s_barrier
	s_setprio 1
	s_waitcnt lgkmcnt(0)
	v_mfma_f32_16x16x32_bf16 v[122:125], v[164:167], v[196:199], v[122:125]
	v_mfma_f32_16x16x32_bf16 v[118:121], v[172:175], v[196:199], v[118:121]
	v_mfma_f32_16x16x32_bf16 v[110:113], v[164:167], v[204:207], v[110:113]
	v_mfma_f32_16x16x32_bf16 v[102:105], v[172:175], v[204:207], v[102:105]
	v_mfma_f32_16x16x32_bf16 v[94:97], v[164:167], v[212:215], v[94:97]
	v_mfma_f32_16x16x32_bf16 v[86:89], v[172:175], v[212:215], v[86:89]
	v_mfma_f32_16x16x32_bf16 v[78:81], v[164:167], v[220:223], v[78:81]
	v_mfma_f32_16x16x32_bf16 v[70:73], v[172:175], v[220:223], v[70:73]
	v_mfma_f32_16x16x32_bf16 v[122:125], v[168:171], v[200:203], v[122:125]
	v_mfma_f32_16x16x32_bf16 v[118:121], v[176:179], v[200:203], v[118:121]
	v_mfma_f32_16x16x32_bf16 v[110:113], v[168:171], v[208:211], v[110:113]
	v_mfma_f32_16x16x32_bf16 v[102:105], v[176:179], v[208:211], v[102:105]
	v_mfma_f32_16x16x32_bf16 v[94:97], v[168:171], v[216:219], v[94:97]
	v_mfma_f32_16x16x32_bf16 v[86:89], v[176:179], v[216:219], v[86:89]
	v_mfma_f32_16x16x32_bf16 v[78:81], v[168:171], v[224:227], v[78:81]
	v_mfma_f32_16x16x32_bf16 v[70:73], v[176:179], v[224:227], v[70:73]
	s_setprio 0
	s_setprio 1
	v_mfma_f32_16x16x32_bf16 v[126:129], v[180:183], v[196:199], v[126:129]
	v_mfma_f32_16x16x32_bf16 v[114:117], v[188:191], v[196:199], v[114:117]
	v_mfma_f32_16x16x32_bf16 v[106:109], v[180:183], v[204:207], v[106:109]
	v_mfma_f32_16x16x32_bf16 v[98:101], v[188:191], v[204:207], v[98:101]
	v_mfma_f32_16x16x32_bf16 v[90:93], v[180:183], v[212:215], v[90:93]
	v_mfma_f32_16x16x32_bf16 v[82:85], v[188:191], v[212:215], v[82:85]
	v_mfma_f32_16x16x32_bf16 v[74:77], v[180:183], v[220:223], v[74:77]
	v_mfma_f32_16x16x32_bf16 v[66:69], v[188:191], v[220:223], v[66:69]
	v_mfma_f32_16x16x32_bf16 v[126:129], v[184:187], v[200:203], v[126:129]
	v_mfma_f32_16x16x32_bf16 v[114:117], v[192:195], v[200:203], v[114:117]
	v_mfma_f32_16x16x32_bf16 v[106:109], v[184:187], v[208:211], v[106:109]
	v_mfma_f32_16x16x32_bf16 v[98:101], v[192:195], v[208:211], v[98:101]
	v_mfma_f32_16x16x32_bf16 v[90:93], v[184:187], v[216:219], v[90:93]
	v_mfma_f32_16x16x32_bf16 v[82:85], v[192:195], v[216:219], v[82:85]
	v_mfma_f32_16x16x32_bf16 v[74:77], v[184:187], v[224:227], v[74:77]
	v_mfma_f32_16x16x32_bf16 v[66:69], v[192:195], v[224:227], v[66:69]
	s_setprio 0
	s_barrier
	s_add_u32 s96, s96, 0x80
	s_addc_u32 s97, s97, 0
	s_add_u32 s98, s96, 0x40000
	s_addc_u32 s99, s97, 0
	s_add_u32 s94, s94, 0x80
	s_addc_u32 s95, s95, 0
	s_add_i32 s7, s7, s25
	s_mov_b32 m0, s7
	ds_read_b128 v[196:199], v160 offset:49152
	ds_read_b128 v[200:203], v160 offset:50176
	ds_read_b128 v[204:207], v160 offset:51200
	ds_read_b128 v[208:211], v160 offset:52224
	ds_read_b128 v[212:215], v160 offset:53248
	ds_read_b128 v[216:219], v160 offset:54272
	ds_read_b128 v[220:223], v160 offset:55296
	ds_read_b128 v[224:227], v160 offset:56320
	global_load_lds_dwordx4 v132, s[96:97]
	s_add_i32 m0, s7, 0x2000
	s_add_i32 s7, s47, s25
	global_load_lds_dwordx4 v136, s[96:97]
	s_mov_b32 m0, s7
	s_nop 0
	global_load_lds_dwordx4 v132, s[98:99]
	s_add_i32 m0, s7, 0x2000
	s_nop 0
	global_load_lds_dwordx4 v136, s[98:99]
	s_mov_b32 m0, s66
	s_nop 0
	global_load_lds_dwordx4 v130, s[94:95]
	s_mov_b32 m0, s67
	s_nop 0
	global_load_lds_dwordx4 v134, s[94:95]
	s_waitcnt vmcnt(8)
	s_waitcnt lgkmcnt(0)
	s_barrier
	s_setprio 1
	s_waitcnt lgkmcnt(0)
	v_mfma_f32_16x16x32_bf16 v[62:65], v[164:167], v[196:199], v[62:65]
	v_mfma_f32_16x16x32_bf16 v[54:57], v[172:175], v[196:199], v[54:57]
	v_mfma_f32_16x16x32_bf16 v[46:49], v[164:167], v[204:207], v[46:49]
	v_mfma_f32_16x16x32_bf16 v[38:41], v[172:175], v[204:207], v[38:41]
	v_mfma_f32_16x16x32_bf16 v[30:33], v[164:167], v[212:215], v[30:33]
	v_mfma_f32_16x16x32_bf16 v[22:25], v[172:175], v[212:215], v[22:25]
	v_mfma_f32_16x16x32_bf16 v[14:17], v[164:167], v[220:223], v[14:17]
	v_mfma_f32_16x16x32_bf16 v[6:9], v[172:175], v[220:223], v[6:9]
	v_mfma_f32_16x16x32_bf16 v[62:65], v[168:171], v[200:203], v[62:65]
	v_mfma_f32_16x16x32_bf16 v[54:57], v[176:179], v[200:203], v[54:57]
	v_mfma_f32_16x16x32_bf16 v[46:49], v[168:171], v[208:211], v[46:49]
	v_mfma_f32_16x16x32_bf16 v[38:41], v[176:179], v[208:211], v[38:41]
	v_mfma_f32_16x16x32_bf16 v[30:33], v[168:171], v[216:219], v[30:33]
	v_mfma_f32_16x16x32_bf16 v[22:25], v[176:179], v[216:219], v[22:25]
	v_mfma_f32_16x16x32_bf16 v[14:17], v[168:171], v[224:227], v[14:17]
	v_mfma_f32_16x16x32_bf16 v[6:9], v[176:179], v[224:227], v[6:9]
	s_setprio 0
	s_setprio 1
	v_mfma_f32_16x16x32_bf16 v[58:61], v[180:183], v[196:199], v[58:61]
	v_mfma_f32_16x16x32_bf16 v[50:53], v[188:191], v[196:199], v[50:53]
	v_mfma_f32_16x16x32_bf16 v[42:45], v[180:183], v[204:207], v[42:45]
	v_mfma_f32_16x16x32_bf16 v[34:37], v[188:191], v[204:207], v[34:37]
	v_mfma_f32_16x16x32_bf16 v[26:29], v[180:183], v[212:215], v[26:29]
	v_mfma_f32_16x16x32_bf16 v[18:21], v[188:191], v[212:215], v[18:21]
	v_mfma_f32_16x16x32_bf16 v[10:13], v[180:183], v[220:223], v[10:13]
	v_mfma_f32_16x16x32_bf16 v[2:5], v[188:191], v[220:223], v[2:5]
	v_mfma_f32_16x16x32_bf16 v[58:61], v[184:187], v[200:203], v[58:61]
	v_mfma_f32_16x16x32_bf16 v[50:53], v[192:195], v[200:203], v[50:53]
	v_mfma_f32_16x16x32_bf16 v[42:45], v[184:187], v[208:211], v[42:45]
	v_mfma_f32_16x16x32_bf16 v[34:37], v[192:195], v[208:211], v[34:37]
	v_mfma_f32_16x16x32_bf16 v[26:29], v[184:187], v[216:219], v[26:29]
	v_mfma_f32_16x16x32_bf16 v[18:21], v[192:195], v[216:219], v[18:21]
	v_mfma_f32_16x16x32_bf16 v[10:13], v[184:187], v[224:227], v[10:13]
	v_mfma_f32_16x16x32_bf16 v[2:5], v[192:195], v[224:227], v[2:5]
	s_setprio 0
	s_barrier
	v_cmp_ge_i32_e32 vcc, s45, v138
	s_mov_b32 s7, s45
	s_add_u32 s88, s88, 0x100
	s_addc_u32 s89, s89, 0
	s_add_u32 s86, s86, 0x100
	s_addc_u32 s87, s87, 0
	s_cbranch_vccz .LBB0_768

.LBB0_947:
	v_cmp_gt_i32_e32 vcc, 1, v138
	s_cbranch_vccnz .LBB0_1009
	v_lshl_add_u64 v[152:153], v[2:3], 0, s[18:19]
	v_add_u32_e32 v154, -2, v138
	s_waitcnt lgkmcnt(0)
	v_lshl_add_u64 v[150:151], v[4:5], 0, s[22:23]
	s_mov_b32 s7, 0
	s_nop 0
	v_readfirstlane_b32 s86, v152
	v_readfirstlane_b32 s87, v153
	v_readfirstlane_b32 s88, v150
	v_readfirstlane_b32 s89, v151
	v_readfirstlane_b32 s90, v146
	v_readfirstlane_b32 s91, v147
	v_readfirstlane_b32 s92, v148
	v_readfirstlane_b32 s93, v149
	v_readfirstlane_b32 s100, v154
	s_add_u32 s98, s86, 0xfffc0080
	s_addc_u32 s99, s87, -1
	s_cmp_eq_u32 s7, s100
	s_cselect_b64 s[94:95], s[90:91], s[98:99]
	s_cselect_b64 s[96:97], s[92:93], s[88:89]
	v_add_u32_e32 v155, s74, v141
	ds_read_b128 v[164:167], v155
	ds_read_b128 v[168:171], v155 offset:1024
	ds_read_b128 v[172:175], v155 offset:2048
	ds_read_b128 v[176:179], v155 offset:3072
	v_add_u32_e32 v155, s75, v141
	ds_read_b128 v[180:183], v155
	ds_read_b128 v[184:187], v155 offset:1024
	ds_read_b128 v[188:191], v155 offset:2048
	ds_read_b128 v[192:195], v155 offset:3072
	s_add_i32 s47, s7, 2
	s_nop 0
	s_mov_b32 m0, s76
	ds_read_b128 v[196:199], v160
	ds_read_b128 v[200:203], v160 offset:1024
	ds_read_b128 v[204:207], v160 offset:2048
	ds_read_b128 v[208:211], v160 offset:3072
	ds_read_b128 v[212:215], v160 offset:4096
	ds_read_b128 v[216:219], v160 offset:5120
	ds_read_b128 v[220:223], v160 offset:6144
	ds_read_b128 v[224:227], v160 offset:7168
	global_load_lds_dwordx4 v144, s[86:87]
	s_mov_b32 m0, s77
	s_nop 0
	global_load_lds_dwordx4 v142, s[86:87]
	s_waitcnt vmcnt(8)
	s_waitcnt lgkmcnt(0)
	s_barrier
	s_setprio 1
	s_waitcnt lgkmcnt(0)
	v_mfma_f32_16x16x32_bf16 v[122:125], v[164:167], v[196:199], 0
	v_mfma_f32_16x16x32_bf16 v[118:121], v[172:175], v[196:199], 0
	v_mfma_f32_16x16x32_bf16 v[110:113], v[164:167], v[204:207], 0
	v_mfma_f32_16x16x32_bf16 v[102:105], v[172:175], v[204:207], 0
	v_mfma_f32_16x16x32_bf16 v[94:97], v[164:167], v[212:215], 0
	v_mfma_f32_16x16x32_bf16 v[86:89], v[172:175], v[212:215], 0
	v_mfma_f32_16x16x32_bf16 v[78:81], v[164:167], v[220:223], 0
	v_mfma_f32_16x16x32_bf16 v[70:73], v[172:175], v[220:223], 0
	v_mfma_f32_16x16x32_bf16 v[122:125], v[168:171], v[200:203], v[122:125]
	v_mfma_f32_16x16x32_bf16 v[118:121], v[176:179], v[200:203], v[118:121]
	v_mfma_f32_16x16x32_bf16 v[110:113], v[168:171], v[208:211], v[110:113]
	v_mfma_f32_16x16x32_bf16 v[102:105], v[176:179], v[208:211], v[102:105]
	v_mfma_f32_16x16x32_bf16 v[94:97], v[168:171], v[216:219], v[94:97]
	v_mfma_f32_16x16x32_bf16 v[86:89], v[176:179], v[216:219], v[86:89]
	v_mfma_f32_16x16x32_bf16 v[78:81], v[168:171], v[224:227], v[78:81]
	v_mfma_f32_16x16x32_bf16 v[70:73], v[176:179], v[224:227], v[70:73]
	s_setprio 0
	s_setprio 1
	v_mfma_f32_16x16x32_bf16 v[126:129], v[180:183], v[196:199], 0
	v_mfma_f32_16x16x32_bf16 v[114:117], v[188:191], v[196:199], 0
	v_mfma_f32_16x16x32_bf16 v[106:109], v[180:183], v[204:207], 0
	v_mfma_f32_16x16x32_bf16 v[98:101], v[188:191], v[204:207], 0
	v_mfma_f32_16x16x32_bf16 v[90:93], v[180:183], v[212:215], 0
	v_mfma_f32_16x16x32_bf16 v[82:85], v[188:191], v[212:215], 0
	v_mfma_f32_16x16x32_bf16 v[74:77], v[180:183], v[220:223], 0
	v_mfma_f32_16x16x32_bf16 v[66:69], v[188:191], v[220:223], 0
	v_mfma_f32_16x16x32_bf16 v[126:129], v[184:187], v[200:203], v[126:129]
	v_mfma_f32_16x16x32_bf16 v[114:117], v[192:195], v[200:203], v[114:117]
	v_mfma_f32_16x16x32_bf16 v[106:109], v[184:187], v[208:211], v[106:109]
	v_mfma_f32_16x16x32_bf16 v[98:101], v[192:195], v[208:211], v[98:101]
	v_mfma_f32_16x16x32_bf16 v[90:93], v[184:187], v[216:219], v[90:93]
	v_mfma_f32_16x16x32_bf16 v[82:85], v[192:195], v[216:219], v[82:85]
	v_mfma_f32_16x16x32_bf16 v[74:77], v[184:187], v[224:227], v[74:77]
	v_mfma_f32_16x16x32_bf16 v[66:69], v[192:195], v[224:227], v[66:69]
	s_setprio 0
	s_barrier
	s_add_u32 s98, s96, 0x40000
	s_addc_u32 s99, s97, 0
	s_mov_b32 m0, s78
	ds_read_b128 v[196:199], v160 offset:16384
	ds_read_b128 v[200:203], v160 offset:17408
	ds_read_b128 v[204:207], v160 offset:18432
	ds_read_b128 v[208:211], v160 offset:19456
	ds_read_b128 v[212:215], v160 offset:20480
	ds_read_b128 v[216:219], v160 offset:21504
	ds_read_b128 v[220:223], v160 offset:22528
	ds_read_b128 v[224:227], v160 offset:23552
	global_load_lds_dwordx4 v132, s[96:97]
	s_mov_b32 m0, s79
	s_add_i32 s7, s75, s29
	global_load_lds_dwordx4 v136, s[96:97]
	s_mov_b32 m0, s7
	s_nop 0
	global_load_lds_dwordx4 v132, s[98:99]
	s_add_i32 m0, s7, 0x2000
	s_nop 0
	global_load_lds_dwordx4 v136, s[98:99]
	s_mov_b32 m0, s51
	s_nop 0
	global_load_lds_dwordx4 v130, s[94:95]
	s_mov_b32 m0, s60
	s_nop 0
	global_load_lds_dwordx4 v134, s[94:95]
	s_waitcnt vmcnt(8)
	s_waitcnt lgkmcnt(0)
	s_barrier
	s_setprio 1
	s_waitcnt lgkmcnt(0)
	v_mfma_f32_16x16x32_bf16 v[62:65], v[164:167], v[196:199], 0
	v_mfma_f32_16x16x32_bf16 v[54:57], v[172:175], v[196:199], 0
	v_mfma_f32_16x16x32_bf16 v[46:49], v[164:167], v[204:207], 0
	v_mfma_f32_16x16x32_bf16 v[38:41], v[172:175], v[204:207], 0
	v_mfma_f32_16x16x32_bf16 v[30:33], v[164:167], v[212:215], 0
	v_mfma_f32_16x16x32_bf16 v[22:25], v[172:175], v[212:215], 0
	v_mfma_f32_16x16x32_bf16 v[14:17], v[164:167], v[220:223], 0
	v_mfma_f32_16x16x32_bf16 v[6:9], v[172:175], v[220:223], 0
	v_mfma_f32_16x16x32_bf16 v[62:65], v[168:171], v[200:203], v[62:65]
	v_mfma_f32_16x16x32_bf16 v[54:57], v[176:179], v[200:203], v[54:57]
	v_mfma_f32_16x16x32_bf16 v[46:49], v[168:171], v[208:211], v[46:49]
	v_mfma_f32_16x16x32_bf16 v[38:41], v[176:179], v[208:211], v[38:41]
	v_mfma_f32_16x16x32_bf16 v[30:33], v[168:171], v[216:219], v[30:33]
	v_mfma_f32_16x16x32_bf16 v[22:25], v[176:179], v[216:219], v[22:25]
	v_mfma_f32_16x16x32_bf16 v[14:17], v[168:171], v[224:227], v[14:17]
	v_mfma_f32_16x16x32_bf16 v[6:9], v[176:179], v[224:227], v[6:9]
	s_setprio 0
	s_setprio 1
	v_mfma_f32_16x16x32_bf16 v[58:61], v[180:183], v[196:199], 0
	v_mfma_f32_16x16x32_bf16 v[50:53], v[188:191], v[196:199], 0
	v_mfma_f32_16x16x32_bf16 v[42:45], v[180:183], v[204:207], 0
	v_mfma_f32_16x16x32_bf16 v[34:37], v[188:191], v[204:207], 0
	v_mfma_f32_16x16x32_bf16 v[26:29], v[180:183], v[212:215], 0
	v_mfma_f32_16x16x32_bf16 v[18:21], v[188:191], v[212:215], 0
	v_mfma_f32_16x16x32_bf16 v[10:13], v[180:183], v[220:223], 0
	v_mfma_f32_16x16x32_bf16 v[2:5], v[188:191], v[220:223], 0
	v_mfma_f32_16x16x32_bf16 v[58:61], v[184:187], v[200:203], v[58:61]
	v_mfma_f32_16x16x32_bf16 v[50:53], v[192:195], v[200:203], v[50:53]
	v_mfma_f32_16x16x32_bf16 v[42:45], v[184:187], v[208:211], v[42:45]
	v_mfma_f32_16x16x32_bf16 v[34:37], v[192:195], v[208:211], v[34:37]
	v_mfma_f32_16x16x32_bf16 v[26:29], v[184:187], v[216:219], v[26:29]
	v_mfma_f32_16x16x32_bf16 v[18:21], v[192:195], v[216:219], v[18:21]
	v_mfma_f32_16x16x32_bf16 v[10:13], v[184:187], v[224:227], v[10:13]
	v_mfma_f32_16x16x32_bf16 v[2:5], v[192:195], v[224:227], v[2:5]
	s_setprio 0
	s_barrier
	s_add_u32 s98, s94, 0x40000
	s_addc_u32 s99, s95, 0
	s_add_i32 s7, 0, 0x18000
	v_add_u32_e32 v155, s7, v141
	s_add_i32 s49, 0, 0x1c000
	ds_read_b128 v[164:167], v155
	ds_read_b128 v[168:171], v155 offset:1024
	ds_read_b128 v[172:175], v155 offset:2048
	ds_read_b128 v[176:179], v155 offset:3072
	v_add_u32_e32 v155, s49, v141
	ds_read_b128 v[180:183], v155
	ds_read_b128 v[184:187], v155 offset:1024
	ds_read_b128 v[188:191], v155 offset:2048
	ds_read_b128 v[192:195], v155 offset:3072
	s_mov_b32 m0, s61
	ds_read_b128 v[196:199], v160 offset:32768
	ds_read_b128 v[200:203], v160 offset:33792
	ds_read_b128 v[204:207], v160 offset:34816
	ds_read_b128 v[208:211], v160 offset:35840
	ds_read_b128 v[212:215], v160 offset:36864
	ds_read_b128 v[216:219], v160 offset:37888
	ds_read_b128 v[220:223], v160 offset:38912
	ds_read_b128 v[224:227], v160 offset:39936
	global_load_lds_dwordx4 v130, s[98:99]
	s_mov_b32 m0, s62
	s_nop 0
	global_load_lds_dwordx4 v134, s[98:99]
	s_waitcnt vmcnt(8)
	s_waitcnt lgkmcnt(0)
	s_barrier
	s_setprio 1
	s_waitcnt lgkmcnt(0)
	v_mfma_f32_16x16x32_bf16 v[122:125], v[164:167], v[196:199], v[122:125]
	v_mfma_f32_16x16x32_bf16 v[118:121], v[172:175], v[196:199], v[118:121]
	v_mfma_f32_16x16x32_bf16 v[110:113], v[164:167], v[204:207], v[110:113]
	v_mfma_f32_16x16x32_bf16 v[102:105], v[172:175], v[204:207], v[102:105]
	v_mfma_f32_16x16x32_bf16 v[94:97], v[164:167], v[212:215], v[94:97]
	v_mfma_f32_16x16x32_bf16 v[86:89], v[172:175], v[212:215], v[86:89]
	v_mfma_f32_16x16x32_bf16 v[78:81], v[164:167], v[220:223], v[78:81]
	v_mfma_f32_16x16x32_bf16 v[70:73], v[172:175], v[220:223], v[70:73]
	v_mfma_f32_16x16x32_bf16 v[122:125], v[168:171], v[200:203], v[122:125]
	v_mfma_f32_16x16x32_bf16 v[118:121], v[176:179], v[200:203], v[118:121]
	v_mfma_f32_16x16x32_bf16 v[110:113], v[168:171], v[208:211], v[110:113]
	v_mfma_f32_16x16x32_bf16 v[102:105], v[176:179], v[208:211], v[102:105]
	v_mfma_f32_16x16x32_bf16 v[94:97], v[168:171], v[216:219], v[94:97]
	v_mfma_f32_16x16x32_bf16 v[86:89], v[176:179], v[216:219], v[86:89]
	v_mfma_f32_16x16x32_bf16 v[78:81], v[168:171], v[224:227], v[78:81]
	v_mfma_f32_16x16x32_bf16 v[70:73], v[176:179], v[224:227], v[70:73]
	s_setprio 0
	s_setprio 1
	v_mfma_f32_16x16x32_bf16 v[126:129], v[180:183], v[196:199], v[126:129]
	v_mfma_f32_16x16x32_bf16 v[114:117], v[188:191], v[196:199], v[114:117]
	v_mfma_f32_16x16x32_bf16 v[106:109], v[180:183], v[204:207], v[106:109]
	v_mfma_f32_16x16x32_bf16 v[98:101], v[188:191], v[204:207], v[98:101]
	v_mfma_f32_16x16x32_bf16 v[90:93], v[180:183], v[212:215], v[90:93]
	v_mfma_f32_16x16x32_bf16 v[82:85], v[188:191], v[212:215], v[82:85]
	v_mfma_f32_16x16x32_bf16 v[74:77], v[180:183], v[220:223], v[74:77]
	v_mfma_f32_16x16x32_bf16 v[66:69], v[188:191], v[220:223], v[66:69]
	v_mfma_f32_16x16x32_bf16 v[126:129], v[184:187], v[200:203], v[126:129]
	v_mfma_f32_16x16x32_bf16 v[114:117], v[192:195], v[200:203], v[114:117]
	v_mfma_f32_16x16x32_bf16 v[106:109], v[184:187], v[208:211], v[106:109]
	v_mfma_f32_16x16x32_bf16 v[98:101], v[192:195], v[208:211], v[98:101]
	v_mfma_f32_16x16x32_bf16 v[90:93], v[184:187], v[216:219], v[90:93]
	v_mfma_f32_16x16x32_bf16 v[82:85], v[192:195], v[216:219], v[82:85]
	v_mfma_f32_16x16x32_bf16 v[74:77], v[184:187], v[224:227], v[74:77]
	v_mfma_f32_16x16x32_bf16 v[66:69], v[192:195], v[224:227], v[66:69]
	s_setprio 0
	s_barrier
	s_add_u32 s96, s96, 0x80
	s_addc_u32 s97, s97, 0
	s_add_u32 s98, s96, 0x40000
	s_addc_u32 s99, s97, 0
	s_add_u32 s94, s94, 0x80
	s_addc_u32 s95, s95, 0
	s_add_i32 s7, s7, s29
	s_mov_b32 m0, s7
	ds_read_b128 v[196:199], v160 offset:49152
	ds_read_b128 v[200:203], v160 offset:50176
	ds_read_b128 v[204:207], v160 offset:51200
	ds_read_b128 v[208:211], v160 offset:52224
	ds_read_b128 v[212:215], v160 offset:53248
	ds_read_b128 v[216:219], v160 offset:54272
	ds_read_b128 v[220:223], v160 offset:55296
	ds_read_b128 v[224:227], v160 offset:56320
	global_load_lds_dwordx4 v132, s[96:97]
	s_add_i32 m0, s7, 0x2000
	s_add_i32 s7, s49, s29
	global_load_lds_dwordx4 v136, s[96:97]
	s_mov_b32 m0, s7
	s_nop 0
	global_load_lds_dwordx4 v132, s[98:99]
	s_add_i32 m0, s7, 0x2000
	s_nop 0
	global_load_lds_dwordx4 v136, s[98:99]
	s_mov_b32 m0, s63
	s_nop 0
	global_load_lds_dwordx4 v130, s[94:95]
	s_mov_b32 m0, s64
	s_nop 0
	global_load_lds_dwordx4 v134, s[94:95]
	s_waitcnt vmcnt(8)
	s_waitcnt lgkmcnt(0)
	s_barrier
	s_setprio 1
	s_waitcnt lgkmcnt(0)
	v_mfma_f32_16x16x32_bf16 v[62:65], v[164:167], v[196:199], v[62:65]
	v_mfma_f32_16x16x32_bf16 v[54:57], v[172:175], v[196:199], v[54:57]
	v_mfma_f32_16x16x32_bf16 v[46:49], v[164:167], v[204:207], v[46:49]
	v_mfma_f32_16x16x32_bf16 v[38:41], v[172:175], v[204:207], v[38:41]
	v_mfma_f32_16x16x32_bf16 v[30:33], v[164:167], v[212:215], v[30:33]
	v_mfma_f32_16x16x32_bf16 v[22:25], v[172:175], v[212:215], v[22:25]
	v_mfma_f32_16x16x32_bf16 v[14:17], v[164:167], v[220:223], v[14:17]
	v_mfma_f32_16x16x32_bf16 v[6:9], v[172:175], v[220:223], v[6:9]
	v_mfma_f32_16x16x32_bf16 v[62:65], v[168:171], v[200:203], v[62:65]
	v_mfma_f32_16x16x32_bf16 v[54:57], v[176:179], v[200:203], v[54:57]
	v_mfma_f32_16x16x32_bf16 v[46:49], v[168:171], v[208:211], v[46:49]
	v_mfma_f32_16x16x32_bf16 v[38:41], v[176:179], v[208:211], v[38:41]
	v_mfma_f32_16x16x32_bf16 v[30:33], v[168:171], v[216:219], v[30:33]
	v_mfma_f32_16x16x32_bf16 v[22:25], v[176:179], v[216:219], v[22:25]
	v_mfma_f32_16x16x32_bf16 v[14:17], v[168:171], v[224:227], v[14:17]
	v_mfma_f32_16x16x32_bf16 v[6:9], v[176:179], v[224:227], v[6:9]
	s_setprio 0
	s_setprio 1
	v_mfma_f32_16x16x32_bf16 v[58:61], v[180:183], v[196:199], v[58:61]
	v_mfma_f32_16x16x32_bf16 v[50:53], v[188:191], v[196:199], v[50:53]
	v_mfma_f32_16x16x32_bf16 v[42:45], v[180:183], v[204:207], v[42:45]
	v_mfma_f32_16x16x32_bf16 v[34:37], v[188:191], v[204:207], v[34:37]
	v_mfma_f32_16x16x32_bf16 v[26:29], v[180:183], v[212:215], v[26:29]
	v_mfma_f32_16x16x32_bf16 v[18:21], v[188:191], v[212:215], v[18:21]
	v_mfma_f32_16x16x32_bf16 v[10:13], v[180:183], v[220:223], v[10:13]
	v_mfma_f32_16x16x32_bf16 v[2:5], v[188:191], v[220:223], v[2:5]
	v_mfma_f32_16x16x32_bf16 v[58:61], v[184:187], v[200:203], v[58:61]
	v_mfma_f32_16x16x32_bf16 v[50:53], v[192:195], v[200:203], v[50:53]
	v_mfma_f32_16x16x32_bf16 v[42:45], v[184:187], v[208:211], v[42:45]
	v_mfma_f32_16x16x32_bf16 v[34:37], v[192:195], v[208:211], v[34:37]
	v_mfma_f32_16x16x32_bf16 v[26:29], v[184:187], v[216:219], v[26:29]
	v_mfma_f32_16x16x32_bf16 v[18:21], v[192:195], v[216:219], v[18:21]
	v_mfma_f32_16x16x32_bf16 v[10:13], v[184:187], v[224:227], v[10:13]
	v_mfma_f32_16x16x32_bf16 v[2:5], v[192:195], v[224:227], v[2:5]
	s_setprio 0
	s_barrier
	v_cmp_ge_i32_e32 vcc, s47, v138
	s_mov_b32 s7, s47
	s_add_u32 s88, s88, 0x100
	s_addc_u32 s89, s89, 0
	s_add_u32 s86, s86, 0x100
	s_addc_u32 s87, s87, 0
	s_cbranch_vccnz .Lmy_kexit_4
.LBB0_949:
	s_add_u32 s98, s86, 0xfffc0080
	s_addc_u32 s99, s87, -1
	s_cmp_eq_u32 s7, s100
	s_cselect_b64 s[94:95], s[90:91], s[98:99]
	s_cselect_b64 s[96:97], s[92:93], s[88:89]
	v_add_u32_e32 v155, s74, v141
	ds_read_b128 v[164:167], v155
	ds_read_b128 v[168:171], v155 offset:1024
	ds_read_b128 v[172:175], v155 offset:2048
	ds_read_b128 v[176:179], v155 offset:3072
	v_add_u32_e32 v155, s75, v141
	ds_read_b128 v[180:183], v155
	ds_read_b128 v[184:187], v155 offset:1024
	ds_read_b128 v[188:191], v155 offset:2048
	ds_read_b128 v[192:195], v155 offset:3072
	s_add_i32 s47, s7, 2
	s_nop 0
	s_mov_b32 m0, s76
	ds_read_b128 v[196:199], v160
	ds_read_b128 v[200:203], v160 offset:1024
	ds_read_b128 v[204:207], v160 offset:2048
	ds_read_b128 v[208:211], v160 offset:3072
	ds_read_b128 v[212:215], v160 offset:4096
	ds_read_b128 v[216:219], v160 offset:5120
	ds_read_b128 v[220:223], v160 offset:6144
	ds_read_b128 v[224:227], v160 offset:7168
	global_load_lds_dwordx4 v144, s[86:87]
	s_mov_b32 m0, s77
	s_nop 0
	global_load_lds_dwordx4 v142, s[86:87]
	s_waitcnt vmcnt(8)
	s_waitcnt lgkmcnt(0)
	s_barrier
	s_setprio 1
	s_waitcnt lgkmcnt(0)
	v_mfma_f32_16x16x32_bf16 v[122:125], v[164:167], v[196:199], v[122:125]
	v_mfma_f32_16x16x32_bf16 v[118:121], v[172:175], v[196:199], v[118:121]
	v_mfma_f32_16x16x32_bf16 v[110:113], v[164:167], v[204:207], v[110:113]
	v_mfma_f32_16x16x32_bf16 v[102:105], v[172:175], v[204:207], v[102:105]
	v_mfma_f32_16x16x32_bf16 v[94:97], v[164:167], v[212:215], v[94:97]
	v_mfma_f32_16x16x32_bf16 v[86:89], v[172:175], v[212:215], v[86:89]
	v_mfma_f32_16x16x32_bf16 v[78:81], v[164:167], v[220:223], v[78:81]
	v_mfma_f32_16x16x32_bf16 v[70:73], v[172:175], v[220:223], v[70:73]
	v_mfma_f32_16x16x32_bf16 v[122:125], v[168:171], v[200:203], v[122:125]
	v_mfma_f32_16x16x32_bf16 v[118:121], v[176:179], v[200:203], v[118:121]
	v_mfma_f32_16x16x32_bf16 v[110:113], v[168:171], v[208:211], v[110:113]
	v_mfma_f32_16x16x32_bf16 v[102:105], v[176:179], v[208:211], v[102:105]
	v_mfma_f32_16x16x32_bf16 v[94:97], v[168:171], v[216:219], v[94:97]
	v_mfma_f32_16x16x32_bf16 v[86:89], v[176:179], v[216:219], v[86:89]
	v_mfma_f32_16x16x32_bf16 v[78:81], v[168:171], v[224:227], v[78:81]
	v_mfma_f32_16x16x32_bf16 v[70:73], v[176:179], v[224:227], v[70:73]
	s_setprio 0
	s_setprio 1
	v_mfma_f32_16x16x32_bf16 v[126:129], v[180:183], v[196:199], v[126:129]
	v_mfma_f32_16x16x32_bf16 v[114:117], v[188:191], v[196:199], v[114:117]
	v_mfma_f32_16x16x32_bf16 v[106:109], v[180:183], v[204:207], v[106:109]
	v_mfma_f32_16x16x32_bf16 v[98:101], v[188:191], v[204:207], v[98:101]
	v_mfma_f32_16x16x32_bf16 v[90:93], v[180:183], v[212:215], v[90:93]
	v_mfma_f32_16x16x32_bf16 v[82:85], v[188:191], v[212:215], v[82:85]
	v_mfma_f32_16x16x32_bf16 v[74:77], v[180:183], v[220:223], v[74:77]
	v_mfma_f32_16x16x32_bf16 v[66:69], v[188:191], v[220:223], v[66:69]
	v_mfma_f32_16x16x32_bf16 v[126:129], v[184:187], v[200:203], v[126:129]
	v_mfma_f32_16x16x32_bf16 v[114:117], v[192:195], v[200:203], v[114:117]
	v_mfma_f32_16x16x32_bf16 v[106:109], v[184:187], v[208:211], v[106:109]
	v_mfma_f32_16x16x32_bf16 v[98:101], v[192:195], v[208:211], v[98:101]
	v_mfma_f32_16x16x32_bf16 v[90:93], v[184:187], v[216:219], v[90:93]
	v_mfma_f32_16x16x32_bf16 v[82:85], v[192:195], v[216:219], v[82:85]
	v_mfma_f32_16x16x32_bf16 v[74:77], v[184:187], v[224:227], v[74:77]
	v_mfma_f32_16x16x32_bf16 v[66:69], v[192:195], v[224:227], v[66:69]
	s_setprio 0
	s_barrier
	s_add_u32 s98, s96, 0x40000
	s_addc_u32 s99, s97, 0
	s_mov_b32 m0, s78
	ds_read_b128 v[196:199], v160 offset:16384
	ds_read_b128 v[200:203], v160 offset:17408
	ds_read_b128 v[204:207], v160 offset:18432
	ds_read_b128 v[208:211], v160 offset:19456
	ds_read_b128 v[212:215], v160 offset:20480
	ds_read_b128 v[216:219], v160 offset:21504
	ds_read_b128 v[220:223], v160 offset:22528
	ds_read_b128 v[224:227], v160 offset:23552
	global_load_lds_dwordx4 v132, s[96:97]
	s_mov_b32 m0, s79
	s_add_i32 s7, s75, s29
	global_load_lds_dwordx4 v136, s[96:97]
	s_mov_b32 m0, s7
	s_nop 0
	global_load_lds_dwordx4 v132, s[98:99]
	s_add_i32 m0, s7, 0x2000
	s_nop 0
	global_load_lds_dwordx4 v136, s[98:99]
	s_mov_b32 m0, s51
	s_nop 0
	global_load_lds_dwordx4 v130, s[94:95]
	s_mov_b32 m0, s60
	s_nop 0
	global_load_lds_dwordx4 v134, s[94:95]
	s_waitcnt vmcnt(8)
	s_waitcnt lgkmcnt(0)
	s_barrier
	s_setprio 1
	s_waitcnt lgkmcnt(0)
	v_mfma_f32_16x16x32_bf16 v[62:65], v[164:167], v[196:199], v[62:65]
	v_mfma_f32_16x16x32_bf16 v[54:57], v[172:175], v[196:199], v[54:57]
	v_mfma_f32_16x16x32_bf16 v[46:49], v[164:167], v[204:207], v[46:49]
	v_mfma_f32_16x16x32_bf16 v[38:41], v[172:175], v[204:207], v[38:41]
	v_mfma_f32_16x16x32_bf16 v[30:33], v[164:167], v[212:215], v[30:33]
	v_mfma_f32_16x16x32_bf16 v[22:25], v[172:175], v[212:215], v[22:25]
	v_mfma_f32_16x16x32_bf16 v[14:17], v[164:167], v[220:223], v[14:17]
	v_mfma_f32_16x16x32_bf16 v[6:9], v[172:175], v[220:223], v[6:9]
	v_mfma_f32_16x16x32_bf16 v[62:65], v[168:171], v[200:203], v[62:65]
	v_mfma_f32_16x16x32_bf16 v[54:57], v[176:179], v[200:203], v[54:57]
	v_mfma_f32_16x16x32_bf16 v[46:49], v[168:171], v[208:211], v[46:49]
	v_mfma_f32_16x16x32_bf16 v[38:41], v[176:179], v[208:211], v[38:41]
	v_mfma_f32_16x16x32_bf16 v[30:33], v[168:171], v[216:219], v[30:33]
	v_mfma_f32_16x16x32_bf16 v[22:25], v[176:179], v[216:219], v[22:25]
	v_mfma_f32_16x16x32_bf16 v[14:17], v[168:171], v[224:227], v[14:17]
	v_mfma_f32_16x16x32_bf16 v[6:9], v[176:179], v[224:227], v[6:9]
	s_setprio 0
	s_setprio 1
	v_mfma_f32_16x16x32_bf16 v[58:61], v[180:183], v[196:199], v[58:61]
	v_mfma_f32_16x16x32_bf16 v[50:53], v[188:191], v[196:199], v[50:53]
	v_mfma_f32_16x16x32_bf16 v[42:45], v[180:183], v[204:207], v[42:45]
	v_mfma_f32_16x16x32_bf16 v[34:37], v[188:191], v[204:207], v[34:37]
	v_mfma_f32_16x16x32_bf16 v[26:29], v[180:183], v[212:215], v[26:29]
	v_mfma_f32_16x16x32_bf16 v[18:21], v[188:191], v[212:215], v[18:21]
	v_mfma_f32_16x16x32_bf16 v[10:13], v[180:183], v[220:223], v[10:13]
	v_mfma_f32_16x16x32_bf16 v[2:5], v[188:191], v[220:223], v[2:5]
	v_mfma_f32_16x16x32_bf16 v[58:61], v[184:187], v[200:203], v[58:61]
	v_mfma_f32_16x16x32_bf16 v[50:53], v[192:195], v[200:203], v[50:53]
	v_mfma_f32_16x16x32_bf16 v[42:45], v[184:187], v[208:211], v[42:45]
	v_mfma_f32_16x16x32_bf16 v[34:37], v[192:195], v[208:211], v[34:37]
	v_mfma_f32_16x16x32_bf16 v[26:29], v[184:187], v[216:219], v[26:29]
	v_mfma_f32_16x16x32_bf16 v[18:21], v[192:195], v[216:219], v[18:21]
	v_mfma_f32_16x16x32_bf16 v[10:13], v[184:187], v[224:227], v[10:13]
	v_mfma_f32_16x16x32_bf16 v[2:5], v[192:195], v[224:227], v[2:5]
	s_setprio 0
	s_barrier
	s_add_u32 s98, s94, 0x40000
	s_addc_u32 s99, s95, 0
	s_add_i32 s7, 0, 0x18000
	v_add_u32_e32 v155, s7, v141
	s_add_i32 s49, 0, 0x1c000
	ds_read_b128 v[164:167], v155
	ds_read_b128 v[168:171], v155 offset:1024
	ds_read_b128 v[172:175], v155 offset:2048
	ds_read_b128 v[176:179], v155 offset:3072
	v_add_u32_e32 v155, s49, v141
	ds_read_b128 v[180:183], v155
	ds_read_b128 v[184:187], v155 offset:1024
	ds_read_b128 v[188:191], v155 offset:2048
	ds_read_b128 v[192:195], v155 offset:3072
	s_mov_b32 m0, s61
	ds_read_b128 v[196:199], v160 offset:32768
	ds_read_b128 v[200:203], v160 offset:33792
	ds_read_b128 v[204:207], v160 offset:34816
	ds_read_b128 v[208:211], v160 offset:35840
	ds_read_b128 v[212:215], v160 offset:36864
	ds_read_b128 v[216:219], v160 offset:37888
	ds_read_b128 v[220:223], v160 offset:38912
	ds_read_b128 v[224:227], v160 offset:39936
	global_load_lds_dwordx4 v130, s[98:99]
	s_mov_b32 m0, s62
	s_nop 0
	global_load_lds_dwordx4 v134, s[98:99]
	s_waitcnt vmcnt(8)
	s_waitcnt lgkmcnt(0)
	s_barrier
	s_setprio 1
	s_waitcnt lgkmcnt(0)
	v_mfma_f32_16x16x32_bf16 v[122:125], v[164:167], v[196:199], v[122:125]
	v_mfma_f32_16x16x32_bf16 v[118:121], v[172:175], v[196:199], v[118:121]
	v_mfma_f32_16x16x32_bf16 v[110:113], v[164:167], v[204:207], v[110:113]
	v_mfma_f32_16x16x32_bf16 v[102:105], v[172:175], v[204:207], v[102:105]
	v_mfma_f32_16x16x32_bf16 v[94:97], v[164:167], v[212:215], v[94:97]
	v_mfma_f32_16x16x32_bf16 v[86:89], v[172:175], v[212:215], v[86:89]
	v_mfma_f32_16x16x32_bf16 v[78:81], v[164:167], v[220:223], v[78:81]
	v_mfma_f32_16x16x32_bf16 v[70:73], v[172:175], v[220:223], v[70:73]
	v_mfma_f32_16x16x32_bf16 v[122:125], v[168:171], v[200:203], v[122:125]
	v_mfma_f32_16x16x32_bf16 v[118:121], v[176:179], v[200:203], v[118:121]
	v_mfma_f32_16x16x32_bf16 v[110:113], v[168:171], v[208:211], v[110:113]
	v_mfma_f32_16x16x32_bf16 v[102:105], v[176:179], v[208:211], v[102:105]
	v_mfma_f32_16x16x32_bf16 v[94:97], v[168:171], v[216:219], v[94:97]
	v_mfma_f32_16x16x32_bf16 v[86:89], v[176:179], v[216:219], v[86:89]
	v_mfma_f32_16x16x32_bf16 v[78:81], v[168:171], v[224:227], v[78:81]
	v_mfma_f32_16x16x32_bf16 v[70:73], v[176:179], v[224:227], v[70:73]
	s_setprio 0
	s_setprio 1
	v_mfma_f32_16x16x32_bf16 v[126:129], v[180:183], v[196:199], v[126:129]
	v_mfma_f32_16x16x32_bf16 v[114:117], v[188:191], v[196:199], v[114:117]
	v_mfma_f32_16x16x32_bf16 v[106:109], v[180:183], v[204:207], v[106:109]
	v_mfma_f32_16x16x32_bf16 v[98:101], v[188:191], v[204:207], v[98:101]
	v_mfma_f32_16x16x32_bf16 v[90:93], v[180:183], v[212:215], v[90:93]
	v_mfma_f32_16x16x32_bf16 v[82:85], v[188:191], v[212:215], v[82:85]
	v_mfma_f32_16x16x32_bf16 v[74:77], v[180:183], v[220:223], v[74:77]
	v_mfma_f32_16x16x32_bf16 v[66:69], v[188:191], v[220:223], v[66:69]
	v_mfma_f32_16x16x32_bf16 v[126:129], v[184:187], v[200:203], v[126:129]
	v_mfma_f32_16x16x32_bf16 v[114:117], v[192:195], v[200:203], v[114:117]
	v_mfma_f32_16x16x32_bf16 v[106:109], v[184:187], v[208:211], v[106:109]
	v_mfma_f32_16x16x32_bf16 v[98:101], v[192:195], v[208:211], v[98:101]
	v_mfma_f32_16x16x32_bf16 v[90:93], v[184:187], v[216:219], v[90:93]
	v_mfma_f32_16x16x32_bf16 v[82:85], v[192:195], v[216:219], v[82:85]
	v_mfma_f32_16x16x32_bf16 v[74:77], v[184:187], v[224:227], v[74:77]
	v_mfma_f32_16x16x32_bf16 v[66:69], v[192:195], v[224:227], v[66:69]
	s_setprio 0
	s_barrier
	s_add_u32 s96, s96, 0x80
	s_addc_u32 s97, s97, 0
	s_add_u32 s98, s96, 0x40000
	s_addc_u32 s99, s97, 0
	s_add_u32 s94, s94, 0x80
	s_addc_u32 s95, s95, 0
	s_add_i32 s7, s7, s29
	s_mov_b32 m0, s7
	ds_read_b128 v[196:199], v160 offset:49152
	ds_read_b128 v[200:203], v160 offset:50176
	ds_read_b128 v[204:207], v160 offset:51200
	ds_read_b128 v[208:211], v160 offset:52224
	ds_read_b128 v[212:215], v160 offset:53248
	ds_read_b128 v[216:219], v160 offset:54272
	ds_read_b128 v[220:223], v160 offset:55296
	ds_read_b128 v[224:227], v160 offset:56320
	global_load_lds_dwordx4 v132, s[96:97]
	s_add_i32 m0, s7, 0x2000
	s_add_i32 s7, s49, s29
	global_load_lds_dwordx4 v136, s[96:97]
	s_mov_b32 m0, s7
	s_nop 0
	global_load_lds_dwordx4 v132, s[98:99]
	s_add_i32 m0, s7, 0x2000
	s_nop 0
	global_load_lds_dwordx4 v136, s[98:99]
	s_mov_b32 m0, s63
	s_nop 0
	global_load_lds_dwordx4 v130, s[94:95]
	s_mov_b32 m0, s64
	s_nop 0
	global_load_lds_dwordx4 v134, s[94:95]
	s_waitcnt vmcnt(8)
	s_waitcnt lgkmcnt(0)
	s_barrier
	s_setprio 1
	s_waitcnt lgkmcnt(0)
	v_mfma_f32_16x16x32_bf16 v[62:65], v[164:167], v[196:199], v[62:65]
	v_mfma_f32_16x16x32_bf16 v[54:57], v[172:175], v[196:199], v[54:57]
	v_mfma_f32_16x16x32_bf16 v[46:49], v[164:167], v[204:207], v[46:49]
	v_mfma_f32_16x16x32_bf16 v[38:41], v[172:175], v[204:207], v[38:41]
	v_mfma_f32_16x16x32_bf16 v[30:33], v[164:167], v[212:215], v[30:33]
	v_mfma_f32_16x16x32_bf16 v[22:25], v[172:175], v[212:215], v[22:25]
	v_mfma_f32_16x16x32_bf16 v[14:17], v[164:167], v[220:223], v[14:17]
	v_mfma_f32_16x16x32_bf16 v[6:9], v[172:175], v[220:223], v[6:9]
	v_mfma_f32_16x16x32_bf16 v[62:65], v[168:171], v[200:203], v[62:65]
	v_mfma_f32_16x16x32_bf16 v[54:57], v[176:179], v[200:203], v[54:57]
	v_mfma_f32_16x16x32_bf16 v[46:49], v[168:171], v[208:211], v[46:49]
	v_mfma_f32_16x16x32_bf16 v[38:41], v[176:179], v[208:211], v[38:41]
	v_mfma_f32_16x16x32_bf16 v[30:33], v[168:171], v[216:219], v[30:33]
	v_mfma_f32_16x16x32_bf16 v[22:25], v[176:179], v[216:219], v[22:25]
	v_mfma_f32_16x16x32_bf16 v[14:17], v[168:171], v[224:227], v[14:17]
	v_mfma_f32_16x16x32_bf16 v[6:9], v[176:179], v[224:227], v[6:9]
	s_setprio 0
	s_setprio 1
	v_mfma_f32_16x16x32_bf16 v[58:61], v[180:183], v[196:199], v[58:61]
	v_mfma_f32_16x16x32_bf16 v[50:53], v[188:191], v[196:199], v[50:53]
	v_mfma_f32_16x16x32_bf16 v[42:45], v[180:183], v[204:207], v[42:45]
	v_mfma_f32_16x16x32_bf16 v[34:37], v[188:191], v[204:207], v[34:37]
	v_mfma_f32_16x16x32_bf16 v[26:29], v[180:183], v[212:215], v[26:29]
	v_mfma_f32_16x16x32_bf16 v[18:21], v[188:191], v[212:215], v[18:21]
	v_mfma_f32_16x16x32_bf16 v[10:13], v[180:183], v[220:223], v[10:13]
	v_mfma_f32_16x16x32_bf16 v[2:5], v[188:191], v[220:223], v[2:5]
	v_mfma_f32_16x16x32_bf16 v[58:61], v[184:187], v[200:203], v[58:61]
	v_mfma_f32_16x16x32_bf16 v[50:53], v[192:195], v[200:203], v[50:53]
	v_mfma_f32_16x16x32_bf16 v[42:45], v[184:187], v[208:211], v[42:45]
	v_mfma_f32_16x16x32_bf16 v[34:37], v[192:195], v[208:211], v[34:37]
	v_mfma_f32_16x16x32_bf16 v[26:29], v[184:187], v[216:219], v[26:29]
	v_mfma_f32_16x16x32_bf16 v[18:21], v[192:195], v[216:219], v[18:21]
	v_mfma_f32_16x16x32_bf16 v[10:13], v[184:187], v[224:227], v[10:13]
	v_mfma_f32_16x16x32_bf16 v[2:5], v[192:195], v[224:227], v[2:5]
	s_setprio 0
	s_barrier
	v_cmp_ge_i32_e32 vcc, s47, v138
	s_mov_b32 s7, s47
	s_add_u32 s88, s88, 0x100
	s_addc_u32 s89, s89, 0
	s_add_u32 s86, s86, 0x100
	s_addc_u32 s87, s87, 0
	s_cbranch_vccz .LBB0_949

.LBB0_1078:
	v_cmp_gt_i32_e32 vcc, 1, v156
	s_cbranch_vccnz .LBB0_1140
	v_lshl_add_u64 v[152:153], v[2:3], 0, s[20:21]
	v_add_u32_e32 v138, -2, v156
	s_mov_b32 s6, 0
	s_nop 0
	v_readfirstlane_b32 s86, v150
	v_readfirstlane_b32 s87, v151
	v_readfirstlane_b32 s88, v152
	v_readfirstlane_b32 s89, v153
	v_readfirstlane_b32 s90, v146
	v_readfirstlane_b32 s91, v147
	v_readfirstlane_b32 s92, v148
	v_readfirstlane_b32 s93, v149
	v_readfirstlane_b32 s100, v138
	s_add_u32 s98, s86, 0x100
	s_addc_u32 s99, s87, 0
	s_cmp_eq_u32 s6, s100
	s_cselect_b64 s[94:95], s[90:91], s[98:99]
	s_cselect_b64 s[96:97], s[92:93], s[88:89]
	v_add_u32_e32 v157, s67, v141
	ds_read_b128 v[164:167], v157
	ds_read_b128 v[168:171], v157 offset:1024
	ds_read_b128 v[172:175], v157 offset:2048
	ds_read_b128 v[176:179], v157 offset:3072
	v_add_u32_e32 v157, s68, v141
	ds_read_b128 v[180:183], v157
	ds_read_b128 v[184:187], v157 offset:1024
	ds_read_b128 v[188:191], v157 offset:2048
	ds_read_b128 v[192:195], v157 offset:3072
	s_add_i32 s7, s6, 2
	s_nop 0
	s_add_i32 m0, s46, 0xc000
	ds_read_b128 v[196:199], v160
	ds_read_b128 v[200:203], v160 offset:1024
	ds_read_b128 v[204:207], v160 offset:2048
	ds_read_b128 v[208:211], v160 offset:3072
	ds_read_b128 v[212:215], v160 offset:4096
	ds_read_b128 v[216:219], v160 offset:5120
	ds_read_b128 v[220:223], v160 offset:6144
	ds_read_b128 v[224:227], v160 offset:7168
	global_load_lds_dwordx4 v144, s[86:87]
	s_add_i32 m0, s46, 0xe000
	s_nop 0
	global_load_lds_dwordx4 v142, s[86:87]
	s_waitcnt vmcnt(8)
	s_waitcnt lgkmcnt(0)
	s_barrier
	s_setprio 1
	s_waitcnt lgkmcnt(0)
	v_mfma_f32_16x16x32_bf16 v[122:125], v[164:167], v[196:199], 0
	v_mfma_f32_16x16x32_bf16 v[118:121], v[172:175], v[196:199], 0
	v_mfma_f32_16x16x32_bf16 v[110:113], v[164:167], v[204:207], 0
	v_mfma_f32_16x16x32_bf16 v[102:105], v[172:175], v[204:207], 0
	v_mfma_f32_16x16x32_bf16 v[94:97], v[164:167], v[212:215], 0
	v_mfma_f32_16x16x32_bf16 v[86:89], v[172:175], v[212:215], 0
	v_mfma_f32_16x16x32_bf16 v[78:81], v[164:167], v[220:223], 0
	v_mfma_f32_16x16x32_bf16 v[70:73], v[172:175], v[220:223], 0
	v_mfma_f32_16x16x32_bf16 v[122:125], v[168:171], v[200:203], v[122:125]
	v_mfma_f32_16x16x32_bf16 v[118:121], v[176:179], v[200:203], v[118:121]
	v_mfma_f32_16x16x32_bf16 v[110:113], v[168:171], v[208:211], v[110:113]
	v_mfma_f32_16x16x32_bf16 v[102:105], v[176:179], v[208:211], v[102:105]
	v_mfma_f32_16x16x32_bf16 v[94:97], v[168:171], v[216:219], v[94:97]
	v_mfma_f32_16x16x32_bf16 v[86:89], v[176:179], v[216:219], v[86:89]
	v_mfma_f32_16x16x32_bf16 v[78:81], v[168:171], v[224:227], v[78:81]
	v_mfma_f32_16x16x32_bf16 v[70:73], v[176:179], v[224:227], v[70:73]
	s_setprio 0
	s_setprio 1
	v_mfma_f32_16x16x32_bf16 v[126:129], v[180:183], v[196:199], 0
	v_mfma_f32_16x16x32_bf16 v[114:117], v[188:191], v[196:199], 0
	v_mfma_f32_16x16x32_bf16 v[106:109], v[180:183], v[204:207], 0
	v_mfma_f32_16x16x32_bf16 v[98:101], v[188:191], v[204:207], 0
	v_mfma_f32_16x16x32_bf16 v[90:93], v[180:183], v[212:215], 0
	v_mfma_f32_16x16x32_bf16 v[82:85], v[188:191], v[212:215], 0
	v_mfma_f32_16x16x32_bf16 v[74:77], v[180:183], v[220:223], 0
	v_mfma_f32_16x16x32_bf16 v[66:69], v[188:191], v[220:223], 0
	v_mfma_f32_16x16x32_bf16 v[126:129], v[184:187], v[200:203], v[126:129]
	v_mfma_f32_16x16x32_bf16 v[114:117], v[192:195], v[200:203], v[114:117]
	v_mfma_f32_16x16x32_bf16 v[106:109], v[184:187], v[208:211], v[106:109]
	v_mfma_f32_16x16x32_bf16 v[98:101], v[192:195], v[208:211], v[98:101]
	v_mfma_f32_16x16x32_bf16 v[90:93], v[184:187], v[216:219], v[90:93]
	v_mfma_f32_16x16x32_bf16 v[82:85], v[192:195], v[216:219], v[82:85]
	v_mfma_f32_16x16x32_bf16 v[74:77], v[184:187], v[224:227], v[74:77]
	v_mfma_f32_16x16x32_bf16 v[66:69], v[192:195], v[224:227], v[66:69]
	s_setprio 0
	s_barrier
	s_add_u32 s98, s96, 0xb0000
	s_addc_u32 s99, s97, 0
	s_add_i32 s6, s67, s23
	s_mov_b32 m0, s6
	ds_read_b128 v[196:199], v160 offset:16384
	ds_read_b128 v[200:203], v160 offset:17408
	ds_read_b128 v[204:207], v160 offset:18432
	ds_read_b128 v[208:211], v160 offset:19456
	ds_read_b128 v[212:215], v160 offset:20480
	ds_read_b128 v[216:219], v160 offset:21504
	ds_read_b128 v[220:223], v160 offset:22528
	ds_read_b128 v[224:227], v160 offset:23552
	global_load_lds_dwordx4 v132, s[96:97]
	s_add_i32 m0, s6, 0x2000
	s_add_i32 s6, s68, s23
	global_load_lds_dwordx4 v136, s[96:97]
	s_mov_b32 m0, s6
	s_nop 0
	global_load_lds_dwordx4 v132, s[98:99]
	s_add_i32 m0, s6, 0x2000
	s_nop 0
	global_load_lds_dwordx4 v136, s[98:99]
	s_mov_b32 m0, s46
	s_nop 0
	global_load_lds_dwordx4 v130, s[94:95]
	s_mov_b32 m0, s47
	s_nop 0
	global_load_lds_dwordx4 v134, s[94:95]
	s_waitcnt vmcnt(8)
	s_waitcnt lgkmcnt(0)
	s_barrier
	s_setprio 1
	s_waitcnt lgkmcnt(0)
	v_mfma_f32_16x16x32_bf16 v[62:65], v[164:167], v[196:199], 0
	v_mfma_f32_16x16x32_bf16 v[54:57], v[172:175], v[196:199], 0
	v_mfma_f32_16x16x32_bf16 v[46:49], v[164:167], v[204:207], 0
	v_mfma_f32_16x16x32_bf16 v[38:41], v[172:175], v[204:207], 0
	v_mfma_f32_16x16x32_bf16 v[30:33], v[164:167], v[212:215], 0
	v_mfma_f32_16x16x32_bf16 v[22:25], v[172:175], v[212:215], 0
	v_mfma_f32_16x16x32_bf16 v[14:17], v[164:167], v[220:223], 0
	v_mfma_f32_16x16x32_bf16 v[6:9], v[172:175], v[220:223], 0
	v_mfma_f32_16x16x32_bf16 v[62:65], v[168:171], v[200:203], v[62:65]
	v_mfma_f32_16x16x32_bf16 v[54:57], v[176:179], v[200:203], v[54:57]
	v_mfma_f32_16x16x32_bf16 v[46:49], v[168:171], v[208:211], v[46:49]
	v_mfma_f32_16x16x32_bf16 v[38:41], v[176:179], v[208:211], v[38:41]
	v_mfma_f32_16x16x32_bf16 v[30:33], v[168:171], v[216:219], v[30:33]
	v_mfma_f32_16x16x32_bf16 v[22:25], v[176:179], v[216:219], v[22:25]
	v_mfma_f32_16x16x32_bf16 v[14:17], v[168:171], v[224:227], v[14:17]
	v_mfma_f32_16x16x32_bf16 v[6:9], v[176:179], v[224:227], v[6:9]
	s_setprio 0
	s_setprio 1
	v_mfma_f32_16x16x32_bf16 v[58:61], v[180:183], v[196:199], 0
	v_mfma_f32_16x16x32_bf16 v[50:53], v[188:191], v[196:199], 0
	v_mfma_f32_16x16x32_bf16 v[42:45], v[180:183], v[204:207], 0
	v_mfma_f32_16x16x32_bf16 v[34:37], v[188:191], v[204:207], 0
	v_mfma_f32_16x16x32_bf16 v[26:29], v[180:183], v[212:215], 0
	v_mfma_f32_16x16x32_bf16 v[18:21], v[188:191], v[212:215], 0
	v_mfma_f32_16x16x32_bf16 v[10:13], v[180:183], v[220:223], 0
	v_mfma_f32_16x16x32_bf16 v[2:5], v[188:191], v[220:223], 0
	v_mfma_f32_16x16x32_bf16 v[58:61], v[184:187], v[200:203], v[58:61]
	v_mfma_f32_16x16x32_bf16 v[50:53], v[192:195], v[200:203], v[50:53]
	v_mfma_f32_16x16x32_bf16 v[42:45], v[184:187], v[208:211], v[42:45]
	v_mfma_f32_16x16x32_bf16 v[34:37], v[192:195], v[208:211], v[34:37]
	v_mfma_f32_16x16x32_bf16 v[26:29], v[184:187], v[216:219], v[26:29]
	v_mfma_f32_16x16x32_bf16 v[18:21], v[192:195], v[216:219], v[18:21]
	v_mfma_f32_16x16x32_bf16 v[10:13], v[184:187], v[224:227], v[10:13]
	v_mfma_f32_16x16x32_bf16 v[2:5], v[192:195], v[224:227], v[2:5]
	s_setprio 0
	s_barrier
	s_add_u32 s98, s94, 0xb0000
	s_addc_u32 s99, s95, 0
	s_add_i32 s6, 0, 0x18000
	v_add_u32_e32 v157, s6, v141
	s_add_i32 s29, 0, 0x1c000
	ds_read_b128 v[164:167], v157
	ds_read_b128 v[168:171], v157 offset:1024
	ds_read_b128 v[172:175], v157 offset:2048
	ds_read_b128 v[176:179], v157 offset:3072
	v_add_u32_e32 v157, s29, v141
	ds_read_b128 v[180:183], v157
	ds_read_b128 v[184:187], v157 offset:1024
	ds_read_b128 v[188:191], v157 offset:2048
	ds_read_b128 v[192:195], v157 offset:3072
	s_mov_b32 m0, s48
	ds_read_b128 v[196:199], v160 offset:32768
	ds_read_b128 v[200:203], v160 offset:33792
	ds_read_b128 v[204:207], v160 offset:34816
	ds_read_b128 v[208:211], v160 offset:35840
	ds_read_b128 v[212:215], v160 offset:36864
	ds_read_b128 v[216:219], v160 offset:37888
	ds_read_b128 v[220:223], v160 offset:38912
	ds_read_b128 v[224:227], v160 offset:39936
	global_load_lds_dwordx4 v130, s[98:99]
	s_mov_b32 m0, s49
	s_nop 0
	global_load_lds_dwordx4 v134, s[98:99]
	s_waitcnt vmcnt(8)
	s_waitcnt lgkmcnt(0)
	s_barrier
	s_setprio 1
	s_waitcnt lgkmcnt(0)
	v_mfma_f32_16x16x32_bf16 v[122:125], v[164:167], v[196:199], v[122:125]
	v_mfma_f32_16x16x32_bf16 v[118:121], v[172:175], v[196:199], v[118:121]
	v_mfma_f32_16x16x32_bf16 v[110:113], v[164:167], v[204:207], v[110:113]
	v_mfma_f32_16x16x32_bf16 v[102:105], v[172:175], v[204:207], v[102:105]
	v_mfma_f32_16x16x32_bf16 v[94:97], v[164:167], v[212:215], v[94:97]
	v_mfma_f32_16x16x32_bf16 v[86:89], v[172:175], v[212:215], v[86:89]
	v_mfma_f32_16x16x32_bf16 v[78:81], v[164:167], v[220:223], v[78:81]
	v_mfma_f32_16x16x32_bf16 v[70:73], v[172:175], v[220:223], v[70:73]
	v_mfma_f32_16x16x32_bf16 v[122:125], v[168:171], v[200:203], v[122:125]
	v_mfma_f32_16x16x32_bf16 v[118:121], v[176:179], v[200:203], v[118:121]
	v_mfma_f32_16x16x32_bf16 v[110:113], v[168:171], v[208:211], v[110:113]
	v_mfma_f32_16x16x32_bf16 v[102:105], v[176:179], v[208:211], v[102:105]
	v_mfma_f32_16x16x32_bf16 v[94:97], v[168:171], v[216:219], v[94:97]
	v_mfma_f32_16x16x32_bf16 v[86:89], v[176:179], v[216:219], v[86:89]
	v_mfma_f32_16x16x32_bf16 v[78:81], v[168:171], v[224:227], v[78:81]
	v_mfma_f32_16x16x32_bf16 v[70:73], v[176:179], v[224:227], v[70:73]
	s_setprio 0
	s_setprio 1
	v_mfma_f32_16x16x32_bf16 v[126:129], v[180:183], v[196:199], v[126:129]
	v_mfma_f32_16x16x32_bf16 v[114:117], v[188:191], v[196:199], v[114:117]
	v_mfma_f32_16x16x32_bf16 v[106:109], v[180:183], v[204:207], v[106:109]
	v_mfma_f32_16x16x32_bf16 v[98:101], v[188:191], v[204:207], v[98:101]
	v_mfma_f32_16x16x32_bf16 v[90:93], v[180:183], v[212:215], v[90:93]
	v_mfma_f32_16x16x32_bf16 v[82:85], v[188:191], v[212:215], v[82:85]
	v_mfma_f32_16x16x32_bf16 v[74:77], v[180:183], v[220:223], v[74:77]
	v_mfma_f32_16x16x32_bf16 v[66:69], v[188:191], v[220:223], v[66:69]
	v_mfma_f32_16x16x32_bf16 v[126:129], v[184:187], v[200:203], v[126:129]
	v_mfma_f32_16x16x32_bf16 v[114:117], v[192:195], v[200:203], v[114:117]
	v_mfma_f32_16x16x32_bf16 v[106:109], v[184:187], v[208:211], v[106:109]
	v_mfma_f32_16x16x32_bf16 v[98:101], v[192:195], v[208:211], v[98:101]
	v_mfma_f32_16x16x32_bf16 v[90:93], v[184:187], v[216:219], v[90:93]
	v_mfma_f32_16x16x32_bf16 v[82:85], v[192:195], v[216:219], v[82:85]
	v_mfma_f32_16x16x32_bf16 v[74:77], v[184:187], v[224:227], v[74:77]
	v_mfma_f32_16x16x32_bf16 v[66:69], v[192:195], v[224:227], v[66:69]
	s_setprio 0
	s_barrier
	s_add_u32 s96, s96, 0x80
	s_addc_u32 s97, s97, 0
	s_add_u32 s98, s96, 0xb0000
	s_addc_u32 s99, s97, 0
	s_add_u32 s94, s94, 0x80
	s_addc_u32 s95, s95, 0
	s_add_i32 s6, s6, s23
	s_mov_b32 m0, s6
	ds_read_b128 v[196:199], v160 offset:49152
	ds_read_b128 v[200:203], v160 offset:50176
	ds_read_b128 v[204:207], v160 offset:51200
	ds_read_b128 v[208:211], v160 offset:52224
	ds_read_b128 v[212:215], v160 offset:53248
	ds_read_b128 v[216:219], v160 offset:54272
	ds_read_b128 v[220:223], v160 offset:55296
	ds_read_b128 v[224:227], v160 offset:56320
	global_load_lds_dwordx4 v132, s[96:97]
	s_add_i32 m0, s6, 0x2000
	s_add_i32 s6, s29, s23
	global_load_lds_dwordx4 v136, s[96:97]
	s_mov_b32 m0, s6
	s_nop 0
	global_load_lds_dwordx4 v132, s[98:99]
	s_add_i32 m0, s6, 0x2000
	s_nop 0
	global_load_lds_dwordx4 v136, s[98:99]
	s_mov_b32 m0, s59
	s_nop 0
	global_load_lds_dwordx4 v130, s[94:95]
	s_mov_b32 m0, s60
	s_nop 0
	global_load_lds_dwordx4 v134, s[94:95]
	s_waitcnt vmcnt(8)
	s_waitcnt lgkmcnt(0)
	s_barrier
	s_setprio 1
	s_waitcnt lgkmcnt(0)
	v_mfma_f32_16x16x32_bf16 v[62:65], v[164:167], v[196:199], v[62:65]
	v_mfma_f32_16x16x32_bf16 v[54:57], v[172:175], v[196:199], v[54:57]
	v_mfma_f32_16x16x32_bf16 v[46:49], v[164:167], v[204:207], v[46:49]
	v_mfma_f32_16x16x32_bf16 v[38:41], v[172:175], v[204:207], v[38:41]
	v_mfma_f32_16x16x32_bf16 v[30:33], v[164:167], v[212:215], v[30:33]
	v_mfma_f32_16x16x32_bf16 v[22:25], v[172:175], v[212:215], v[22:25]
	v_mfma_f32_16x16x32_bf16 v[14:17], v[164:167], v[220:223], v[14:17]
	v_mfma_f32_16x16x32_bf16 v[6:9], v[172:175], v[220:223], v[6:9]
	v_mfma_f32_16x16x32_bf16 v[62:65], v[168:171], v[200:203], v[62:65]
	v_mfma_f32_16x16x32_bf16 v[54:57], v[176:179], v[200:203], v[54:57]
	v_mfma_f32_16x16x32_bf16 v[46:49], v[168:171], v[208:211], v[46:49]
	v_mfma_f32_16x16x32_bf16 v[38:41], v[176:179], v[208:211], v[38:41]
	v_mfma_f32_16x16x32_bf16 v[30:33], v[168:171], v[216:219], v[30:33]
	v_mfma_f32_16x16x32_bf16 v[22:25], v[176:179], v[216:219], v[22:25]
	v_mfma_f32_16x16x32_bf16 v[14:17], v[168:171], v[224:227], v[14:17]
	v_mfma_f32_16x16x32_bf16 v[6:9], v[176:179], v[224:227], v[6:9]
	s_setprio 0
	s_setprio 1
	v_mfma_f32_16x16x32_bf16 v[58:61], v[180:183], v[196:199], v[58:61]
	v_mfma_f32_16x16x32_bf16 v[50:53], v[188:191], v[196:199], v[50:53]
	v_mfma_f32_16x16x32_bf16 v[42:45], v[180:183], v[204:207], v[42:45]
	v_mfma_f32_16x16x32_bf16 v[34:37], v[188:191], v[204:207], v[34:37]
	v_mfma_f32_16x16x32_bf16 v[26:29], v[180:183], v[212:215], v[26:29]
	v_mfma_f32_16x16x32_bf16 v[18:21], v[188:191], v[212:215], v[18:21]
	v_mfma_f32_16x16x32_bf16 v[10:13], v[180:183], v[220:223], v[10:13]
	v_mfma_f32_16x16x32_bf16 v[2:5], v[188:191], v[220:223], v[2:5]
	v_mfma_f32_16x16x32_bf16 v[58:61], v[184:187], v[200:203], v[58:61]
	v_mfma_f32_16x16x32_bf16 v[50:53], v[192:195], v[200:203], v[50:53]
	v_mfma_f32_16x16x32_bf16 v[42:45], v[184:187], v[208:211], v[42:45]
	v_mfma_f32_16x16x32_bf16 v[34:37], v[192:195], v[208:211], v[34:37]
	v_mfma_f32_16x16x32_bf16 v[26:29], v[184:187], v[216:219], v[26:29]
	v_mfma_f32_16x16x32_bf16 v[18:21], v[192:195], v[216:219], v[18:21]
	v_mfma_f32_16x16x32_bf16 v[10:13], v[184:187], v[224:227], v[10:13]
	v_mfma_f32_16x16x32_bf16 v[2:5], v[192:195], v[224:227], v[2:5]
	s_setprio 0
	s_barrier
	v_cmp_ge_i32_e32 vcc, s7, v156
	s_mov_b32 s6, s7
	s_add_u32 s88, s88, 0x100
	s_addc_u32 s89, s89, 0
	s_add_u32 s86, s86, 0x100
	s_addc_u32 s87, s87, 0
	s_cbranch_vccnz .Lmy_kexit_5
.LBB0_1080:
	s_add_u32 s98, s86, 0x100
	s_addc_u32 s99, s87, 0
	s_cmp_eq_u32 s6, s100
	s_cselect_b64 s[94:95], s[90:91], s[98:99]
	s_cselect_b64 s[96:97], s[92:93], s[88:89]
	v_add_u32_e32 v157, s67, v141
	ds_read_b128 v[164:167], v157
	ds_read_b128 v[168:171], v157 offset:1024
	ds_read_b128 v[172:175], v157 offset:2048
	ds_read_b128 v[176:179], v157 offset:3072
	v_add_u32_e32 v157, s68, v141
	ds_read_b128 v[180:183], v157
	ds_read_b128 v[184:187], v157 offset:1024
	ds_read_b128 v[188:191], v157 offset:2048
	ds_read_b128 v[192:195], v157 offset:3072
	s_add_i32 s7, s6, 2
	s_nop 0
	s_add_i32 m0, s46, 0xc000
	ds_read_b128 v[196:199], v160
	ds_read_b128 v[200:203], v160 offset:1024
	ds_read_b128 v[204:207], v160 offset:2048
	ds_read_b128 v[208:211], v160 offset:3072
	ds_read_b128 v[212:215], v160 offset:4096
	ds_read_b128 v[216:219], v160 offset:5120
	ds_read_b128 v[220:223], v160 offset:6144
	ds_read_b128 v[224:227], v160 offset:7168
	global_load_lds_dwordx4 v144, s[86:87]
	s_add_i32 m0, s46, 0xe000
	s_nop 0
	global_load_lds_dwordx4 v142, s[86:87]
	s_waitcnt vmcnt(8)
	s_waitcnt lgkmcnt(0)
	s_barrier
	s_setprio 1
	s_waitcnt lgkmcnt(0)
	v_mfma_f32_16x16x32_bf16 v[122:125], v[164:167], v[196:199], v[122:125]
	v_mfma_f32_16x16x32_bf16 v[118:121], v[172:175], v[196:199], v[118:121]
	v_mfma_f32_16x16x32_bf16 v[110:113], v[164:167], v[204:207], v[110:113]
	v_mfma_f32_16x16x32_bf16 v[102:105], v[172:175], v[204:207], v[102:105]
	v_mfma_f32_16x16x32_bf16 v[94:97], v[164:167], v[212:215], v[94:97]
	v_mfma_f32_16x16x32_bf16 v[86:89], v[172:175], v[212:215], v[86:89]
	v_mfma_f32_16x16x32_bf16 v[78:81], v[164:167], v[220:223], v[78:81]
	v_mfma_f32_16x16x32_bf16 v[70:73], v[172:175], v[220:223], v[70:73]
	v_mfma_f32_16x16x32_bf16 v[122:125], v[168:171], v[200:203], v[122:125]
	v_mfma_f32_16x16x32_bf16 v[118:121], v[176:179], v[200:203], v[118:121]
	v_mfma_f32_16x16x32_bf16 v[110:113], v[168:171], v[208:211], v[110:113]
	v_mfma_f32_16x16x32_bf16 v[102:105], v[176:179], v[208:211], v[102:105]
	v_mfma_f32_16x16x32_bf16 v[94:97], v[168:171], v[216:219], v[94:97]
	v_mfma_f32_16x16x32_bf16 v[86:89], v[176:179], v[216:219], v[86:89]
	v_mfma_f32_16x16x32_bf16 v[78:81], v[168:171], v[224:227], v[78:81]
	v_mfma_f32_16x16x32_bf16 v[70:73], v[176:179], v[224:227], v[70:73]
	s_setprio 0
	s_setprio 1
	v_mfma_f32_16x16x32_bf16 v[126:129], v[180:183], v[196:199], v[126:129]
	v_mfma_f32_16x16x32_bf16 v[114:117], v[188:191], v[196:199], v[114:117]
	v_mfma_f32_16x16x32_bf16 v[106:109], v[180:183], v[204:207], v[106:109]
	v_mfma_f32_16x16x32_bf16 v[98:101], v[188:191], v[204:207], v[98:101]
	v_mfma_f32_16x16x32_bf16 v[90:93], v[180:183], v[212:215], v[90:93]
	v_mfma_f32_16x16x32_bf16 v[82:85], v[188:191], v[212:215], v[82:85]
	v_mfma_f32_16x16x32_bf16 v[74:77], v[180:183], v[220:223], v[74:77]
	v_mfma_f32_16x16x32_bf16 v[66:69], v[188:191], v[220:223], v[66:69]
	v_mfma_f32_16x16x32_bf16 v[126:129], v[184:187], v[200:203], v[126:129]
	v_mfma_f32_16x16x32_bf16 v[114:117], v[192:195], v[200:203], v[114:117]
	v_mfma_f32_16x16x32_bf16 v[106:109], v[184:187], v[208:211], v[106:109]
	v_mfma_f32_16x16x32_bf16 v[98:101], v[192:195], v[208:211], v[98:101]
	v_mfma_f32_16x16x32_bf16 v[90:93], v[184:187], v[216:219], v[90:93]
	v_mfma_f32_16x16x32_bf16 v[82:85], v[192:195], v[216:219], v[82:85]
	v_mfma_f32_16x16x32_bf16 v[74:77], v[184:187], v[224:227], v[74:77]
	v_mfma_f32_16x16x32_bf16 v[66:69], v[192:195], v[224:227], v[66:69]
	s_setprio 0
	s_barrier
	s_add_u32 s98, s96, 0xb0000
	s_addc_u32 s99, s97, 0
	s_add_i32 s6, s67, s23
	s_mov_b32 m0, s6
	ds_read_b128 v[196:199], v160 offset:16384
	ds_read_b128 v[200:203], v160 offset:17408
	ds_read_b128 v[204:207], v160 offset:18432
	ds_read_b128 v[208:211], v160 offset:19456
	ds_read_b128 v[212:215], v160 offset:20480
	ds_read_b128 v[216:219], v160 offset:21504
	ds_read_b128 v[220:223], v160 offset:22528
	ds_read_b128 v[224:227], v160 offset:23552
	global_load_lds_dwordx4 v132, s[96:97]
	s_add_i32 m0, s6, 0x2000
	s_add_i32 s6, s68, s23
	global_load_lds_dwordx4 v136, s[96:97]
	s_mov_b32 m0, s6
	s_nop 0
	global_load_lds_dwordx4 v132, s[98:99]
	s_add_i32 m0, s6, 0x2000
	s_nop 0
	global_load_lds_dwordx4 v136, s[98:99]
	s_mov_b32 m0, s46
	s_nop 0
	global_load_lds_dwordx4 v130, s[94:95]
	s_mov_b32 m0, s47
	s_nop 0
	global_load_lds_dwordx4 v134, s[94:95]
	s_waitcnt vmcnt(8)
	s_waitcnt lgkmcnt(0)
	s_barrier
	s_setprio 1
	s_waitcnt lgkmcnt(0)
	v_mfma_f32_16x16x32_bf16 v[62:65], v[164:167], v[196:199], v[62:65]
	v_mfma_f32_16x16x32_bf16 v[54:57], v[172:175], v[196:199], v[54:57]
	v_mfma_f32_16x16x32_bf16 v[46:49], v[164:167], v[204:207], v[46:49]
	v_mfma_f32_16x16x32_bf16 v[38:41], v[172:175], v[204:207], v[38:41]
	v_mfma_f32_16x16x32_bf16 v[30:33], v[164:167], v[212:215], v[30:33]
	v_mfma_f32_16x16x32_bf16 v[22:25], v[172:175], v[212:215], v[22:25]
	v_mfma_f32_16x16x32_bf16 v[14:17], v[164:167], v[220:223], v[14:17]
	v_mfma_f32_16x16x32_bf16 v[6:9], v[172:175], v[220:223], v[6:9]
	v_mfma_f32_16x16x32_bf16 v[62:65], v[168:171], v[200:203], v[62:65]
	v_mfma_f32_16x16x32_bf16 v[54:57], v[176:179], v[200:203], v[54:57]
	v_mfma_f32_16x16x32_bf16 v[46:49], v[168:171], v[208:211], v[46:49]
	v_mfma_f32_16x16x32_bf16 v[38:41], v[176:179], v[208:211], v[38:41]
	v_mfma_f32_16x16x32_bf16 v[30:33], v[168:171], v[216:219], v[30:33]
	v_mfma_f32_16x16x32_bf16 v[22:25], v[176:179], v[216:219], v[22:25]
	v_mfma_f32_16x16x32_bf16 v[14:17], v[168:171], v[224:227], v[14:17]
	v_mfma_f32_16x16x32_bf16 v[6:9], v[176:179], v[224:227], v[6:9]
	s_setprio 0
	s_setprio 1
	v_mfma_f32_16x16x32_bf16 v[58:61], v[180:183], v[196:199], v[58:61]
	v_mfma_f32_16x16x32_bf16 v[50:53], v[188:191], v[196:199], v[50:53]
	v_mfma_f32_16x16x32_bf16 v[42:45], v[180:183], v[204:207], v[42:45]
	v_mfma_f32_16x16x32_bf16 v[34:37], v[188:191], v[204:207], v[34:37]
	v_mfma_f32_16x16x32_bf16 v[26:29], v[180:183], v[212:215], v[26:29]
	v_mfma_f32_16x16x32_bf16 v[18:21], v[188:191], v[212:215], v[18:21]
	v_mfma_f32_16x16x32_bf16 v[10:13], v[180:183], v[220:223], v[10:13]
	v_mfma_f32_16x16x32_bf16 v[2:5], v[188:191], v[220:223], v[2:5]
	v_mfma_f32_16x16x32_bf16 v[58:61], v[184:187], v[200:203], v[58:61]
	v_mfma_f32_16x16x32_bf16 v[50:53], v[192:195], v[200:203], v[50:53]
	v_mfma_f32_16x16x32_bf16 v[42:45], v[184:187], v[208:211], v[42:45]
	v_mfma_f32_16x16x32_bf16 v[34:37], v[192:195], v[208:211], v[34:37]
	v_mfma_f32_16x16x32_bf16 v[26:29], v[184:187], v[216:219], v[26:29]
	v_mfma_f32_16x16x32_bf16 v[18:21], v[192:195], v[216:219], v[18:21]
	v_mfma_f32_16x16x32_bf16 v[10:13], v[184:187], v[224:227], v[10:13]
	v_mfma_f32_16x16x32_bf16 v[2:5], v[192:195], v[224:227], v[2:5]
	s_setprio 0
	s_barrier
	s_add_u32 s98, s94, 0xb0000
	s_addc_u32 s99, s95, 0
	s_add_i32 s6, 0, 0x18000
	v_add_u32_e32 v157, s6, v141
	s_add_i32 s29, 0, 0x1c000
	ds_read_b128 v[164:167], v157
	ds_read_b128 v[168:171], v157 offset:1024
	ds_read_b128 v[172:175], v157 offset:2048
	ds_read_b128 v[176:179], v157 offset:3072
	v_add_u32_e32 v157, s29, v141
	ds_read_b128 v[180:183], v157
	ds_read_b128 v[184:187], v157 offset:1024
	ds_read_b128 v[188:191], v157 offset:2048
	ds_read_b128 v[192:195], v157 offset:3072
	s_mov_b32 m0, s48
	ds_read_b128 v[196:199], v160 offset:32768
	ds_read_b128 v[200:203], v160 offset:33792
	ds_read_b128 v[204:207], v160 offset:34816
	ds_read_b128 v[208:211], v160 offset:35840
	ds_read_b128 v[212:215], v160 offset:36864
	ds_read_b128 v[216:219], v160 offset:37888
	ds_read_b128 v[220:223], v160 offset:38912
	ds_read_b128 v[224:227], v160 offset:39936
	global_load_lds_dwordx4 v130, s[98:99]
	s_mov_b32 m0, s49
	s_nop 0
	global_load_lds_dwordx4 v134, s[98:99]
	s_waitcnt vmcnt(8)
	s_waitcnt lgkmcnt(0)
	s_barrier
	s_setprio 1
	s_waitcnt lgkmcnt(0)
	v_mfma_f32_16x16x32_bf16 v[122:125], v[164:167], v[196:199], v[122:125]
	v_mfma_f32_16x16x32_bf16 v[118:121], v[172:175], v[196:199], v[118:121]
	v_mfma_f32_16x16x32_bf16 v[110:113], v[164:167], v[204:207], v[110:113]
	v_mfma_f32_16x16x32_bf16 v[102:105], v[172:175], v[204:207], v[102:105]
	v_mfma_f32_16x16x32_bf16 v[94:97], v[164:167], v[212:215], v[94:97]
	v_mfma_f32_16x16x32_bf16 v[86:89], v[172:175], v[212:215], v[86:89]
	v_mfma_f32_16x16x32_bf16 v[78:81], v[164:167], v[220:223], v[78:81]
	v_mfma_f32_16x16x32_bf16 v[70:73], v[172:175], v[220:223], v[70:73]
	v_mfma_f32_16x16x32_bf16 v[122:125], v[168:171], v[200:203], v[122:125]
	v_mfma_f32_16x16x32_bf16 v[118:121], v[176:179], v[200:203], v[118:121]
	v_mfma_f32_16x16x32_bf16 v[110:113], v[168:171], v[208:211], v[110:113]
	v_mfma_f32_16x16x32_bf16 v[102:105], v[176:179], v[208:211], v[102:105]
	v_mfma_f32_16x16x32_bf16 v[94:97], v[168:171], v[216:219], v[94:97]
	v_mfma_f32_16x16x32_bf16 v[86:89], v[176:179], v[216:219], v[86:89]
	v_mfma_f32_16x16x32_bf16 v[78:81], v[168:171], v[224:227], v[78:81]
	v_mfma_f32_16x16x32_bf16 v[70:73], v[176:179], v[224:227], v[70:73]
	s_setprio 0
	s_setprio 1
	v_mfma_f32_16x16x32_bf16 v[126:129], v[180:183], v[196:199], v[126:129]
	v_mfma_f32_16x16x32_bf16 v[114:117], v[188:191], v[196:199], v[114:117]
	v_mfma_f32_16x16x32_bf16 v[106:109], v[180:183], v[204:207], v[106:109]
	v_mfma_f32_16x16x32_bf16 v[98:101], v[188:191], v[204:207], v[98:101]
	v_mfma_f32_16x16x32_bf16 v[90:93], v[180:183], v[212:215], v[90:93]
	v_mfma_f32_16x16x32_bf16 v[82:85], v[188:191], v[212:215], v[82:85]
	v_mfma_f32_16x16x32_bf16 v[74:77], v[180:183], v[220:223], v[74:77]
	v_mfma_f32_16x16x32_bf16 v[66:69], v[188:191], v[220:223], v[66:69]
	v_mfma_f32_16x16x32_bf16 v[126:129], v[184:187], v[200:203], v[126:129]
	v_mfma_f32_16x16x32_bf16 v[114:117], v[192:195], v[200:203], v[114:117]
	v_mfma_f32_16x16x32_bf16 v[106:109], v[184:187], v[208:211], v[106:109]
	v_mfma_f32_16x16x32_bf16 v[98:101], v[192:195], v[208:211], v[98:101]
	v_mfma_f32_16x16x32_bf16 v[90:93], v[184:187], v[216:219], v[90:93]
	v_mfma_f32_16x16x32_bf16 v[82:85], v[192:195], v[216:219], v[82:85]
	v_mfma_f32_16x16x32_bf16 v[74:77], v[184:187], v[224:227], v[74:77]
	v_mfma_f32_16x16x32_bf16 v[66:69], v[192:195], v[224:227], v[66:69]
	s_setprio 0
	s_barrier
	s_add_u32 s96, s96, 0x80
	s_addc_u32 s97, s97, 0
	s_add_u32 s98, s96, 0xb0000
	s_addc_u32 s99, s97, 0
	s_add_u32 s94, s94, 0x80
	s_addc_u32 s95, s95, 0
	s_add_i32 s6, s6, s23
	s_mov_b32 m0, s6
	ds_read_b128 v[196:199], v160 offset:49152
	ds_read_b128 v[200:203], v160 offset:50176
	ds_read_b128 v[204:207], v160 offset:51200
	ds_read_b128 v[208:211], v160 offset:52224
	ds_read_b128 v[212:215], v160 offset:53248
	ds_read_b128 v[216:219], v160 offset:54272
	ds_read_b128 v[220:223], v160 offset:55296
	ds_read_b128 v[224:227], v160 offset:56320
	global_load_lds_dwordx4 v132, s[96:97]
	s_add_i32 m0, s6, 0x2000
	s_add_i32 s6, s29, s23
	global_load_lds_dwordx4 v136, s[96:97]
	s_mov_b32 m0, s6
	s_nop 0
	global_load_lds_dwordx4 v132, s[98:99]
	s_add_i32 m0, s6, 0x2000
	s_nop 0
	global_load_lds_dwordx4 v136, s[98:99]
	s_mov_b32 m0, s59
	s_nop 0
	global_load_lds_dwordx4 v130, s[94:95]
	s_mov_b32 m0, s60
	s_nop 0
	global_load_lds_dwordx4 v134, s[94:95]
	s_waitcnt vmcnt(8)
	s_waitcnt lgkmcnt(0)
	s_barrier
	s_setprio 1
	s_waitcnt lgkmcnt(0)
	v_mfma_f32_16x16x32_bf16 v[62:65], v[164:167], v[196:199], v[62:65]
	v_mfma_f32_16x16x32_bf16 v[54:57], v[172:175], v[196:199], v[54:57]
	v_mfma_f32_16x16x32_bf16 v[46:49], v[164:167], v[204:207], v[46:49]
	v_mfma_f32_16x16x32_bf16 v[38:41], v[172:175], v[204:207], v[38:41]
	v_mfma_f32_16x16x32_bf16 v[30:33], v[164:167], v[212:215], v[30:33]
	v_mfma_f32_16x16x32_bf16 v[22:25], v[172:175], v[212:215], v[22:25]
	v_mfma_f32_16x16x32_bf16 v[14:17], v[164:167], v[220:223], v[14:17]
	v_mfma_f32_16x16x32_bf16 v[6:9], v[172:175], v[220:223], v[6:9]
	v_mfma_f32_16x16x32_bf16 v[62:65], v[168:171], v[200:203], v[62:65]
	v_mfma_f32_16x16x32_bf16 v[54:57], v[176:179], v[200:203], v[54:57]
	v_mfma_f32_16x16x32_bf16 v[46:49], v[168:171], v[208:211], v[46:49]
	v_mfma_f32_16x16x32_bf16 v[38:41], v[176:179], v[208:211], v[38:41]
	v_mfma_f32_16x16x32_bf16 v[30:33], v[168:171], v[216:219], v[30:33]
	v_mfma_f32_16x16x32_bf16 v[22:25], v[176:179], v[216:219], v[22:25]
	v_mfma_f32_16x16x32_bf16 v[14:17], v[168:171], v[224:227], v[14:17]
	v_mfma_f32_16x16x32_bf16 v[6:9], v[176:179], v[224:227], v[6:9]
	s_setprio 0
	s_setprio 1
	v_mfma_f32_16x16x32_bf16 v[58:61], v[180:183], v[196:199], v[58:61]
	v_mfma_f32_16x16x32_bf16 v[50:53], v[188:191], v[196:199], v[50:53]
	v_mfma_f32_16x16x32_bf16 v[42:45], v[180:183], v[204:207], v[42:45]
	v_mfma_f32_16x16x32_bf16 v[34:37], v[188:191], v[204:207], v[34:37]
	v_mfma_f32_16x16x32_bf16 v[26:29], v[180:183], v[212:215], v[26:29]
	v_mfma_f32_16x16x32_bf16 v[18:21], v[188:191], v[212:215], v[18:21]
	v_mfma_f32_16x16x32_bf16 v[10:13], v[180:183], v[220:223], v[10:13]
	v_mfma_f32_16x16x32_bf16 v[2:5], v[188:191], v[220:223], v[2:5]
	v_mfma_f32_16x16x32_bf16 v[58:61], v[184:187], v[200:203], v[58:61]
	v_mfma_f32_16x16x32_bf16 v[50:53], v[192:195], v[200:203], v[50:53]
	v_mfma_f32_16x16x32_bf16 v[42:45], v[184:187], v[208:211], v[42:45]
	v_mfma_f32_16x16x32_bf16 v[34:37], v[192:195], v[208:211], v[34:37]
	v_mfma_f32_16x16x32_bf16 v[26:29], v[184:187], v[216:219], v[26:29]
	v_mfma_f32_16x16x32_bf16 v[18:21], v[192:195], v[216:219], v[18:21]
	v_mfma_f32_16x16x32_bf16 v[10:13], v[184:187], v[224:227], v[10:13]
	v_mfma_f32_16x16x32_bf16 v[2:5], v[192:195], v[224:227], v[2:5]
	s_setprio 0
	s_barrier
	v_cmp_ge_i32_e32 vcc, s7, v156
	s_mov_b32 s6, s7
	s_add_u32 s88, s88, 0x100
	s_addc_u32 s89, s89, 0
	s_add_u32 s86, s86, 0x100
	s_addc_u32 s87, s87, 0
	s_cbranch_vccz .LBB0_1080

.LBB0_1390:
	v_cmp_gt_i32_e32 vcc, 1, v156
	s_cbranch_vccnz .LBB0_1452
	v_lshl_add_u64 v[152:153], v[2:3], 0, s[20:21]
	v_add_u32_e32 v138, -2, v156
	s_mov_b32 s6, 0
	s_nop 0
	v_readfirstlane_b32 s86, v150
	v_readfirstlane_b32 s87, v151
	v_readfirstlane_b32 s88, v152
	v_readfirstlane_b32 s89, v153
	v_readfirstlane_b32 s90, v146
	v_readfirstlane_b32 s91, v147
	v_readfirstlane_b32 s92, v148
	v_readfirstlane_b32 s93, v149
	v_readfirstlane_b32 s100, v138
	s_add_u32 s98, s86, 0x100
	s_addc_u32 s99, s87, 0
	s_cmp_eq_u32 s6, s100
	s_cselect_b64 s[94:95], s[90:91], s[98:99]
	s_cselect_b64 s[96:97], s[92:93], s[88:89]
	v_add_u32_e32 v157, s67, v141
	ds_read_b128 v[164:167], v157
	ds_read_b128 v[168:171], v157 offset:1024
	ds_read_b128 v[172:175], v157 offset:2048
	ds_read_b128 v[176:179], v157 offset:3072
	v_add_u32_e32 v157, s70, v141
	ds_read_b128 v[180:183], v157
	ds_read_b128 v[184:187], v157 offset:1024
	ds_read_b128 v[188:191], v157 offset:2048
	ds_read_b128 v[192:195], v157 offset:3072
	s_add_i32 s7, s6, 2
	s_nop 0
	s_add_i32 m0, s46, 0xc000
	ds_read_b128 v[196:199], v160
	ds_read_b128 v[200:203], v160 offset:1024
	ds_read_b128 v[204:207], v160 offset:2048
	ds_read_b128 v[208:211], v160 offset:3072
	ds_read_b128 v[212:215], v160 offset:4096
	ds_read_b128 v[216:219], v160 offset:5120
	ds_read_b128 v[220:223], v160 offset:6144
	ds_read_b128 v[224:227], v160 offset:7168
	global_load_lds_dwordx4 v144, s[86:87]
	s_add_i32 m0, s46, 0xe000
	s_nop 0
	global_load_lds_dwordx4 v142, s[86:87]
	s_waitcnt vmcnt(8)
	s_waitcnt lgkmcnt(0)
	s_barrier
	s_setprio 1
	s_waitcnt lgkmcnt(0)
	v_mfma_f32_16x16x32_bf16 v[122:125], v[164:167], v[196:199], 0
	v_mfma_f32_16x16x32_bf16 v[118:121], v[172:175], v[196:199], 0
	v_mfma_f32_16x16x32_bf16 v[110:113], v[164:167], v[204:207], 0
	v_mfma_f32_16x16x32_bf16 v[102:105], v[172:175], v[204:207], 0
	v_mfma_f32_16x16x32_bf16 v[94:97], v[164:167], v[212:215], 0
	v_mfma_f32_16x16x32_bf16 v[86:89], v[172:175], v[212:215], 0
	v_mfma_f32_16x16x32_bf16 v[78:81], v[164:167], v[220:223], 0
	v_mfma_f32_16x16x32_bf16 v[70:73], v[172:175], v[220:223], 0
	v_mfma_f32_16x16x32_bf16 v[122:125], v[168:171], v[200:203], v[122:125]
	v_mfma_f32_16x16x32_bf16 v[118:121], v[176:179], v[200:203], v[118:121]
	v_mfma_f32_16x16x32_bf16 v[110:113], v[168:171], v[208:211], v[110:113]
	v_mfma_f32_16x16x32_bf16 v[102:105], v[176:179], v[208:211], v[102:105]
	v_mfma_f32_16x16x32_bf16 v[94:97], v[168:171], v[216:219], v[94:97]
	v_mfma_f32_16x16x32_bf16 v[86:89], v[176:179], v[216:219], v[86:89]
	v_mfma_f32_16x16x32_bf16 v[78:81], v[168:171], v[224:227], v[78:81]
	v_mfma_f32_16x16x32_bf16 v[70:73], v[176:179], v[224:227], v[70:73]
	s_setprio 0
	s_setprio 1
	v_mfma_f32_16x16x32_bf16 v[126:129], v[180:183], v[196:199], 0
	v_mfma_f32_16x16x32_bf16 v[114:117], v[188:191], v[196:199], 0
	v_mfma_f32_16x16x32_bf16 v[106:109], v[180:183], v[204:207], 0
	v_mfma_f32_16x16x32_bf16 v[98:101], v[188:191], v[204:207], 0
	v_mfma_f32_16x16x32_bf16 v[90:93], v[180:183], v[212:215], 0
	v_mfma_f32_16x16x32_bf16 v[82:85], v[188:191], v[212:215], 0
	v_mfma_f32_16x16x32_bf16 v[74:77], v[180:183], v[220:223], 0
	v_mfma_f32_16x16x32_bf16 v[66:69], v[188:191], v[220:223], 0
	v_mfma_f32_16x16x32_bf16 v[126:129], v[184:187], v[200:203], v[126:129]
	v_mfma_f32_16x16x32_bf16 v[114:117], v[192:195], v[200:203], v[114:117]
	v_mfma_f32_16x16x32_bf16 v[106:109], v[184:187], v[208:211], v[106:109]
	v_mfma_f32_16x16x32_bf16 v[98:101], v[192:195], v[208:211], v[98:101]
	v_mfma_f32_16x16x32_bf16 v[90:93], v[184:187], v[216:219], v[90:93]
	v_mfma_f32_16x16x32_bf16 v[82:85], v[192:195], v[216:219], v[82:85]
	v_mfma_f32_16x16x32_bf16 v[74:77], v[184:187], v[224:227], v[74:77]
	v_mfma_f32_16x16x32_bf16 v[66:69], v[192:195], v[224:227], v[66:69]
	s_setprio 0
	s_barrier
	s_add_u32 s98, s96, 0xb0000
	s_addc_u32 s99, s97, 0
	s_add_i32 s6, s67, s23
	s_mov_b32 m0, s6
	ds_read_b128 v[196:199], v160 offset:16384
	ds_read_b128 v[200:203], v160 offset:17408
	ds_read_b128 v[204:207], v160 offset:18432
	ds_read_b128 v[208:211], v160 offset:19456
	ds_read_b128 v[212:215], v160 offset:20480
	ds_read_b128 v[216:219], v160 offset:21504
	ds_read_b128 v[220:223], v160 offset:22528
	ds_read_b128 v[224:227], v160 offset:23552
	global_load_lds_dwordx4 v132, s[96:97]
	s_add_i32 m0, s6, 0x2000
	s_add_i32 s6, s70, s23
	global_load_lds_dwordx4 v136, s[96:97]
	s_mov_b32 m0, s6
	s_nop 0
	global_load_lds_dwordx4 v132, s[98:99]
	s_add_i32 m0, s6, 0x2000
	s_nop 0
	global_load_lds_dwordx4 v136, s[98:99]
	s_mov_b32 m0, s46
	s_nop 0
	global_load_lds_dwordx4 v130, s[94:95]
	s_mov_b32 m0, s47
	s_nop 0
	global_load_lds_dwordx4 v134, s[94:95]
	s_waitcnt vmcnt(8)
	s_waitcnt lgkmcnt(0)
	s_barrier
	s_setprio 1
	s_waitcnt lgkmcnt(0)
	v_mfma_f32_16x16x32_bf16 v[62:65], v[164:167], v[196:199], 0
	v_mfma_f32_16x16x32_bf16 v[54:57], v[172:175], v[196:199], 0
	v_mfma_f32_16x16x32_bf16 v[46:49], v[164:167], v[204:207], 0
	v_mfma_f32_16x16x32_bf16 v[38:41], v[172:175], v[204:207], 0
	v_mfma_f32_16x16x32_bf16 v[30:33], v[164:167], v[212:215], 0
	v_mfma_f32_16x16x32_bf16 v[22:25], v[172:175], v[212:215], 0
	v_mfma_f32_16x16x32_bf16 v[14:17], v[164:167], v[220:223], 0
	v_mfma_f32_16x16x32_bf16 v[6:9], v[172:175], v[220:223], 0
	v_mfma_f32_16x16x32_bf16 v[62:65], v[168:171], v[200:203], v[62:65]
	v_mfma_f32_16x16x32_bf16 v[54:57], v[176:179], v[200:203], v[54:57]
	v_mfma_f32_16x16x32_bf16 v[46:49], v[168:171], v[208:211], v[46:49]
	v_mfma_f32_16x16x32_bf16 v[38:41], v[176:179], v[208:211], v[38:41]
	v_mfma_f32_16x16x32_bf16 v[30:33], v[168:171], v[216:219], v[30:33]
	v_mfma_f32_16x16x32_bf16 v[22:25], v[176:179], v[216:219], v[22:25]
	v_mfma_f32_16x16x32_bf16 v[14:17], v[168:171], v[224:227], v[14:17]
	v_mfma_f32_16x16x32_bf16 v[6:9], v[176:179], v[224:227], v[6:9]
	s_setprio 0
	s_setprio 1
	v_mfma_f32_16x16x32_bf16 v[58:61], v[180:183], v[196:199], 0
	v_mfma_f32_16x16x32_bf16 v[50:53], v[188:191], v[196:199], 0
	v_mfma_f32_16x16x32_bf16 v[42:45], v[180:183], v[204:207], 0
	v_mfma_f32_16x16x32_bf16 v[34:37], v[188:191], v[204:207], 0
	v_mfma_f32_16x16x32_bf16 v[26:29], v[180:183], v[212:215], 0
	v_mfma_f32_16x16x32_bf16 v[18:21], v[188:191], v[212:215], 0
	v_mfma_f32_16x16x32_bf16 v[10:13], v[180:183], v[220:223], 0
	v_mfma_f32_16x16x32_bf16 v[2:5], v[188:191], v[220:223], 0
	v_mfma_f32_16x16x32_bf16 v[58:61], v[184:187], v[200:203], v[58:61]
	v_mfma_f32_16x16x32_bf16 v[50:53], v[192:195], v[200:203], v[50:53]
	v_mfma_f32_16x16x32_bf16 v[42:45], v[184:187], v[208:211], v[42:45]
	v_mfma_f32_16x16x32_bf16 v[34:37], v[192:195], v[208:211], v[34:37]
	v_mfma_f32_16x16x32_bf16 v[26:29], v[184:187], v[216:219], v[26:29]
	v_mfma_f32_16x16x32_bf16 v[18:21], v[192:195], v[216:219], v[18:21]
	v_mfma_f32_16x16x32_bf16 v[10:13], v[184:187], v[224:227], v[10:13]
	v_mfma_f32_16x16x32_bf16 v[2:5], v[192:195], v[224:227], v[2:5]
	s_setprio 0
	s_barrier
	s_add_u32 s98, s94, 0xb0000
	s_addc_u32 s99, s95, 0
	s_add_i32 s6, 0, 0x18000
	v_add_u32_e32 v157, s6, v141
	s_add_i32 s29, 0, 0x1c000
	ds_read_b128 v[164:167], v157
	ds_read_b128 v[168:171], v157 offset:1024
	ds_read_b128 v[172:175], v157 offset:2048
	ds_read_b128 v[176:179], v157 offset:3072
	v_add_u32_e32 v157, s29, v141
	ds_read_b128 v[180:183], v157
	ds_read_b128 v[184:187], v157 offset:1024
	ds_read_b128 v[188:191], v157 offset:2048
	ds_read_b128 v[192:195], v157 offset:3072
	s_mov_b32 m0, s48
	ds_read_b128 v[196:199], v160 offset:32768
	ds_read_b128 v[200:203], v160 offset:33792
	ds_read_b128 v[204:207], v160 offset:34816
	ds_read_b128 v[208:211], v160 offset:35840
	ds_read_b128 v[212:215], v160 offset:36864
	ds_read_b128 v[216:219], v160 offset:37888
	ds_read_b128 v[220:223], v160 offset:38912
	ds_read_b128 v[224:227], v160 offset:39936
	global_load_lds_dwordx4 v130, s[98:99]
	s_mov_b32 m0, s49
	s_nop 0
	global_load_lds_dwordx4 v134, s[98:99]
	s_waitcnt vmcnt(8)
	s_waitcnt lgkmcnt(0)
	s_barrier
	s_setprio 1
	s_waitcnt lgkmcnt(0)
	v_mfma_f32_16x16x32_bf16 v[122:125], v[164:167], v[196:199], v[122:125]
	v_mfma_f32_16x16x32_bf16 v[118:121], v[172:175], v[196:199], v[118:121]
	v_mfma_f32_16x16x32_bf16 v[110:113], v[164:167], v[204:207], v[110:113]
	v_mfma_f32_16x16x32_bf16 v[102:105], v[172:175], v[204:207], v[102:105]
	v_mfma_f32_16x16x32_bf16 v[94:97], v[164:167], v[212:215], v[94:97]
	v_mfma_f32_16x16x32_bf16 v[86:89], v[172:175], v[212:215], v[86:89]
	v_mfma_f32_16x16x32_bf16 v[78:81], v[164:167], v[220:223], v[78:81]
	v_mfma_f32_16x16x32_bf16 v[70:73], v[172:175], v[220:223], v[70:73]
	v_mfma_f32_16x16x32_bf16 v[122:125], v[168:171], v[200:203], v[122:125]
	v_mfma_f32_16x16x32_bf16 v[118:121], v[176:179], v[200:203], v[118:121]
	v_mfma_f32_16x16x32_bf16 v[110:113], v[168:171], v[208:211], v[110:113]
	v_mfma_f32_16x16x32_bf16 v[102:105], v[176:179], v[208:211], v[102:105]
	v_mfma_f32_16x16x32_bf16 v[94:97], v[168:171], v[216:219], v[94:97]
	v_mfma_f32_16x16x32_bf16 v[86:89], v[176:179], v[216:219], v[86:89]
	v_mfma_f32_16x16x32_bf16 v[78:81], v[168:171], v[224:227], v[78:81]
	v_mfma_f32_16x16x32_bf16 v[70:73], v[176:179], v[224:227], v[70:73]
	s_setprio 0
	s_setprio 1
	v_mfma_f32_16x16x32_bf16 v[126:129], v[180:183], v[196:199], v[126:129]
	v_mfma_f32_16x16x32_bf16 v[114:117], v[188:191], v[196:199], v[114:117]
	v_mfma_f32_16x16x32_bf16 v[106:109], v[180:183], v[204:207], v[106:109]
	v_mfma_f32_16x16x32_bf16 v[98:101], v[188:191], v[204:207], v[98:101]
	v_mfma_f32_16x16x32_bf16 v[90:93], v[180:183], v[212:215], v[90:93]
	v_mfma_f32_16x16x32_bf16 v[82:85], v[188:191], v[212:215], v[82:85]
	v_mfma_f32_16x16x32_bf16 v[74:77], v[180:183], v[220:223], v[74:77]
	v_mfma_f32_16x16x32_bf16 v[66:69], v[188:191], v[220:223], v[66:69]
	v_mfma_f32_16x16x32_bf16 v[126:129], v[184:187], v[200:203], v[126:129]
	v_mfma_f32_16x16x32_bf16 v[114:117], v[192:195], v[200:203], v[114:117]
	v_mfma_f32_16x16x32_bf16 v[106:109], v[184:187], v[208:211], v[106:109]
	v_mfma_f32_16x16x32_bf16 v[98:101], v[192:195], v[208:211], v[98:101]
	v_mfma_f32_16x16x32_bf16 v[90:93], v[184:187], v[216:219], v[90:93]
	v_mfma_f32_16x16x32_bf16 v[82:85], v[192:195], v[216:219], v[82:85]
	v_mfma_f32_16x16x32_bf16 v[74:77], v[184:187], v[224:227], v[74:77]
	v_mfma_f32_16x16x32_bf16 v[66:69], v[192:195], v[224:227], v[66:69]
	s_setprio 0
	s_barrier
	s_add_u32 s96, s96, 0x80
	s_addc_u32 s97, s97, 0
	s_add_u32 s98, s96, 0xb0000
	s_addc_u32 s99, s97, 0
	s_add_u32 s94, s94, 0x80
	s_addc_u32 s95, s95, 0
	s_add_i32 s6, s6, s23
	s_mov_b32 m0, s6
	ds_read_b128 v[196:199], v160 offset:49152
	ds_read_b128 v[200:203], v160 offset:50176
	ds_read_b128 v[204:207], v160 offset:51200
	ds_read_b128 v[208:211], v160 offset:52224
	ds_read_b128 v[212:215], v160 offset:53248
	ds_read_b128 v[216:219], v160 offset:54272
	ds_read_b128 v[220:223], v160 offset:55296
	ds_read_b128 v[224:227], v160 offset:56320
	global_load_lds_dwordx4 v132, s[96:97]
	s_add_i32 m0, s6, 0x2000
	s_add_i32 s6, s29, s23
	global_load_lds_dwordx4 v136, s[96:97]
	s_mov_b32 m0, s6
	s_nop 0
	global_load_lds_dwordx4 v132, s[98:99]
	s_add_i32 m0, s6, 0x2000
	s_nop 0
	global_load_lds_dwordx4 v136, s[98:99]
	s_mov_b32 m0, s59
	s_nop 0
	global_load_lds_dwordx4 v130, s[94:95]
	s_mov_b32 m0, s60
	s_nop 0
	global_load_lds_dwordx4 v134, s[94:95]
	s_waitcnt vmcnt(8)
	s_waitcnt lgkmcnt(0)
	s_barrier
	s_setprio 1
	s_waitcnt lgkmcnt(0)
	v_mfma_f32_16x16x32_bf16 v[62:65], v[164:167], v[196:199], v[62:65]
	v_mfma_f32_16x16x32_bf16 v[54:57], v[172:175], v[196:199], v[54:57]
	v_mfma_f32_16x16x32_bf16 v[46:49], v[164:167], v[204:207], v[46:49]
	v_mfma_f32_16x16x32_bf16 v[38:41], v[172:175], v[204:207], v[38:41]
	v_mfma_f32_16x16x32_bf16 v[30:33], v[164:167], v[212:215], v[30:33]
	v_mfma_f32_16x16x32_bf16 v[22:25], v[172:175], v[212:215], v[22:25]
	v_mfma_f32_16x16x32_bf16 v[14:17], v[164:167], v[220:223], v[14:17]
	v_mfma_f32_16x16x32_bf16 v[6:9], v[172:175], v[220:223], v[6:9]
	v_mfma_f32_16x16x32_bf16 v[62:65], v[168:171], v[200:203], v[62:65]
	v_mfma_f32_16x16x32_bf16 v[54:57], v[176:179], v[200:203], v[54:57]
	v_mfma_f32_16x16x32_bf16 v[46:49], v[168:171], v[208:211], v[46:49]
	v_mfma_f32_16x16x32_bf16 v[38:41], v[176:179], v[208:211], v[38:41]
	v_mfma_f32_16x16x32_bf16 v[30:33], v[168:171], v[216:219], v[30:33]
	v_mfma_f32_16x16x32_bf16 v[22:25], v[176:179], v[216:219], v[22:25]
	v_mfma_f32_16x16x32_bf16 v[14:17], v[168:171], v[224:227], v[14:17]
	v_mfma_f32_16x16x32_bf16 v[6:9], v[176:179], v[224:227], v[6:9]
	s_setprio 0
	s_setprio 1
	v_mfma_f32_16x16x32_bf16 v[58:61], v[180:183], v[196:199], v[58:61]
	v_mfma_f32_16x16x32_bf16 v[50:53], v[188:191], v[196:199], v[50:53]
	v_mfma_f32_16x16x32_bf16 v[42:45], v[180:183], v[204:207], v[42:45]
	v_mfma_f32_16x16x32_bf16 v[34:37], v[188:191], v[204:207], v[34:37]
	v_mfma_f32_16x16x32_bf16 v[26:29], v[180:183], v[212:215], v[26:29]
	v_mfma_f32_16x16x32_bf16 v[18:21], v[188:191], v[212:215], v[18:21]
	v_mfma_f32_16x16x32_bf16 v[10:13], v[180:183], v[220:223], v[10:13]
	v_mfma_f32_16x16x32_bf16 v[2:5], v[188:191], v[220:223], v[2:5]
	v_mfma_f32_16x16x32_bf16 v[58:61], v[184:187], v[200:203], v[58:61]
	v_mfma_f32_16x16x32_bf16 v[50:53], v[192:195], v[200:203], v[50:53]
	v_mfma_f32_16x16x32_bf16 v[42:45], v[184:187], v[208:211], v[42:45]
	v_mfma_f32_16x16x32_bf16 v[34:37], v[192:195], v[208:211], v[34:37]
	v_mfma_f32_16x16x32_bf16 v[26:29], v[184:187], v[216:219], v[26:29]
	v_mfma_f32_16x16x32_bf16 v[18:21], v[192:195], v[216:219], v[18:21]
	v_mfma_f32_16x16x32_bf16 v[10:13], v[184:187], v[224:227], v[10:13]
	v_mfma_f32_16x16x32_bf16 v[2:5], v[192:195], v[224:227], v[2:5]
	s_setprio 0
	s_barrier
	v_cmp_ge_i32_e32 vcc, s7, v156
	s_mov_b32 s6, s7
	s_add_u32 s88, s88, 0x100
	s_addc_u32 s89, s89, 0
	s_add_u32 s86, s86, 0x100
	s_addc_u32 s87, s87, 0
	s_cbranch_vccnz .Lmy_kexit_7
.LBB0_1392:
	s_add_u32 s98, s86, 0x100
	s_addc_u32 s99, s87, 0
	s_cmp_eq_u32 s6, s100
	s_cselect_b64 s[94:95], s[90:91], s[98:99]
	s_cselect_b64 s[96:97], s[92:93], s[88:89]
	v_add_u32_e32 v157, s67, v141
	ds_read_b128 v[164:167], v157
	ds_read_b128 v[168:171], v157 offset:1024
	ds_read_b128 v[172:175], v157 offset:2048
	ds_read_b128 v[176:179], v157 offset:3072
	v_add_u32_e32 v157, s70, v141
	ds_read_b128 v[180:183], v157
	ds_read_b128 v[184:187], v157 offset:1024
	ds_read_b128 v[188:191], v157 offset:2048
	ds_read_b128 v[192:195], v157 offset:3072
	s_add_i32 s7, s6, 2
	s_nop 0
	s_add_i32 m0, s46, 0xc000
	ds_read_b128 v[196:199], v160
	ds_read_b128 v[200:203], v160 offset:1024
	ds_read_b128 v[204:207], v160 offset:2048
	ds_read_b128 v[208:211], v160 offset:3072
	ds_read_b128 v[212:215], v160 offset:4096
	ds_read_b128 v[216:219], v160 offset:5120
	ds_read_b128 v[220:223], v160 offset:6144
	ds_read_b128 v[224:227], v160 offset:7168
	global_load_lds_dwordx4 v144, s[86:87]
	s_add_i32 m0, s46, 0xe000
	s_nop 0
	global_load_lds_dwordx4 v142, s[86:87]
	s_waitcnt vmcnt(8)
	s_waitcnt lgkmcnt(0)
	s_barrier
	s_setprio 1
	s_waitcnt lgkmcnt(0)
	v_mfma_f32_16x16x32_bf16 v[122:125], v[164:167], v[196:199], v[122:125]
	v_mfma_f32_16x16x32_bf16 v[118:121], v[172:175], v[196:199], v[118:121]
	v_mfma_f32_16x16x32_bf16 v[110:113], v[164:167], v[204:207], v[110:113]
	v_mfma_f32_16x16x32_bf16 v[102:105], v[172:175], v[204:207], v[102:105]
	v_mfma_f32_16x16x32_bf16 v[94:97], v[164:167], v[212:215], v[94:97]
	v_mfma_f32_16x16x32_bf16 v[86:89], v[172:175], v[212:215], v[86:89]
	v_mfma_f32_16x16x32_bf16 v[78:81], v[164:167], v[220:223], v[78:81]
	v_mfma_f32_16x16x32_bf16 v[70:73], v[172:175], v[220:223], v[70:73]
	v_mfma_f32_16x16x32_bf16 v[122:125], v[168:171], v[200:203], v[122:125]
	v_mfma_f32_16x16x32_bf16 v[118:121], v[176:179], v[200:203], v[118:121]
	v_mfma_f32_16x16x32_bf16 v[110:113], v[168:171], v[208:211], v[110:113]
	v_mfma_f32_16x16x32_bf16 v[102:105], v[176:179], v[208:211], v[102:105]
	v_mfma_f32_16x16x32_bf16 v[94:97], v[168:171], v[216:219], v[94:97]
	v_mfma_f32_16x16x32_bf16 v[86:89], v[176:179], v[216:219], v[86:89]
	v_mfma_f32_16x16x32_bf16 v[78:81], v[168:171], v[224:227], v[78:81]
	v_mfma_f32_16x16x32_bf16 v[70:73], v[176:179], v[224:227], v[70:73]
	s_setprio 0
	s_setprio 1
	v_mfma_f32_16x16x32_bf16 v[126:129], v[180:183], v[196:199], v[126:129]
	v_mfma_f32_16x16x32_bf16 v[114:117], v[188:191], v[196:199], v[114:117]
	v_mfma_f32_16x16x32_bf16 v[106:109], v[180:183], v[204:207], v[106:109]
	v_mfma_f32_16x16x32_bf16 v[98:101], v[188:191], v[204:207], v[98:101]
	v_mfma_f32_16x16x32_bf16 v[90:93], v[180:183], v[212:215], v[90:93]
	v_mfma_f32_16x16x32_bf16 v[82:85], v[188:191], v[212:215], v[82:85]
	v_mfma_f32_16x16x32_bf16 v[74:77], v[180:183], v[220:223], v[74:77]
	v_mfma_f32_16x16x32_bf16 v[66:69], v[188:191], v[220:223], v[66:69]
	v_mfma_f32_16x16x32_bf16 v[126:129], v[184:187], v[200:203], v[126:129]
	v_mfma_f32_16x16x32_bf16 v[114:117], v[192:195], v[200:203], v[114:117]
	v_mfma_f32_16x16x32_bf16 v[106:109], v[184:187], v[208:211], v[106:109]
	v_mfma_f32_16x16x32_bf16 v[98:101], v[192:195], v[208:211], v[98:101]
	v_mfma_f32_16x16x32_bf16 v[90:93], v[184:187], v[216:219], v[90:93]
	v_mfma_f32_16x16x32_bf16 v[82:85], v[192:195], v[216:219], v[82:85]
	v_mfma_f32_16x16x32_bf16 v[74:77], v[184:187], v[224:227], v[74:77]
	v_mfma_f32_16x16x32_bf16 v[66:69], v[192:195], v[224:227], v[66:69]
	s_setprio 0
	s_barrier
	s_add_u32 s98, s96, 0xb0000
	s_addc_u32 s99, s97, 0
	s_add_i32 s6, s67, s23
	s_mov_b32 m0, s6
	ds_read_b128 v[196:199], v160 offset:16384
	ds_read_b128 v[200:203], v160 offset:17408
	ds_read_b128 v[204:207], v160 offset:18432
	ds_read_b128 v[208:211], v160 offset:19456
	ds_read_b128 v[212:215], v160 offset:20480
	ds_read_b128 v[216:219], v160 offset:21504
	ds_read_b128 v[220:223], v160 offset:22528
	ds_read_b128 v[224:227], v160 offset:23552
	global_load_lds_dwordx4 v132, s[96:97]
	s_add_i32 m0, s6, 0x2000
	s_add_i32 s6, s70, s23
	global_load_lds_dwordx4 v136, s[96:97]
	s_mov_b32 m0, s6
	s_nop 0
	global_load_lds_dwordx4 v132, s[98:99]
	s_add_i32 m0, s6, 0x2000
	s_nop 0
	global_load_lds_dwordx4 v136, s[98:99]
	s_mov_b32 m0, s46
	s_nop 0
	global_load_lds_dwordx4 v130, s[94:95]
	s_mov_b32 m0, s47
	s_nop 0
	global_load_lds_dwordx4 v134, s[94:95]
	s_waitcnt vmcnt(8)
	s_waitcnt lgkmcnt(0)
	s_barrier
	s_setprio 1
	s_waitcnt lgkmcnt(0)
	v_mfma_f32_16x16x32_bf16 v[62:65], v[164:167], v[196:199], v[62:65]
	v_mfma_f32_16x16x32_bf16 v[54:57], v[172:175], v[196:199], v[54:57]
	v_mfma_f32_16x16x32_bf16 v[46:49], v[164:167], v[204:207], v[46:49]
	v_mfma_f32_16x16x32_bf16 v[38:41], v[172:175], v[204:207], v[38:41]
	v_mfma_f32_16x16x32_bf16 v[30:33], v[164:167], v[212:215], v[30:33]
	v_mfma_f32_16x16x32_bf16 v[22:25], v[172:175], v[212:215], v[22:25]
	v_mfma_f32_16x16x32_bf16 v[14:17], v[164:167], v[220:223], v[14:17]
	v_mfma_f32_16x16x32_bf16 v[6:9], v[172:175], v[220:223], v[6:9]
	v_mfma_f32_16x16x32_bf16 v[62:65], v[168:171], v[200:203], v[62:65]
	v_mfma_f32_16x16x32_bf16 v[54:57], v[176:179], v[200:203], v[54:57]
	v_mfma_f32_16x16x32_bf16 v[46:49], v[168:171], v[208:211], v[46:49]
	v_mfma_f32_16x16x32_bf16 v[38:41], v[176:179], v[208:211], v[38:41]
	v_mfma_f32_16x16x32_bf16 v[30:33], v[168:171], v[216:219], v[30:33]
	v_mfma_f32_16x16x32_bf16 v[22:25], v[176:179], v[216:219], v[22:25]
	v_mfma_f32_16x16x32_bf16 v[14:17], v[168:171], v[224:227], v[14:17]
	v_mfma_f32_16x16x32_bf16 v[6:9], v[176:179], v[224:227], v[6:9]
	s_setprio 0
	s_setprio 1
	v_mfma_f32_16x16x32_bf16 v[58:61], v[180:183], v[196:199], v[58:61]
	v_mfma_f32_16x16x32_bf16 v[50:53], v[188:191], v[196:199], v[50:53]
	v_mfma_f32_16x16x32_bf16 v[42:45], v[180:183], v[204:207], v[42:45]
	v_mfma_f32_16x16x32_bf16 v[34:37], v[188:191], v[204:207], v[34:37]
	v_mfma_f32_16x16x32_bf16 v[26:29], v[180:183], v[212:215], v[26:29]
	v_mfma_f32_16x16x32_bf16 v[18:21], v[188:191], v[212:215], v[18:21]
	v_mfma_f32_16x16x32_bf16 v[10:13], v[180:183], v[220:223], v[10:13]
	v_mfma_f32_16x16x32_bf16 v[2:5], v[188:191], v[220:223], v[2:5]
	v_mfma_f32_16x16x32_bf16 v[58:61], v[184:187], v[200:203], v[58:61]
	v_mfma_f32_16x16x32_bf16 v[50:53], v[192:195], v[200:203], v[50:53]
	v_mfma_f32_16x16x32_bf16 v[42:45], v[184:187], v[208:211], v[42:45]
	v_mfma_f32_16x16x32_bf16 v[34:37], v[192:195], v[208:211], v[34:37]
	v_mfma_f32_16x16x32_bf16 v[26:29], v[184:187], v[216:219], v[26:29]
	v_mfma_f32_16x16x32_bf16 v[18:21], v[192:195], v[216:219], v[18:21]
	v_mfma_f32_16x16x32_bf16 v[10:13], v[184:187], v[224:227], v[10:13]
	v_mfma_f32_16x16x32_bf16 v[2:5], v[192:195], v[224:227], v[2:5]
	s_setprio 0
	s_barrier
	s_add_u32 s98, s94, 0xb0000
	s_addc_u32 s99, s95, 0
	s_add_i32 s6, 0, 0x18000
	v_add_u32_e32 v157, s6, v141
	s_add_i32 s29, 0, 0x1c000
	ds_read_b128 v[164:167], v157
	ds_read_b128 v[168:171], v157 offset:1024
	ds_read_b128 v[172:175], v157 offset:2048
	ds_read_b128 v[176:179], v157 offset:3072
	v_add_u32_e32 v157, s29, v141
	ds_read_b128 v[180:183], v157
	ds_read_b128 v[184:187], v157 offset:1024
	ds_read_b128 v[188:191], v157 offset:2048
	ds_read_b128 v[192:195], v157 offset:3072
	s_mov_b32 m0, s48
	ds_read_b128 v[196:199], v160 offset:32768
	ds_read_b128 v[200:203], v160 offset:33792
	ds_read_b128 v[204:207], v160 offset:34816
	ds_read_b128 v[208:211], v160 offset:35840
	ds_read_b128 v[212:215], v160 offset:36864
	ds_read_b128 v[216:219], v160 offset:37888
	ds_read_b128 v[220:223], v160 offset:38912
	ds_read_b128 v[224:227], v160 offset:39936
	global_load_lds_dwordx4 v130, s[98:99]
	s_mov_b32 m0, s49
	s_nop 0
	global_load_lds_dwordx4 v134, s[98:99]
	s_waitcnt vmcnt(8)
	s_waitcnt lgkmcnt(0)
	s_barrier
	s_setprio 1
	s_waitcnt lgkmcnt(0)
	v_mfma_f32_16x16x32_bf16 v[122:125], v[164:167], v[196:199], v[122:125]
	v_mfma_f32_16x16x32_bf16 v[118:121], v[172:175], v[196:199], v[118:121]
	v_mfma_f32_16x16x32_bf16 v[110:113], v[164:167], v[204:207], v[110:113]
	v_mfma_f32_16x16x32_bf16 v[102:105], v[172:175], v[204:207], v[102:105]
	v_mfma_f32_16x16x32_bf16 v[94:97], v[164:167], v[212:215], v[94:97]
	v_mfma_f32_16x16x32_bf16 v[86:89], v[172:175], v[212:215], v[86:89]
	v_mfma_f32_16x16x32_bf16 v[78:81], v[164:167], v[220:223], v[78:81]
	v_mfma_f32_16x16x32_bf16 v[70:73], v[172:175], v[220:223], v[70:73]
	v_mfma_f32_16x16x32_bf16 v[122:125], v[168:171], v[200:203], v[122:125]
	v_mfma_f32_16x16x32_bf16 v[118:121], v[176:179], v[200:203], v[118:121]
	v_mfma_f32_16x16x32_bf16 v[110:113], v[168:171], v[208:211], v[110:113]
	v_mfma_f32_16x16x32_bf16 v[102:105], v[176:179], v[208:211], v[102:105]
	v_mfma_f32_16x16x32_bf16 v[94:97], v[168:171], v[216:219], v[94:97]
	v_mfma_f32_16x16x32_bf16 v[86:89], v[176:179], v[216:219], v[86:89]
	v_mfma_f32_16x16x32_bf16 v[78:81], v[168:171], v[224:227], v[78:81]
	v_mfma_f32_16x16x32_bf16 v[70:73], v[176:179], v[224:227], v[70:73]
	s_setprio 0
	s_setprio 1
	v_mfma_f32_16x16x32_bf16 v[126:129], v[180:183], v[196:199], v[126:129]
	v_mfma_f32_16x16x32_bf16 v[114:117], v[188:191], v[196:199], v[114:117]
	v_mfma_f32_16x16x32_bf16 v[106:109], v[180:183], v[204:207], v[106:109]
	v_mfma_f32_16x16x32_bf16 v[98:101], v[188:191], v[204:207], v[98:101]
	v_mfma_f32_16x16x32_bf16 v[90:93], v[180:183], v[212:215], v[90:93]
	v_mfma_f32_16x16x32_bf16 v[82:85], v[188:191], v[212:215], v[82:85]
	v_mfma_f32_16x16x32_bf16 v[74:77], v[180:183], v[220:223], v[74:77]
	v_mfma_f32_16x16x32_bf16 v[66:69], v[188:191], v[220:223], v[66:69]
	v_mfma_f32_16x16x32_bf16 v[126:129], v[184:187], v[200:203], v[126:129]
	v_mfma_f32_16x16x32_bf16 v[114:117], v[192:195], v[200:203], v[114:117]
	v_mfma_f32_16x16x32_bf16 v[106:109], v[184:187], v[208:211], v[106:109]
	v_mfma_f32_16x16x32_bf16 v[98:101], v[192:195], v[208:211], v[98:101]
	v_mfma_f32_16x16x32_bf16 v[90:93], v[184:187], v[216:219], v[90:93]
	v_mfma_f32_16x16x32_bf16 v[82:85], v[192:195], v[216:219], v[82:85]
	v_mfma_f32_16x16x32_bf16 v[74:77], v[184:187], v[224:227], v[74:77]
	v_mfma_f32_16x16x32_bf16 v[66:69], v[192:195], v[224:227], v[66:69]
	s_setprio 0
	s_barrier
	s_add_u32 s96, s96, 0x80
	s_addc_u32 s97, s97, 0
	s_add_u32 s98, s96, 0xb0000
	s_addc_u32 s99, s97, 0
	s_add_u32 s94, s94, 0x80
	s_addc_u32 s95, s95, 0
	s_add_i32 s6, s6, s23
	s_mov_b32 m0, s6
	ds_read_b128 v[196:199], v160 offset:49152
	ds_read_b128 v[200:203], v160 offset:50176
	ds_read_b128 v[204:207], v160 offset:51200
	ds_read_b128 v[208:211], v160 offset:52224
	ds_read_b128 v[212:215], v160 offset:53248
	ds_read_b128 v[216:219], v160 offset:54272
	ds_read_b128 v[220:223], v160 offset:55296
	ds_read_b128 v[224:227], v160 offset:56320
	global_load_lds_dwordx4 v132, s[96:97]
	s_add_i32 m0, s6, 0x2000
	s_add_i32 s6, s29, s23
	global_load_lds_dwordx4 v136, s[96:97]
	s_mov_b32 m0, s6
	s_nop 0
	global_load_lds_dwordx4 v132, s[98:99]
	s_add_i32 m0, s6, 0x2000
	s_nop 0
	global_load_lds_dwordx4 v136, s[98:99]
	s_mov_b32 m0, s59
	s_nop 0
	global_load_lds_dwordx4 v130, s[94:95]
	s_mov_b32 m0, s60
	s_nop 0
	global_load_lds_dwordx4 v134, s[94:95]
	s_waitcnt vmcnt(8)
	s_waitcnt lgkmcnt(0)
	s_barrier
	s_setprio 1
	s_waitcnt lgkmcnt(0)
	v_mfma_f32_16x16x32_bf16 v[62:65], v[164:167], v[196:199], v[62:65]
	v_mfma_f32_16x16x32_bf16 v[54:57], v[172:175], v[196:199], v[54:57]
	v_mfma_f32_16x16x32_bf16 v[46:49], v[164:167], v[204:207], v[46:49]
	v_mfma_f32_16x16x32_bf16 v[38:41], v[172:175], v[204:207], v[38:41]
	v_mfma_f32_16x16x32_bf16 v[30:33], v[164:167], v[212:215], v[30:33]
	v_mfma_f32_16x16x32_bf16 v[22:25], v[172:175], v[212:215], v[22:25]
	v_mfma_f32_16x16x32_bf16 v[14:17], v[164:167], v[220:223], v[14:17]
	v_mfma_f32_16x16x32_bf16 v[6:9], v[172:175], v[220:223], v[6:9]
	v_mfma_f32_16x16x32_bf16 v[62:65], v[168:171], v[200:203], v[62:65]
	v_mfma_f32_16x16x32_bf16 v[54:57], v[176:179], v[200:203], v[54:57]
	v_mfma_f32_16x16x32_bf16 v[46:49], v[168:171], v[208:211], v[46:49]
	v_mfma_f32_16x16x32_bf16 v[38:41], v[176:179], v[208:211], v[38:41]
	v_mfma_f32_16x16x32_bf16 v[30:33], v[168:171], v[216:219], v[30:33]
	v_mfma_f32_16x16x32_bf16 v[22:25], v[176:179], v[216:219], v[22:25]
	v_mfma_f32_16x16x32_bf16 v[14:17], v[168:171], v[224:227], v[14:17]
	v_mfma_f32_16x16x32_bf16 v[6:9], v[176:179], v[224:227], v[6:9]
	s_setprio 0
	s_setprio 1
	v_mfma_f32_16x16x32_bf16 v[58:61], v[180:183], v[196:199], v[58:61]
	v_mfma_f32_16x16x32_bf16 v[50:53], v[188:191], v[196:199], v[50:53]
	v_mfma_f32_16x16x32_bf16 v[42:45], v[180:183], v[204:207], v[42:45]
	v_mfma_f32_16x16x32_bf16 v[34:37], v[188:191], v[204:207], v[34:37]
	v_mfma_f32_16x16x32_bf16 v[26:29], v[180:183], v[212:215], v[26:29]
	v_mfma_f32_16x16x32_bf16 v[18:21], v[188:191], v[212:215], v[18:21]
	v_mfma_f32_16x16x32_bf16 v[10:13], v[180:183], v[220:223], v[10:13]
	v_mfma_f32_16x16x32_bf16 v[2:5], v[188:191], v[220:223], v[2:5]
	v_mfma_f32_16x16x32_bf16 v[58:61], v[184:187], v[200:203], v[58:61]
	v_mfma_f32_16x16x32_bf16 v[50:53], v[192:195], v[200:203], v[50:53]
	v_mfma_f32_16x16x32_bf16 v[42:45], v[184:187], v[208:211], v[42:45]
	v_mfma_f32_16x16x32_bf16 v[34:37], v[192:195], v[208:211], v[34:37]
	v_mfma_f32_16x16x32_bf16 v[26:29], v[184:187], v[216:219], v[26:29]
	v_mfma_f32_16x16x32_bf16 v[18:21], v[192:195], v[216:219], v[18:21]
	v_mfma_f32_16x16x32_bf16 v[10:13], v[184:187], v[224:227], v[10:13]
	v_mfma_f32_16x16x32_bf16 v[2:5], v[192:195], v[224:227], v[2:5]
	s_setprio 0
	s_barrier
	v_cmp_ge_i32_e32 vcc, s7, v156
	s_mov_b32 s6, s7
	s_add_u32 s88, s88, 0x100
	s_addc_u32 s89, s89, 0
	s_add_u32 s86, s86, 0x100
	s_addc_u32 s87, s87, 0
	s_cbranch_vccz .LBB0_1392

.LBB0_1571:
	v_cmp_gt_i32_e32 vcc, 1, v141
	s_cbranch_vccnz .LBB0_1633
	v_lshl_add_u64 v[154:155], v[2:3], 0, s[18:19]
	v_add_u32_e32 v138, -2, v141
	v_lshl_add_u64 v[152:153], v[4:5], 0, s[22:23]
	s_mov_b32 s7, 0
	s_nop 0
	v_readfirstlane_b32 s86, v154
	v_readfirstlane_b32 s87, v155
	v_readfirstlane_b32 s88, v152
	v_readfirstlane_b32 s89, v153
	v_readfirstlane_b32 s90, v148
	v_readfirstlane_b32 s91, v149
	v_readfirstlane_b32 s92, v150
	v_readfirstlane_b32 s93, v151
	v_readfirstlane_b32 s100, v138
	s_add_u32 s98, s86, 0xfffc0080
	s_addc_u32 s99, s87, -1
	s_cmp_eq_u32 s7, s100
	s_cselect_b64 s[94:95], s[90:91], s[98:99]
	s_cselect_b64 s[96:97], s[92:93], s[88:89]
	v_add_u32_e32 v146, s71, v160
	ds_read_b128 v[156:159], v146
	ds_read_b128 v[166:169], v146 offset:1024
	ds_read_b128 v[170:173], v146 offset:2048
	ds_read_b128 v[174:177], v146 offset:3072
	v_add_u32_e32 v146, s72, v160
	ds_read_b128 v[178:181], v146
	ds_read_b128 v[182:185], v146 offset:1024
	ds_read_b128 v[186:189], v146 offset:2048
	ds_read_b128 v[190:193], v146 offset:3072
	s_add_i32 s47, s7, 2
	s_nop 0
	s_mov_b32 m0, s74
	ds_read_b128 v[194:197], v163
	ds_read_b128 v[198:201], v163 offset:1024
	ds_read_b128 v[202:205], v163 offset:2048
	ds_read_b128 v[206:209], v163 offset:3072
	ds_read_b128 v[210:213], v163 offset:4096
	ds_read_b128 v[214:217], v163 offset:5120
	ds_read_b128 v[218:221], v163 offset:6144
	ds_read_b128 v[222:225], v163 offset:7168
	global_load_lds_dwordx4 v144, s[86:87]
	s_mov_b32 m0, s75
	s_nop 0
	global_load_lds_dwordx4 v142, s[86:87]
	s_waitcnt vmcnt(8)
	s_waitcnt lgkmcnt(0)
	s_barrier
	s_setprio 1
	s_waitcnt lgkmcnt(0)
	v_mfma_f32_16x16x32_bf16 v[122:125], v[156:159], v[194:197], 0
	v_mfma_f32_16x16x32_bf16 v[118:121], v[170:173], v[194:197], 0
	v_mfma_f32_16x16x32_bf16 v[110:113], v[156:159], v[202:205], 0
	v_mfma_f32_16x16x32_bf16 v[102:105], v[170:173], v[202:205], 0
	v_mfma_f32_16x16x32_bf16 v[94:97], v[156:159], v[210:213], 0
	v_mfma_f32_16x16x32_bf16 v[86:89], v[170:173], v[210:213], 0
	v_mfma_f32_16x16x32_bf16 v[78:81], v[156:159], v[218:221], 0
	v_mfma_f32_16x16x32_bf16 v[70:73], v[170:173], v[218:221], 0
	v_mfma_f32_16x16x32_bf16 v[122:125], v[166:169], v[198:201], v[122:125]
	v_mfma_f32_16x16x32_bf16 v[118:121], v[174:177], v[198:201], v[118:121]
	v_mfma_f32_16x16x32_bf16 v[110:113], v[166:169], v[206:209], v[110:113]
	v_mfma_f32_16x16x32_bf16 v[102:105], v[174:177], v[206:209], v[102:105]
	v_mfma_f32_16x16x32_bf16 v[94:97], v[166:169], v[214:217], v[94:97]
	v_mfma_f32_16x16x32_bf16 v[86:89], v[174:177], v[214:217], v[86:89]
	v_mfma_f32_16x16x32_bf16 v[78:81], v[166:169], v[222:225], v[78:81]
	v_mfma_f32_16x16x32_bf16 v[70:73], v[174:177], v[222:225], v[70:73]
	s_setprio 0
	s_setprio 1
	v_mfma_f32_16x16x32_bf16 v[126:129], v[178:181], v[194:197], 0
	v_mfma_f32_16x16x32_bf16 v[114:117], v[186:189], v[194:197], 0
	v_mfma_f32_16x16x32_bf16 v[106:109], v[178:181], v[202:205], 0
	v_mfma_f32_16x16x32_bf16 v[98:101], v[186:189], v[202:205], 0
	v_mfma_f32_16x16x32_bf16 v[90:93], v[178:181], v[210:213], 0
	v_mfma_f32_16x16x32_bf16 v[82:85], v[186:189], v[210:213], 0
	v_mfma_f32_16x16x32_bf16 v[74:77], v[178:181], v[218:221], 0
	v_mfma_f32_16x16x32_bf16 v[66:69], v[186:189], v[218:221], 0
	v_mfma_f32_16x16x32_bf16 v[126:129], v[182:185], v[198:201], v[126:129]
	v_mfma_f32_16x16x32_bf16 v[114:117], v[190:193], v[198:201], v[114:117]
	v_mfma_f32_16x16x32_bf16 v[106:109], v[182:185], v[206:209], v[106:109]
	v_mfma_f32_16x16x32_bf16 v[98:101], v[190:193], v[206:209], v[98:101]
	v_mfma_f32_16x16x32_bf16 v[90:93], v[182:185], v[214:217], v[90:93]
	v_mfma_f32_16x16x32_bf16 v[82:85], v[190:193], v[214:217], v[82:85]
	v_mfma_f32_16x16x32_bf16 v[74:77], v[182:185], v[222:225], v[74:77]
	v_mfma_f32_16x16x32_bf16 v[66:69], v[190:193], v[222:225], v[66:69]
	s_setprio 0
	s_barrier
	s_add_u32 s98, s96, 0x40000
	s_addc_u32 s99, s97, 0
	s_add_i32 s7, s71, s29
	s_mov_b32 m0, s7
	ds_read_b128 v[194:197], v163 offset:16384
	ds_read_b128 v[198:201], v163 offset:17408
	ds_read_b128 v[202:205], v163 offset:18432
	ds_read_b128 v[206:209], v163 offset:19456
	ds_read_b128 v[210:213], v163 offset:20480
	ds_read_b128 v[214:217], v163 offset:21504
	ds_read_b128 v[218:221], v163 offset:22528
	ds_read_b128 v[222:225], v163 offset:23552
	global_load_lds_dwordx4 v132, s[96:97]
	s_add_i32 m0, s7, 0x2000
	s_add_i32 s7, s72, s29
	global_load_lds_dwordx4 v136, s[96:97]
	s_mov_b32 m0, s7
	s_nop 0
	global_load_lds_dwordx4 v132, s[98:99]
	s_add_i32 m0, s7, 0x2000
	s_nop 0
	global_load_lds_dwordx4 v136, s[98:99]
	s_mov_b32 m0, s51
	s_nop 0
	global_load_lds_dwordx4 v130, s[94:95]
	s_mov_b32 m0, s60
	s_nop 0
	global_load_lds_dwordx4 v134, s[94:95]
	s_waitcnt vmcnt(8)
	s_waitcnt lgkmcnt(0)
	s_barrier
	s_setprio 1
	s_waitcnt lgkmcnt(0)
	v_mfma_f32_16x16x32_bf16 v[62:65], v[156:159], v[194:197], 0
	v_mfma_f32_16x16x32_bf16 v[54:57], v[170:173], v[194:197], 0
	v_mfma_f32_16x16x32_bf16 v[46:49], v[156:159], v[202:205], 0
	v_mfma_f32_16x16x32_bf16 v[38:41], v[170:173], v[202:205], 0
	v_mfma_f32_16x16x32_bf16 v[30:33], v[156:159], v[210:213], 0
	v_mfma_f32_16x16x32_bf16 v[22:25], v[170:173], v[210:213], 0
	v_mfma_f32_16x16x32_bf16 v[14:17], v[156:159], v[218:221], 0
	v_mfma_f32_16x16x32_bf16 v[6:9], v[170:173], v[218:221], 0
	v_mfma_f32_16x16x32_bf16 v[62:65], v[166:169], v[198:201], v[62:65]
	v_mfma_f32_16x16x32_bf16 v[54:57], v[174:177], v[198:201], v[54:57]
	v_mfma_f32_16x16x32_bf16 v[46:49], v[166:169], v[206:209], v[46:49]
	v_mfma_f32_16x16x32_bf16 v[38:41], v[174:177], v[206:209], v[38:41]
	v_mfma_f32_16x16x32_bf16 v[30:33], v[166:169], v[214:217], v[30:33]
	v_mfma_f32_16x16x32_bf16 v[22:25], v[174:177], v[214:217], v[22:25]
	v_mfma_f32_16x16x32_bf16 v[14:17], v[166:169], v[222:225], v[14:17]
	v_mfma_f32_16x16x32_bf16 v[6:9], v[174:177], v[222:225], v[6:9]
	s_setprio 0
	s_setprio 1
	v_mfma_f32_16x16x32_bf16 v[58:61], v[178:181], v[194:197], 0
	v_mfma_f32_16x16x32_bf16 v[50:53], v[186:189], v[194:197], 0
	v_mfma_f32_16x16x32_bf16 v[42:45], v[178:181], v[202:205], 0
	v_mfma_f32_16x16x32_bf16 v[34:37], v[186:189], v[202:205], 0
	v_mfma_f32_16x16x32_bf16 v[26:29], v[178:181], v[210:213], 0
	v_mfma_f32_16x16x32_bf16 v[18:21], v[186:189], v[210:213], 0
	v_mfma_f32_16x16x32_bf16 v[10:13], v[178:181], v[218:221], 0
	v_mfma_f32_16x16x32_bf16 v[2:5], v[186:189], v[218:221], 0
	v_mfma_f32_16x16x32_bf16 v[58:61], v[182:185], v[198:201], v[58:61]
	v_mfma_f32_16x16x32_bf16 v[50:53], v[190:193], v[198:201], v[50:53]
	v_mfma_f32_16x16x32_bf16 v[42:45], v[182:185], v[206:209], v[42:45]
	v_mfma_f32_16x16x32_bf16 v[34:37], v[190:193], v[206:209], v[34:37]
	v_mfma_f32_16x16x32_bf16 v[26:29], v[182:185], v[214:217], v[26:29]
	v_mfma_f32_16x16x32_bf16 v[18:21], v[190:193], v[214:217], v[18:21]
	v_mfma_f32_16x16x32_bf16 v[10:13], v[182:185], v[222:225], v[10:13]
	v_mfma_f32_16x16x32_bf16 v[2:5], v[190:193], v[222:225], v[2:5]
	s_setprio 0
	s_barrier
	s_add_u32 s98, s94, 0x40000
	s_addc_u32 s99, s95, 0
	s_add_i32 s7, 0, 0x18000
	v_add_u32_e32 v146, s7, v160
	s_add_i32 s49, 0, 0x1c000
	ds_read_b128 v[156:159], v146
	ds_read_b128 v[166:169], v146 offset:1024
	ds_read_b128 v[170:173], v146 offset:2048
	ds_read_b128 v[174:177], v146 offset:3072
	v_add_u32_e32 v146, s49, v160
	ds_read_b128 v[178:181], v146
	ds_read_b128 v[182:185], v146 offset:1024
	ds_read_b128 v[186:189], v146 offset:2048
	ds_read_b128 v[190:193], v146 offset:3072
	s_mov_b32 m0, s61
	ds_read_b128 v[194:197], v163 offset:32768
	ds_read_b128 v[198:201], v163 offset:33792
	ds_read_b128 v[202:205], v163 offset:34816
	ds_read_b128 v[206:209], v163 offset:35840
	ds_read_b128 v[210:213], v163 offset:36864
	ds_read_b128 v[214:217], v163 offset:37888
	ds_read_b128 v[218:221], v163 offset:38912
	ds_read_b128 v[222:225], v163 offset:39936
	global_load_lds_dwordx4 v130, s[98:99]
	s_mov_b32 m0, s62
	s_nop 0
	global_load_lds_dwordx4 v134, s[98:99]
	s_waitcnt vmcnt(8)
	s_waitcnt lgkmcnt(0)
	s_barrier
	s_setprio 1
	s_waitcnt lgkmcnt(0)
	v_mfma_f32_16x16x32_bf16 v[122:125], v[156:159], v[194:197], v[122:125]
	v_mfma_f32_16x16x32_bf16 v[118:121], v[170:173], v[194:197], v[118:121]
	v_mfma_f32_16x16x32_bf16 v[110:113], v[156:159], v[202:205], v[110:113]
	v_mfma_f32_16x16x32_bf16 v[102:105], v[170:173], v[202:205], v[102:105]
	v_mfma_f32_16x16x32_bf16 v[94:97], v[156:159], v[210:213], v[94:97]
	v_mfma_f32_16x16x32_bf16 v[86:89], v[170:173], v[210:213], v[86:89]
	v_mfma_f32_16x16x32_bf16 v[78:81], v[156:159], v[218:221], v[78:81]
	v_mfma_f32_16x16x32_bf16 v[70:73], v[170:173], v[218:221], v[70:73]
	v_mfma_f32_16x16x32_bf16 v[122:125], v[166:169], v[198:201], v[122:125]
	v_mfma_f32_16x16x32_bf16 v[118:121], v[174:177], v[198:201], v[118:121]
	v_mfma_f32_16x16x32_bf16 v[110:113], v[166:169], v[206:209], v[110:113]
	v_mfma_f32_16x16x32_bf16 v[102:105], v[174:177], v[206:209], v[102:105]
	v_mfma_f32_16x16x32_bf16 v[94:97], v[166:169], v[214:217], v[94:97]
	v_mfma_f32_16x16x32_bf16 v[86:89], v[174:177], v[214:217], v[86:89]
	v_mfma_f32_16x16x32_bf16 v[78:81], v[166:169], v[222:225], v[78:81]
	v_mfma_f32_16x16x32_bf16 v[70:73], v[174:177], v[222:225], v[70:73]
	s_setprio 0
	s_setprio 1
	v_mfma_f32_16x16x32_bf16 v[126:129], v[178:181], v[194:197], v[126:129]
	v_mfma_f32_16x16x32_bf16 v[114:117], v[186:189], v[194:197], v[114:117]
	v_mfma_f32_16x16x32_bf16 v[106:109], v[178:181], v[202:205], v[106:109]
	v_mfma_f32_16x16x32_bf16 v[98:101], v[186:189], v[202:205], v[98:101]
	v_mfma_f32_16x16x32_bf16 v[90:93], v[178:181], v[210:213], v[90:93]
	v_mfma_f32_16x16x32_bf16 v[82:85], v[186:189], v[210:213], v[82:85]
	v_mfma_f32_16x16x32_bf16 v[74:77], v[178:181], v[218:221], v[74:77]
	v_mfma_f32_16x16x32_bf16 v[66:69], v[186:189], v[218:221], v[66:69]
	v_mfma_f32_16x16x32_bf16 v[126:129], v[182:185], v[198:201], v[126:129]
	v_mfma_f32_16x16x32_bf16 v[114:117], v[190:193], v[198:201], v[114:117]
	v_mfma_f32_16x16x32_bf16 v[106:109], v[182:185], v[206:209], v[106:109]
	v_mfma_f32_16x16x32_bf16 v[98:101], v[190:193], v[206:209], v[98:101]
	v_mfma_f32_16x16x32_bf16 v[90:93], v[182:185], v[214:217], v[90:93]
	v_mfma_f32_16x16x32_bf16 v[82:85], v[190:193], v[214:217], v[82:85]
	v_mfma_f32_16x16x32_bf16 v[74:77], v[182:185], v[222:225], v[74:77]
	v_mfma_f32_16x16x32_bf16 v[66:69], v[190:193], v[222:225], v[66:69]
	s_setprio 0
	s_barrier
	s_add_u32 s96, s96, 0x80
	s_addc_u32 s97, s97, 0
	s_add_u32 s98, s96, 0x40000
	s_addc_u32 s99, s97, 0
	s_add_u32 s94, s94, 0x80
	s_addc_u32 s95, s95, 0
	s_add_i32 s7, s7, s29
	s_mov_b32 m0, s7
	ds_read_b128 v[194:197], v163 offset:49152
	ds_read_b128 v[198:201], v163 offset:50176
	ds_read_b128 v[202:205], v163 offset:51200
	ds_read_b128 v[206:209], v163 offset:52224
	ds_read_b128 v[210:213], v163 offset:53248
	ds_read_b128 v[214:217], v163 offset:54272
	ds_read_b128 v[218:221], v163 offset:55296
	ds_read_b128 v[222:225], v163 offset:56320
	global_load_lds_dwordx4 v132, s[96:97]
	s_add_i32 m0, s7, 0x2000
	s_add_i32 s7, s49, s29
	global_load_lds_dwordx4 v136, s[96:97]
	s_mov_b32 m0, s7
	s_nop 0
	global_load_lds_dwordx4 v132, s[98:99]
	s_add_i32 m0, s7, 0x2000
	s_nop 0
	global_load_lds_dwordx4 v136, s[98:99]
	s_mov_b32 m0, s63
	s_nop 0
	global_load_lds_dwordx4 v130, s[94:95]
	s_mov_b32 m0, s64
	s_nop 0
	global_load_lds_dwordx4 v134, s[94:95]
	s_waitcnt vmcnt(8)
	s_waitcnt lgkmcnt(0)
	s_barrier
	s_setprio 1
	s_waitcnt lgkmcnt(0)
	v_mfma_f32_16x16x32_bf16 v[62:65], v[156:159], v[194:197], v[62:65]
	v_mfma_f32_16x16x32_bf16 v[54:57], v[170:173], v[194:197], v[54:57]
	v_mfma_f32_16x16x32_bf16 v[46:49], v[156:159], v[202:205], v[46:49]
	v_mfma_f32_16x16x32_bf16 v[38:41], v[170:173], v[202:205], v[38:41]
	v_mfma_f32_16x16x32_bf16 v[30:33], v[156:159], v[210:213], v[30:33]
	v_mfma_f32_16x16x32_bf16 v[22:25], v[170:173], v[210:213], v[22:25]
	v_mfma_f32_16x16x32_bf16 v[14:17], v[156:159], v[218:221], v[14:17]
	v_mfma_f32_16x16x32_bf16 v[6:9], v[170:173], v[218:221], v[6:9]
	v_mfma_f32_16x16x32_bf16 v[62:65], v[166:169], v[198:201], v[62:65]
	v_mfma_f32_16x16x32_bf16 v[54:57], v[174:177], v[198:201], v[54:57]
	v_mfma_f32_16x16x32_bf16 v[46:49], v[166:169], v[206:209], v[46:49]
	v_mfma_f32_16x16x32_bf16 v[38:41], v[174:177], v[206:209], v[38:41]
	v_mfma_f32_16x16x32_bf16 v[30:33], v[166:169], v[214:217], v[30:33]
	v_mfma_f32_16x16x32_bf16 v[22:25], v[174:177], v[214:217], v[22:25]
	v_mfma_f32_16x16x32_bf16 v[14:17], v[166:169], v[222:225], v[14:17]
	v_mfma_f32_16x16x32_bf16 v[6:9], v[174:177], v[222:225], v[6:9]
	s_setprio 0
	s_setprio 1
	v_mfma_f32_16x16x32_bf16 v[58:61], v[178:181], v[194:197], v[58:61]
	v_mfma_f32_16x16x32_bf16 v[50:53], v[186:189], v[194:197], v[50:53]
	v_mfma_f32_16x16x32_bf16 v[42:45], v[178:181], v[202:205], v[42:45]
	v_mfma_f32_16x16x32_bf16 v[34:37], v[186:189], v[202:205], v[34:37]
	v_mfma_f32_16x16x32_bf16 v[26:29], v[178:181], v[210:213], v[26:29]
	v_mfma_f32_16x16x32_bf16 v[18:21], v[186:189], v[210:213], v[18:21]
	v_mfma_f32_16x16x32_bf16 v[10:13], v[178:181], v[218:221], v[10:13]
	v_mfma_f32_16x16x32_bf16 v[2:5], v[186:189], v[218:221], v[2:5]
	v_mfma_f32_16x16x32_bf16 v[58:61], v[182:185], v[198:201], v[58:61]
	v_mfma_f32_16x16x32_bf16 v[50:53], v[190:193], v[198:201], v[50:53]
	v_mfma_f32_16x16x32_bf16 v[42:45], v[182:185], v[206:209], v[42:45]
	v_mfma_f32_16x16x32_bf16 v[34:37], v[190:193], v[206:209], v[34:37]
	v_mfma_f32_16x16x32_bf16 v[26:29], v[182:185], v[214:217], v[26:29]
	v_mfma_f32_16x16x32_bf16 v[18:21], v[190:193], v[214:217], v[18:21]
	v_mfma_f32_16x16x32_bf16 v[10:13], v[182:185], v[222:225], v[10:13]
	v_mfma_f32_16x16x32_bf16 v[2:5], v[190:193], v[222:225], v[2:5]
	s_setprio 0
	s_barrier
	v_cmp_ge_i32_e32 vcc, s47, v141
	s_mov_b32 s7, s47
	s_add_u32 s88, s88, 0x100
	s_addc_u32 s89, s89, 0
	s_add_u32 s86, s86, 0x100
	s_addc_u32 s87, s87, 0
	s_cbranch_vccnz .Lmy_kexit_8
.LBB0_1573:
	s_add_u32 s98, s86, 0xfffc0080
	s_addc_u32 s99, s87, -1
	s_cmp_eq_u32 s7, s100
	s_cselect_b64 s[94:95], s[90:91], s[98:99]
	s_cselect_b64 s[96:97], s[92:93], s[88:89]
	v_add_u32_e32 v146, s71, v160
	ds_read_b128 v[156:159], v146
	ds_read_b128 v[166:169], v146 offset:1024
	ds_read_b128 v[170:173], v146 offset:2048
	ds_read_b128 v[174:177], v146 offset:3072
	v_add_u32_e32 v146, s72, v160
	ds_read_b128 v[178:181], v146
	ds_read_b128 v[182:185], v146 offset:1024
	ds_read_b128 v[186:189], v146 offset:2048
	ds_read_b128 v[190:193], v146 offset:3072
	s_add_i32 s47, s7, 2
	s_nop 0
	s_mov_b32 m0, s74
	ds_read_b128 v[194:197], v163
	ds_read_b128 v[198:201], v163 offset:1024
	ds_read_b128 v[202:205], v163 offset:2048
	ds_read_b128 v[206:209], v163 offset:3072
	ds_read_b128 v[210:213], v163 offset:4096
	ds_read_b128 v[214:217], v163 offset:5120
	ds_read_b128 v[218:221], v163 offset:6144
	ds_read_b128 v[222:225], v163 offset:7168
	global_load_lds_dwordx4 v144, s[86:87]
	s_mov_b32 m0, s75
	s_nop 0
	global_load_lds_dwordx4 v142, s[86:87]
	s_waitcnt vmcnt(8)
	s_waitcnt lgkmcnt(0)
	s_barrier
	s_setprio 1
	s_waitcnt lgkmcnt(0)
	v_mfma_f32_16x16x32_bf16 v[122:125], v[156:159], v[194:197], v[122:125]
	v_mfma_f32_16x16x32_bf16 v[118:121], v[170:173], v[194:197], v[118:121]
	v_mfma_f32_16x16x32_bf16 v[110:113], v[156:159], v[202:205], v[110:113]
	v_mfma_f32_16x16x32_bf16 v[102:105], v[170:173], v[202:205], v[102:105]
	v_mfma_f32_16x16x32_bf16 v[94:97], v[156:159], v[210:213], v[94:97]
	v_mfma_f32_16x16x32_bf16 v[86:89], v[170:173], v[210:213], v[86:89]
	v_mfma_f32_16x16x32_bf16 v[78:81], v[156:159], v[218:221], v[78:81]
	v_mfma_f32_16x16x32_bf16 v[70:73], v[170:173], v[218:221], v[70:73]
	v_mfma_f32_16x16x32_bf16 v[122:125], v[166:169], v[198:201], v[122:125]
	v_mfma_f32_16x16x32_bf16 v[118:121], v[174:177], v[198:201], v[118:121]
	v_mfma_f32_16x16x32_bf16 v[110:113], v[166:169], v[206:209], v[110:113]
	v_mfma_f32_16x16x32_bf16 v[102:105], v[174:177], v[206:209], v[102:105]
	v_mfma_f32_16x16x32_bf16 v[94:97], v[166:169], v[214:217], v[94:97]
	v_mfma_f32_16x16x32_bf16 v[86:89], v[174:177], v[214:217], v[86:89]
	v_mfma_f32_16x16x32_bf16 v[78:81], v[166:169], v[222:225], v[78:81]
	v_mfma_f32_16x16x32_bf16 v[70:73], v[174:177], v[222:225], v[70:73]
	s_setprio 0
	s_setprio 1
	v_mfma_f32_16x16x32_bf16 v[126:129], v[178:181], v[194:197], v[126:129]
	v_mfma_f32_16x16x32_bf16 v[114:117], v[186:189], v[194:197], v[114:117]
	v_mfma_f32_16x16x32_bf16 v[106:109], v[178:181], v[202:205], v[106:109]
	v_mfma_f32_16x16x32_bf16 v[98:101], v[186:189], v[202:205], v[98:101]
	v_mfma_f32_16x16x32_bf16 v[90:93], v[178:181], v[210:213], v[90:93]
	v_mfma_f32_16x16x32_bf16 v[82:85], v[186:189], v[210:213], v[82:85]
	v_mfma_f32_16x16x32_bf16 v[74:77], v[178:181], v[218:221], v[74:77]
	v_mfma_f32_16x16x32_bf16 v[66:69], v[186:189], v[218:221], v[66:69]
	v_mfma_f32_16x16x32_bf16 v[126:129], v[182:185], v[198:201], v[126:129]
	v_mfma_f32_16x16x32_bf16 v[114:117], v[190:193], v[198:201], v[114:117]
	v_mfma_f32_16x16x32_bf16 v[106:109], v[182:185], v[206:209], v[106:109]
	v_mfma_f32_16x16x32_bf16 v[98:101], v[190:193], v[206:209], v[98:101]
	v_mfma_f32_16x16x32_bf16 v[90:93], v[182:185], v[214:217], v[90:93]
	v_mfma_f32_16x16x32_bf16 v[82:85], v[190:193], v[214:217], v[82:85]
	v_mfma_f32_16x16x32_bf16 v[74:77], v[182:185], v[222:225], v[74:77]
	v_mfma_f32_16x16x32_bf16 v[66:69], v[190:193], v[222:225], v[66:69]
	s_setprio 0
	s_barrier
	s_add_u32 s98, s96, 0x40000
	s_addc_u32 s99, s97, 0
	s_add_i32 s7, s71, s29
	s_mov_b32 m0, s7
	ds_read_b128 v[194:197], v163 offset:16384
	ds_read_b128 v[198:201], v163 offset:17408
	ds_read_b128 v[202:205], v163 offset:18432
	ds_read_b128 v[206:209], v163 offset:19456
	ds_read_b128 v[210:213], v163 offset:20480
	ds_read_b128 v[214:217], v163 offset:21504
	ds_read_b128 v[218:221], v163 offset:22528
	ds_read_b128 v[222:225], v163 offset:23552
	global_load_lds_dwordx4 v132, s[96:97]
	s_add_i32 m0, s7, 0x2000
	s_add_i32 s7, s72, s29
	global_load_lds_dwordx4 v136, s[96:97]
	s_mov_b32 m0, s7
	s_nop 0
	global_load_lds_dwordx4 v132, s[98:99]
	s_add_i32 m0, s7, 0x2000
	s_nop 0
	global_load_lds_dwordx4 v136, s[98:99]
	s_mov_b32 m0, s51
	s_nop 0
	global_load_lds_dwordx4 v130, s[94:95]
	s_mov_b32 m0, s60
	s_nop 0
	global_load_lds_dwordx4 v134, s[94:95]
	s_waitcnt vmcnt(8)
	s_waitcnt lgkmcnt(0)
	s_barrier
	s_setprio 1
	s_waitcnt lgkmcnt(0)
	v_mfma_f32_16x16x32_bf16 v[62:65], v[156:159], v[194:197], v[62:65]
	v_mfma_f32_16x16x32_bf16 v[54:57], v[170:173], v[194:197], v[54:57]
	v_mfma_f32_16x16x32_bf16 v[46:49], v[156:159], v[202:205], v[46:49]
	v_mfma_f32_16x16x32_bf16 v[38:41], v[170:173], v[202:205], v[38:41]
	v_mfma_f32_16x16x32_bf16 v[30:33], v[156:159], v[210:213], v[30:33]
	v_mfma_f32_16x16x32_bf16 v[22:25], v[170:173], v[210:213], v[22:25]
	v_mfma_f32_16x16x32_bf16 v[14:17], v[156:159], v[218:221], v[14:17]
	v_mfma_f32_16x16x32_bf16 v[6:9], v[170:173], v[218:221], v[6:9]
	v_mfma_f32_16x16x32_bf16 v[62:65], v[166:169], v[198:201], v[62:65]
	v_mfma_f32_16x16x32_bf16 v[54:57], v[174:177], v[198:201], v[54:57]
	v_mfma_f32_16x16x32_bf16 v[46:49], v[166:169], v[206:209], v[46:49]
	v_mfma_f32_16x16x32_bf16 v[38:41], v[174:177], v[206:209], v[38:41]
	v_mfma_f32_16x16x32_bf16 v[30:33], v[166:169], v[214:217], v[30:33]
	v_mfma_f32_16x16x32_bf16 v[22:25], v[174:177], v[214:217], v[22:25]
	v_mfma_f32_16x16x32_bf16 v[14:17], v[166:169], v[222:225], v[14:17]
	v_mfma_f32_16x16x32_bf16 v[6:9], v[174:177], v[222:225], v[6:9]
	s_setprio 0
	s_setprio 1
	v_mfma_f32_16x16x32_bf16 v[58:61], v[178:181], v[194:197], v[58:61]
	v_mfma_f32_16x16x32_bf16 v[50:53], v[186:189], v[194:197], v[50:53]
	v_mfma_f32_16x16x32_bf16 v[42:45], v[178:181], v[202:205], v[42:45]
	v_mfma_f32_16x16x32_bf16 v[34:37], v[186:189], v[202:205], v[34:37]
	v_mfma_f32_16x16x32_bf16 v[26:29], v[178:181], v[210:213], v[26:29]
	v_mfma_f32_16x16x32_bf16 v[18:21], v[186:189], v[210:213], v[18:21]
	v_mfma_f32_16x16x32_bf16 v[10:13], v[178:181], v[218:221], v[10:13]
	v_mfma_f32_16x16x32_bf16 v[2:5], v[186:189], v[218:221], v[2:5]
	v_mfma_f32_16x16x32_bf16 v[58:61], v[182:185], v[198:201], v[58:61]
	v_mfma_f32_16x16x32_bf16 v[50:53], v[190:193], v[198:201], v[50:53]
	v_mfma_f32_16x16x32_bf16 v[42:45], v[182:185], v[206:209], v[42:45]
	v_mfma_f32_16x16x32_bf16 v[34:37], v[190:193], v[206:209], v[34:37]
	v_mfma_f32_16x16x32_bf16 v[26:29], v[182:185], v[214:217], v[26:29]
	v_mfma_f32_16x16x32_bf16 v[18:21], v[190:193], v[214:217], v[18:21]
	v_mfma_f32_16x16x32_bf16 v[10:13], v[182:185], v[222:225], v[10:13]
	v_mfma_f32_16x16x32_bf16 v[2:5], v[190:193], v[222:225], v[2:5]
	s_setprio 0
	s_barrier
	s_add_u32 s98, s94, 0x40000
	s_addc_u32 s99, s95, 0
	s_add_i32 s7, 0, 0x18000
	v_add_u32_e32 v146, s7, v160
	s_add_i32 s49, 0, 0x1c000
	ds_read_b128 v[156:159], v146
	ds_read_b128 v[166:169], v146 offset:1024
	ds_read_b128 v[170:173], v146 offset:2048
	ds_read_b128 v[174:177], v146 offset:3072
	v_add_u32_e32 v146, s49, v160
	ds_read_b128 v[178:181], v146
	ds_read_b128 v[182:185], v146 offset:1024
	ds_read_b128 v[186:189], v146 offset:2048
	ds_read_b128 v[190:193], v146 offset:3072
	s_mov_b32 m0, s61
	ds_read_b128 v[194:197], v163 offset:32768
	ds_read_b128 v[198:201], v163 offset:33792
	ds_read_b128 v[202:205], v163 offset:34816
	ds_read_b128 v[206:209], v163 offset:35840
	ds_read_b128 v[210:213], v163 offset:36864
	ds_read_b128 v[214:217], v163 offset:37888
	ds_read_b128 v[218:221], v163 offset:38912
	ds_read_b128 v[222:225], v163 offset:39936
	global_load_lds_dwordx4 v130, s[98:99]
	s_mov_b32 m0, s62
	s_nop 0
	global_load_lds_dwordx4 v134, s[98:99]
	s_waitcnt vmcnt(8)
	s_waitcnt lgkmcnt(0)
	s_barrier
	s_setprio 1
	s_waitcnt lgkmcnt(0)
	v_mfma_f32_16x16x32_bf16 v[122:125], v[156:159], v[194:197], v[122:125]
	v_mfma_f32_16x16x32_bf16 v[118:121], v[170:173], v[194:197], v[118:121]
	v_mfma_f32_16x16x32_bf16 v[110:113], v[156:159], v[202:205], v[110:113]
	v_mfma_f32_16x16x32_bf16 v[102:105], v[170:173], v[202:205], v[102:105]
	v_mfma_f32_16x16x32_bf16 v[94:97], v[156:159], v[210:213], v[94:97]
	v_mfma_f32_16x16x32_bf16 v[86:89], v[170:173], v[210:213], v[86:89]
	v_mfma_f32_16x16x32_bf16 v[78:81], v[156:159], v[218:221], v[78:81]
	v_mfma_f32_16x16x32_bf16 v[70:73], v[170:173], v[218:221], v[70:73]
	v_mfma_f32_16x16x32_bf16 v[122:125], v[166:169], v[198:201], v[122:125]
	v_mfma_f32_16x16x32_bf16 v[118:121], v[174:177], v[198:201], v[118:121]
	v_mfma_f32_16x16x32_bf16 v[110:113], v[166:169], v[206:209], v[110:113]
	v_mfma_f32_16x16x32_bf16 v[102:105], v[174:177], v[206:209], v[102:105]
	v_mfma_f32_16x16x32_bf16 v[94:97], v[166:169], v[214:217], v[94:97]
	v_mfma_f32_16x16x32_bf16 v[86:89], v[174:177], v[214:217], v[86:89]
	v_mfma_f32_16x16x32_bf16 v[78:81], v[166:169], v[222:225], v[78:81]
	v_mfma_f32_16x16x32_bf16 v[70:73], v[174:177], v[222:225], v[70:73]
	s_setprio 0
	s_setprio 1
	v_mfma_f32_16x16x32_bf16 v[126:129], v[178:181], v[194:197], v[126:129]
	v_mfma_f32_16x16x32_bf16 v[114:117], v[186:189], v[194:197], v[114:117]
	v_mfma_f32_16x16x32_bf16 v[106:109], v[178:181], v[202:205], v[106:109]
	v_mfma_f32_16x16x32_bf16 v[98:101], v[186:189], v[202:205], v[98:101]
	v_mfma_f32_16x16x32_bf16 v[90:93], v[178:181], v[210:213], v[90:93]
	v_mfma_f32_16x16x32_bf16 v[82:85], v[186:189], v[210:213], v[82:85]
	v_mfma_f32_16x16x32_bf16 v[74:77], v[178:181], v[218:221], v[74:77]
	v_mfma_f32_16x16x32_bf16 v[66:69], v[186:189], v[218:221], v[66:69]
	v_mfma_f32_16x16x32_bf16 v[126:129], v[182:185], v[198:201], v[126:129]
	v_mfma_f32_16x16x32_bf16 v[114:117], v[190:193], v[198:201], v[114:117]
	v_mfma_f32_16x16x32_bf16 v[106:109], v[182:185], v[206:209], v[106:109]
	v_mfma_f32_16x16x32_bf16 v[98:101], v[190:193], v[206:209], v[98:101]
	v_mfma_f32_16x16x32_bf16 v[90:93], v[182:185], v[214:217], v[90:93]
	v_mfma_f32_16x16x32_bf16 v[82:85], v[190:193], v[214:217], v[82:85]
	v_mfma_f32_16x16x32_bf16 v[74:77], v[182:185], v[222:225], v[74:77]
	v_mfma_f32_16x16x32_bf16 v[66:69], v[190:193], v[222:225], v[66:69]
	s_setprio 0
	s_barrier
	s_add_u32 s96, s96, 0x80
	s_addc_u32 s97, s97, 0
	s_add_u32 s98, s96, 0x40000
	s_addc_u32 s99, s97, 0
	s_add_u32 s94, s94, 0x80
	s_addc_u32 s95, s95, 0
	s_add_i32 s7, s7, s29
	s_mov_b32 m0, s7
	ds_read_b128 v[194:197], v163 offset:49152
	ds_read_b128 v[198:201], v163 offset:50176
	ds_read_b128 v[202:205], v163 offset:51200
	ds_read_b128 v[206:209], v163 offset:52224
	ds_read_b128 v[210:213], v163 offset:53248
	ds_read_b128 v[214:217], v163 offset:54272
	ds_read_b128 v[218:221], v163 offset:55296
	ds_read_b128 v[222:225], v163 offset:56320
	global_load_lds_dwordx4 v132, s[96:97]
	s_add_i32 m0, s7, 0x2000
	s_add_i32 s7, s49, s29
	global_load_lds_dwordx4 v136, s[96:97]
	s_mov_b32 m0, s7
	s_nop 0
	global_load_lds_dwordx4 v132, s[98:99]
	s_add_i32 m0, s7, 0x2000
	s_nop 0
	global_load_lds_dwordx4 v136, s[98:99]
	s_mov_b32 m0, s63
	s_nop 0
	global_load_lds_dwordx4 v130, s[94:95]
	s_mov_b32 m0, s64
	s_nop 0
	global_load_lds_dwordx4 v134, s[94:95]
	s_waitcnt vmcnt(8)
	s_waitcnt lgkmcnt(0)
	s_barrier
	s_setprio 1
	s_waitcnt lgkmcnt(0)
	v_mfma_f32_16x16x32_bf16 v[62:65], v[156:159], v[194:197], v[62:65]
	v_mfma_f32_16x16x32_bf16 v[54:57], v[170:173], v[194:197], v[54:57]
	v_mfma_f32_16x16x32_bf16 v[46:49], v[156:159], v[202:205], v[46:49]
	v_mfma_f32_16x16x32_bf16 v[38:41], v[170:173], v[202:205], v[38:41]
	v_mfma_f32_16x16x32_bf16 v[30:33], v[156:159], v[210:213], v[30:33]
	v_mfma_f32_16x16x32_bf16 v[22:25], v[170:173], v[210:213], v[22:25]
	v_mfma_f32_16x16x32_bf16 v[14:17], v[156:159], v[218:221], v[14:17]
	v_mfma_f32_16x16x32_bf16 v[6:9], v[170:173], v[218:221], v[6:9]
	v_mfma_f32_16x16x32_bf16 v[62:65], v[166:169], v[198:201], v[62:65]
	v_mfma_f32_16x16x32_bf16 v[54:57], v[174:177], v[198:201], v[54:57]
	v_mfma_f32_16x16x32_bf16 v[46:49], v[166:169], v[206:209], v[46:49]
	v_mfma_f32_16x16x32_bf16 v[38:41], v[174:177], v[206:209], v[38:41]
	v_mfma_f32_16x16x32_bf16 v[30:33], v[166:169], v[214:217], v[30:33]
	v_mfma_f32_16x16x32_bf16 v[22:25], v[174:177], v[214:217], v[22:25]
	v_mfma_f32_16x16x32_bf16 v[14:17], v[166:169], v[222:225], v[14:17]
	v_mfma_f32_16x16x32_bf16 v[6:9], v[174:177], v[222:225], v[6:9]
	s_setprio 0
	s_setprio 1
	v_mfma_f32_16x16x32_bf16 v[58:61], v[178:181], v[194:197], v[58:61]
	v_mfma_f32_16x16x32_bf16 v[50:53], v[186:189], v[194:197], v[50:53]
	v_mfma_f32_16x16x32_bf16 v[42:45], v[178:181], v[202:205], v[42:45]
	v_mfma_f32_16x16x32_bf16 v[34:37], v[186:189], v[202:205], v[34:37]
	v_mfma_f32_16x16x32_bf16 v[26:29], v[178:181], v[210:213], v[26:29]
	v_mfma_f32_16x16x32_bf16 v[18:21], v[186:189], v[210:213], v[18:21]
	v_mfma_f32_16x16x32_bf16 v[10:13], v[178:181], v[218:221], v[10:13]
	v_mfma_f32_16x16x32_bf16 v[2:5], v[186:189], v[218:221], v[2:5]
	v_mfma_f32_16x16x32_bf16 v[58:61], v[182:185], v[198:201], v[58:61]
	v_mfma_f32_16x16x32_bf16 v[50:53], v[190:193], v[198:201], v[50:53]
	v_mfma_f32_16x16x32_bf16 v[42:45], v[182:185], v[206:209], v[42:45]
	v_mfma_f32_16x16x32_bf16 v[34:37], v[190:193], v[206:209], v[34:37]
	v_mfma_f32_16x16x32_bf16 v[26:29], v[182:185], v[214:217], v[26:29]
	v_mfma_f32_16x16x32_bf16 v[18:21], v[190:193], v[214:217], v[18:21]
	v_mfma_f32_16x16x32_bf16 v[10:13], v[182:185], v[222:225], v[10:13]
	v_mfma_f32_16x16x32_bf16 v[2:5], v[190:193], v[222:225], v[2:5]
	s_setprio 0
	s_barrier
	v_cmp_ge_i32_e32 vcc, s47, v141
	s_mov_b32 s7, s47
	s_add_u32 s88, s88, 0x100
	s_addc_u32 s89, s89, 0
	s_add_u32 s86, s86, 0x100
	s_addc_u32 s87, s87, 0
	s_cbranch_vccz .LBB0_1573

.LBB0_1761:
	v_cmp_gt_i32_e32 vcc, 1, v138
	s_cbranch_vccnz .LBB0_1823
	v_lshl_add_u64 v[152:153], v[2:3], 0, s[14:15]
	v_add_u32_e32 v154, -2, v138
	s_waitcnt lgkmcnt(0)
	v_lshl_add_u64 v[150:151], v[4:5], 0, s[18:19]
	s_mov_b32 s5, 0
	s_nop 0
	v_readfirstlane_b32 s86, v152
	v_readfirstlane_b32 s87, v153
	v_readfirstlane_b32 s88, v150
	v_readfirstlane_b32 s89, v151
	v_readfirstlane_b32 s90, v146
	v_readfirstlane_b32 s91, v147
	v_readfirstlane_b32 s92, v148
	v_readfirstlane_b32 s93, v149
	v_readfirstlane_b32 s100, v154
	s_add_u32 s98, s86, 0xfffc0080
	s_addc_u32 s99, s87, -1
	s_cmp_eq_u32 s5, s100
	s_cselect_b64 s[94:95], s[90:91], s[98:99]
	s_cselect_b64 s[96:97], s[92:93], s[88:89]
	v_add_u32_e32 v155, s74, v141
	ds_read_b128 v[164:167], v155
	ds_read_b128 v[168:171], v155 offset:1024
	ds_read_b128 v[172:175], v155 offset:2048
	ds_read_b128 v[176:179], v155 offset:3072
	v_add_u32_e32 v155, s75, v141
	ds_read_b128 v[180:183], v155
	ds_read_b128 v[184:187], v155 offset:1024
	ds_read_b128 v[188:191], v155 offset:2048
	ds_read_b128 v[192:195], v155 offset:3072
	s_add_i32 s29, s5, 2
	s_nop 0
	s_add_i32 m0, s47, 0xc000
	ds_read_b128 v[196:199], v160
	ds_read_b128 v[200:203], v160 offset:1024
	ds_read_b128 v[204:207], v160 offset:2048
	ds_read_b128 v[208:211], v160 offset:3072
	ds_read_b128 v[212:215], v160 offset:4096
	ds_read_b128 v[216:219], v160 offset:5120
	ds_read_b128 v[220:223], v160 offset:6144
	ds_read_b128 v[224:227], v160 offset:7168
	global_load_lds_dwordx4 v144, s[86:87]
	s_add_i32 m0, s47, 0xe000
	s_nop 0
	global_load_lds_dwordx4 v142, s[86:87]
	s_waitcnt vmcnt(8)
	s_waitcnt lgkmcnt(0)
	s_barrier
	s_setprio 1
	s_waitcnt lgkmcnt(0)
	v_mfma_f32_16x16x32_bf16 v[122:125], v[164:167], v[196:199], 0
	v_mfma_f32_16x16x32_bf16 v[118:121], v[172:175], v[196:199], 0
	v_mfma_f32_16x16x32_bf16 v[110:113], v[164:167], v[204:207], 0
	v_mfma_f32_16x16x32_bf16 v[102:105], v[172:175], v[204:207], 0
	v_mfma_f32_16x16x32_bf16 v[94:97], v[164:167], v[212:215], 0
	v_mfma_f32_16x16x32_bf16 v[86:89], v[172:175], v[212:215], 0
	v_mfma_f32_16x16x32_bf16 v[78:81], v[164:167], v[220:223], 0
	v_mfma_f32_16x16x32_bf16 v[70:73], v[172:175], v[220:223], 0
	v_mfma_f32_16x16x32_bf16 v[122:125], v[168:171], v[200:203], v[122:125]
	v_mfma_f32_16x16x32_bf16 v[118:121], v[176:179], v[200:203], v[118:121]
	v_mfma_f32_16x16x32_bf16 v[110:113], v[168:171], v[208:211], v[110:113]
	v_mfma_f32_16x16x32_bf16 v[102:105], v[176:179], v[208:211], v[102:105]
	v_mfma_f32_16x16x32_bf16 v[94:97], v[168:171], v[216:219], v[94:97]
	v_mfma_f32_16x16x32_bf16 v[86:89], v[176:179], v[216:219], v[86:89]
	v_mfma_f32_16x16x32_bf16 v[78:81], v[168:171], v[224:227], v[78:81]
	v_mfma_f32_16x16x32_bf16 v[70:73], v[176:179], v[224:227], v[70:73]
	s_setprio 0
	s_setprio 1
	v_mfma_f32_16x16x32_bf16 v[126:129], v[180:183], v[196:199], 0
	v_mfma_f32_16x16x32_bf16 v[114:117], v[188:191], v[196:199], 0
	v_mfma_f32_16x16x32_bf16 v[106:109], v[180:183], v[204:207], 0
	v_mfma_f32_16x16x32_bf16 v[98:101], v[188:191], v[204:207], 0
	v_mfma_f32_16x16x32_bf16 v[90:93], v[180:183], v[212:215], 0
	v_mfma_f32_16x16x32_bf16 v[82:85], v[188:191], v[212:215], 0
	v_mfma_f32_16x16x32_bf16 v[74:77], v[180:183], v[220:223], 0
	v_mfma_f32_16x16x32_bf16 v[66:69], v[188:191], v[220:223], 0
	v_mfma_f32_16x16x32_bf16 v[126:129], v[184:187], v[200:203], v[126:129]
	v_mfma_f32_16x16x32_bf16 v[114:117], v[192:195], v[200:203], v[114:117]
	v_mfma_f32_16x16x32_bf16 v[106:109], v[184:187], v[208:211], v[106:109]
	v_mfma_f32_16x16x32_bf16 v[98:101], v[192:195], v[208:211], v[98:101]
	v_mfma_f32_16x16x32_bf16 v[90:93], v[184:187], v[216:219], v[90:93]
	v_mfma_f32_16x16x32_bf16 v[82:85], v[192:195], v[216:219], v[82:85]
	v_mfma_f32_16x16x32_bf16 v[74:77], v[184:187], v[224:227], v[74:77]
	v_mfma_f32_16x16x32_bf16 v[66:69], v[192:195], v[224:227], v[66:69]
	s_setprio 0
	s_barrier
	s_add_u32 s98, s96, 0x40000
	s_addc_u32 s99, s97, 0
	s_add_i32 s5, s74, s23
	s_mov_b32 m0, s5
	ds_read_b128 v[196:199], v160 offset:16384
	ds_read_b128 v[200:203], v160 offset:17408
	ds_read_b128 v[204:207], v160 offset:18432
	ds_read_b128 v[208:211], v160 offset:19456
	ds_read_b128 v[212:215], v160 offset:20480
	ds_read_b128 v[216:219], v160 offset:21504
	ds_read_b128 v[220:223], v160 offset:22528
	ds_read_b128 v[224:227], v160 offset:23552
	global_load_lds_dwordx4 v132, s[96:97]
	s_add_i32 m0, s5, 0x2000
	s_add_i32 s5, s75, s23
	global_load_lds_dwordx4 v136, s[96:97]
	s_mov_b32 m0, s5
	s_nop 0
	global_load_lds_dwordx4 v132, s[98:99]
	s_add_i32 m0, s5, 0x2000
	s_nop 0
	global_load_lds_dwordx4 v136, s[98:99]
	s_mov_b32 m0, s47
	s_nop 0
	global_load_lds_dwordx4 v130, s[94:95]
	s_mov_b32 m0, s56
	s_nop 0
	global_load_lds_dwordx4 v134, s[94:95]
	s_waitcnt vmcnt(8)
	s_waitcnt lgkmcnt(0)
	s_barrier
	s_setprio 1
	s_waitcnt lgkmcnt(0)
	v_mfma_f32_16x16x32_bf16 v[62:65], v[164:167], v[196:199], 0
	v_mfma_f32_16x16x32_bf16 v[54:57], v[172:175], v[196:199], 0
	v_mfma_f32_16x16x32_bf16 v[46:49], v[164:167], v[204:207], 0
	v_mfma_f32_16x16x32_bf16 v[38:41], v[172:175], v[204:207], 0
	v_mfma_f32_16x16x32_bf16 v[30:33], v[164:167], v[212:215], 0
	v_mfma_f32_16x16x32_bf16 v[22:25], v[172:175], v[212:215], 0
	v_mfma_f32_16x16x32_bf16 v[14:17], v[164:167], v[220:223], 0
	v_mfma_f32_16x16x32_bf16 v[6:9], v[172:175], v[220:223], 0
	v_mfma_f32_16x16x32_bf16 v[62:65], v[168:171], v[200:203], v[62:65]
	v_mfma_f32_16x16x32_bf16 v[54:57], v[176:179], v[200:203], v[54:57]
	v_mfma_f32_16x16x32_bf16 v[46:49], v[168:171], v[208:211], v[46:49]
	v_mfma_f32_16x16x32_bf16 v[38:41], v[176:179], v[208:211], v[38:41]
	v_mfma_f32_16x16x32_bf16 v[30:33], v[168:171], v[216:219], v[30:33]
	v_mfma_f32_16x16x32_bf16 v[22:25], v[176:179], v[216:219], v[22:25]
	v_mfma_f32_16x16x32_bf16 v[14:17], v[168:171], v[224:227], v[14:17]
	v_mfma_f32_16x16x32_bf16 v[6:9], v[176:179], v[224:227], v[6:9]
	s_setprio 0
	s_setprio 1
	v_mfma_f32_16x16x32_bf16 v[58:61], v[180:183], v[196:199], 0
	v_mfma_f32_16x16x32_bf16 v[50:53], v[188:191], v[196:199], 0
	v_mfma_f32_16x16x32_bf16 v[42:45], v[180:183], v[204:207], 0
	v_mfma_f32_16x16x32_bf16 v[34:37], v[188:191], v[204:207], 0
	v_mfma_f32_16x16x32_bf16 v[26:29], v[180:183], v[212:215], 0
	v_mfma_f32_16x16x32_bf16 v[18:21], v[188:191], v[212:215], 0
	v_mfma_f32_16x16x32_bf16 v[10:13], v[180:183], v[220:223], 0
	v_mfma_f32_16x16x32_bf16 v[2:5], v[188:191], v[220:223], 0
	v_mfma_f32_16x16x32_bf16 v[58:61], v[184:187], v[200:203], v[58:61]
	v_mfma_f32_16x16x32_bf16 v[50:53], v[192:195], v[200:203], v[50:53]
	v_mfma_f32_16x16x32_bf16 v[42:45], v[184:187], v[208:211], v[42:45]
	v_mfma_f32_16x16x32_bf16 v[34:37], v[192:195], v[208:211], v[34:37]
	v_mfma_f32_16x16x32_bf16 v[26:29], v[184:187], v[216:219], v[26:29]
	v_mfma_f32_16x16x32_bf16 v[18:21], v[192:195], v[216:219], v[18:21]
	v_mfma_f32_16x16x32_bf16 v[10:13], v[184:187], v[224:227], v[10:13]
	v_mfma_f32_16x16x32_bf16 v[2:5], v[192:195], v[224:227], v[2:5]
	s_setprio 0
	s_barrier
	s_add_u32 s98, s94, 0x40000
	s_addc_u32 s99, s95, 0
	s_add_i32 s5, 0, 0x18000
	v_add_u32_e32 v155, s5, v141
	s_add_i32 s45, 0, 0x1c000
	ds_read_b128 v[164:167], v155
	ds_read_b128 v[168:171], v155 offset:1024
	ds_read_b128 v[172:175], v155 offset:2048
	ds_read_b128 v[176:179], v155 offset:3072
	v_add_u32_e32 v155, s45, v141
	ds_read_b128 v[180:183], v155
	ds_read_b128 v[184:187], v155 offset:1024
	ds_read_b128 v[188:191], v155 offset:2048
	ds_read_b128 v[192:195], v155 offset:3072
	s_mov_b32 m0, s57
	ds_read_b128 v[196:199], v160 offset:32768
	ds_read_b128 v[200:203], v160 offset:33792
	ds_read_b128 v[204:207], v160 offset:34816
	ds_read_b128 v[208:211], v160 offset:35840
	ds_read_b128 v[212:215], v160 offset:36864
	ds_read_b128 v[216:219], v160 offset:37888
	ds_read_b128 v[220:223], v160 offset:38912
	ds_read_b128 v[224:227], v160 offset:39936
	global_load_lds_dwordx4 v130, s[98:99]
	s_mov_b32 m0, s58
	s_nop 0
	global_load_lds_dwordx4 v134, s[98:99]
	s_waitcnt vmcnt(8)
	s_waitcnt lgkmcnt(0)
	s_barrier
	s_setprio 1
	s_waitcnt lgkmcnt(0)
	v_mfma_f32_16x16x32_bf16 v[122:125], v[164:167], v[196:199], v[122:125]
	v_mfma_f32_16x16x32_bf16 v[118:121], v[172:175], v[196:199], v[118:121]
	v_mfma_f32_16x16x32_bf16 v[110:113], v[164:167], v[204:207], v[110:113]
	v_mfma_f32_16x16x32_bf16 v[102:105], v[172:175], v[204:207], v[102:105]
	v_mfma_f32_16x16x32_bf16 v[94:97], v[164:167], v[212:215], v[94:97]
	v_mfma_f32_16x16x32_bf16 v[86:89], v[172:175], v[212:215], v[86:89]
	v_mfma_f32_16x16x32_bf16 v[78:81], v[164:167], v[220:223], v[78:81]
	v_mfma_f32_16x16x32_bf16 v[70:73], v[172:175], v[220:223], v[70:73]
	v_mfma_f32_16x16x32_bf16 v[122:125], v[168:171], v[200:203], v[122:125]
	v_mfma_f32_16x16x32_bf16 v[118:121], v[176:179], v[200:203], v[118:121]
	v_mfma_f32_16x16x32_bf16 v[110:113], v[168:171], v[208:211], v[110:113]
	v_mfma_f32_16x16x32_bf16 v[102:105], v[176:179], v[208:211], v[102:105]
	v_mfma_f32_16x16x32_bf16 v[94:97], v[168:171], v[216:219], v[94:97]
	v_mfma_f32_16x16x32_bf16 v[86:89], v[176:179], v[216:219], v[86:89]
	v_mfma_f32_16x16x32_bf16 v[78:81], v[168:171], v[224:227], v[78:81]
	v_mfma_f32_16x16x32_bf16 v[70:73], v[176:179], v[224:227], v[70:73]
	s_setprio 0
	s_setprio 1
	v_mfma_f32_16x16x32_bf16 v[126:129], v[180:183], v[196:199], v[126:129]
	v_mfma_f32_16x16x32_bf16 v[114:117], v[188:191], v[196:199], v[114:117]
	v_mfma_f32_16x16x32_bf16 v[106:109], v[180:183], v[204:207], v[106:109]
	v_mfma_f32_16x16x32_bf16 v[98:101], v[188:191], v[204:207], v[98:101]
	v_mfma_f32_16x16x32_bf16 v[90:93], v[180:183], v[212:215], v[90:93]
	v_mfma_f32_16x16x32_bf16 v[82:85], v[188:191], v[212:215], v[82:85]
	v_mfma_f32_16x16x32_bf16 v[74:77], v[180:183], v[220:223], v[74:77]
	v_mfma_f32_16x16x32_bf16 v[66:69], v[188:191], v[220:223], v[66:69]
	v_mfma_f32_16x16x32_bf16 v[126:129], v[184:187], v[200:203], v[126:129]
	v_mfma_f32_16x16x32_bf16 v[114:117], v[192:195], v[200:203], v[114:117]
	v_mfma_f32_16x16x32_bf16 v[106:109], v[184:187], v[208:211], v[106:109]
	v_mfma_f32_16x16x32_bf16 v[98:101], v[192:195], v[208:211], v[98:101]
	v_mfma_f32_16x16x32_bf16 v[90:93], v[184:187], v[216:219], v[90:93]
	v_mfma_f32_16x16x32_bf16 v[82:85], v[192:195], v[216:219], v[82:85]
	v_mfma_f32_16x16x32_bf16 v[74:77], v[184:187], v[224:227], v[74:77]
	v_mfma_f32_16x16x32_bf16 v[66:69], v[192:195], v[224:227], v[66:69]
	s_setprio 0
	s_barrier
	s_add_u32 s96, s96, 0x80
	s_addc_u32 s97, s97, 0
	s_add_u32 s98, s96, 0x40000
	s_addc_u32 s99, s97, 0
	s_add_u32 s94, s94, 0x80
	s_addc_u32 s95, s95, 0
	s_add_i32 s5, s5, s23
	s_mov_b32 m0, s5
	ds_read_b128 v[196:199], v160 offset:49152
	ds_read_b128 v[200:203], v160 offset:50176
	ds_read_b128 v[204:207], v160 offset:51200
	ds_read_b128 v[208:211], v160 offset:52224
	ds_read_b128 v[212:215], v160 offset:53248
	ds_read_b128 v[216:219], v160 offset:54272
	ds_read_b128 v[220:223], v160 offset:55296
	ds_read_b128 v[224:227], v160 offset:56320
	global_load_lds_dwordx4 v132, s[96:97]
	s_add_i32 m0, s5, 0x2000
	s_add_i32 s5, s45, s23
	global_load_lds_dwordx4 v136, s[96:97]
	s_mov_b32 m0, s5
	s_nop 0
	global_load_lds_dwordx4 v132, s[98:99]
	s_add_i32 m0, s5, 0x2000
	s_nop 0
	global_load_lds_dwordx4 v136, s[98:99]
	s_mov_b32 m0, s64
	s_nop 0
	global_load_lds_dwordx4 v130, s[94:95]
	s_mov_b32 m0, s65
	s_nop 0
	global_load_lds_dwordx4 v134, s[94:95]
	s_waitcnt vmcnt(8)
	s_waitcnt lgkmcnt(0)
	s_barrier
	s_setprio 1
	s_waitcnt lgkmcnt(0)
	v_mfma_f32_16x16x32_bf16 v[62:65], v[164:167], v[196:199], v[62:65]
	v_mfma_f32_16x16x32_bf16 v[54:57], v[172:175], v[196:199], v[54:57]
	v_mfma_f32_16x16x32_bf16 v[46:49], v[164:167], v[204:207], v[46:49]
	v_mfma_f32_16x16x32_bf16 v[38:41], v[172:175], v[204:207], v[38:41]
	v_mfma_f32_16x16x32_bf16 v[30:33], v[164:167], v[212:215], v[30:33]
	v_mfma_f32_16x16x32_bf16 v[22:25], v[172:175], v[212:215], v[22:25]
	v_mfma_f32_16x16x32_bf16 v[14:17], v[164:167], v[220:223], v[14:17]
	v_mfma_f32_16x16x32_bf16 v[6:9], v[172:175], v[220:223], v[6:9]
	v_mfma_f32_16x16x32_bf16 v[62:65], v[168:171], v[200:203], v[62:65]
	v_mfma_f32_16x16x32_bf16 v[54:57], v[176:179], v[200:203], v[54:57]
	v_mfma_f32_16x16x32_bf16 v[46:49], v[168:171], v[208:211], v[46:49]
	v_mfma_f32_16x16x32_bf16 v[38:41], v[176:179], v[208:211], v[38:41]
	v_mfma_f32_16x16x32_bf16 v[30:33], v[168:171], v[216:219], v[30:33]
	v_mfma_f32_16x16x32_bf16 v[22:25], v[176:179], v[216:219], v[22:25]
	v_mfma_f32_16x16x32_bf16 v[14:17], v[168:171], v[224:227], v[14:17]
	v_mfma_f32_16x16x32_bf16 v[6:9], v[176:179], v[224:227], v[6:9]
	s_setprio 0
	s_setprio 1
	v_mfma_f32_16x16x32_bf16 v[58:61], v[180:183], v[196:199], v[58:61]
	v_mfma_f32_16x16x32_bf16 v[50:53], v[188:191], v[196:199], v[50:53]
	v_mfma_f32_16x16x32_bf16 v[42:45], v[180:183], v[204:207], v[42:45]
	v_mfma_f32_16x16x32_bf16 v[34:37], v[188:191], v[204:207], v[34:37]
	v_mfma_f32_16x16x32_bf16 v[26:29], v[180:183], v[212:215], v[26:29]
	v_mfma_f32_16x16x32_bf16 v[18:21], v[188:191], v[212:215], v[18:21]
	v_mfma_f32_16x16x32_bf16 v[10:13], v[180:183], v[220:223], v[10:13]
	v_mfma_f32_16x16x32_bf16 v[2:5], v[188:191], v[220:223], v[2:5]
	v_mfma_f32_16x16x32_bf16 v[58:61], v[184:187], v[200:203], v[58:61]
	v_mfma_f32_16x16x32_bf16 v[50:53], v[192:195], v[200:203], v[50:53]
	v_mfma_f32_16x16x32_bf16 v[42:45], v[184:187], v[208:211], v[42:45]
	v_mfma_f32_16x16x32_bf16 v[34:37], v[192:195], v[208:211], v[34:37]
	v_mfma_f32_16x16x32_bf16 v[26:29], v[184:187], v[216:219], v[26:29]
	v_mfma_f32_16x16x32_bf16 v[18:21], v[192:195], v[216:219], v[18:21]
	v_mfma_f32_16x16x32_bf16 v[10:13], v[184:187], v[224:227], v[10:13]
	v_mfma_f32_16x16x32_bf16 v[2:5], v[192:195], v[224:227], v[2:5]
	s_setprio 0
	s_barrier
	v_cmp_ge_i32_e32 vcc, s29, v138
	s_mov_b32 s5, s29
	s_add_u32 s88, s88, 0x100
	s_addc_u32 s89, s89, 0
	s_add_u32 s86, s86, 0x100
	s_addc_u32 s87, s87, 0
	s_cbranch_vccnz .Lmy_kexit_9
.LBB0_1763:
	s_add_u32 s98, s86, 0xfffc0080
	s_addc_u32 s99, s87, -1
	s_cmp_eq_u32 s5, s100
	s_cselect_b64 s[94:95], s[90:91], s[98:99]
	s_cselect_b64 s[96:97], s[92:93], s[88:89]
	v_add_u32_e32 v155, s74, v141
	ds_read_b128 v[164:167], v155
	ds_read_b128 v[168:171], v155 offset:1024
	ds_read_b128 v[172:175], v155 offset:2048
	ds_read_b128 v[176:179], v155 offset:3072
	v_add_u32_e32 v155, s75, v141
	ds_read_b128 v[180:183], v155
	ds_read_b128 v[184:187], v155 offset:1024
	ds_read_b128 v[188:191], v155 offset:2048
	ds_read_b128 v[192:195], v155 offset:3072
	s_add_i32 s29, s5, 2
	s_nop 0
	s_add_i32 m0, s47, 0xc000
	ds_read_b128 v[196:199], v160
	ds_read_b128 v[200:203], v160 offset:1024
	ds_read_b128 v[204:207], v160 offset:2048
	ds_read_b128 v[208:211], v160 offset:3072
	ds_read_b128 v[212:215], v160 offset:4096
	ds_read_b128 v[216:219], v160 offset:5120
	ds_read_b128 v[220:223], v160 offset:6144
	ds_read_b128 v[224:227], v160 offset:7168
	global_load_lds_dwordx4 v144, s[86:87]
	s_add_i32 m0, s47, 0xe000
	s_nop 0
	global_load_lds_dwordx4 v142, s[86:87]
	s_waitcnt vmcnt(8)
	s_waitcnt lgkmcnt(0)
	s_barrier
	s_setprio 1
	s_waitcnt lgkmcnt(0)
	v_mfma_f32_16x16x32_bf16 v[122:125], v[164:167], v[196:199], v[122:125]
	v_mfma_f32_16x16x32_bf16 v[118:121], v[172:175], v[196:199], v[118:121]
	v_mfma_f32_16x16x32_bf16 v[110:113], v[164:167], v[204:207], v[110:113]
	v_mfma_f32_16x16x32_bf16 v[102:105], v[172:175], v[204:207], v[102:105]
	v_mfma_f32_16x16x32_bf16 v[94:97], v[164:167], v[212:215], v[94:97]
	v_mfma_f32_16x16x32_bf16 v[86:89], v[172:175], v[212:215], v[86:89]
	v_mfma_f32_16x16x32_bf16 v[78:81], v[164:167], v[220:223], v[78:81]
	v_mfma_f32_16x16x32_bf16 v[70:73], v[172:175], v[220:223], v[70:73]
	v_mfma_f32_16x16x32_bf16 v[122:125], v[168:171], v[200:203], v[122:125]
	v_mfma_f32_16x16x32_bf16 v[118:121], v[176:179], v[200:203], v[118:121]
	v_mfma_f32_16x16x32_bf16 v[110:113], v[168:171], v[208:211], v[110:113]
	v_mfma_f32_16x16x32_bf16 v[102:105], v[176:179], v[208:211], v[102:105]
	v_mfma_f32_16x16x32_bf16 v[94:97], v[168:171], v[216:219], v[94:97]
	v_mfma_f32_16x16x32_bf16 v[86:89], v[176:179], v[216:219], v[86:89]
	v_mfma_f32_16x16x32_bf16 v[78:81], v[168:171], v[224:227], v[78:81]
	v_mfma_f32_16x16x32_bf16 v[70:73], v[176:179], v[224:227], v[70:73]
	s_setprio 0
	s_setprio 1
	v_mfma_f32_16x16x32_bf16 v[126:129], v[180:183], v[196:199], v[126:129]
	v_mfma_f32_16x16x32_bf16 v[114:117], v[188:191], v[196:199], v[114:117]
	v_mfma_f32_16x16x32_bf16 v[106:109], v[180:183], v[204:207], v[106:109]
	v_mfma_f32_16x16x32_bf16 v[98:101], v[188:191], v[204:207], v[98:101]
	v_mfma_f32_16x16x32_bf16 v[90:93], v[180:183], v[212:215], v[90:93]
	v_mfma_f32_16x16x32_bf16 v[82:85], v[188:191], v[212:215], v[82:85]
	v_mfma_f32_16x16x32_bf16 v[74:77], v[180:183], v[220:223], v[74:77]
	v_mfma_f32_16x16x32_bf16 v[66:69], v[188:191], v[220:223], v[66:69]
	v_mfma_f32_16x16x32_bf16 v[126:129], v[184:187], v[200:203], v[126:129]
	v_mfma_f32_16x16x32_bf16 v[114:117], v[192:195], v[200:203], v[114:117]
	v_mfma_f32_16x16x32_bf16 v[106:109], v[184:187], v[208:211], v[106:109]
	v_mfma_f32_16x16x32_bf16 v[98:101], v[192:195], v[208:211], v[98:101]
	v_mfma_f32_16x16x32_bf16 v[90:93], v[184:187], v[216:219], v[90:93]
	v_mfma_f32_16x16x32_bf16 v[82:85], v[192:195], v[216:219], v[82:85]
	v_mfma_f32_16x16x32_bf16 v[74:77], v[184:187], v[224:227], v[74:77]
	v_mfma_f32_16x16x32_bf16 v[66:69], v[192:195], v[224:227], v[66:69]
	s_setprio 0
	s_barrier
	s_add_u32 s98, s96, 0x40000
	s_addc_u32 s99, s97, 0
	s_add_i32 s5, s74, s23
	s_mov_b32 m0, s5
	ds_read_b128 v[196:199], v160 offset:16384
	ds_read_b128 v[200:203], v160 offset:17408
	ds_read_b128 v[204:207], v160 offset:18432
	ds_read_b128 v[208:211], v160 offset:19456
	ds_read_b128 v[212:215], v160 offset:20480
	ds_read_b128 v[216:219], v160 offset:21504
	ds_read_b128 v[220:223], v160 offset:22528
	ds_read_b128 v[224:227], v160 offset:23552
	global_load_lds_dwordx4 v132, s[96:97]
	s_add_i32 m0, s5, 0x2000
	s_add_i32 s5, s75, s23
	global_load_lds_dwordx4 v136, s[96:97]
	s_mov_b32 m0, s5
	s_nop 0
	global_load_lds_dwordx4 v132, s[98:99]
	s_add_i32 m0, s5, 0x2000
	s_nop 0
	global_load_lds_dwordx4 v136, s[98:99]
	s_mov_b32 m0, s47
	s_nop 0
	global_load_lds_dwordx4 v130, s[94:95]
	s_mov_b32 m0, s56
	s_nop 0
	global_load_lds_dwordx4 v134, s[94:95]
	s_waitcnt vmcnt(8)
	s_waitcnt lgkmcnt(0)
	s_barrier
	s_setprio 1
	s_waitcnt lgkmcnt(0)
	v_mfma_f32_16x16x32_bf16 v[62:65], v[164:167], v[196:199], v[62:65]
	v_mfma_f32_16x16x32_bf16 v[54:57], v[172:175], v[196:199], v[54:57]
	v_mfma_f32_16x16x32_bf16 v[46:49], v[164:167], v[204:207], v[46:49]
	v_mfma_f32_16x16x32_bf16 v[38:41], v[172:175], v[204:207], v[38:41]
	v_mfma_f32_16x16x32_bf16 v[30:33], v[164:167], v[212:215], v[30:33]
	v_mfma_f32_16x16x32_bf16 v[22:25], v[172:175], v[212:215], v[22:25]
	v_mfma_f32_16x16x32_bf16 v[14:17], v[164:167], v[220:223], v[14:17]
	v_mfma_f32_16x16x32_bf16 v[6:9], v[172:175], v[220:223], v[6:9]
	v_mfma_f32_16x16x32_bf16 v[62:65], v[168:171], v[200:203], v[62:65]
	v_mfma_f32_16x16x32_bf16 v[54:57], v[176:179], v[200:203], v[54:57]
	v_mfma_f32_16x16x32_bf16 v[46:49], v[168:171], v[208:211], v[46:49]
	v_mfma_f32_16x16x32_bf16 v[38:41], v[176:179], v[208:211], v[38:41]
	v_mfma_f32_16x16x32_bf16 v[30:33], v[168:171], v[216:219], v[30:33]
	v_mfma_f32_16x16x32_bf16 v[22:25], v[176:179], v[216:219], v[22:25]
	v_mfma_f32_16x16x32_bf16 v[14:17], v[168:171], v[224:227], v[14:17]
	v_mfma_f32_16x16x32_bf16 v[6:9], v[176:179], v[224:227], v[6:9]
	s_setprio 0
	s_setprio 1
	v_mfma_f32_16x16x32_bf16 v[58:61], v[180:183], v[196:199], v[58:61]
	v_mfma_f32_16x16x32_bf16 v[50:53], v[188:191], v[196:199], v[50:53]
	v_mfma_f32_16x16x32_bf16 v[42:45], v[180:183], v[204:207], v[42:45]
	v_mfma_f32_16x16x32_bf16 v[34:37], v[188:191], v[204:207], v[34:37]
	v_mfma_f32_16x16x32_bf16 v[26:29], v[180:183], v[212:215], v[26:29]
	v_mfma_f32_16x16x32_bf16 v[18:21], v[188:191], v[212:215], v[18:21]
	v_mfma_f32_16x16x32_bf16 v[10:13], v[180:183], v[220:223], v[10:13]
	v_mfma_f32_16x16x32_bf16 v[2:5], v[188:191], v[220:223], v[2:5]
	v_mfma_f32_16x16x32_bf16 v[58:61], v[184:187], v[200:203], v[58:61]
	v_mfma_f32_16x16x32_bf16 v[50:53], v[192:195], v[200:203], v[50:53]
	v_mfma_f32_16x16x32_bf16 v[42:45], v[184:187], v[208:211], v[42:45]
	v_mfma_f32_16x16x32_bf16 v[34:37], v[192:195], v[208:211], v[34:37]
	v_mfma_f32_16x16x32_bf16 v[26:29], v[184:187], v[216:219], v[26:29]
	v_mfma_f32_16x16x32_bf16 v[18:21], v[192:195], v[216:219], v[18:21]
	v_mfma_f32_16x16x32_bf16 v[10:13], v[184:187], v[224:227], v[10:13]
	v_mfma_f32_16x16x32_bf16 v[2:5], v[192:195], v[224:227], v[2:5]
	s_setprio 0
	s_barrier
	s_add_u32 s98, s94, 0x40000
	s_addc_u32 s99, s95, 0
	s_add_i32 s5, 0, 0x18000
	v_add_u32_e32 v155, s5, v141
	s_add_i32 s45, 0, 0x1c000
	ds_read_b128 v[164:167], v155
	ds_read_b128 v[168:171], v155 offset:1024
	ds_read_b128 v[172:175], v155 offset:2048
	ds_read_b128 v[176:179], v155 offset:3072
	v_add_u32_e32 v155, s45, v141
	ds_read_b128 v[180:183], v155
	ds_read_b128 v[184:187], v155 offset:1024
	ds_read_b128 v[188:191], v155 offset:2048
	ds_read_b128 v[192:195], v155 offset:3072
	s_mov_b32 m0, s57
	ds_read_b128 v[196:199], v160 offset:32768
	ds_read_b128 v[200:203], v160 offset:33792
	ds_read_b128 v[204:207], v160 offset:34816
	ds_read_b128 v[208:211], v160 offset:35840
	ds_read_b128 v[212:215], v160 offset:36864
	ds_read_b128 v[216:219], v160 offset:37888
	ds_read_b128 v[220:223], v160 offset:38912
	ds_read_b128 v[224:227], v160 offset:39936
	global_load_lds_dwordx4 v130, s[98:99]
	s_mov_b32 m0, s58
	s_nop 0
	global_load_lds_dwordx4 v134, s[98:99]
	s_waitcnt vmcnt(8)
	s_waitcnt lgkmcnt(0)
	s_barrier
	s_setprio 1
	s_waitcnt lgkmcnt(0)
	v_mfma_f32_16x16x32_bf16 v[122:125], v[164:167], v[196:199], v[122:125]
	v_mfma_f32_16x16x32_bf16 v[118:121], v[172:175], v[196:199], v[118:121]
	v_mfma_f32_16x16x32_bf16 v[110:113], v[164:167], v[204:207], v[110:113]
	v_mfma_f32_16x16x32_bf16 v[102:105], v[172:175], v[204:207], v[102:105]
	v_mfma_f32_16x16x32_bf16 v[94:97], v[164:167], v[212:215], v[94:97]
	v_mfma_f32_16x16x32_bf16 v[86:89], v[172:175], v[212:215], v[86:89]
	v_mfma_f32_16x16x32_bf16 v[78:81], v[164:167], v[220:223], v[78:81]
	v_mfma_f32_16x16x32_bf16 v[70:73], v[172:175], v[220:223], v[70:73]
	v_mfma_f32_16x16x32_bf16 v[122:125], v[168:171], v[200:203], v[122:125]
	v_mfma_f32_16x16x32_bf16 v[118:121], v[176:179], v[200:203], v[118:121]
	v_mfma_f32_16x16x32_bf16 v[110:113], v[168:171], v[208:211], v[110:113]
	v_mfma_f32_16x16x32_bf16 v[102:105], v[176:179], v[208:211], v[102:105]
	v_mfma_f32_16x16x32_bf16 v[94:97], v[168:171], v[216:219], v[94:97]
	v_mfma_f32_16x16x32_bf16 v[86:89], v[176:179], v[216:219], v[86:89]
	v_mfma_f32_16x16x32_bf16 v[78:81], v[168:171], v[224:227], v[78:81]
	v_mfma_f32_16x16x32_bf16 v[70:73], v[176:179], v[224:227], v[70:73]
	s_setprio 0
	s_setprio 1
	v_mfma_f32_16x16x32_bf16 v[126:129], v[180:183], v[196:199], v[126:129]
	v_mfma_f32_16x16x32_bf16 v[114:117], v[188:191], v[196:199], v[114:117]
	v_mfma_f32_16x16x32_bf16 v[106:109], v[180:183], v[204:207], v[106:109]
	v_mfma_f32_16x16x32_bf16 v[98:101], v[188:191], v[204:207], v[98:101]
	v_mfma_f32_16x16x32_bf16 v[90:93], v[180:183], v[212:215], v[90:93]
	v_mfma_f32_16x16x32_bf16 v[82:85], v[188:191], v[212:215], v[82:85]
	v_mfma_f32_16x16x32_bf16 v[74:77], v[180:183], v[220:223], v[74:77]
	v_mfma_f32_16x16x32_bf16 v[66:69], v[188:191], v[220:223], v[66:69]
	v_mfma_f32_16x16x32_bf16 v[126:129], v[184:187], v[200:203], v[126:129]
	v_mfma_f32_16x16x32_bf16 v[114:117], v[192:195], v[200:203], v[114:117]
	v_mfma_f32_16x16x32_bf16 v[106:109], v[184:187], v[208:211], v[106:109]
	v_mfma_f32_16x16x32_bf16 v[98:101], v[192:195], v[208:211], v[98:101]
	v_mfma_f32_16x16x32_bf16 v[90:93], v[184:187], v[216:219], v[90:93]
	v_mfma_f32_16x16x32_bf16 v[82:85], v[192:195], v[216:219], v[82:85]
	v_mfma_f32_16x16x32_bf16 v[74:77], v[184:187], v[224:227], v[74:77]
	v_mfma_f32_16x16x32_bf16 v[66:69], v[192:195], v[224:227], v[66:69]
	s_setprio 0
	s_barrier
	s_add_u32 s96, s96, 0x80
	s_addc_u32 s97, s97, 0
	s_add_u32 s98, s96, 0x40000
	s_addc_u32 s99, s97, 0
	s_add_u32 s94, s94, 0x80
	s_addc_u32 s95, s95, 0
	s_add_i32 s5, s5, s23
	s_mov_b32 m0, s5
	ds_read_b128 v[196:199], v160 offset:49152
	ds_read_b128 v[200:203], v160 offset:50176
	ds_read_b128 v[204:207], v160 offset:51200
	ds_read_b128 v[208:211], v160 offset:52224
	ds_read_b128 v[212:215], v160 offset:53248
	ds_read_b128 v[216:219], v160 offset:54272
	ds_read_b128 v[220:223], v160 offset:55296
	ds_read_b128 v[224:227], v160 offset:56320
	global_load_lds_dwordx4 v132, s[96:97]
	s_add_i32 m0, s5, 0x2000
	s_add_i32 s5, s45, s23
	global_load_lds_dwordx4 v136, s[96:97]
	s_mov_b32 m0, s5
	s_nop 0
	global_load_lds_dwordx4 v132, s[98:99]
	s_add_i32 m0, s5, 0x2000
	s_nop 0
	global_load_lds_dwordx4 v136, s[98:99]
	s_mov_b32 m0, s64
	s_nop 0
	global_load_lds_dwordx4 v130, s[94:95]
	s_mov_b32 m0, s65
	s_nop 0
	global_load_lds_dwordx4 v134, s[94:95]
	s_waitcnt vmcnt(8)
	s_waitcnt lgkmcnt(0)
	s_barrier
	s_setprio 1
	s_waitcnt lgkmcnt(0)
	v_mfma_f32_16x16x32_bf16 v[62:65], v[164:167], v[196:199], v[62:65]
	v_mfma_f32_16x16x32_bf16 v[54:57], v[172:175], v[196:199], v[54:57]
	v_mfma_f32_16x16x32_bf16 v[46:49], v[164:167], v[204:207], v[46:49]
	v_mfma_f32_16x16x32_bf16 v[38:41], v[172:175], v[204:207], v[38:41]
	v_mfma_f32_16x16x32_bf16 v[30:33], v[164:167], v[212:215], v[30:33]
	v_mfma_f32_16x16x32_bf16 v[22:25], v[172:175], v[212:215], v[22:25]
	v_mfma_f32_16x16x32_bf16 v[14:17], v[164:167], v[220:223], v[14:17]
	v_mfma_f32_16x16x32_bf16 v[6:9], v[172:175], v[220:223], v[6:9]
	v_mfma_f32_16x16x32_bf16 v[62:65], v[168:171], v[200:203], v[62:65]
	v_mfma_f32_16x16x32_bf16 v[54:57], v[176:179], v[200:203], v[54:57]
	v_mfma_f32_16x16x32_bf16 v[46:49], v[168:171], v[208:211], v[46:49]
	v_mfma_f32_16x16x32_bf16 v[38:41], v[176:179], v[208:211], v[38:41]
	v_mfma_f32_16x16x32_bf16 v[30:33], v[168:171], v[216:219], v[30:33]
	v_mfma_f32_16x16x32_bf16 v[22:25], v[176:179], v[216:219], v[22:25]
	v_mfma_f32_16x16x32_bf16 v[14:17], v[168:171], v[224:227], v[14:17]
	v_mfma_f32_16x16x32_bf16 v[6:9], v[176:179], v[224:227], v[6:9]
	s_setprio 0
	s_setprio 1
	v_mfma_f32_16x16x32_bf16 v[58:61], v[180:183], v[196:199], v[58:61]
	v_mfma_f32_16x16x32_bf16 v[50:53], v[188:191], v[196:199], v[50:53]
	v_mfma_f32_16x16x32_bf16 v[42:45], v[180:183], v[204:207], v[42:45]
	v_mfma_f32_16x16x32_bf16 v[34:37], v[188:191], v[204:207], v[34:37]
	v_mfma_f32_16x16x32_bf16 v[26:29], v[180:183], v[212:215], v[26:29]
	v_mfma_f32_16x16x32_bf16 v[18:21], v[188:191], v[212:215], v[18:21]
	v_mfma_f32_16x16x32_bf16 v[10:13], v[180:183], v[220:223], v[10:13]
	v_mfma_f32_16x16x32_bf16 v[2:5], v[188:191], v[220:223], v[2:5]
	v_mfma_f32_16x16x32_bf16 v[58:61], v[184:187], v[200:203], v[58:61]
	v_mfma_f32_16x16x32_bf16 v[50:53], v[192:195], v[200:203], v[50:53]
	v_mfma_f32_16x16x32_bf16 v[42:45], v[184:187], v[208:211], v[42:45]
	v_mfma_f32_16x16x32_bf16 v[34:37], v[192:195], v[208:211], v[34:37]
	v_mfma_f32_16x16x32_bf16 v[26:29], v[184:187], v[216:219], v[26:29]
	v_mfma_f32_16x16x32_bf16 v[18:21], v[192:195], v[216:219], v[18:21]
	v_mfma_f32_16x16x32_bf16 v[10:13], v[184:187], v[224:227], v[10:13]
	v_mfma_f32_16x16x32_bf16 v[2:5], v[192:195], v[224:227], v[2:5]
	s_setprio 0
	s_barrier
	v_cmp_ge_i32_e32 vcc, s29, v138
	s_mov_b32 s5, s29
	s_add_u32 s88, s88, 0x100
	s_addc_u32 s89, s89, 0
	s_add_u32 s86, s86, 0x100
	s_addc_u32 s87, s87, 0
	s_cbranch_vccz .LBB0_1763

.LBB0_1942:
	v_cmp_gt_i32_e32 vcc, 1, v138
	s_cbranch_vccnz .LBB0_2004
	v_lshl_add_u64 v[152:153], v[2:3], 0, s[16:17]
	v_add_u32_e32 v154, -2, v138
	s_waitcnt lgkmcnt(0)
	v_lshl_add_u64 v[150:151], v[4:5], 0, s[20:21]
	s_mov_b32 s5, 0
	s_nop 0
	v_readfirstlane_b32 s86, v152
	v_readfirstlane_b32 s87, v153
	v_readfirstlane_b32 s88, v150
	v_readfirstlane_b32 s89, v151
	v_readfirstlane_b32 s90, v146
	v_readfirstlane_b32 s91, v147
	v_readfirstlane_b32 s92, v148
	v_readfirstlane_b32 s93, v149
	v_readfirstlane_b32 s100, v154
	s_add_u32 s98, s86, 0xfffc0080
	s_addc_u32 s99, s87, -1
	s_cmp_eq_u32 s5, s100
	s_cselect_b64 s[94:95], s[90:91], s[98:99]
	s_cselect_b64 s[96:97], s[92:93], s[88:89]
	v_add_u32_e32 v155, s72, v141
	ds_read_b128 v[164:167], v155
	ds_read_b128 v[168:171], v155 offset:1024
	ds_read_b128 v[172:175], v155 offset:2048
	ds_read_b128 v[176:179], v155 offset:3072
	v_add_u32_e32 v155, s73, v141
	ds_read_b128 v[180:183], v155
	ds_read_b128 v[184:187], v155 offset:1024
	ds_read_b128 v[188:191], v155 offset:2048
	ds_read_b128 v[192:195], v155 offset:3072
	s_add_i32 s45, s5, 2
	s_nop 0
	s_mov_b32 m0, s74
	ds_read_b128 v[196:199], v160
	ds_read_b128 v[200:203], v160 offset:1024
	ds_read_b128 v[204:207], v160 offset:2048
	ds_read_b128 v[208:211], v160 offset:3072
	ds_read_b128 v[212:215], v160 offset:4096
	ds_read_b128 v[216:219], v160 offset:5120
	ds_read_b128 v[220:223], v160 offset:6144
	ds_read_b128 v[224:227], v160 offset:7168
	global_load_lds_dwordx4 v144, s[86:87]
	s_mov_b32 m0, s75
	s_nop 0
	global_load_lds_dwordx4 v142, s[86:87]
	s_waitcnt vmcnt(8)
	s_waitcnt lgkmcnt(0)
	s_barrier
	s_setprio 1
	s_waitcnt lgkmcnt(0)
	v_mfma_f32_16x16x32_bf16 v[122:125], v[164:167], v[196:199], 0
	v_mfma_f32_16x16x32_bf16 v[118:121], v[172:175], v[196:199], 0
	v_mfma_f32_16x16x32_bf16 v[110:113], v[164:167], v[204:207], 0
	v_mfma_f32_16x16x32_bf16 v[102:105], v[172:175], v[204:207], 0
	v_mfma_f32_16x16x32_bf16 v[94:97], v[164:167], v[212:215], 0
	v_mfma_f32_16x16x32_bf16 v[86:89], v[172:175], v[212:215], 0
	v_mfma_f32_16x16x32_bf16 v[78:81], v[164:167], v[220:223], 0
	v_mfma_f32_16x16x32_bf16 v[70:73], v[172:175], v[220:223], 0
	v_mfma_f32_16x16x32_bf16 v[122:125], v[168:171], v[200:203], v[122:125]
	v_mfma_f32_16x16x32_bf16 v[118:121], v[176:179], v[200:203], v[118:121]
	v_mfma_f32_16x16x32_bf16 v[110:113], v[168:171], v[208:211], v[110:113]
	v_mfma_f32_16x16x32_bf16 v[102:105], v[176:179], v[208:211], v[102:105]
	v_mfma_f32_16x16x32_bf16 v[94:97], v[168:171], v[216:219], v[94:97]
	v_mfma_f32_16x16x32_bf16 v[86:89], v[176:179], v[216:219], v[86:89]
	v_mfma_f32_16x16x32_bf16 v[78:81], v[168:171], v[224:227], v[78:81]
	v_mfma_f32_16x16x32_bf16 v[70:73], v[176:179], v[224:227], v[70:73]
	s_setprio 0
	s_setprio 1
	v_mfma_f32_16x16x32_bf16 v[126:129], v[180:183], v[196:199], 0
	v_mfma_f32_16x16x32_bf16 v[114:117], v[188:191], v[196:199], 0
	v_mfma_f32_16x16x32_bf16 v[106:109], v[180:183], v[204:207], 0
	v_mfma_f32_16x16x32_bf16 v[98:101], v[188:191], v[204:207], 0
	v_mfma_f32_16x16x32_bf16 v[90:93], v[180:183], v[212:215], 0
	v_mfma_f32_16x16x32_bf16 v[82:85], v[188:191], v[212:215], 0
	v_mfma_f32_16x16x32_bf16 v[74:77], v[180:183], v[220:223], 0
	v_mfma_f32_16x16x32_bf16 v[66:69], v[188:191], v[220:223], 0
	v_mfma_f32_16x16x32_bf16 v[126:129], v[184:187], v[200:203], v[126:129]
	v_mfma_f32_16x16x32_bf16 v[114:117], v[192:195], v[200:203], v[114:117]
	v_mfma_f32_16x16x32_bf16 v[106:109], v[184:187], v[208:211], v[106:109]
	v_mfma_f32_16x16x32_bf16 v[98:101], v[192:195], v[208:211], v[98:101]
	v_mfma_f32_16x16x32_bf16 v[90:93], v[184:187], v[216:219], v[90:93]
	v_mfma_f32_16x16x32_bf16 v[82:85], v[192:195], v[216:219], v[82:85]
	v_mfma_f32_16x16x32_bf16 v[74:77], v[184:187], v[224:227], v[74:77]
	v_mfma_f32_16x16x32_bf16 v[66:69], v[192:195], v[224:227], v[66:69]
	s_setprio 0
	s_barrier
	s_add_u32 s98, s96, 0x40000
	s_addc_u32 s99, s97, 0
	s_mov_b32 m0, s76
	ds_read_b128 v[196:199], v160 offset:16384
	ds_read_b128 v[200:203], v160 offset:17408
	ds_read_b128 v[204:207], v160 offset:18432
	ds_read_b128 v[208:211], v160 offset:19456
	ds_read_b128 v[212:215], v160 offset:20480
	ds_read_b128 v[216:219], v160 offset:21504
	ds_read_b128 v[220:223], v160 offset:22528
	ds_read_b128 v[224:227], v160 offset:23552
	global_load_lds_dwordx4 v132, s[96:97]
	s_mov_b32 m0, s77
	s_add_i32 s5, s73, s25
	global_load_lds_dwordx4 v136, s[96:97]
	s_mov_b32 m0, s5
	s_nop 0
	global_load_lds_dwordx4 v132, s[98:99]
	s_add_i32 m0, s5, 0x2000
	s_nop 0
	global_load_lds_dwordx4 v136, s[98:99]
	s_mov_b32 m0, s49
	s_nop 0
	global_load_lds_dwordx4 v130, s[94:95]
	s_mov_b32 m0, s58
	s_nop 0
	global_load_lds_dwordx4 v134, s[94:95]
	s_waitcnt vmcnt(8)
	s_waitcnt lgkmcnt(0)
	s_barrier
	s_setprio 1
	s_waitcnt lgkmcnt(0)
	v_mfma_f32_16x16x32_bf16 v[62:65], v[164:167], v[196:199], 0
	v_mfma_f32_16x16x32_bf16 v[54:57], v[172:175], v[196:199], 0
	v_mfma_f32_16x16x32_bf16 v[46:49], v[164:167], v[204:207], 0
	v_mfma_f32_16x16x32_bf16 v[38:41], v[172:175], v[204:207], 0
	v_mfma_f32_16x16x32_bf16 v[30:33], v[164:167], v[212:215], 0
	v_mfma_f32_16x16x32_bf16 v[22:25], v[172:175], v[212:215], 0
	v_mfma_f32_16x16x32_bf16 v[14:17], v[164:167], v[220:223], 0
	v_mfma_f32_16x16x32_bf16 v[6:9], v[172:175], v[220:223], 0
	v_mfma_f32_16x16x32_bf16 v[62:65], v[168:171], v[200:203], v[62:65]
	v_mfma_f32_16x16x32_bf16 v[54:57], v[176:179], v[200:203], v[54:57]
	v_mfma_f32_16x16x32_bf16 v[46:49], v[168:171], v[208:211], v[46:49]
	v_mfma_f32_16x16x32_bf16 v[38:41], v[176:179], v[208:211], v[38:41]
	v_mfma_f32_16x16x32_bf16 v[30:33], v[168:171], v[216:219], v[30:33]
	v_mfma_f32_16x16x32_bf16 v[22:25], v[176:179], v[216:219], v[22:25]
	v_mfma_f32_16x16x32_bf16 v[14:17], v[168:171], v[224:227], v[14:17]
	v_mfma_f32_16x16x32_bf16 v[6:9], v[176:179], v[224:227], v[6:9]
	s_setprio 0
	s_setprio 1
	v_mfma_f32_16x16x32_bf16 v[58:61], v[180:183], v[196:199], 0
	v_mfma_f32_16x16x32_bf16 v[50:53], v[188:191], v[196:199], 0
	v_mfma_f32_16x16x32_bf16 v[42:45], v[180:183], v[204:207], 0
	v_mfma_f32_16x16x32_bf16 v[34:37], v[188:191], v[204:207], 0
	v_mfma_f32_16x16x32_bf16 v[26:29], v[180:183], v[212:215], 0
	v_mfma_f32_16x16x32_bf16 v[18:21], v[188:191], v[212:215], 0
	v_mfma_f32_16x16x32_bf16 v[10:13], v[180:183], v[220:223], 0
	v_mfma_f32_16x16x32_bf16 v[2:5], v[188:191], v[220:223], 0
	v_mfma_f32_16x16x32_bf16 v[58:61], v[184:187], v[200:203], v[58:61]
	v_mfma_f32_16x16x32_bf16 v[50:53], v[192:195], v[200:203], v[50:53]
	v_mfma_f32_16x16x32_bf16 v[42:45], v[184:187], v[208:211], v[42:45]
	v_mfma_f32_16x16x32_bf16 v[34:37], v[192:195], v[208:211], v[34:37]
	v_mfma_f32_16x16x32_bf16 v[26:29], v[184:187], v[216:219], v[26:29]
	v_mfma_f32_16x16x32_bf16 v[18:21], v[192:195], v[216:219], v[18:21]
	v_mfma_f32_16x16x32_bf16 v[10:13], v[184:187], v[224:227], v[10:13]
	v_mfma_f32_16x16x32_bf16 v[2:5], v[192:195], v[224:227], v[2:5]
	s_setprio 0
	s_barrier
	s_add_u32 s98, s94, 0x40000
	s_addc_u32 s99, s95, 0
	s_add_i32 s5, 0, 0x18000
	v_add_u32_e32 v155, s5, v141
	s_add_i32 s47, 0, 0x1c000
	ds_read_b128 v[164:167], v155
	ds_read_b128 v[168:171], v155 offset:1024
	ds_read_b128 v[172:175], v155 offset:2048
	ds_read_b128 v[176:179], v155 offset:3072
	v_add_u32_e32 v155, s47, v141
	ds_read_b128 v[180:183], v155
	ds_read_b128 v[184:187], v155 offset:1024
	ds_read_b128 v[188:191], v155 offset:2048
	ds_read_b128 v[192:195], v155 offset:3072
	s_mov_b32 m0, s59
	ds_read_b128 v[196:199], v160 offset:32768
	ds_read_b128 v[200:203], v160 offset:33792
	ds_read_b128 v[204:207], v160 offset:34816
	ds_read_b128 v[208:211], v160 offset:35840
	ds_read_b128 v[212:215], v160 offset:36864
	ds_read_b128 v[216:219], v160 offset:37888
	ds_read_b128 v[220:223], v160 offset:38912
	ds_read_b128 v[224:227], v160 offset:39936
	global_load_lds_dwordx4 v130, s[98:99]
	s_mov_b32 m0, s60
	s_nop 0
	global_load_lds_dwordx4 v134, s[98:99]
	s_waitcnt vmcnt(8)
	s_waitcnt lgkmcnt(0)
	s_barrier
	s_setprio 1
	s_waitcnt lgkmcnt(0)
	v_mfma_f32_16x16x32_bf16 v[122:125], v[164:167], v[196:199], v[122:125]
	v_mfma_f32_16x16x32_bf16 v[118:121], v[172:175], v[196:199], v[118:121]
	v_mfma_f32_16x16x32_bf16 v[110:113], v[164:167], v[204:207], v[110:113]
	v_mfma_f32_16x16x32_bf16 v[102:105], v[172:175], v[204:207], v[102:105]
	v_mfma_f32_16x16x32_bf16 v[94:97], v[164:167], v[212:215], v[94:97]
	v_mfma_f32_16x16x32_bf16 v[86:89], v[172:175], v[212:215], v[86:89]
	v_mfma_f32_16x16x32_bf16 v[78:81], v[164:167], v[220:223], v[78:81]
	v_mfma_f32_16x16x32_bf16 v[70:73], v[172:175], v[220:223], v[70:73]
	v_mfma_f32_16x16x32_bf16 v[122:125], v[168:171], v[200:203], v[122:125]
	v_mfma_f32_16x16x32_bf16 v[118:121], v[176:179], v[200:203], v[118:121]
	v_mfma_f32_16x16x32_bf16 v[110:113], v[168:171], v[208:211], v[110:113]
	v_mfma_f32_16x16x32_bf16 v[102:105], v[176:179], v[208:211], v[102:105]
	v_mfma_f32_16x16x32_bf16 v[94:97], v[168:171], v[216:219], v[94:97]
	v_mfma_f32_16x16x32_bf16 v[86:89], v[176:179], v[216:219], v[86:89]
	v_mfma_f32_16x16x32_bf16 v[78:81], v[168:171], v[224:227], v[78:81]
	v_mfma_f32_16x16x32_bf16 v[70:73], v[176:179], v[224:227], v[70:73]
	s_setprio 0
	s_setprio 1
	v_mfma_f32_16x16x32_bf16 v[126:129], v[180:183], v[196:199], v[126:129]
	v_mfma_f32_16x16x32_bf16 v[114:117], v[188:191], v[196:199], v[114:117]
	v_mfma_f32_16x16x32_bf16 v[106:109], v[180:183], v[204:207], v[106:109]
	v_mfma_f32_16x16x32_bf16 v[98:101], v[188:191], v[204:207], v[98:101]
	v_mfma_f32_16x16x32_bf16 v[90:93], v[180:183], v[212:215], v[90:93]
	v_mfma_f32_16x16x32_bf16 v[82:85], v[188:191], v[212:215], v[82:85]
	v_mfma_f32_16x16x32_bf16 v[74:77], v[180:183], v[220:223], v[74:77]
	v_mfma_f32_16x16x32_bf16 v[66:69], v[188:191], v[220:223], v[66:69]
	v_mfma_f32_16x16x32_bf16 v[126:129], v[184:187], v[200:203], v[126:129]
	v_mfma_f32_16x16x32_bf16 v[114:117], v[192:195], v[200:203], v[114:117]
	v_mfma_f32_16x16x32_bf16 v[106:109], v[184:187], v[208:211], v[106:109]
	v_mfma_f32_16x16x32_bf16 v[98:101], v[192:195], v[208:211], v[98:101]
	v_mfma_f32_16x16x32_bf16 v[90:93], v[184:187], v[216:219], v[90:93]
	v_mfma_f32_16x16x32_bf16 v[82:85], v[192:195], v[216:219], v[82:85]
	v_mfma_f32_16x16x32_bf16 v[74:77], v[184:187], v[224:227], v[74:77]
	v_mfma_f32_16x16x32_bf16 v[66:69], v[192:195], v[224:227], v[66:69]
	s_setprio 0
	s_barrier
	s_add_u32 s96, s96, 0x80
	s_addc_u32 s97, s97, 0
	s_add_u32 s98, s96, 0x40000
	s_addc_u32 s99, s97, 0
	s_add_u32 s94, s94, 0x80
	s_addc_u32 s95, s95, 0
	s_add_i32 s5, s5, s25
	s_mov_b32 m0, s5
	ds_read_b128 v[196:199], v160 offset:49152
	ds_read_b128 v[200:203], v160 offset:50176
	ds_read_b128 v[204:207], v160 offset:51200
	ds_read_b128 v[208:211], v160 offset:52224
	ds_read_b128 v[212:215], v160 offset:53248
	ds_read_b128 v[216:219], v160 offset:54272
	ds_read_b128 v[220:223], v160 offset:55296
	ds_read_b128 v[224:227], v160 offset:56320
	global_load_lds_dwordx4 v132, s[96:97]
	s_add_i32 m0, s5, 0x2000
	s_add_i32 s5, s47, s25
	global_load_lds_dwordx4 v136, s[96:97]
	s_mov_b32 m0, s5
	s_nop 0
	global_load_lds_dwordx4 v132, s[98:99]
	s_add_i32 m0, s5, 0x2000
	s_nop 0
	global_load_lds_dwordx4 v136, s[98:99]
	s_mov_b32 m0, s61
	s_nop 0
	global_load_lds_dwordx4 v130, s[94:95]
	s_mov_b32 m0, s62
	s_nop 0
	global_load_lds_dwordx4 v134, s[94:95]
	s_waitcnt vmcnt(8)
	s_waitcnt lgkmcnt(0)
	s_barrier
	s_setprio 1
	s_waitcnt lgkmcnt(0)
	v_mfma_f32_16x16x32_bf16 v[62:65], v[164:167], v[196:199], v[62:65]
	v_mfma_f32_16x16x32_bf16 v[54:57], v[172:175], v[196:199], v[54:57]
	v_mfma_f32_16x16x32_bf16 v[46:49], v[164:167], v[204:207], v[46:49]
	v_mfma_f32_16x16x32_bf16 v[38:41], v[172:175], v[204:207], v[38:41]
	v_mfma_f32_16x16x32_bf16 v[30:33], v[164:167], v[212:215], v[30:33]
	v_mfma_f32_16x16x32_bf16 v[22:25], v[172:175], v[212:215], v[22:25]
	v_mfma_f32_16x16x32_bf16 v[14:17], v[164:167], v[220:223], v[14:17]
	v_mfma_f32_16x16x32_bf16 v[6:9], v[172:175], v[220:223], v[6:9]
	v_mfma_f32_16x16x32_bf16 v[62:65], v[168:171], v[200:203], v[62:65]
	v_mfma_f32_16x16x32_bf16 v[54:57], v[176:179], v[200:203], v[54:57]
	v_mfma_f32_16x16x32_bf16 v[46:49], v[168:171], v[208:211], v[46:49]
	v_mfma_f32_16x16x32_bf16 v[38:41], v[176:179], v[208:211], v[38:41]
	v_mfma_f32_16x16x32_bf16 v[30:33], v[168:171], v[216:219], v[30:33]
	v_mfma_f32_16x16x32_bf16 v[22:25], v[176:179], v[216:219], v[22:25]
	v_mfma_f32_16x16x32_bf16 v[14:17], v[168:171], v[224:227], v[14:17]
	v_mfma_f32_16x16x32_bf16 v[6:9], v[176:179], v[224:227], v[6:9]
	s_setprio 0
	s_setprio 1
	v_mfma_f32_16x16x32_bf16 v[58:61], v[180:183], v[196:199], v[58:61]
	v_mfma_f32_16x16x32_bf16 v[50:53], v[188:191], v[196:199], v[50:53]
	v_mfma_f32_16x16x32_bf16 v[42:45], v[180:183], v[204:207], v[42:45]
	v_mfma_f32_16x16x32_bf16 v[34:37], v[188:191], v[204:207], v[34:37]
	v_mfma_f32_16x16x32_bf16 v[26:29], v[180:183], v[212:215], v[26:29]
	v_mfma_f32_16x16x32_bf16 v[18:21], v[188:191], v[212:215], v[18:21]
	v_mfma_f32_16x16x32_bf16 v[10:13], v[180:183], v[220:223], v[10:13]
	v_mfma_f32_16x16x32_bf16 v[2:5], v[188:191], v[220:223], v[2:5]
	v_mfma_f32_16x16x32_bf16 v[58:61], v[184:187], v[200:203], v[58:61]
	v_mfma_f32_16x16x32_bf16 v[50:53], v[192:195], v[200:203], v[50:53]
	v_mfma_f32_16x16x32_bf16 v[42:45], v[184:187], v[208:211], v[42:45]
	v_mfma_f32_16x16x32_bf16 v[34:37], v[192:195], v[208:211], v[34:37]
	v_mfma_f32_16x16x32_bf16 v[26:29], v[184:187], v[216:219], v[26:29]
	v_mfma_f32_16x16x32_bf16 v[18:21], v[192:195], v[216:219], v[18:21]
	v_mfma_f32_16x16x32_bf16 v[10:13], v[184:187], v[224:227], v[10:13]
	v_mfma_f32_16x16x32_bf16 v[2:5], v[192:195], v[224:227], v[2:5]
	s_setprio 0
	s_barrier
	v_cmp_ge_i32_e32 vcc, s45, v138
	s_mov_b32 s5, s45
	s_add_u32 s88, s88, 0x100
	s_addc_u32 s89, s89, 0
	s_add_u32 s86, s86, 0x100
	s_addc_u32 s87, s87, 0
	s_cbranch_vccnz .Lmy_kexit_10
.LBB0_1944:
	s_add_u32 s98, s86, 0xfffc0080
	s_addc_u32 s99, s87, -1
	s_cmp_eq_u32 s5, s100
	s_cselect_b64 s[94:95], s[90:91], s[98:99]
	s_cselect_b64 s[96:97], s[92:93], s[88:89]
	v_add_u32_e32 v155, s72, v141
	ds_read_b128 v[164:167], v155
	ds_read_b128 v[168:171], v155 offset:1024
	ds_read_b128 v[172:175], v155 offset:2048
	ds_read_b128 v[176:179], v155 offset:3072
	v_add_u32_e32 v155, s73, v141
	ds_read_b128 v[180:183], v155
	ds_read_b128 v[184:187], v155 offset:1024
	ds_read_b128 v[188:191], v155 offset:2048
	ds_read_b128 v[192:195], v155 offset:3072
	s_add_i32 s45, s5, 2
	s_nop 0
	s_mov_b32 m0, s74
	ds_read_b128 v[196:199], v160
	ds_read_b128 v[200:203], v160 offset:1024
	ds_read_b128 v[204:207], v160 offset:2048
	ds_read_b128 v[208:211], v160 offset:3072
	ds_read_b128 v[212:215], v160 offset:4096
	ds_read_b128 v[216:219], v160 offset:5120
	ds_read_b128 v[220:223], v160 offset:6144
	ds_read_b128 v[224:227], v160 offset:7168
	global_load_lds_dwordx4 v144, s[86:87]
	s_mov_b32 m0, s75
	s_nop 0
	global_load_lds_dwordx4 v142, s[86:87]
	s_waitcnt vmcnt(8)
	s_waitcnt lgkmcnt(0)
	s_barrier
	s_setprio 1
	s_waitcnt lgkmcnt(0)
	v_mfma_f32_16x16x32_bf16 v[122:125], v[164:167], v[196:199], v[122:125]
	v_mfma_f32_16x16x32_bf16 v[118:121], v[172:175], v[196:199], v[118:121]
	v_mfma_f32_16x16x32_bf16 v[110:113], v[164:167], v[204:207], v[110:113]
	v_mfma_f32_16x16x32_bf16 v[102:105], v[172:175], v[204:207], v[102:105]
	v_mfma_f32_16x16x32_bf16 v[94:97], v[164:167], v[212:215], v[94:97]
	v_mfma_f32_16x16x32_bf16 v[86:89], v[172:175], v[212:215], v[86:89]
	v_mfma_f32_16x16x32_bf16 v[78:81], v[164:167], v[220:223], v[78:81]
	v_mfma_f32_16x16x32_bf16 v[70:73], v[172:175], v[220:223], v[70:73]
	v_mfma_f32_16x16x32_bf16 v[122:125], v[168:171], v[200:203], v[122:125]
	v_mfma_f32_16x16x32_bf16 v[118:121], v[176:179], v[200:203], v[118:121]
	v_mfma_f32_16x16x32_bf16 v[110:113], v[168:171], v[208:211], v[110:113]
	v_mfma_f32_16x16x32_bf16 v[102:105], v[176:179], v[208:211], v[102:105]
	v_mfma_f32_16x16x32_bf16 v[94:97], v[168:171], v[216:219], v[94:97]
	v_mfma_f32_16x16x32_bf16 v[86:89], v[176:179], v[216:219], v[86:89]
	v_mfma_f32_16x16x32_bf16 v[78:81], v[168:171], v[224:227], v[78:81]
	v_mfma_f32_16x16x32_bf16 v[70:73], v[176:179], v[224:227], v[70:73]
	s_setprio 0
	s_setprio 1
	v_mfma_f32_16x16x32_bf16 v[126:129], v[180:183], v[196:199], v[126:129]
	v_mfma_f32_16x16x32_bf16 v[114:117], v[188:191], v[196:199], v[114:117]
	v_mfma_f32_16x16x32_bf16 v[106:109], v[180:183], v[204:207], v[106:109]
	v_mfma_f32_16x16x32_bf16 v[98:101], v[188:191], v[204:207], v[98:101]
	v_mfma_f32_16x16x32_bf16 v[90:93], v[180:183], v[212:215], v[90:93]
	v_mfma_f32_16x16x32_bf16 v[82:85], v[188:191], v[212:215], v[82:85]
	v_mfma_f32_16x16x32_bf16 v[74:77], v[180:183], v[220:223], v[74:77]
	v_mfma_f32_16x16x32_bf16 v[66:69], v[188:191], v[220:223], v[66:69]
	v_mfma_f32_16x16x32_bf16 v[126:129], v[184:187], v[200:203], v[126:129]
	v_mfma_f32_16x16x32_bf16 v[114:117], v[192:195], v[200:203], v[114:117]
	v_mfma_f32_16x16x32_bf16 v[106:109], v[184:187], v[208:211], v[106:109]
	v_mfma_f32_16x16x32_bf16 v[98:101], v[192:195], v[208:211], v[98:101]
	v_mfma_f32_16x16x32_bf16 v[90:93], v[184:187], v[216:219], v[90:93]
	v_mfma_f32_16x16x32_bf16 v[82:85], v[192:195], v[216:219], v[82:85]
	v_mfma_f32_16x16x32_bf16 v[74:77], v[184:187], v[224:227], v[74:77]
	v_mfma_f32_16x16x32_bf16 v[66:69], v[192:195], v[224:227], v[66:69]
	s_setprio 0
	s_barrier
	s_add_u32 s98, s96, 0x40000
	s_addc_u32 s99, s97, 0
	s_mov_b32 m0, s76
	ds_read_b128 v[196:199], v160 offset:16384
	ds_read_b128 v[200:203], v160 offset:17408
	ds_read_b128 v[204:207], v160 offset:18432
	ds_read_b128 v[208:211], v160 offset:19456
	ds_read_b128 v[212:215], v160 offset:20480
	ds_read_b128 v[216:219], v160 offset:21504
	ds_read_b128 v[220:223], v160 offset:22528
	ds_read_b128 v[224:227], v160 offset:23552
	global_load_lds_dwordx4 v132, s[96:97]
	s_mov_b32 m0, s77
	s_add_i32 s5, s73, s25
	global_load_lds_dwordx4 v136, s[96:97]
	s_mov_b32 m0, s5
	s_nop 0
	global_load_lds_dwordx4 v132, s[98:99]
	s_add_i32 m0, s5, 0x2000
	s_nop 0
	global_load_lds_dwordx4 v136, s[98:99]
	s_mov_b32 m0, s49
	s_nop 0
	global_load_lds_dwordx4 v130, s[94:95]
	s_mov_b32 m0, s58
	s_nop 0
	global_load_lds_dwordx4 v134, s[94:95]
	s_waitcnt vmcnt(8)
	s_waitcnt lgkmcnt(0)
	s_barrier
	s_setprio 1
	s_waitcnt lgkmcnt(0)
	v_mfma_f32_16x16x32_bf16 v[62:65], v[164:167], v[196:199], v[62:65]
	v_mfma_f32_16x16x32_bf16 v[54:57], v[172:175], v[196:199], v[54:57]
	v_mfma_f32_16x16x32_bf16 v[46:49], v[164:167], v[204:207], v[46:49]
	v_mfma_f32_16x16x32_bf16 v[38:41], v[172:175], v[204:207], v[38:41]
	v_mfma_f32_16x16x32_bf16 v[30:33], v[164:167], v[212:215], v[30:33]
	v_mfma_f32_16x16x32_bf16 v[22:25], v[172:175], v[212:215], v[22:25]
	v_mfma_f32_16x16x32_bf16 v[14:17], v[164:167], v[220:223], v[14:17]
	v_mfma_f32_16x16x32_bf16 v[6:9], v[172:175], v[220:223], v[6:9]
	v_mfma_f32_16x16x32_bf16 v[62:65], v[168:171], v[200:203], v[62:65]
	v_mfma_f32_16x16x32_bf16 v[54:57], v[176:179], v[200:203], v[54:57]
	v_mfma_f32_16x16x32_bf16 v[46:49], v[168:171], v[208:211], v[46:49]
	v_mfma_f32_16x16x32_bf16 v[38:41], v[176:179], v[208:211], v[38:41]
	v_mfma_f32_16x16x32_bf16 v[30:33], v[168:171], v[216:219], v[30:33]
	v_mfma_f32_16x16x32_bf16 v[22:25], v[176:179], v[216:219], v[22:25]
	v_mfma_f32_16x16x32_bf16 v[14:17], v[168:171], v[224:227], v[14:17]
	v_mfma_f32_16x16x32_bf16 v[6:9], v[176:179], v[224:227], v[6:9]
	s_setprio 0
	s_setprio 1
	v_mfma_f32_16x16x32_bf16 v[58:61], v[180:183], v[196:199], v[58:61]
	v_mfma_f32_16x16x32_bf16 v[50:53], v[188:191], v[196:199], v[50:53]
	v_mfma_f32_16x16x32_bf16 v[42:45], v[180:183], v[204:207], v[42:45]
	v_mfma_f32_16x16x32_bf16 v[34:37], v[188:191], v[204:207], v[34:37]
	v_mfma_f32_16x16x32_bf16 v[26:29], v[180:183], v[212:215], v[26:29]
	v_mfma_f32_16x16x32_bf16 v[18:21], v[188:191], v[212:215], v[18:21]
	v_mfma_f32_16x16x32_bf16 v[10:13], v[180:183], v[220:223], v[10:13]
	v_mfma_f32_16x16x32_bf16 v[2:5], v[188:191], v[220:223], v[2:5]
	v_mfma_f32_16x16x32_bf16 v[58:61], v[184:187], v[200:203], v[58:61]
	v_mfma_f32_16x16x32_bf16 v[50:53], v[192:195], v[200:203], v[50:53]
	v_mfma_f32_16x16x32_bf16 v[42:45], v[184:187], v[208:211], v[42:45]
	v_mfma_f32_16x16x32_bf16 v[34:37], v[192:195], v[208:211], v[34:37]
	v_mfma_f32_16x16x32_bf16 v[26:29], v[184:187], v[216:219], v[26:29]
	v_mfma_f32_16x16x32_bf16 v[18:21], v[192:195], v[216:219], v[18:21]
	v_mfma_f32_16x16x32_bf16 v[10:13], v[184:187], v[224:227], v[10:13]
	v_mfma_f32_16x16x32_bf16 v[2:5], v[192:195], v[224:227], v[2:5]
	s_setprio 0
	s_barrier
	s_add_u32 s98, s94, 0x40000
	s_addc_u32 s99, s95, 0
	s_add_i32 s5, 0, 0x18000
	v_add_u32_e32 v155, s5, v141
	s_add_i32 s47, 0, 0x1c000
	ds_read_b128 v[164:167], v155
	ds_read_b128 v[168:171], v155 offset:1024
	ds_read_b128 v[172:175], v155 offset:2048
	ds_read_b128 v[176:179], v155 offset:3072
	v_add_u32_e32 v155, s47, v141
	ds_read_b128 v[180:183], v155
	ds_read_b128 v[184:187], v155 offset:1024
	ds_read_b128 v[188:191], v155 offset:2048
	ds_read_b128 v[192:195], v155 offset:3072
	s_mov_b32 m0, s59
	ds_read_b128 v[196:199], v160 offset:32768
	ds_read_b128 v[200:203], v160 offset:33792
	ds_read_b128 v[204:207], v160 offset:34816
	ds_read_b128 v[208:211], v160 offset:35840
	ds_read_b128 v[212:215], v160 offset:36864
	ds_read_b128 v[216:219], v160 offset:37888
	ds_read_b128 v[220:223], v160 offset:38912
	ds_read_b128 v[224:227], v160 offset:39936
	global_load_lds_dwordx4 v130, s[98:99]
	s_mov_b32 m0, s60
	s_nop 0
	global_load_lds_dwordx4 v134, s[98:99]
	s_waitcnt vmcnt(8)
	s_waitcnt lgkmcnt(0)
	s_barrier
	s_setprio 1
	s_waitcnt lgkmcnt(0)
	v_mfma_f32_16x16x32_bf16 v[122:125], v[164:167], v[196:199], v[122:125]
	v_mfma_f32_16x16x32_bf16 v[118:121], v[172:175], v[196:199], v[118:121]
	v_mfma_f32_16x16x32_bf16 v[110:113], v[164:167], v[204:207], v[110:113]
	v_mfma_f32_16x16x32_bf16 v[102:105], v[172:175], v[204:207], v[102:105]
	v_mfma_f32_16x16x32_bf16 v[94:97], v[164:167], v[212:215], v[94:97]
	v_mfma_f32_16x16x32_bf16 v[86:89], v[172:175], v[212:215], v[86:89]
	v_mfma_f32_16x16x32_bf16 v[78:81], v[164:167], v[220:223], v[78:81]
	v_mfma_f32_16x16x32_bf16 v[70:73], v[172:175], v[220:223], v[70:73]
	v_mfma_f32_16x16x32_bf16 v[122:125], v[168:171], v[200:203], v[122:125]
	v_mfma_f32_16x16x32_bf16 v[118:121], v[176:179], v[200:203], v[118:121]
	v_mfma_f32_16x16x32_bf16 v[110:113], v[168:171], v[208:211], v[110:113]
	v_mfma_f32_16x16x32_bf16 v[102:105], v[176:179], v[208:211], v[102:105]
	v_mfma_f32_16x16x32_bf16 v[94:97], v[168:171], v[216:219], v[94:97]
	v_mfma_f32_16x16x32_bf16 v[86:89], v[176:179], v[216:219], v[86:89]
	v_mfma_f32_16x16x32_bf16 v[78:81], v[168:171], v[224:227], v[78:81]
	v_mfma_f32_16x16x32_bf16 v[70:73], v[176:179], v[224:227], v[70:73]
	s_setprio 0
	s_setprio 1
	v_mfma_f32_16x16x32_bf16 v[126:129], v[180:183], v[196:199], v[126:129]
	v_mfma_f32_16x16x32_bf16 v[114:117], v[188:191], v[196:199], v[114:117]
	v_mfma_f32_16x16x32_bf16 v[106:109], v[180:183], v[204:207], v[106:109]
	v_mfma_f32_16x16x32_bf16 v[98:101], v[188:191], v[204:207], v[98:101]
	v_mfma_f32_16x16x32_bf16 v[90:93], v[180:183], v[212:215], v[90:93]
	v_mfma_f32_16x16x32_bf16 v[82:85], v[188:191], v[212:215], v[82:85]
	v_mfma_f32_16x16x32_bf16 v[74:77], v[180:183], v[220:223], v[74:77]
	v_mfma_f32_16x16x32_bf16 v[66:69], v[188:191], v[220:223], v[66:69]
	v_mfma_f32_16x16x32_bf16 v[126:129], v[184:187], v[200:203], v[126:129]
	v_mfma_f32_16x16x32_bf16 v[114:117], v[192:195], v[200:203], v[114:117]
	v_mfma_f32_16x16x32_bf16 v[106:109], v[184:187], v[208:211], v[106:109]
	v_mfma_f32_16x16x32_bf16 v[98:101], v[192:195], v[208:211], v[98:101]
	v_mfma_f32_16x16x32_bf16 v[90:93], v[184:187], v[216:219], v[90:93]
	v_mfma_f32_16x16x32_bf16 v[82:85], v[192:195], v[216:219], v[82:85]
	v_mfma_f32_16x16x32_bf16 v[74:77], v[184:187], v[224:227], v[74:77]
	v_mfma_f32_16x16x32_bf16 v[66:69], v[192:195], v[224:227], v[66:69]
	s_setprio 0
	s_barrier
	s_add_u32 s96, s96, 0x80
	s_addc_u32 s97, s97, 0
	s_add_u32 s98, s96, 0x40000
	s_addc_u32 s99, s97, 0
	s_add_u32 s94, s94, 0x80
	s_addc_u32 s95, s95, 0
	s_add_i32 s5, s5, s25
	s_mov_b32 m0, s5
	ds_read_b128 v[196:199], v160 offset:49152
	ds_read_b128 v[200:203], v160 offset:50176
	ds_read_b128 v[204:207], v160 offset:51200
	ds_read_b128 v[208:211], v160 offset:52224
	ds_read_b128 v[212:215], v160 offset:53248
	ds_read_b128 v[216:219], v160 offset:54272
	ds_read_b128 v[220:223], v160 offset:55296
	ds_read_b128 v[224:227], v160 offset:56320
	global_load_lds_dwordx4 v132, s[96:97]
	s_add_i32 m0, s5, 0x2000
	s_add_i32 s5, s47, s25
	global_load_lds_dwordx4 v136, s[96:97]
	s_mov_b32 m0, s5
	s_nop 0
	global_load_lds_dwordx4 v132, s[98:99]
	s_add_i32 m0, s5, 0x2000
	s_nop 0
	global_load_lds_dwordx4 v136, s[98:99]
	s_mov_b32 m0, s61
	s_nop 0
	global_load_lds_dwordx4 v130, s[94:95]
	s_mov_b32 m0, s62
	s_nop 0
	global_load_lds_dwordx4 v134, s[94:95]
	s_waitcnt vmcnt(8)
	s_waitcnt lgkmcnt(0)
	s_barrier
	s_setprio 1
	s_waitcnt lgkmcnt(0)
	v_mfma_f32_16x16x32_bf16 v[62:65], v[164:167], v[196:199], v[62:65]
	v_mfma_f32_16x16x32_bf16 v[54:57], v[172:175], v[196:199], v[54:57]
	v_mfma_f32_16x16x32_bf16 v[46:49], v[164:167], v[204:207], v[46:49]
	v_mfma_f32_16x16x32_bf16 v[38:41], v[172:175], v[204:207], v[38:41]
	v_mfma_f32_16x16x32_bf16 v[30:33], v[164:167], v[212:215], v[30:33]
	v_mfma_f32_16x16x32_bf16 v[22:25], v[172:175], v[212:215], v[22:25]
	v_mfma_f32_16x16x32_bf16 v[14:17], v[164:167], v[220:223], v[14:17]
	v_mfma_f32_16x16x32_bf16 v[6:9], v[172:175], v[220:223], v[6:9]
	v_mfma_f32_16x16x32_bf16 v[62:65], v[168:171], v[200:203], v[62:65]
	v_mfma_f32_16x16x32_bf16 v[54:57], v[176:179], v[200:203], v[54:57]
	v_mfma_f32_16x16x32_bf16 v[46:49], v[168:171], v[208:211], v[46:49]
	v_mfma_f32_16x16x32_bf16 v[38:41], v[176:179], v[208:211], v[38:41]
	v_mfma_f32_16x16x32_bf16 v[30:33], v[168:171], v[216:219], v[30:33]
	v_mfma_f32_16x16x32_bf16 v[22:25], v[176:179], v[216:219], v[22:25]
	v_mfma_f32_16x16x32_bf16 v[14:17], v[168:171], v[224:227], v[14:17]
	v_mfma_f32_16x16x32_bf16 v[6:9], v[176:179], v[224:227], v[6:9]
	s_setprio 0
	s_setprio 1
	v_mfma_f32_16x16x32_bf16 v[58:61], v[180:183], v[196:199], v[58:61]
	v_mfma_f32_16x16x32_bf16 v[50:53], v[188:191], v[196:199], v[50:53]
	v_mfma_f32_16x16x32_bf16 v[42:45], v[180:183], v[204:207], v[42:45]
	v_mfma_f32_16x16x32_bf16 v[34:37], v[188:191], v[204:207], v[34:37]
	v_mfma_f32_16x16x32_bf16 v[26:29], v[180:183], v[212:215], v[26:29]
	v_mfma_f32_16x16x32_bf16 v[18:21], v[188:191], v[212:215], v[18:21]
	v_mfma_f32_16x16x32_bf16 v[10:13], v[180:183], v[220:223], v[10:13]
	v_mfma_f32_16x16x32_bf16 v[2:5], v[188:191], v[220:223], v[2:5]
	v_mfma_f32_16x16x32_bf16 v[58:61], v[184:187], v[200:203], v[58:61]
	v_mfma_f32_16x16x32_bf16 v[50:53], v[192:195], v[200:203], v[50:53]
	v_mfma_f32_16x16x32_bf16 v[42:45], v[184:187], v[208:211], v[42:45]
	v_mfma_f32_16x16x32_bf16 v[34:37], v[192:195], v[208:211], v[34:37]
	v_mfma_f32_16x16x32_bf16 v[26:29], v[184:187], v[216:219], v[26:29]
	v_mfma_f32_16x16x32_bf16 v[18:21], v[192:195], v[216:219], v[18:21]
	v_mfma_f32_16x16x32_bf16 v[10:13], v[184:187], v[224:227], v[10:13]
	v_mfma_f32_16x16x32_bf16 v[2:5], v[192:195], v[224:227], v[2:5]
	s_setprio 0
	s_barrier
	v_cmp_ge_i32_e32 vcc, s45, v138
	s_mov_b32 s5, s45
	s_add_u32 s88, s88, 0x100
	s_addc_u32 s89, s89, 0
	s_add_u32 s86, s86, 0x100
	s_addc_u32 s87, s87, 0
	s_cbranch_vccz .LBB0_1944

.LBB0_2073:
	v_cmp_gt_i32_e32 vcc, 1, v156
	s_cbranch_vccnz .LBB0_2135
	v_lshl_add_u64 v[152:153], v[2:3], 0, s[18:19]
	v_add_u32_e32 v138, -2, v156
	s_mov_b32 s4, 0
	s_nop 0
	v_readfirstlane_b32 s86, v150
	v_readfirstlane_b32 s87, v151
	v_readfirstlane_b32 s88, v152
	v_readfirstlane_b32 s89, v153
	v_readfirstlane_b32 s90, v146
	v_readfirstlane_b32 s91, v147
	v_readfirstlane_b32 s92, v148
	v_readfirstlane_b32 s93, v149
	v_readfirstlane_b32 s100, v138
	s_add_u32 s98, s86, 0x100
	s_addc_u32 s99, s87, 0
	s_cmp_eq_u32 s4, s100
	s_cselect_b64 s[94:95], s[90:91], s[98:99]
	s_cselect_b64 s[96:97], s[92:93], s[88:89]
	v_add_u32_e32 v157, s65, v141
	ds_read_b128 v[164:167], v157
	ds_read_b128 v[168:171], v157 offset:1024
	ds_read_b128 v[172:175], v157 offset:2048
	ds_read_b128 v[176:179], v157 offset:3072
	v_add_u32_e32 v157, s66, v141
	ds_read_b128 v[180:183], v157
	ds_read_b128 v[184:187], v157 offset:1024
	ds_read_b128 v[188:191], v157 offset:2048
	ds_read_b128 v[192:195], v157 offset:3072
	s_add_i32 s5, s4, 2
	s_nop 0
	s_add_i32 m0, s44, 0xc000
	ds_read_b128 v[196:199], v160
	ds_read_b128 v[200:203], v160 offset:1024
	ds_read_b128 v[204:207], v160 offset:2048
	ds_read_b128 v[208:211], v160 offset:3072
	ds_read_b128 v[212:215], v160 offset:4096
	ds_read_b128 v[216:219], v160 offset:5120
	ds_read_b128 v[220:223], v160 offset:6144
	ds_read_b128 v[224:227], v160 offset:7168
	global_load_lds_dwordx4 v144, s[86:87]
	s_add_i32 m0, s44, 0xe000
	s_nop 0
	global_load_lds_dwordx4 v142, s[86:87]
	s_waitcnt vmcnt(8)
	s_waitcnt lgkmcnt(0)
	s_barrier
	s_setprio 1
	s_waitcnt lgkmcnt(0)
	v_mfma_f32_16x16x32_bf16 v[122:125], v[164:167], v[196:199], 0
	v_mfma_f32_16x16x32_bf16 v[118:121], v[172:175], v[196:199], 0
	v_mfma_f32_16x16x32_bf16 v[110:113], v[164:167], v[204:207], 0
	v_mfma_f32_16x16x32_bf16 v[102:105], v[172:175], v[204:207], 0
	v_mfma_f32_16x16x32_bf16 v[94:97], v[164:167], v[212:215], 0
	v_mfma_f32_16x16x32_bf16 v[86:89], v[172:175], v[212:215], 0
	v_mfma_f32_16x16x32_bf16 v[78:81], v[164:167], v[220:223], 0
	v_mfma_f32_16x16x32_bf16 v[70:73], v[172:175], v[220:223], 0
	v_mfma_f32_16x16x32_bf16 v[122:125], v[168:171], v[200:203], v[122:125]
	v_mfma_f32_16x16x32_bf16 v[118:121], v[176:179], v[200:203], v[118:121]
	v_mfma_f32_16x16x32_bf16 v[110:113], v[168:171], v[208:211], v[110:113]
	v_mfma_f32_16x16x32_bf16 v[102:105], v[176:179], v[208:211], v[102:105]
	v_mfma_f32_16x16x32_bf16 v[94:97], v[168:171], v[216:219], v[94:97]
	v_mfma_f32_16x16x32_bf16 v[86:89], v[176:179], v[216:219], v[86:89]
	v_mfma_f32_16x16x32_bf16 v[78:81], v[168:171], v[224:227], v[78:81]
	v_mfma_f32_16x16x32_bf16 v[70:73], v[176:179], v[224:227], v[70:73]
	s_setprio 0
	s_setprio 1
	v_mfma_f32_16x16x32_bf16 v[126:129], v[180:183], v[196:199], 0
	v_mfma_f32_16x16x32_bf16 v[114:117], v[188:191], v[196:199], 0
	v_mfma_f32_16x16x32_bf16 v[106:109], v[180:183], v[204:207], 0
	v_mfma_f32_16x16x32_bf16 v[98:101], v[188:191], v[204:207], 0
	v_mfma_f32_16x16x32_bf16 v[90:93], v[180:183], v[212:215], 0
	v_mfma_f32_16x16x32_bf16 v[82:85], v[188:191], v[212:215], 0
	v_mfma_f32_16x16x32_bf16 v[74:77], v[180:183], v[220:223], 0
	v_mfma_f32_16x16x32_bf16 v[66:69], v[188:191], v[220:223], 0
	v_mfma_f32_16x16x32_bf16 v[126:129], v[184:187], v[200:203], v[126:129]
	v_mfma_f32_16x16x32_bf16 v[114:117], v[192:195], v[200:203], v[114:117]
	v_mfma_f32_16x16x32_bf16 v[106:109], v[184:187], v[208:211], v[106:109]
	v_mfma_f32_16x16x32_bf16 v[98:101], v[192:195], v[208:211], v[98:101]
	v_mfma_f32_16x16x32_bf16 v[90:93], v[184:187], v[216:219], v[90:93]
	v_mfma_f32_16x16x32_bf16 v[82:85], v[192:195], v[216:219], v[82:85]
	v_mfma_f32_16x16x32_bf16 v[74:77], v[184:187], v[224:227], v[74:77]
	v_mfma_f32_16x16x32_bf16 v[66:69], v[192:195], v[224:227], v[66:69]
	s_setprio 0
	s_barrier
	s_add_u32 s98, s96, 0xb0000
	s_addc_u32 s99, s97, 0
	s_add_i32 s4, s65, s21
	s_mov_b32 m0, s4
	ds_read_b128 v[196:199], v160 offset:16384
	ds_read_b128 v[200:203], v160 offset:17408
	ds_read_b128 v[204:207], v160 offset:18432
	ds_read_b128 v[208:211], v160 offset:19456
	ds_read_b128 v[212:215], v160 offset:20480
	ds_read_b128 v[216:219], v160 offset:21504
	ds_read_b128 v[220:223], v160 offset:22528
	ds_read_b128 v[224:227], v160 offset:23552
	global_load_lds_dwordx4 v132, s[96:97]
	s_add_i32 m0, s4, 0x2000
	s_add_i32 s4, s66, s21
	global_load_lds_dwordx4 v136, s[96:97]
	s_mov_b32 m0, s4
	s_nop 0
	global_load_lds_dwordx4 v132, s[98:99]
	s_add_i32 m0, s4, 0x2000
	s_nop 0
	global_load_lds_dwordx4 v136, s[98:99]
	s_mov_b32 m0, s44
	s_nop 0
	global_load_lds_dwordx4 v130, s[94:95]
	s_mov_b32 m0, s45
	s_nop 0
	global_load_lds_dwordx4 v134, s[94:95]
	s_waitcnt vmcnt(8)
	s_waitcnt lgkmcnt(0)
	s_barrier
	s_setprio 1
	s_waitcnt lgkmcnt(0)
	v_mfma_f32_16x16x32_bf16 v[62:65], v[164:167], v[196:199], 0
	v_mfma_f32_16x16x32_bf16 v[54:57], v[172:175], v[196:199], 0
	v_mfma_f32_16x16x32_bf16 v[46:49], v[164:167], v[204:207], 0
	v_mfma_f32_16x16x32_bf16 v[38:41], v[172:175], v[204:207], 0
	v_mfma_f32_16x16x32_bf16 v[30:33], v[164:167], v[212:215], 0
	v_mfma_f32_16x16x32_bf16 v[22:25], v[172:175], v[212:215], 0
	v_mfma_f32_16x16x32_bf16 v[14:17], v[164:167], v[220:223], 0
	v_mfma_f32_16x16x32_bf16 v[6:9], v[172:175], v[220:223], 0
	v_mfma_f32_16x16x32_bf16 v[62:65], v[168:171], v[200:203], v[62:65]
	v_mfma_f32_16x16x32_bf16 v[54:57], v[176:179], v[200:203], v[54:57]
	v_mfma_f32_16x16x32_bf16 v[46:49], v[168:171], v[208:211], v[46:49]
	v_mfma_f32_16x16x32_bf16 v[38:41], v[176:179], v[208:211], v[38:41]
	v_mfma_f32_16x16x32_bf16 v[30:33], v[168:171], v[216:219], v[30:33]
	v_mfma_f32_16x16x32_bf16 v[22:25], v[176:179], v[216:219], v[22:25]
	v_mfma_f32_16x16x32_bf16 v[14:17], v[168:171], v[224:227], v[14:17]
	v_mfma_f32_16x16x32_bf16 v[6:9], v[176:179], v[224:227], v[6:9]
	s_setprio 0
	s_setprio 1
	v_mfma_f32_16x16x32_bf16 v[58:61], v[180:183], v[196:199], 0
	v_mfma_f32_16x16x32_bf16 v[50:53], v[188:191], v[196:199], 0
	v_mfma_f32_16x16x32_bf16 v[42:45], v[180:183], v[204:207], 0
	v_mfma_f32_16x16x32_bf16 v[34:37], v[188:191], v[204:207], 0
	v_mfma_f32_16x16x32_bf16 v[26:29], v[180:183], v[212:215], 0
	v_mfma_f32_16x16x32_bf16 v[18:21], v[188:191], v[212:215], 0
	v_mfma_f32_16x16x32_bf16 v[10:13], v[180:183], v[220:223], 0
	v_mfma_f32_16x16x32_bf16 v[2:5], v[188:191], v[220:223], 0
	v_mfma_f32_16x16x32_bf16 v[58:61], v[184:187], v[200:203], v[58:61]
	v_mfma_f32_16x16x32_bf16 v[50:53], v[192:195], v[200:203], v[50:53]
	v_mfma_f32_16x16x32_bf16 v[42:45], v[184:187], v[208:211], v[42:45]
	v_mfma_f32_16x16x32_bf16 v[34:37], v[192:195], v[208:211], v[34:37]
	v_mfma_f32_16x16x32_bf16 v[26:29], v[184:187], v[216:219], v[26:29]
	v_mfma_f32_16x16x32_bf16 v[18:21], v[192:195], v[216:219], v[18:21]
	v_mfma_f32_16x16x32_bf16 v[10:13], v[184:187], v[224:227], v[10:13]
	v_mfma_f32_16x16x32_bf16 v[2:5], v[192:195], v[224:227], v[2:5]
	s_setprio 0
	s_barrier
	s_add_u32 s98, s94, 0xb0000
	s_addc_u32 s99, s95, 0
	s_add_i32 s4, 0, 0x18000
	v_add_u32_e32 v157, s4, v141
	s_add_i32 s25, 0, 0x1c000
	ds_read_b128 v[164:167], v157
	ds_read_b128 v[168:171], v157 offset:1024
	ds_read_b128 v[172:175], v157 offset:2048
	ds_read_b128 v[176:179], v157 offset:3072
	v_add_u32_e32 v157, s25, v141
	ds_read_b128 v[180:183], v157
	ds_read_b128 v[184:187], v157 offset:1024
	ds_read_b128 v[188:191], v157 offset:2048
	ds_read_b128 v[192:195], v157 offset:3072
	s_mov_b32 m0, s46
	ds_read_b128 v[196:199], v160 offset:32768
	ds_read_b128 v[200:203], v160 offset:33792
	ds_read_b128 v[204:207], v160 offset:34816
	ds_read_b128 v[208:211], v160 offset:35840
	ds_read_b128 v[212:215], v160 offset:36864
	ds_read_b128 v[216:219], v160 offset:37888
	ds_read_b128 v[220:223], v160 offset:38912
	ds_read_b128 v[224:227], v160 offset:39936
	global_load_lds_dwordx4 v130, s[98:99]
	s_mov_b32 m0, s47
	s_nop 0
	global_load_lds_dwordx4 v134, s[98:99]
	s_waitcnt vmcnt(8)
	s_waitcnt lgkmcnt(0)
	s_barrier
	s_setprio 1
	s_waitcnt lgkmcnt(0)
	v_mfma_f32_16x16x32_bf16 v[122:125], v[164:167], v[196:199], v[122:125]
	v_mfma_f32_16x16x32_bf16 v[118:121], v[172:175], v[196:199], v[118:121]
	v_mfma_f32_16x16x32_bf16 v[110:113], v[164:167], v[204:207], v[110:113]
	v_mfma_f32_16x16x32_bf16 v[102:105], v[172:175], v[204:207], v[102:105]
	v_mfma_f32_16x16x32_bf16 v[94:97], v[164:167], v[212:215], v[94:97]
	v_mfma_f32_16x16x32_bf16 v[86:89], v[172:175], v[212:215], v[86:89]
	v_mfma_f32_16x16x32_bf16 v[78:81], v[164:167], v[220:223], v[78:81]
	v_mfma_f32_16x16x32_bf16 v[70:73], v[172:175], v[220:223], v[70:73]
	v_mfma_f32_16x16x32_bf16 v[122:125], v[168:171], v[200:203], v[122:125]
	v_mfma_f32_16x16x32_bf16 v[118:121], v[176:179], v[200:203], v[118:121]
	v_mfma_f32_16x16x32_bf16 v[110:113], v[168:171], v[208:211], v[110:113]
	v_mfma_f32_16x16x32_bf16 v[102:105], v[176:179], v[208:211], v[102:105]
	v_mfma_f32_16x16x32_bf16 v[94:97], v[168:171], v[216:219], v[94:97]
	v_mfma_f32_16x16x32_bf16 v[86:89], v[176:179], v[216:219], v[86:89]
	v_mfma_f32_16x16x32_bf16 v[78:81], v[168:171], v[224:227], v[78:81]
	v_mfma_f32_16x16x32_bf16 v[70:73], v[176:179], v[224:227], v[70:73]
	s_setprio 0
	s_setprio 1
	v_mfma_f32_16x16x32_bf16 v[126:129], v[180:183], v[196:199], v[126:129]
	v_mfma_f32_16x16x32_bf16 v[114:117], v[188:191], v[196:199], v[114:117]
	v_mfma_f32_16x16x32_bf16 v[106:109], v[180:183], v[204:207], v[106:109]
	v_mfma_f32_16x16x32_bf16 v[98:101], v[188:191], v[204:207], v[98:101]
	v_mfma_f32_16x16x32_bf16 v[90:93], v[180:183], v[212:215], v[90:93]
	v_mfma_f32_16x16x32_bf16 v[82:85], v[188:191], v[212:215], v[82:85]
	v_mfma_f32_16x16x32_bf16 v[74:77], v[180:183], v[220:223], v[74:77]
	v_mfma_f32_16x16x32_bf16 v[66:69], v[188:191], v[220:223], v[66:69]
	v_mfma_f32_16x16x32_bf16 v[126:129], v[184:187], v[200:203], v[126:129]
	v_mfma_f32_16x16x32_bf16 v[114:117], v[192:195], v[200:203], v[114:117]
	v_mfma_f32_16x16x32_bf16 v[106:109], v[184:187], v[208:211], v[106:109]
	v_mfma_f32_16x16x32_bf16 v[98:101], v[192:195], v[208:211], v[98:101]
	v_mfma_f32_16x16x32_bf16 v[90:93], v[184:187], v[216:219], v[90:93]
	v_mfma_f32_16x16x32_bf16 v[82:85], v[192:195], v[216:219], v[82:85]
	v_mfma_f32_16x16x32_bf16 v[74:77], v[184:187], v[224:227], v[74:77]
	v_mfma_f32_16x16x32_bf16 v[66:69], v[192:195], v[224:227], v[66:69]
	s_setprio 0
	s_barrier
	s_add_u32 s96, s96, 0x80
	s_addc_u32 s97, s97, 0
	s_add_u32 s98, s96, 0xb0000
	s_addc_u32 s99, s97, 0
	s_add_u32 s94, s94, 0x80
	s_addc_u32 s95, s95, 0
	s_add_i32 s4, s4, s21
	s_mov_b32 m0, s4
	ds_read_b128 v[196:199], v160 offset:49152
	ds_read_b128 v[200:203], v160 offset:50176
	ds_read_b128 v[204:207], v160 offset:51200
	ds_read_b128 v[208:211], v160 offset:52224
	ds_read_b128 v[212:215], v160 offset:53248
	ds_read_b128 v[216:219], v160 offset:54272
	ds_read_b128 v[220:223], v160 offset:55296
	ds_read_b128 v[224:227], v160 offset:56320
	global_load_lds_dwordx4 v132, s[96:97]
	s_add_i32 m0, s4, 0x2000
	s_add_i32 s4, s25, s21
	global_load_lds_dwordx4 v136, s[96:97]
	s_mov_b32 m0, s4
	s_nop 0
	global_load_lds_dwordx4 v132, s[98:99]
	s_add_i32 m0, s4, 0x2000
	s_nop 0
	global_load_lds_dwordx4 v136, s[98:99]
	s_mov_b32 m0, s57
	s_nop 0
	global_load_lds_dwordx4 v130, s[94:95]
	s_mov_b32 m0, s58
	s_nop 0
	global_load_lds_dwordx4 v134, s[94:95]
	s_waitcnt vmcnt(8)
	s_waitcnt lgkmcnt(0)
	s_barrier
	s_setprio 1
	s_waitcnt lgkmcnt(0)
	v_mfma_f32_16x16x32_bf16 v[62:65], v[164:167], v[196:199], v[62:65]
	v_mfma_f32_16x16x32_bf16 v[54:57], v[172:175], v[196:199], v[54:57]
	v_mfma_f32_16x16x32_bf16 v[46:49], v[164:167], v[204:207], v[46:49]
	v_mfma_f32_16x16x32_bf16 v[38:41], v[172:175], v[204:207], v[38:41]
	v_mfma_f32_16x16x32_bf16 v[30:33], v[164:167], v[212:215], v[30:33]
	v_mfma_f32_16x16x32_bf16 v[22:25], v[172:175], v[212:215], v[22:25]
	v_mfma_f32_16x16x32_bf16 v[14:17], v[164:167], v[220:223], v[14:17]
	v_mfma_f32_16x16x32_bf16 v[6:9], v[172:175], v[220:223], v[6:9]
	v_mfma_f32_16x16x32_bf16 v[62:65], v[168:171], v[200:203], v[62:65]
	v_mfma_f32_16x16x32_bf16 v[54:57], v[176:179], v[200:203], v[54:57]
	v_mfma_f32_16x16x32_bf16 v[46:49], v[168:171], v[208:211], v[46:49]
	v_mfma_f32_16x16x32_bf16 v[38:41], v[176:179], v[208:211], v[38:41]
	v_mfma_f32_16x16x32_bf16 v[30:33], v[168:171], v[216:219], v[30:33]
	v_mfma_f32_16x16x32_bf16 v[22:25], v[176:179], v[216:219], v[22:25]
	v_mfma_f32_16x16x32_bf16 v[14:17], v[168:171], v[224:227], v[14:17]
	v_mfma_f32_16x16x32_bf16 v[6:9], v[176:179], v[224:227], v[6:9]
	s_setprio 0
	s_setprio 1
	v_mfma_f32_16x16x32_bf16 v[58:61], v[180:183], v[196:199], v[58:61]
	v_mfma_f32_16x16x32_bf16 v[50:53], v[188:191], v[196:199], v[50:53]
	v_mfma_f32_16x16x32_bf16 v[42:45], v[180:183], v[204:207], v[42:45]
	v_mfma_f32_16x16x32_bf16 v[34:37], v[188:191], v[204:207], v[34:37]
	v_mfma_f32_16x16x32_bf16 v[26:29], v[180:183], v[212:215], v[26:29]
	v_mfma_f32_16x16x32_bf16 v[18:21], v[188:191], v[212:215], v[18:21]
	v_mfma_f32_16x16x32_bf16 v[10:13], v[180:183], v[220:223], v[10:13]
	v_mfma_f32_16x16x32_bf16 v[2:5], v[188:191], v[220:223], v[2:5]
	v_mfma_f32_16x16x32_bf16 v[58:61], v[184:187], v[200:203], v[58:61]
	v_mfma_f32_16x16x32_bf16 v[50:53], v[192:195], v[200:203], v[50:53]
	v_mfma_f32_16x16x32_bf16 v[42:45], v[184:187], v[208:211], v[42:45]
	v_mfma_f32_16x16x32_bf16 v[34:37], v[192:195], v[208:211], v[34:37]
	v_mfma_f32_16x16x32_bf16 v[26:29], v[184:187], v[216:219], v[26:29]
	v_mfma_f32_16x16x32_bf16 v[18:21], v[192:195], v[216:219], v[18:21]
	v_mfma_f32_16x16x32_bf16 v[10:13], v[184:187], v[224:227], v[10:13]
	v_mfma_f32_16x16x32_bf16 v[2:5], v[192:195], v[224:227], v[2:5]
	s_setprio 0
	s_barrier
	v_cmp_ge_i32_e32 vcc, s5, v156
	s_mov_b32 s4, s5
	s_add_u32 s88, s88, 0x100
	s_addc_u32 s89, s89, 0
	s_add_u32 s86, s86, 0x100
	s_addc_u32 s87, s87, 0
	s_cbranch_vccnz .Lmy_kexit_11
.LBB0_2075:
	s_add_u32 s98, s86, 0x100
	s_addc_u32 s99, s87, 0
	s_cmp_eq_u32 s4, s100
	s_cselect_b64 s[94:95], s[90:91], s[98:99]
	s_cselect_b64 s[96:97], s[92:93], s[88:89]
	v_add_u32_e32 v157, s65, v141
	ds_read_b128 v[164:167], v157
	ds_read_b128 v[168:171], v157 offset:1024
	ds_read_b128 v[172:175], v157 offset:2048
	ds_read_b128 v[176:179], v157 offset:3072
	v_add_u32_e32 v157, s66, v141
	ds_read_b128 v[180:183], v157
	ds_read_b128 v[184:187], v157 offset:1024
	ds_read_b128 v[188:191], v157 offset:2048
	ds_read_b128 v[192:195], v157 offset:3072
	s_add_i32 s5, s4, 2
	s_nop 0
	s_add_i32 m0, s44, 0xc000
	ds_read_b128 v[196:199], v160
	ds_read_b128 v[200:203], v160 offset:1024
	ds_read_b128 v[204:207], v160 offset:2048
	ds_read_b128 v[208:211], v160 offset:3072
	ds_read_b128 v[212:215], v160 offset:4096
	ds_read_b128 v[216:219], v160 offset:5120
	ds_read_b128 v[220:223], v160 offset:6144
	ds_read_b128 v[224:227], v160 offset:7168
	global_load_lds_dwordx4 v144, s[86:87]
	s_add_i32 m0, s44, 0xe000
	s_nop 0
	global_load_lds_dwordx4 v142, s[86:87]
	s_waitcnt vmcnt(8)
	s_waitcnt lgkmcnt(0)
	s_barrier
	s_setprio 1
	s_waitcnt lgkmcnt(0)
	v_mfma_f32_16x16x32_bf16 v[122:125], v[164:167], v[196:199], v[122:125]
	v_mfma_f32_16x16x32_bf16 v[118:121], v[172:175], v[196:199], v[118:121]
	v_mfma_f32_16x16x32_bf16 v[110:113], v[164:167], v[204:207], v[110:113]
	v_mfma_f32_16x16x32_bf16 v[102:105], v[172:175], v[204:207], v[102:105]
	v_mfma_f32_16x16x32_bf16 v[94:97], v[164:167], v[212:215], v[94:97]
	v_mfma_f32_16x16x32_bf16 v[86:89], v[172:175], v[212:215], v[86:89]
	v_mfma_f32_16x16x32_bf16 v[78:81], v[164:167], v[220:223], v[78:81]
	v_mfma_f32_16x16x32_bf16 v[70:73], v[172:175], v[220:223], v[70:73]
	v_mfma_f32_16x16x32_bf16 v[122:125], v[168:171], v[200:203], v[122:125]
	v_mfma_f32_16x16x32_bf16 v[118:121], v[176:179], v[200:203], v[118:121]
	v_mfma_f32_16x16x32_bf16 v[110:113], v[168:171], v[208:211], v[110:113]
	v_mfma_f32_16x16x32_bf16 v[102:105], v[176:179], v[208:211], v[102:105]
	v_mfma_f32_16x16x32_bf16 v[94:97], v[168:171], v[216:219], v[94:97]
	v_mfma_f32_16x16x32_bf16 v[86:89], v[176:179], v[216:219], v[86:89]
	v_mfma_f32_16x16x32_bf16 v[78:81], v[168:171], v[224:227], v[78:81]
	v_mfma_f32_16x16x32_bf16 v[70:73], v[176:179], v[224:227], v[70:73]
	s_setprio 0
	s_setprio 1
	v_mfma_f32_16x16x32_bf16 v[126:129], v[180:183], v[196:199], v[126:129]
	v_mfma_f32_16x16x32_bf16 v[114:117], v[188:191], v[196:199], v[114:117]
	v_mfma_f32_16x16x32_bf16 v[106:109], v[180:183], v[204:207], v[106:109]
	v_mfma_f32_16x16x32_bf16 v[98:101], v[188:191], v[204:207], v[98:101]
	v_mfma_f32_16x16x32_bf16 v[90:93], v[180:183], v[212:215], v[90:93]
	v_mfma_f32_16x16x32_bf16 v[82:85], v[188:191], v[212:215], v[82:85]
	v_mfma_f32_16x16x32_bf16 v[74:77], v[180:183], v[220:223], v[74:77]
	v_mfma_f32_16x16x32_bf16 v[66:69], v[188:191], v[220:223], v[66:69]
	v_mfma_f32_16x16x32_bf16 v[126:129], v[184:187], v[200:203], v[126:129]
	v_mfma_f32_16x16x32_bf16 v[114:117], v[192:195], v[200:203], v[114:117]
	v_mfma_f32_16x16x32_bf16 v[106:109], v[184:187], v[208:211], v[106:109]
	v_mfma_f32_16x16x32_bf16 v[98:101], v[192:195], v[208:211], v[98:101]
	v_mfma_f32_16x16x32_bf16 v[90:93], v[184:187], v[216:219], v[90:93]
	v_mfma_f32_16x16x32_bf16 v[82:85], v[192:195], v[216:219], v[82:85]
	v_mfma_f32_16x16x32_bf16 v[74:77], v[184:187], v[224:227], v[74:77]
	v_mfma_f32_16x16x32_bf16 v[66:69], v[192:195], v[224:227], v[66:69]
	s_setprio 0
	s_barrier
	s_add_u32 s98, s96, 0xb0000
	s_addc_u32 s99, s97, 0
	s_add_i32 s4, s65, s21
	s_mov_b32 m0, s4
	ds_read_b128 v[196:199], v160 offset:16384
	ds_read_b128 v[200:203], v160 offset:17408
	ds_read_b128 v[204:207], v160 offset:18432
	ds_read_b128 v[208:211], v160 offset:19456
	ds_read_b128 v[212:215], v160 offset:20480
	ds_read_b128 v[216:219], v160 offset:21504
	ds_read_b128 v[220:223], v160 offset:22528
	ds_read_b128 v[224:227], v160 offset:23552
	global_load_lds_dwordx4 v132, s[96:97]
	s_add_i32 m0, s4, 0x2000
	s_add_i32 s4, s66, s21
	global_load_lds_dwordx4 v136, s[96:97]
	s_mov_b32 m0, s4
	s_nop 0
	global_load_lds_dwordx4 v132, s[98:99]
	s_add_i32 m0, s4, 0x2000
	s_nop 0
	global_load_lds_dwordx4 v136, s[98:99]
	s_mov_b32 m0, s44
	s_nop 0
	global_load_lds_dwordx4 v130, s[94:95]
	s_mov_b32 m0, s45
	s_nop 0
	global_load_lds_dwordx4 v134, s[94:95]
	s_waitcnt vmcnt(8)
	s_waitcnt lgkmcnt(0)
	s_barrier
	s_setprio 1
	s_waitcnt lgkmcnt(0)
	v_mfma_f32_16x16x32_bf16 v[62:65], v[164:167], v[196:199], v[62:65]
	v_mfma_f32_16x16x32_bf16 v[54:57], v[172:175], v[196:199], v[54:57]
	v_mfma_f32_16x16x32_bf16 v[46:49], v[164:167], v[204:207], v[46:49]
	v_mfma_f32_16x16x32_bf16 v[38:41], v[172:175], v[204:207], v[38:41]
	v_mfma_f32_16x16x32_bf16 v[30:33], v[164:167], v[212:215], v[30:33]
	v_mfma_f32_16x16x32_bf16 v[22:25], v[172:175], v[212:215], v[22:25]
	v_mfma_f32_16x16x32_bf16 v[14:17], v[164:167], v[220:223], v[14:17]
	v_mfma_f32_16x16x32_bf16 v[6:9], v[172:175], v[220:223], v[6:9]
	v_mfma_f32_16x16x32_bf16 v[62:65], v[168:171], v[200:203], v[62:65]
	v_mfma_f32_16x16x32_bf16 v[54:57], v[176:179], v[200:203], v[54:57]
	v_mfma_f32_16x16x32_bf16 v[46:49], v[168:171], v[208:211], v[46:49]
	v_mfma_f32_16x16x32_bf16 v[38:41], v[176:179], v[208:211], v[38:41]
	v_mfma_f32_16x16x32_bf16 v[30:33], v[168:171], v[216:219], v[30:33]
	v_mfma_f32_16x16x32_bf16 v[22:25], v[176:179], v[216:219], v[22:25]
	v_mfma_f32_16x16x32_bf16 v[14:17], v[168:171], v[224:227], v[14:17]
	v_mfma_f32_16x16x32_bf16 v[6:9], v[176:179], v[224:227], v[6:9]
	s_setprio 0
	s_setprio 1
	v_mfma_f32_16x16x32_bf16 v[58:61], v[180:183], v[196:199], v[58:61]
	v_mfma_f32_16x16x32_bf16 v[50:53], v[188:191], v[196:199], v[50:53]
	v_mfma_f32_16x16x32_bf16 v[42:45], v[180:183], v[204:207], v[42:45]
	v_mfma_f32_16x16x32_bf16 v[34:37], v[188:191], v[204:207], v[34:37]
	v_mfma_f32_16x16x32_bf16 v[26:29], v[180:183], v[212:215], v[26:29]
	v_mfma_f32_16x16x32_bf16 v[18:21], v[188:191], v[212:215], v[18:21]
	v_mfma_f32_16x16x32_bf16 v[10:13], v[180:183], v[220:223], v[10:13]
	v_mfma_f32_16x16x32_bf16 v[2:5], v[188:191], v[220:223], v[2:5]
	v_mfma_f32_16x16x32_bf16 v[58:61], v[184:187], v[200:203], v[58:61]
	v_mfma_f32_16x16x32_bf16 v[50:53], v[192:195], v[200:203], v[50:53]
	v_mfma_f32_16x16x32_bf16 v[42:45], v[184:187], v[208:211], v[42:45]
	v_mfma_f32_16x16x32_bf16 v[34:37], v[192:195], v[208:211], v[34:37]
	v_mfma_f32_16x16x32_bf16 v[26:29], v[184:187], v[216:219], v[26:29]
	v_mfma_f32_16x16x32_bf16 v[18:21], v[192:195], v[216:219], v[18:21]
	v_mfma_f32_16x16x32_bf16 v[10:13], v[184:187], v[224:227], v[10:13]
	v_mfma_f32_16x16x32_bf16 v[2:5], v[192:195], v[224:227], v[2:5]
	s_setprio 0
	s_barrier
	s_add_u32 s98, s94, 0xb0000
	s_addc_u32 s99, s95, 0
	s_add_i32 s4, 0, 0x18000
	v_add_u32_e32 v157, s4, v141
	s_add_i32 s25, 0, 0x1c000
	ds_read_b128 v[164:167], v157
	ds_read_b128 v[168:171], v157 offset:1024
	ds_read_b128 v[172:175], v157 offset:2048
	ds_read_b128 v[176:179], v157 offset:3072
	v_add_u32_e32 v157, s25, v141
	ds_read_b128 v[180:183], v157
	ds_read_b128 v[184:187], v157 offset:1024
	ds_read_b128 v[188:191], v157 offset:2048
	ds_read_b128 v[192:195], v157 offset:3072
	s_mov_b32 m0, s46
	ds_read_b128 v[196:199], v160 offset:32768
	ds_read_b128 v[200:203], v160 offset:33792
	ds_read_b128 v[204:207], v160 offset:34816
	ds_read_b128 v[208:211], v160 offset:35840
	ds_read_b128 v[212:215], v160 offset:36864
	ds_read_b128 v[216:219], v160 offset:37888
	ds_read_b128 v[220:223], v160 offset:38912
	ds_read_b128 v[224:227], v160 offset:39936
	global_load_lds_dwordx4 v130, s[98:99]
	s_mov_b32 m0, s47
	s_nop 0
	global_load_lds_dwordx4 v134, s[98:99]
	s_waitcnt vmcnt(8)
	s_waitcnt lgkmcnt(0)
	s_barrier
	s_setprio 1
	s_waitcnt lgkmcnt(0)
	v_mfma_f32_16x16x32_bf16 v[122:125], v[164:167], v[196:199], v[122:125]
	v_mfma_f32_16x16x32_bf16 v[118:121], v[172:175], v[196:199], v[118:121]
	v_mfma_f32_16x16x32_bf16 v[110:113], v[164:167], v[204:207], v[110:113]
	v_mfma_f32_16x16x32_bf16 v[102:105], v[172:175], v[204:207], v[102:105]
	v_mfma_f32_16x16x32_bf16 v[94:97], v[164:167], v[212:215], v[94:97]
	v_mfma_f32_16x16x32_bf16 v[86:89], v[172:175], v[212:215], v[86:89]
	v_mfma_f32_16x16x32_bf16 v[78:81], v[164:167], v[220:223], v[78:81]
	v_mfma_f32_16x16x32_bf16 v[70:73], v[172:175], v[220:223], v[70:73]
	v_mfma_f32_16x16x32_bf16 v[122:125], v[168:171], v[200:203], v[122:125]
	v_mfma_f32_16x16x32_bf16 v[118:121], v[176:179], v[200:203], v[118:121]
	v_mfma_f32_16x16x32_bf16 v[110:113], v[168:171], v[208:211], v[110:113]
	v_mfma_f32_16x16x32_bf16 v[102:105], v[176:179], v[208:211], v[102:105]
	v_mfma_f32_16x16x32_bf16 v[94:97], v[168:171], v[216:219], v[94:97]
	v_mfma_f32_16x16x32_bf16 v[86:89], v[176:179], v[216:219], v[86:89]
	v_mfma_f32_16x16x32_bf16 v[78:81], v[168:171], v[224:227], v[78:81]
	v_mfma_f32_16x16x32_bf16 v[70:73], v[176:179], v[224:227], v[70:73]
	s_setprio 0
	s_setprio 1
	v_mfma_f32_16x16x32_bf16 v[126:129], v[180:183], v[196:199], v[126:129]
	v_mfma_f32_16x16x32_bf16 v[114:117], v[188:191], v[196:199], v[114:117]
	v_mfma_f32_16x16x32_bf16 v[106:109], v[180:183], v[204:207], v[106:109]
	v_mfma_f32_16x16x32_bf16 v[98:101], v[188:191], v[204:207], v[98:101]
	v_mfma_f32_16x16x32_bf16 v[90:93], v[180:183], v[212:215], v[90:93]
	v_mfma_f32_16x16x32_bf16 v[82:85], v[188:191], v[212:215], v[82:85]
	v_mfma_f32_16x16x32_bf16 v[74:77], v[180:183], v[220:223], v[74:77]
	v_mfma_f32_16x16x32_bf16 v[66:69], v[188:191], v[220:223], v[66:69]
	v_mfma_f32_16x16x32_bf16 v[126:129], v[184:187], v[200:203], v[126:129]
	v_mfma_f32_16x16x32_bf16 v[114:117], v[192:195], v[200:203], v[114:117]
	v_mfma_f32_16x16x32_bf16 v[106:109], v[184:187], v[208:211], v[106:109]
	v_mfma_f32_16x16x32_bf16 v[98:101], v[192:195], v[208:211], v[98:101]
	v_mfma_f32_16x16x32_bf16 v[90:93], v[184:187], v[216:219], v[90:93]
	v_mfma_f32_16x16x32_bf16 v[82:85], v[192:195], v[216:219], v[82:85]
	v_mfma_f32_16x16x32_bf16 v[74:77], v[184:187], v[224:227], v[74:77]
	v_mfma_f32_16x16x32_bf16 v[66:69], v[192:195], v[224:227], v[66:69]
	s_setprio 0
	s_barrier
	s_add_u32 s96, s96, 0x80
	s_addc_u32 s97, s97, 0
	s_add_u32 s98, s96, 0xb0000
	s_addc_u32 s99, s97, 0
	s_add_u32 s94, s94, 0x80
	s_addc_u32 s95, s95, 0
	s_add_i32 s4, s4, s21
	s_mov_b32 m0, s4
	ds_read_b128 v[196:199], v160 offset:49152
	ds_read_b128 v[200:203], v160 offset:50176
	ds_read_b128 v[204:207], v160 offset:51200
	ds_read_b128 v[208:211], v160 offset:52224
	ds_read_b128 v[212:215], v160 offset:53248
	ds_read_b128 v[216:219], v160 offset:54272
	ds_read_b128 v[220:223], v160 offset:55296
	ds_read_b128 v[224:227], v160 offset:56320
	global_load_lds_dwordx4 v132, s[96:97]
	s_add_i32 m0, s4, 0x2000
	s_add_i32 s4, s25, s21
	global_load_lds_dwordx4 v136, s[96:97]
	s_mov_b32 m0, s4
	s_nop 0
	global_load_lds_dwordx4 v132, s[98:99]
	s_add_i32 m0, s4, 0x2000
	s_nop 0
	global_load_lds_dwordx4 v136, s[98:99]
	s_mov_b32 m0, s57
	s_nop 0
	global_load_lds_dwordx4 v130, s[94:95]
	s_mov_b32 m0, s58
	s_nop 0
	global_load_lds_dwordx4 v134, s[94:95]
	s_waitcnt vmcnt(8)
	s_waitcnt lgkmcnt(0)
	s_barrier
	s_setprio 1
	s_waitcnt lgkmcnt(0)
	v_mfma_f32_16x16x32_bf16 v[62:65], v[164:167], v[196:199], v[62:65]
	v_mfma_f32_16x16x32_bf16 v[54:57], v[172:175], v[196:199], v[54:57]
	v_mfma_f32_16x16x32_bf16 v[46:49], v[164:167], v[204:207], v[46:49]
	v_mfma_f32_16x16x32_bf16 v[38:41], v[172:175], v[204:207], v[38:41]
	v_mfma_f32_16x16x32_bf16 v[30:33], v[164:167], v[212:215], v[30:33]
	v_mfma_f32_16x16x32_bf16 v[22:25], v[172:175], v[212:215], v[22:25]
	v_mfma_f32_16x16x32_bf16 v[14:17], v[164:167], v[220:223], v[14:17]
	v_mfma_f32_16x16x32_bf16 v[6:9], v[172:175], v[220:223], v[6:9]
	v_mfma_f32_16x16x32_bf16 v[62:65], v[168:171], v[200:203], v[62:65]
	v_mfma_f32_16x16x32_bf16 v[54:57], v[176:179], v[200:203], v[54:57]
	v_mfma_f32_16x16x32_bf16 v[46:49], v[168:171], v[208:211], v[46:49]
	v_mfma_f32_16x16x32_bf16 v[38:41], v[176:179], v[208:211], v[38:41]
	v_mfma_f32_16x16x32_bf16 v[30:33], v[168:171], v[216:219], v[30:33]
	v_mfma_f32_16x16x32_bf16 v[22:25], v[176:179], v[216:219], v[22:25]
	v_mfma_f32_16x16x32_bf16 v[14:17], v[168:171], v[224:227], v[14:17]
	v_mfma_f32_16x16x32_bf16 v[6:9], v[176:179], v[224:227], v[6:9]
	s_setprio 0
	s_setprio 1
	v_mfma_f32_16x16x32_bf16 v[58:61], v[180:183], v[196:199], v[58:61]
	v_mfma_f32_16x16x32_bf16 v[50:53], v[188:191], v[196:199], v[50:53]
	v_mfma_f32_16x16x32_bf16 v[42:45], v[180:183], v[204:207], v[42:45]
	v_mfma_f32_16x16x32_bf16 v[34:37], v[188:191], v[204:207], v[34:37]
	v_mfma_f32_16x16x32_bf16 v[26:29], v[180:183], v[212:215], v[26:29]
	v_mfma_f32_16x16x32_bf16 v[18:21], v[188:191], v[212:215], v[18:21]
	v_mfma_f32_16x16x32_bf16 v[10:13], v[180:183], v[220:223], v[10:13]
	v_mfma_f32_16x16x32_bf16 v[2:5], v[188:191], v[220:223], v[2:5]
	v_mfma_f32_16x16x32_bf16 v[58:61], v[184:187], v[200:203], v[58:61]
	v_mfma_f32_16x16x32_bf16 v[50:53], v[192:195], v[200:203], v[50:53]
	v_mfma_f32_16x16x32_bf16 v[42:45], v[184:187], v[208:211], v[42:45]
	v_mfma_f32_16x16x32_bf16 v[34:37], v[192:195], v[208:211], v[34:37]
	v_mfma_f32_16x16x32_bf16 v[26:29], v[184:187], v[216:219], v[26:29]
	v_mfma_f32_16x16x32_bf16 v[18:21], v[192:195], v[216:219], v[18:21]
	v_mfma_f32_16x16x32_bf16 v[10:13], v[184:187], v[224:227], v[10:13]
	v_mfma_f32_16x16x32_bf16 v[2:5], v[192:195], v[224:227], v[2:5]
	s_setprio 0
	s_barrier
	v_cmp_ge_i32_e32 vcc, s5, v156
	s_mov_b32 s4, s5
	s_add_u32 s88, s88, 0x100
	s_addc_u32 s89, s89, 0
	s_add_u32 s86, s86, 0x100
	s_addc_u32 s87, s87, 0
	s_cbranch_vccz .LBB0_2075

	.amdhsa_kernel _Z10fwd_kernel4Args
		.amdhsa_group_segment_fixed_size 0
		.amdhsa_private_segment_fixed_size 0
		.amdhsa_kernarg_size 448
		.amdhsa_user_sgpr_count 2
		.amdhsa_user_sgpr_dispatch_ptr 0
		.amdhsa_user_sgpr_queue_ptr 0
		.amdhsa_user_sgpr_kernarg_segment_ptr 1
		.amdhsa_user_sgpr_dispatch_id 0
		.amdhsa_user_sgpr_kernarg_preload_length 0
		.amdhsa_user_sgpr_kernarg_preload_offset 0
		.amdhsa_user_sgpr_private_segment_size 0
		.amdhsa_uses_dynamic_stack 0
		.amdhsa_enable_private_segment 0
		.amdhsa_system_sgpr_workgroup_id_x 1
		.amdhsa_system_sgpr_workgroup_id_y 0
		.amdhsa_system_sgpr_workgroup_id_z 0
		.amdhsa_system_sgpr_workgroup_info 0
		.amdhsa_system_vgpr_workitem_id 2
		.amdhsa_next_free_vgpr 240
		.amdhsa_next_free_sgpr 102
		.amdhsa_accum_offset 240
		.amdhsa_reserve_vcc 1
		.amdhsa_float_round_mode_32 0
		.amdhsa_float_round_mode_16_64 0
		.amdhsa_float_denorm_mode_32 3
		.amdhsa_float_denorm_mode_16_64 3
		.amdhsa_dx10_clamp 1
		.amdhsa_ieee_mode 1
		.amdhsa_fp16_overflow 0
		.amdhsa_tg_split 0
		.amdhsa_exception_fp_ieee_invalid_op 0
		.amdhsa_exception_fp_denorm_src 0
		.amdhsa_exception_fp_ieee_div_zero 0
		.amdhsa_exception_fp_ieee_overflow 0
		.amdhsa_exception_fp_ieee_underflow 0
		.amdhsa_exception_fp_ieee_inexact 0
		.amdhsa_exception_int_div_zero 0
	.end_amdhsa_kernel

amdhsa.kernels:
  - .agpr_count:     0
    .args:
      - .offset:         0
        .size:           192
        .value_kind:     by_value
      - .offset:         192
        .size:           4
        .value_kind:     hidden_block_count_x
      - .offset:         196
        .size:           4
        .value_kind:     hidden_block_count_y
      - .offset:         200
        .size:           4
        .value_kind:     hidden_block_count_z
      - .offset:         204
        .size:           2
        .value_kind:     hidden_group_size_x
      - .offset:         206
        .size:           2
        .value_kind:     hidden_group_size_y
      - .offset:         208
        .size:           2
        .value_kind:     hidden_group_size_z
      - .offset:         210
        .size:           2
        .value_kind:     hidden_remainder_x
      - .offset:         212
        .size:           2
        .value_kind:     hidden_remainder_y
      - .offset:         214
        .size:           2
        .value_kind:     hidden_remainder_z
      - .offset:         232
        .size:           8
        .value_kind:     hidden_global_offset_x
      - .offset:         240
        .size:           8
        .value_kind:     hidden_global_offset_y
      - .offset:         248
        .size:           8
        .value_kind:     hidden_global_offset_z
      - .offset:         256
        .size:           2
        .value_kind:     hidden_grid_dims
      - .offset:         280
        .size:           8
        .value_kind:     hidden_multigrid_sync_arg
      - .offset:         312
        .size:           4
        .value_kind:     hidden_dynamic_lds_size
    .group_segment_fixed_size: 0
    .kernarg_segment_align: 8
    .kernarg_segment_size: 448
    .language:       OpenCL C
    .language_version:
      - 2
      - 0
    .max_flat_workgroup_size: 512
    .name:           _Z10fwd_kernel4Args
    .private_segment_fixed_size: 0
    .sgpr_count:     108
    .sgpr_spill_count: 0
    .symbol:         _Z10fwd_kernel4Args.kd
    .uniform_work_group_size: 1
    .uses_dynamic_stack: false
    .vgpr_count:     240
    .vgpr_spill_count: 0
    .wavefront_size: 64
